# 16-byte global stores made write-through (sc1) to shrink the L2 write-back at grid barriers
# baseline (speedup 1.0000x reference)
.LBB0_20:
	s_or_b64 exec, exec, s[4:5]
	s_waitcnt vmcnt(0)
	ds_write_b32 v21, v12
	ds_write_b32 v21, v11 offset:1040
	ds_write_b32 v21, v26 offset:2080
	ds_write_b32 v21, v25 offset:3120
	ds_write_b32 v21, v28 offset:4160
	ds_write_b32 v21, v27 offset:5200
	ds_write_b32 v21, v30 offset:6240
	ds_write_b32 v21, v29 offset:7280
	ds_write_b32 v21, v32 offset:8320
	ds_write_b32 v21, v31 offset:9360
	ds_write_b32 v21, v34 offset:10400
	ds_write_b32 v21, v33 offset:11440
	ds_write_b32 v21, v36 offset:12480
	ds_write_b32 v21, v35 offset:13520
	ds_write_b32 v21, v38 offset:14560
	ds_write_b32 v21, v37 offset:15600
	v_ashrrev_i32_e32 v11, 31, v10
	s_waitcnt lgkmcnt(0)
	s_barrier
	v_lshl_add_u64 v[4:5], v[10:11], 1, v[4:5]
	ds_read2_b32 v[8:9], v19 offset1:32
	ds_read2_b32 v[10:11], v19 offset0:65 offset1:97
	ds_read2_b32 v[12:13], v19 offset0:130 offset1:162
	ds_read2_b32 v[24:25], v19 offset0:195 offset1:227
	v_add_u32_e32 v6, 0x400, v19
	ds_read2_b32 v[26:27], v6 offset0:4 offset1:36
	ds_read2_b32 v[28:29], v6 offset0:69 offset1:101
	ds_read2_b32 v[30:31], v6 offset0:134 offset1:166
	ds_read2_b32 v[32:33], v6 offset0:199 offset1:231
	v_lshl_add_u64 v[34:35], v[4:5], 0, v[0:1]
	s_waitcnt lgkmcnt(6)
	v_cvt_pk_bf16_f32 v4, v8, v10
	v_or_b32_e32 v8, v23, v18
	v_ashrrev_i32_e32 v10, 31, v23
	v_mul_lo_u32 v10, v10, v22
	v_mad_u64_u32 v[36:37], s[4:5], v8, v22, 0
	v_add_u32_e32 v37, v37, v10
	s_waitcnt lgkmcnt(4)
	v_cvt_pk_bf16_f32 v5, v12, v24
	s_waitcnt lgkmcnt(2)
	v_cvt_pk_bf16_f32 v6, v26, v28
	s_waitcnt lgkmcnt(0)
	v_cvt_pk_bf16_f32 v7, v30, v32
	v_lshl_add_u64 v[36:37], v[36:37], 1, v[34:35]
	v_or_b32_e32 v8, v23, v20
	global_store_dwordx4 v[36:37], v[4:7], off sc1
	s_add_i32 s3, s3, s16
	s_cmpk_lt_i32 s3, 0x1740
	v_cvt_pk_bf16_f32 v4, v9, v11
	v_mad_u64_u32 v[8:9], s[4:5], v8, v22, 0
	v_add_u32_e32 v9, v9, v10
	v_cvt_pk_bf16_f32 v5, v13, v25
	v_cvt_pk_bf16_f32 v6, v27, v29
	v_cvt_pk_bf16_f32 v7, v31, v33
	v_lshl_add_u64 v[8:9], v[8:9], 1, v[34:35]
	global_store_dwordx4 v[8:9], v[4:7], off sc1
	s_cbranch_scc0 .LBB0_75

.LBB0_77:
	s_or_b64 exec, exec, s[4:5]
	s_waitcnt vmcnt(0)
	v_mul_f32_e32 v15, v13, v15
	v_mul_f32_e32 v18, 0x3fb8aa3b, v15
	v_fma_f32 v19, v15, s19, -v18
	v_rndne_f32_e32 v21, v18
	v_fmac_f32_e32 v19, 0x32a5705f, v15
	v_sub_f32_e32 v18, v18, v21
	v_add_f32_e32 v18, v18, v19
	v_cvt_i32_f32_e32 v19, v21
	v_exp_f32_e32 v18, v18
	v_cmp_ngt_f32_e32 vcc, s20, v15
	s_brev_b32 s4, 1
	s_load_dwordx16 s[68:83], s[0:1], 0x80
	v_ldexp_f32 v18, v18, v19
	v_cndmask_b32_e32 v18, 0, v18, vcc
	v_cmp_nlt_f32_e32 vcc, s21, v15
	v_mul_f32_e32 v15, v17, v17
	s_nop 0
	v_cndmask_b32_e32 v21, v6, v18, vcc
	v_fmamk_f32 v18, v15, 0xb94c1982, v7
	v_fmaak_f32 v18, v15, v18, 0xbe2aaa9d
	v_mul_f32_e32 v18, v15, v18
	v_fmac_f32_e32 v17, v17, v18
	v_fmamk_f32 v18, v15, 0x37d75334, v8
	v_fmaak_f32 v18, v15, v18, 0x3d2aabf7
	v_fmaak_f32 v18, v15, v18, 0xbf000004
	v_fma_f32 v15, v15, v18, 1.0
	v_and_b32_e32 v18, 1, v16
	v_cmp_eq_u32_e32 vcc, 0, v18
	v_lshlrev_b32_e32 v16, 30, v16
	s_nop 0
	v_cndmask_b32_e64 v15, -v17, v15, vcc
	v_bitop3_b32 v15, v16, v15, s4 bitop3:0x6c
	s_movk_i32 s4, 0x1f8
	v_cmp_class_f32_e64 vcc, v3, s4
	v_xor_b32_e32 v3, v14, v3
	s_nop 0
	v_cndmask_b32_e32 v22, v11, v15, vcc
	v_mul_f32_e32 v15, v20, v20
	v_fmamk_f32 v17, v15, 0xb94c1982, v7
	v_fmaak_f32 v17, v15, v17, 0xbe2aaa9d
	v_mul_f32_e32 v17, v15, v17
	v_fmac_f32_e32 v20, v20, v17
	v_fmamk_f32 v17, v15, 0x37d75334, v8
	v_fmaak_f32 v17, v15, v17, 0x3d2aabf7
	v_fmaak_f32 v17, v15, v17, 0xbf000004
	v_fma_f32 v15, v15, v17, 1.0
	v_and_b32_e32 v17, 1, v4
	v_lshlrev_b32_e32 v4, 30, v4
	v_cmp_eq_u32_e64 s[4:5], 0, v17
	v_and_b32_e32 v4, 0x80000000, v4
	v_xor_b32_e32 v3, v3, v4
	v_cndmask_b32_e64 v15, v15, v20, s[4:5]
	v_mul_f32_e32 v16, v21, v22
	v_xor_b32_e32 v3, v3, v15
	v_lshl_add_u64 v[14:15], v[0:1], 2, s[40:41]
	s_movk_i32 s4, 0x4000
	v_cndmask_b32_e32 v3, v11, v3, vcc
	global_store_dword v[14:15], v16, off
	v_add_co_u32_e32 v14, vcc, s4, v14
	v_mul_f32_e32 v4, v21, v3
	s_nop 0
	v_addc_co_u32_e32 v15, vcc, 0, v15, vcc
	v_ashrrev_i32_e32 v3, 31, v2
	global_store_dword v[14:15], v4, off
	v_lshlrev_b64 v[14:15], 2, v[2:3]
	s_waitcnt lgkmcnt(0)
	v_lshl_add_u64 v[18:19], s[78:79], 0, v[14:15]
	v_lshl_add_u64 v[16:17], s[76:77], 0, v[14:15]
	global_load_dwordx4 v[40:43], v[16:17], off
	global_load_dwordx4 v[44:47], v[16:17], off offset:16
	global_load_dwordx4 v[48:51], v[16:17], off offset:32
	global_load_dwordx4 v[52:55], v[16:17], off offset:48
	global_load_dwordx4 v[56:59], v[18:19], off
	global_load_dwordx4 v[60:63], v[18:19], off offset:16
	global_load_dwordx4 v[64:67], v[18:19], off offset:32
	global_load_dwordx4 v[68:71], v[18:19], off offset:48
	v_fma_f32 v20, v21, v22, -1.0
	v_mul_f32_e32 v21, v12, v12
	v_mul_f32_e32 v22, v12, v4
	v_fmac_f32_e32 v21, v13, v13
	v_fmac_f32_e32 v22, v13, v20
	v_div_scale_f32 v23, s[4:5], v21, v21, v22
	v_rcp_f32_e32 v24, v23
	v_mul_f32_e32 v12, v12, v20
	v_fma_f32 v4, v13, v4, -v12
	v_div_scale_f32 v12, s[4:5], v21, v21, v4
	v_fma_f32 v25, -v23, v24, 1.0
	v_fmac_f32_e32 v24, v25, v24
	v_div_scale_f32 v25, vcc, v22, v21, v22
	v_mul_f32_e32 v26, v25, v24
	v_fma_f32 v27, -v23, v26, v25
	v_rcp_f32_e32 v13, v12
	v_fmac_f32_e32 v26, v27, v24
	v_fma_f32 v23, -v23, v26, v25
	v_div_fmas_f32 v20, v23, v24, v26
	v_div_fixup_f32 v20, v20, v21, v22
	v_fma_f32 v22, -v12, v13, 1.0
	v_fmac_f32_e32 v13, v22, v13
	v_div_scale_f32 v22, vcc, v4, v21, v4
	v_mul_f32_e32 v23, v22, v13
	v_fma_f32 v24, -v12, v23, v22
	v_fmac_f32_e32 v23, v24, v13
	v_fma_f32 v12, -v12, v23, v22
	v_div_fmas_f32 v12, v12, v13, v23
	v_div_fixup_f32 v4, v12, v21, v4
	s_mov_b32 s4, 0x40000
	v_add_u32_e32 v0, s3, v0
	v_add_u32_e32 v2, s18, v2
	v_lshl_add_u64 v[12:13], s[42:43], 0, v[14:15]
	s_nop 0
	v_add_co_u32_e32 v14, vcc, s4, v12
	s_nop 1
	v_addc_co_u32_e32 v15, vcc, 0, v13, vcc
	s_movk_i32 s4, 0xfff
	v_cmp_lt_i32_e32 vcc, s4, v0
	s_or_b64 s[12:13], vcc, s[12:13]
	s_waitcnt vmcnt(0)
	v_mul_f32_e32 v72, v56, v4
	v_mul_f32_e32 v56, v56, v20
	v_fma_f32 v72, v40, v20, -v72
	v_fmac_f32_e32 v56, v40, v4
	v_mul_f32_e32 v73, v57, v4
	v_mul_f32_e32 v57, v57, v20
	v_fma_f32 v73, v41, v20, -v73
	v_fmac_f32_e32 v57, v41, v4
	v_mul_f32_e32 v74, v58, v4
	v_mul_f32_e32 v58, v58, v20
	v_fma_f32 v74, v42, v20, -v74
	v_fmac_f32_e32 v58, v42, v4
	v_mul_f32_e32 v75, v59, v4
	v_mul_f32_e32 v59, v59, v20
	v_fma_f32 v75, v43, v20, -v75
	v_fmac_f32_e32 v59, v43, v4
	v_mul_f32_e32 v76, v60, v4
	v_mul_f32_e32 v60, v60, v20
	v_fma_f32 v76, v44, v20, -v76
	v_fmac_f32_e32 v60, v44, v4
	v_mul_f32_e32 v77, v61, v4
	v_mul_f32_e32 v61, v61, v20
	v_fma_f32 v77, v45, v20, -v77
	v_fmac_f32_e32 v61, v45, v4
	v_mul_f32_e32 v78, v62, v4
	v_mul_f32_e32 v62, v62, v20
	v_fma_f32 v78, v46, v20, -v78
	v_fmac_f32_e32 v62, v46, v4
	v_mul_f32_e32 v79, v63, v4
	v_mul_f32_e32 v63, v63, v20
	v_fma_f32 v79, v47, v20, -v79
	v_fmac_f32_e32 v63, v47, v4
	v_mul_f32_e32 v80, v64, v4
	v_mul_f32_e32 v64, v64, v20
	v_fma_f32 v80, v48, v20, -v80
	v_fmac_f32_e32 v64, v48, v4
	v_mul_f32_e32 v81, v65, v4
	v_mul_f32_e32 v65, v65, v20
	v_fma_f32 v81, v49, v20, -v81
	v_fmac_f32_e32 v65, v49, v4
	v_mul_f32_e32 v82, v66, v4
	v_mul_f32_e32 v66, v66, v20
	v_fma_f32 v82, v50, v20, -v82
	v_fmac_f32_e32 v66, v50, v4
	v_mul_f32_e32 v83, v67, v4
	v_mul_f32_e32 v67, v67, v20
	v_fma_f32 v83, v51, v20, -v83
	v_fmac_f32_e32 v67, v51, v4
	v_mul_f32_e32 v84, v68, v4
	v_mul_f32_e32 v68, v68, v20
	v_fma_f32 v84, v52, v20, -v84
	v_fmac_f32_e32 v68, v52, v4
	v_mul_f32_e32 v85, v69, v4
	v_mul_f32_e32 v69, v69, v20
	v_fma_f32 v85, v53, v20, -v85
	v_fmac_f32_e32 v69, v53, v4
	v_mul_f32_e32 v86, v70, v4
	v_mul_f32_e32 v70, v70, v20
	v_fma_f32 v86, v54, v20, -v86
	v_fmac_f32_e32 v70, v54, v4
	v_mul_f32_e32 v87, v71, v4
	v_mul_f32_e32 v71, v71, v20
	v_fma_f32 v87, v55, v20, -v87
	v_fmac_f32_e32 v71, v55, v4
	global_store_dwordx4 v[12:13], v[72:75], off sc1
	global_store_dwordx4 v[12:13], v[76:79], off offset:16 sc1
	global_store_dwordx4 v[12:13], v[80:83], off offset:32 sc1
	global_store_dwordx4 v[12:13], v[84:87], off offset:48 sc1
	global_store_dwordx4 v[14:15], v[56:59], off sc1
	global_store_dwordx4 v[14:15], v[60:63], off offset:16 sc1
	global_store_dwordx4 v[14:15], v[64:67], off offset:32 sc1
	global_store_dwordx4 v[14:15], v[68:71], off offset:48 sc1
	s_andn2_b64 exec, exec, s[12:13]
	s_cbranch_execz .LBB0_86

.LBB0_155:
	ds_read_b128 v[154:157], v150
	ds_read_b128 v[158:161], v150 offset:1024
	ds_read_b128 v[162:165], v150 offset:2048
	ds_read_b128 v[166:169], v150 offset:3072
	s_add_u32 s26, s20, 0xfffc0080
	s_addc_u32 s27, s21, -1
	s_cmp_eq_u32 s86, 12
	s_cselect_b32 s29, s15, s27
	s_cselect_b32 s28, s82, s26
	s_cselect_b32 s27, s13, s85
	s_cselect_b32 s26, s83, s84
	v_lshl_add_u64 v[202:203], s[20:21], 0, v[138:139]
	s_add_i32 m0, s11, 0xc000
	ds_read_b128 v[170:173], v151
	ds_read_b128 v[174:177], v151 offset:1024
	ds_read_b128 v[178:181], v151 offset:2048
	ds_read_b128 v[182:185], v151 offset:3072
	ds_read_b128 v[186:189], v151 offset:4096
	ds_read_b128 v[190:193], v151 offset:5120
	ds_read_b128 v[194:197], v151 offset:6144
	ds_read_b128 v[198:201], v151 offset:7168
	global_load_lds_dwordx4 v[202:203], off
	v_lshl_add_u64 v[202:203], s[20:21], 0, v[140:141]
	s_add_i32 m0, s11, 0xe000
	s_nop 0
	global_load_lds_dwordx4 v[202:203], off
	s_waitcnt lgkmcnt(8)
	s_barrier
	s_waitcnt lgkmcnt(0)
	s_setprio 1
	s_waitcnt lgkmcnt(0)
	v_mfma_f32_16x16x32_bf16 v[124:127], v[154:157], v[170:173], v[124:127]
	v_mfma_f32_16x16x32_bf16 v[120:123], v[162:165], v[170:173], v[120:123]
	v_mfma_f32_16x16x32_bf16 v[116:119], v[154:157], v[178:181], v[116:119]
	v_mfma_f32_16x16x32_bf16 v[112:115], v[162:165], v[178:181], v[112:115]
	v_mfma_f32_16x16x32_bf16 v[100:103], v[154:157], v[186:189], v[100:103]
	v_mfma_f32_16x16x32_bf16 v[96:99], v[162:165], v[186:189], v[96:99]
	v_mfma_f32_16x16x32_bf16 v[84:87], v[154:157], v[194:197], v[84:87]
	v_mfma_f32_16x16x32_bf16 v[80:83], v[162:165], v[194:197], v[80:83]
	v_mfma_f32_16x16x32_bf16 v[124:127], v[158:161], v[174:177], v[124:127]
	v_mfma_f32_16x16x32_bf16 v[120:123], v[166:169], v[174:177], v[120:123]
	v_mfma_f32_16x16x32_bf16 v[116:119], v[158:161], v[182:185], v[116:119]
	v_mfma_f32_16x16x32_bf16 v[112:115], v[166:169], v[182:185], v[112:115]
	v_mfma_f32_16x16x32_bf16 v[100:103], v[158:161], v[190:193], v[100:103]
	v_mfma_f32_16x16x32_bf16 v[96:99], v[166:169], v[190:193], v[96:99]
	v_mfma_f32_16x16x32_bf16 v[84:87], v[158:161], v[198:201], v[84:87]
	v_mfma_f32_16x16x32_bf16 v[80:83], v[166:169], v[198:201], v[80:83]
	s_setprio 0
	s_barrier
	s_add_i32 s87, s72, s34
	v_lshl_add_u64 v[218:219], s[26:27], 0, v[134:135]
	s_mov_b32 m0, s87
	ds_read_b128 v[202:205], v152
	ds_read_b128 v[206:209], v152 offset:1024
	ds_read_b128 v[210:213], v152 offset:2048
	ds_read_b128 v[214:217], v152 offset:3072
	global_load_lds_dwordx4 v[218:219], off
	v_lshl_add_u64 v[220:221], s[26:27], 0, v[130:131]
	s_add_i32 m0, s87, 0x2000
	s_nop 0
	global_load_lds_dwordx4 v[220:221], off
	s_barrier
	s_waitcnt lgkmcnt(0)
	s_setprio 1
	s_waitcnt lgkmcnt(0)
	v_mfma_f32_16x16x32_bf16 v[108:111], v[202:205], v[170:173], v[108:111]
	v_mfma_f32_16x16x32_bf16 v[104:107], v[210:213], v[170:173], v[104:107]
	v_mfma_f32_16x16x32_bf16 v[92:95], v[202:205], v[178:181], v[92:95]
	v_mfma_f32_16x16x32_bf16 v[88:91], v[210:213], v[178:181], v[88:91]
	v_mfma_f32_16x16x32_bf16 v[76:79], v[202:205], v[186:189], v[76:79]
	v_mfma_f32_16x16x32_bf16 v[72:75], v[210:213], v[186:189], v[72:75]
	v_mfma_f32_16x16x32_bf16 v[68:71], v[202:205], v[194:197], v[68:71]
	v_mfma_f32_16x16x32_bf16 v[64:67], v[210:213], v[194:197], v[64:67]
	v_mfma_f32_16x16x32_bf16 v[108:111], v[206:209], v[174:177], v[108:111]
	v_mfma_f32_16x16x32_bf16 v[104:107], v[214:217], v[174:177], v[104:107]
	v_mfma_f32_16x16x32_bf16 v[92:95], v[206:209], v[182:185], v[92:95]
	v_mfma_f32_16x16x32_bf16 v[88:91], v[214:217], v[182:185], v[88:91]
	v_mfma_f32_16x16x32_bf16 v[76:79], v[206:209], v[190:193], v[76:79]
	v_mfma_f32_16x16x32_bf16 v[72:75], v[214:217], v[190:193], v[72:75]
	v_mfma_f32_16x16x32_bf16 v[68:71], v[206:209], v[198:201], v[68:71]
	v_mfma_f32_16x16x32_bf16 v[64:67], v[214:217], v[198:201], v[64:67]
	s_setprio 0
	s_mov_b32 m0, s11
	v_lshl_add_u64 v[222:223], s[28:29], 0, v[136:137]
	s_barrier
	ds_read_b128 v[170:173], v151 offset:16384
	ds_read_b128 v[174:177], v151 offset:17408
	ds_read_b128 v[178:181], v151 offset:18432
	ds_read_b128 v[182:185], v151 offset:19456
	ds_read_b128 v[186:189], v151 offset:20480
	ds_read_b128 v[190:193], v151 offset:21504
	ds_read_b128 v[194:197], v151 offset:22528
	ds_read_b128 v[198:201], v151 offset:23552
	global_load_lds_dwordx4 v[222:223], off
	v_lshl_add_u64 v[224:225], s[28:29], 0, v[132:133]
	s_mov_b32 m0, s35
	s_nop 0
	global_load_lds_dwordx4 v[224:225], off
	s_barrier
	s_waitcnt lgkmcnt(0)
	s_setprio 1
	s_waitcnt lgkmcnt(0)
	v_mfma_f32_16x16x32_bf16 v[60:63], v[154:157], v[170:173], v[60:63]
	v_mfma_f32_16x16x32_bf16 v[56:59], v[162:165], v[170:173], v[56:59]
	v_mfma_f32_16x16x32_bf16 v[52:55], v[154:157], v[178:181], v[52:55]
	v_mfma_f32_16x16x32_bf16 v[48:51], v[162:165], v[178:181], v[48:51]
	v_mfma_f32_16x16x32_bf16 v[36:39], v[154:157], v[186:189], v[36:39]
	v_mfma_f32_16x16x32_bf16 v[32:35], v[162:165], v[186:189], v[32:35]
	v_mfma_f32_16x16x32_bf16 v[20:23], v[154:157], v[194:197], v[20:23]
	v_mfma_f32_16x16x32_bf16 v[16:19], v[162:165], v[194:197], v[16:19]
	v_mfma_f32_16x16x32_bf16 v[60:63], v[158:161], v[174:177], v[60:63]
	v_mfma_f32_16x16x32_bf16 v[56:59], v[166:169], v[174:177], v[56:59]
	v_mfma_f32_16x16x32_bf16 v[52:55], v[158:161], v[182:185], v[52:55]
	v_mfma_f32_16x16x32_bf16 v[48:51], v[166:169], v[182:185], v[48:51]
	v_mfma_f32_16x16x32_bf16 v[36:39], v[158:161], v[190:193], v[36:39]
	v_mfma_f32_16x16x32_bf16 v[32:35], v[166:169], v[190:193], v[32:35]
	v_mfma_f32_16x16x32_bf16 v[20:23], v[158:161], v[198:201], v[20:23]
	v_mfma_f32_16x16x32_bf16 v[16:19], v[166:169], v[198:201], v[16:19]
	s_setprio 0
	s_barrier
	s_add_u32 s88, s26, 0x40000
	s_addc_u32 s89, s27, 0
	s_add_i32 s87, s73, s34
	v_lshl_add_u64 v[154:155], s[88:89], 0, v[134:135]
	s_mov_b32 m0, s87
	s_nop 0
	global_load_lds_dwordx4 v[154:155], off
	v_lshl_add_u64 v[154:155], s[88:89], 0, v[130:131]
	s_add_i32 m0, s87, 0x2000
	s_nop 0
	global_load_lds_dwordx4 v[154:155], off
	s_waitcnt vmcnt(6)
	s_barrier
	s_setprio 1
	v_mfma_f32_16x16x32_bf16 v[44:47], v[202:205], v[170:173], v[44:47]
	v_mfma_f32_16x16x32_bf16 v[40:43], v[210:213], v[170:173], v[40:43]
	v_mfma_f32_16x16x32_bf16 v[28:31], v[202:205], v[178:181], v[28:31]
	v_mfma_f32_16x16x32_bf16 v[24:27], v[210:213], v[178:181], v[24:27]
	v_mfma_f32_16x16x32_bf16 v[12:15], v[202:205], v[186:189], v[12:15]
	v_mfma_f32_16x16x32_bf16 v[8:11], v[210:213], v[186:189], v[8:11]
	v_mfma_f32_16x16x32_bf16 v[4:7], v[202:205], v[194:197], v[4:7]
	v_mfma_f32_16x16x32_bf16 v[0:3], v[210:213], v[194:197], v[0:3]
	v_mfma_f32_16x16x32_bf16 v[44:47], v[206:209], v[174:177], v[44:47]
	v_mfma_f32_16x16x32_bf16 v[40:43], v[214:217], v[174:177], v[40:43]
	v_mfma_f32_16x16x32_bf16 v[28:31], v[206:209], v[182:185], v[28:31]
	v_mfma_f32_16x16x32_bf16 v[24:27], v[214:217], v[182:185], v[24:27]
	v_mfma_f32_16x16x32_bf16 v[12:15], v[206:209], v[190:193], v[12:15]
	v_mfma_f32_16x16x32_bf16 v[8:11], v[214:217], v[190:193], v[8:11]
	v_mfma_f32_16x16x32_bf16 v[4:7], v[206:209], v[198:201], v[4:7]
	v_mfma_f32_16x16x32_bf16 v[0:3], v[214:217], v[198:201], v[0:3]
	s_setprio 0
	s_add_i32 s87, 0, 0x18000
	v_add_u32_e32 v153, s87, v148
	s_barrier
	ds_read_b128 v[154:157], v153
	ds_read_b128 v[158:161], v153 offset:1024
	ds_read_b128 v[162:165], v153 offset:2048
	ds_read_b128 v[166:169], v153 offset:3072
	s_add_u32 s28, s28, 0x40000
	s_addc_u32 s29, s29, 0
	s_mov_b32 m0, s54
	v_lshl_add_u64 v[202:203], s[28:29], 0, v[136:137]
	ds_read_b128 v[170:173], v151 offset:32768
	ds_read_b128 v[174:177], v151 offset:33792
	ds_read_b128 v[178:181], v151 offset:34816
	ds_read_b128 v[182:185], v151 offset:35840
	ds_read_b128 v[186:189], v151 offset:36864
	ds_read_b128 v[190:193], v151 offset:37888
	ds_read_b128 v[194:197], v151 offset:38912
	ds_read_b128 v[198:201], v151 offset:39936
	global_load_lds_dwordx4 v[202:203], off
	v_lshl_add_u64 v[202:203], s[28:29], 0, v[132:133]
	s_mov_b32 m0, s55
	s_nop 0
	global_load_lds_dwordx4 v[202:203], off
	s_waitcnt lgkmcnt(8)
	s_barrier
	s_waitcnt lgkmcnt(0)
	s_setprio 1
	s_waitcnt lgkmcnt(0)
	v_mfma_f32_16x16x32_bf16 v[124:127], v[154:157], v[170:173], v[124:127]
	v_mfma_f32_16x16x32_bf16 v[120:123], v[162:165], v[170:173], v[120:123]
	v_mfma_f32_16x16x32_bf16 v[116:119], v[154:157], v[178:181], v[116:119]
	v_mfma_f32_16x16x32_bf16 v[112:115], v[162:165], v[178:181], v[112:115]
	v_mfma_f32_16x16x32_bf16 v[100:103], v[154:157], v[186:189], v[100:103]
	v_mfma_f32_16x16x32_bf16 v[96:99], v[162:165], v[186:189], v[96:99]
	v_mfma_f32_16x16x32_bf16 v[84:87], v[154:157], v[194:197], v[84:87]
	v_mfma_f32_16x16x32_bf16 v[80:83], v[162:165], v[194:197], v[80:83]
	v_mfma_f32_16x16x32_bf16 v[124:127], v[158:161], v[174:177], v[124:127]
	v_mfma_f32_16x16x32_bf16 v[120:123], v[166:169], v[174:177], v[120:123]
	v_mfma_f32_16x16x32_bf16 v[116:119], v[158:161], v[182:185], v[116:119]
	v_mfma_f32_16x16x32_bf16 v[112:115], v[166:169], v[182:185], v[112:115]
	v_mfma_f32_16x16x32_bf16 v[100:103], v[158:161], v[190:193], v[100:103]
	v_mfma_f32_16x16x32_bf16 v[96:99], v[166:169], v[190:193], v[96:99]
	v_mfma_f32_16x16x32_bf16 v[84:87], v[158:161], v[198:201], v[84:87]
	v_mfma_f32_16x16x32_bf16 v[80:83], v[166:169], v[198:201], v[80:83]
	s_setprio 0
	s_barrier
	s_add_i32 s28, 0, 0x1c000
	s_add_i32 s29, s87, s34
	v_add_u32_e32 v153, s28, v148
	v_lshl_add_u64 v[218:219], v[218:219], 0, s[8:9]
	s_mov_b32 m0, s29
	ds_read_b128 v[202:205], v153
	ds_read_b128 v[206:209], v153 offset:1024
	ds_read_b128 v[210:213], v153 offset:2048
	ds_read_b128 v[214:217], v153 offset:3072
	global_load_lds_dwordx4 v[218:219], off
	v_lshl_add_u64 v[218:219], v[220:221], 0, s[8:9]
	s_add_i32 m0, s29, 0x2000
	s_nop 0
	global_load_lds_dwordx4 v[218:219], off
	s_barrier
	s_waitcnt lgkmcnt(0)
	s_setprio 1
	s_waitcnt lgkmcnt(0)
	v_mfma_f32_16x16x32_bf16 v[108:111], v[202:205], v[170:173], v[108:111]
	v_mfma_f32_16x16x32_bf16 v[104:107], v[210:213], v[170:173], v[104:107]
	v_mfma_f32_16x16x32_bf16 v[92:95], v[202:205], v[178:181], v[92:95]
	v_mfma_f32_16x16x32_bf16 v[88:91], v[210:213], v[178:181], v[88:91]
	v_mfma_f32_16x16x32_bf16 v[76:79], v[202:205], v[186:189], v[76:79]
	v_mfma_f32_16x16x32_bf16 v[72:75], v[210:213], v[186:189], v[72:75]
	v_mfma_f32_16x16x32_bf16 v[68:71], v[202:205], v[194:197], v[68:71]
	v_mfma_f32_16x16x32_bf16 v[64:67], v[210:213], v[194:197], v[64:67]
	v_mfma_f32_16x16x32_bf16 v[108:111], v[206:209], v[174:177], v[108:111]
	v_mfma_f32_16x16x32_bf16 v[104:107], v[214:217], v[174:177], v[104:107]
	v_mfma_f32_16x16x32_bf16 v[92:95], v[206:209], v[182:185], v[92:95]
	v_mfma_f32_16x16x32_bf16 v[88:91], v[214:217], v[182:185], v[88:91]
	v_mfma_f32_16x16x32_bf16 v[76:79], v[206:209], v[190:193], v[76:79]
	v_mfma_f32_16x16x32_bf16 v[72:75], v[214:217], v[190:193], v[72:75]
	v_mfma_f32_16x16x32_bf16 v[68:71], v[206:209], v[198:201], v[68:71]
	v_mfma_f32_16x16x32_bf16 v[64:67], v[214:217], v[198:201], v[64:67]
	s_setprio 0
	s_mov_b32 m0, s57
	v_lshl_add_u64 v[218:219], v[222:223], 0, s[8:9]
	s_barrier
	ds_read_b128 v[170:173], v151 offset:49152
	ds_read_b128 v[174:177], v151 offset:50176
	ds_read_b128 v[178:181], v151 offset:51200
	ds_read_b128 v[182:185], v151 offset:52224
	ds_read_b128 v[186:189], v151 offset:53248
	ds_read_b128 v[190:193], v151 offset:54272
	ds_read_b128 v[194:197], v151 offset:55296
	ds_read_b128 v[198:201], v151 offset:56320
	global_load_lds_dwordx4 v[218:219], off
	v_lshl_add_u64 v[218:219], v[224:225], 0, s[8:9]
	s_mov_b32 m0, s70
	s_nop 0
	global_load_lds_dwordx4 v[218:219], off
	s_barrier
	s_waitcnt lgkmcnt(0)
	s_setprio 1
	s_waitcnt lgkmcnt(0)
	v_mfma_f32_16x16x32_bf16 v[60:63], v[154:157], v[170:173], v[60:63]
	v_mfma_f32_16x16x32_bf16 v[56:59], v[162:165], v[170:173], v[56:59]
	v_mfma_f32_16x16x32_bf16 v[52:55], v[154:157], v[178:181], v[52:55]
	v_mfma_f32_16x16x32_bf16 v[48:51], v[162:165], v[178:181], v[48:51]
	v_mfma_f32_16x16x32_bf16 v[36:39], v[154:157], v[186:189], v[36:39]
	v_mfma_f32_16x16x32_bf16 v[32:35], v[162:165], v[186:189], v[32:35]
	v_mfma_f32_16x16x32_bf16 v[20:23], v[154:157], v[194:197], v[20:23]
	v_mfma_f32_16x16x32_bf16 v[16:19], v[162:165], v[194:197], v[16:19]
	v_mfma_f32_16x16x32_bf16 v[60:63], v[158:161], v[174:177], v[60:63]
	v_mfma_f32_16x16x32_bf16 v[56:59], v[166:169], v[174:177], v[56:59]
	v_mfma_f32_16x16x32_bf16 v[52:55], v[158:161], v[182:185], v[52:55]
	v_mfma_f32_16x16x32_bf16 v[48:51], v[166:169], v[182:185], v[48:51]
	v_mfma_f32_16x16x32_bf16 v[36:39], v[158:161], v[190:193], v[36:39]
	v_mfma_f32_16x16x32_bf16 v[32:35], v[166:169], v[190:193], v[32:35]
	v_mfma_f32_16x16x32_bf16 v[20:23], v[158:161], v[198:201], v[20:23]
	v_mfma_f32_16x16x32_bf16 v[16:19], v[166:169], v[198:201], v[16:19]
	s_setprio 0
	s_barrier
	s_add_u32 s26, s26, 0x40080
	s_addc_u32 s27, s27, 0
	s_add_i32 s28, s28, s34
	v_lshl_add_u64 v[154:155], s[26:27], 0, v[134:135]
	s_mov_b32 m0, s28
	s_nop 0
	global_load_lds_dwordx4 v[154:155], off
	v_lshl_add_u64 v[154:155], s[26:27], 0, v[130:131]
	s_add_i32 m0, s28, 0x2000
	s_nop 0
	global_load_lds_dwordx4 v[154:155], off
	s_waitcnt vmcnt(6)
	s_barrier
	s_setprio 1
	v_mfma_f32_16x16x32_bf16 v[44:47], v[202:205], v[170:173], v[44:47]
	v_mfma_f32_16x16x32_bf16 v[40:43], v[210:213], v[170:173], v[40:43]
	v_mfma_f32_16x16x32_bf16 v[28:31], v[202:205], v[178:181], v[28:31]
	v_mfma_f32_16x16x32_bf16 v[24:27], v[210:213], v[178:181], v[24:27]
	v_mfma_f32_16x16x32_bf16 v[12:15], v[202:205], v[186:189], v[12:15]
	v_mfma_f32_16x16x32_bf16 v[8:11], v[210:213], v[186:189], v[8:11]
	v_mfma_f32_16x16x32_bf16 v[4:7], v[202:205], v[194:197], v[4:7]
	v_mfma_f32_16x16x32_bf16 v[0:3], v[210:213], v[194:197], v[0:3]
	v_mfma_f32_16x16x32_bf16 v[44:47], v[206:209], v[174:177], v[44:47]
	v_mfma_f32_16x16x32_bf16 v[40:43], v[214:217], v[174:177], v[40:43]
	v_mfma_f32_16x16x32_bf16 v[28:31], v[206:209], v[182:185], v[28:31]
	v_mfma_f32_16x16x32_bf16 v[24:27], v[214:217], v[182:185], v[24:27]
	v_mfma_f32_16x16x32_bf16 v[12:15], v[206:209], v[190:193], v[12:15]
	v_mfma_f32_16x16x32_bf16 v[8:11], v[214:217], v[190:193], v[8:11]
	v_mfma_f32_16x16x32_bf16 v[4:7], v[206:209], v[198:201], v[4:7]
	v_mfma_f32_16x16x32_bf16 v[0:3], v[214:217], v[198:201], v[0:3]
	s_setprio 0
	s_add_i32 s86, s86, 2
	s_add_u32 s20, s20, 0x100
	s_addc_u32 s21, s21, 0
	s_add_u32 s84, s84, 0x100
	s_addc_u32 s85, s85, 0
	s_cmp_gt_u32 s86, 13
	s_barrier
	s_cbranch_scc0 .LBB0_155
	v_lshl_add_u32 v153, s10, 8, v147
	v_lshl_or_b32 v154, s75, 8, v149
	v_mov_b64_e32 v[156:157], s[46:47]
	v_ashrrev_i32_e32 v155, 31, v154
	v_cvt_pk_bf16_f32 v68, v68, v69
	v_cvt_pk_bf16_f32 v69, v70, v71
	v_cvt_pk_bf16_f32 v70, v64, v65
	v_add_u32_e32 v64, 0x80, v153
	v_mad_i64_i32 v[158:159], s[20:21], v153, s74, v[156:157]
	v_cvt_pk_bf16_f32 v124, v124, v125
	v_cvt_pk_bf16_f32 v125, v126, v127
	v_cvt_pk_bf16_f32 v126, v120, v121
	v_lshlrev_b64 v[120:121], 1, v[154:155]
	v_mad_i64_i32 v[64:65], s[20:21], v64, s74, v[156:157]
	v_cvt_pk_bf16_f32 v127, v122, v123
	v_lshl_add_u64 v[122:123], v[158:159], 0, v[120:121]
	v_cvt_pk_bf16_f32 v108, v108, v109
	v_cvt_pk_bf16_f32 v109, v110, v111
	v_cvt_pk_bf16_f32 v110, v104, v105
	v_cvt_pk_bf16_f32 v111, v106, v107
	v_or_b32_e32 v104, 16, v153
	v_cvt_pk_bf16_f32 v60, v60, v61
	v_cvt_pk_bf16_f32 v61, v62, v63
	v_cvt_pk_bf16_f32 v62, v56, v57
	v_lshl_add_u64 v[56:57], v[64:65], 0, v[120:121]
	v_cvt_pk_bf16_f32 v44, v44, v45
	v_cvt_pk_bf16_f32 v45, v46, v47
	v_cvt_pk_bf16_f32 v46, v40, v41
	v_cvt_pk_bf16_f32 v47, v42, v43
	v_add_u32_e32 v40, 0x90, v153
	global_store_dwordx4 v[122:123], v[108:111], off offset:256 sc1
	global_store_dwordx4 v[56:57], v[44:47], off offset:256 sc1
	v_cvt_pk_bf16_f32 v92, v92, v93
	v_mad_i64_i32 v[108:109], s[20:21], v104, s74, v[156:157]
	v_mad_i64_i32 v[44:45], s[20:21], v40, s74, v[156:157]
	v_lshl_add_u64 v[108:109], v[108:109], 0, v[120:121]
	v_cvt_pk_bf16_f32 v93, v94, v95
	v_cvt_pk_bf16_f32 v94, v88, v89
	v_cvt_pk_bf16_f32 v95, v90, v91
	v_or_b32_e32 v88, 32, v153
	v_lshl_add_u64 v[44:45], v[44:45], 0, v[120:121]
	v_cvt_pk_bf16_f32 v28, v28, v29
	v_cvt_pk_bf16_f32 v29, v30, v31
	v_cvt_pk_bf16_f32 v30, v24, v25
	v_cvt_pk_bf16_f32 v31, v26, v27
	v_add_u32_e32 v24, 0xa0, v153
	global_store_dwordx4 v[108:109], v[92:95], off offset:256 sc1
	global_store_dwordx4 v[44:45], v[28:31], off offset:256 sc1
	v_cvt_pk_bf16_f32 v76, v76, v77
	v_mad_i64_i32 v[92:93], s[20:21], v88, s74, v[156:157]
	v_mad_i64_i32 v[28:29], s[20:21], v24, s74, v[156:157]
	v_lshl_add_u64 v[92:93], v[92:93], 0, v[120:121]
	v_cvt_pk_bf16_f32 v77, v78, v79
	v_cvt_pk_bf16_f32 v78, v72, v73
	v_cvt_pk_bf16_f32 v79, v74, v75
	v_or_b32_e32 v72, 48, v153
	v_lshl_add_u64 v[28:29], v[28:29], 0, v[120:121]
	v_cvt_pk_bf16_f32 v12, v12, v13
	v_cvt_pk_bf16_f32 v13, v14, v15
	v_cvt_pk_bf16_f32 v14, v8, v9
	v_cvt_pk_bf16_f32 v15, v10, v11
	v_add_u32_e32 v8, 0xb0, v153
	global_store_dwordx4 v[92:93], v[76:79], off offset:256 sc1
	global_store_dwordx4 v[28:29], v[12:15], off offset:256 sc1
	v_cvt_pk_bf16_f32 v104, v116, v117
	v_mad_i64_i32 v[76:77], s[20:21], v72, s74, v[156:157]
	v_mad_i64_i32 v[12:13], s[20:21], v8, s74, v[156:157]
	v_cvt_pk_bf16_f32 v105, v118, v119
	v_cvt_pk_bf16_f32 v106, v112, v113
	v_cvt_pk_bf16_f32 v107, v114, v115
	v_cvt_pk_bf16_f32 v88, v100, v101
	v_cvt_pk_bf16_f32 v89, v102, v103
	v_cvt_pk_bf16_f32 v90, v96, v97
	v_cvt_pk_bf16_f32 v91, v98, v99
	v_cvt_pk_bf16_f32 v72, v84, v85
	v_cvt_pk_bf16_f32 v73, v86, v87
	v_cvt_pk_bf16_f32 v74, v80, v81
	v_cvt_pk_bf16_f32 v75, v82, v83
	v_lshl_add_u64 v[76:77], v[76:77], 0, v[120:121]
	v_cvt_pk_bf16_f32 v71, v66, v67
	v_cvt_pk_bf16_f32 v63, v58, v59
	v_cvt_pk_bf16_f32 v40, v52, v53
	v_cvt_pk_bf16_f32 v41, v54, v55
	v_cvt_pk_bf16_f32 v42, v48, v49
	v_cvt_pk_bf16_f32 v43, v50, v51
	v_cvt_pk_bf16_f32 v24, v36, v37
	v_cvt_pk_bf16_f32 v25, v38, v39
	v_cvt_pk_bf16_f32 v26, v32, v33
	v_cvt_pk_bf16_f32 v27, v34, v35
	v_cvt_pk_bf16_f32 v8, v20, v21
	v_cvt_pk_bf16_f32 v9, v22, v23
	v_cvt_pk_bf16_f32 v10, v16, v17
	v_cvt_pk_bf16_f32 v11, v18, v19
	v_lshl_add_u64 v[12:13], v[12:13], 0, v[120:121]
	v_cvt_pk_bf16_f32 v4, v4, v5
	v_cvt_pk_bf16_f32 v5, v6, v7
	v_cvt_pk_bf16_f32 v6, v0, v1
	v_cvt_pk_bf16_f32 v7, v2, v3
	s_and_b64 vcc, exec, s[4:5]
	s_mov_b32 s75, s12
	s_mov_b32 s10, s14
	s_mov_b64 s[26:27], s[18:19]
	s_mov_b64 s[20:21], s[16:17]
	global_store_dwordx4 v[122:123], v[124:127], off sc1
	global_store_dwordx4 v[108:109], v[104:107], off sc1
	global_store_dwordx4 v[92:93], v[88:91], off sc1
	global_store_dwordx4 v[76:77], v[72:75], off sc1
	global_store_dwordx4 v[76:77], v[68:71], off offset:256 sc1
	global_store_dwordx4 v[56:57], v[60:63], off sc1
	global_store_dwordx4 v[44:45], v[40:43], off sc1
	global_store_dwordx4 v[28:29], v[24:27], off sc1
	global_store_dwordx4 v[12:13], v[8:11], off sc1
	global_store_dwordx4 v[12:13], v[4:7], off offset:256 sc1
	s_cbranch_vccz .LBB0_152
	s_waitcnt vmcnt(0)
	s_cmpk_gt_u32 s30, 0xff
	s_cbranch_scc1 .LBB0_159
	s_barrier

.Lprep_item:
	s_barrier
	s_lshr_b32 s4, s82, 5
	s_lshl_b32 s4, s4, 11
	s_and_b32 s5, s82, 31
	s_lshl_b32 s5, s5, 6
	s_add_u32 s4, s4, s5
	s_mul_i32 s5, s4, 0x1a00
	s_mul_hi_u32 s6, s4, 0x1a00
	s_add_u32 s20, s46, s5
	s_addc_u32 s21, s47, s6
	s_mov_b64 s[22:23], s[20:21]
	s_add_u32 s30, s20, 0x1800
	s_addc_u32 s31, s21, 0
	s_add_u32 s16, s30, 0x34000
	s_addc_u32 s17, s31, 0
	s_lshl_b32 s5, s82, 16
	s_lshr_b32 s6, s82, 16
	s_add_u32 s26, s46, 0x6b40000
	s_addc_u32 s27, s47, 0
	s_add_u32 s26, s26, s5
	s_addc_u32 s27, s27, s6
	s_mul_i32 s5, s82, 0x1800
	s_add_u32 s28, s46, 0x7b40000
	s_addc_u32 s29, s47, 0
	s_add_u32 s28, s28, s5
	s_addc_u32 s29, s29, 0
	s_mov_b64 s[34:35], s[84:85]
	global_load_ushort v6, v4, s[30:31]
	global_load_ushort v7, v4, s[16:17]
	global_load_dword v16, v0, s[34:35]
	global_load_dword v17, v0, s[34:35] offset:2048
	s_add_u32 s34, s34, 0x1000
	s_addc_u32 s35, s35, 0
	global_load_dword v18, v0, s[34:35]
	global_load_dword v19, v0, s[34:35] offset:2048
	s_add_u32 s34, s34, 0x1000
	s_addc_u32 s35, s35, 0
	global_load_dword v20, v0, s[34:35]
	global_load_dword v21, v0, s[34:35] offset:2048
	s_add_u32 s34, s34, 0x1000
	s_addc_u32 s35, s35, 0
	global_load_dword v22, v0, s[34:35]
	global_load_dword v23, v0, s[34:35] offset:2048
	s_add_u32 s34, s34, 0x1000
	s_addc_u32 s35, s35, 0
	global_load_dword v24, v0, s[34:35]
	global_load_dword v25, v0, s[34:35] offset:2048
	s_add_u32 s34, s34, 0x1000
	s_addc_u32 s35, s35, 0
	global_load_dword v26, v0, s[34:35]
	global_load_dword v27, v0, s[34:35] offset:2048
	s_add_u32 s34, s34, 0x1000
	s_addc_u32 s35, s35, 0
	global_load_dword v28, v0, s[34:35]
	global_load_dword v29, v0, s[34:35] offset:2048
	s_add_u32 s34, s34, 0x1000
	s_addc_u32 s35, s35, 0
	global_load_dword v30, v0, s[34:35]
	global_load_dword v31, v0, s[34:35] offset:2048
	global_load_dword v32, v0, s[80:81]
	s_waitcnt vmcnt(17)
	v_lshlrev_b32_e32 v6, 16, v6
	v_lshlrev_b32_e32 v7, 16, v7
	ds_write_b32 v0, v6
	ds_write_b32 v0, v7 offset:2048
	s_waitcnt lgkmcnt(0)
	s_barrier
	ds_read_b128 v[34:37], v3 offset:0
	ds_read_b128 v[38:41], v3 offset:16
	ds_read_b128 v[42:45], v3 offset:32
	ds_read_b128 v[46:49], v3 offset:48
	ds_read_b128 v[200:203], v3 offset:64
	ds_read_b128 v[204:207], v3 offset:80
	ds_read_b128 v[208:211], v3 offset:96
	ds_read_b128 v[212:215], v3 offset:112
	s_waitcnt vmcnt(0)
	s_waitcnt lgkmcnt(0)
	ds_read_b128 v[216:219], v3 offset:128
	ds_read_b128 v[220:223], v3 offset:144
	ds_read_b128 v[224:227], v3 offset:160
	ds_read_b128 v[232:235], v3 offset:176
	ds_read_b128 v[236:239], v3 offset:192
	ds_read_b128 v[240:243], v3 offset:208
	ds_read_b128 v[244:247], v3 offset:224
	ds_read_b128 v[248:251], v3 offset:240
	global_load_ushort v136, v1, s[20:21]
	global_load_ushort v137, v1, s[20:21] offset:1024
	s_add_u32 s20, s20, 0x1a00
	s_addc_u32 s21, s21, 0
	global_load_ushort v138, v1, s[20:21]
	global_load_ushort v139, v1, s[20:21] offset:1024
	s_add_u32 s20, s20, 0x1a00
	s_addc_u32 s21, s21, 0
	v_fma_f32 v50, v16, v34, v32
	v_fma_f32 v51, v16, v200, v32
	v_fmac_f32_e32 v50, v17, v35
	v_fmac_f32_e32 v51, v17, v201
	v_fmac_f32_e32 v50, v18, v36
	v_fmac_f32_e32 v51, v18, v202
	v_fmac_f32_e32 v50, v19, v37
	v_fmac_f32_e32 v51, v19, v203
	v_fmac_f32_e32 v50, v20, v38
	v_fmac_f32_e32 v51, v20, v204
	v_fmac_f32_e32 v50, v21, v39
	v_fmac_f32_e32 v51, v21, v205
	v_fmac_f32_e32 v50, v22, v40
	v_fmac_f32_e32 v51, v22, v206
	v_fmac_f32_e32 v50, v23, v41
	v_fmac_f32_e32 v51, v23, v207
	v_fmac_f32_e32 v50, v24, v42
	v_fmac_f32_e32 v51, v24, v208
	v_fmac_f32_e32 v50, v25, v43
	v_fmac_f32_e32 v51, v25, v209
	v_fmac_f32_e32 v50, v26, v44
	v_fmac_f32_e32 v51, v26, v210
	v_fmac_f32_e32 v50, v27, v45
	v_fmac_f32_e32 v51, v27, v211
	v_fmac_f32_e32 v50, v28, v46
	v_fmac_f32_e32 v51, v28, v212
	v_fmac_f32_e32 v50, v29, v47
	v_fmac_f32_e32 v51, v29, v213
	v_fmac_f32_e32 v50, v30, v48
	v_fmac_f32_e32 v51, v30, v214
	v_fmac_f32_e32 v50, v31, v49
	v_fmac_f32_e32 v51, v31, v215
	v_mul_f32_e64 v52, |v50|, s7
	v_mul_f32_e64 v53, |v51|, s7
	v_exp_f32_e32 v52, v52
	v_exp_f32_e32 v53, v53
	v_min_f32_e32 v50, 0, v50
	v_add_f32_e32 v52, 1.0, v52
	v_add_f32_e32 v53, 1.0, v53
	v_log_f32_e32 v52, v52
	v_log_f32_e32 v53, v53
	v_min_f32_e32 v51, 0, v51
	v_mul_f32_e32 v54, 0x3f317217, v52
	v_mul_f32_e32 v55, 0x3f317217, v53
	v_fma_f32 v56, v52, s9, -v54
	v_fma_f32 v57, v53, s9, -v55
	v_fmac_f32_e32 v56, 0x3377d1cf, v52
	v_fmac_f32_e32 v57, 0x3377d1cf, v53
	v_add_f32_e32 v54, v54, v56
	v_add_f32_e32 v55, v55, v57
	v_sub_f32_e32 v50, v50, v54
	v_sub_f32_e32 v51, v51, v55
	v_mul_f32_e32 v64, 0x3d800000, v50
	v_fmamk_f32 v65, v51, 0x3d800000, v64
	s_waitcnt lgkmcnt(0)
	ds_read_b128 v[34:37], v3 offset:256
	ds_read_b128 v[38:41], v3 offset:272
	ds_read_b128 v[42:45], v3 offset:288
	ds_read_b128 v[46:49], v3 offset:304
	ds_read_b128 v[200:203], v3 offset:320
	ds_read_b128 v[204:207], v3 offset:336
	ds_read_b128 v[208:211], v3 offset:352
	ds_read_b128 v[212:215], v3 offset:368
	global_load_ushort v140, v1, s[20:21]
	global_load_ushort v141, v1, s[20:21] offset:1024
	s_add_u32 s20, s20, 0x1a00
	s_addc_u32 s21, s21, 0
	global_load_ushort v142, v1, s[20:21]
	global_load_ushort v143, v1, s[20:21] offset:1024
	s_add_u32 s20, s20, 0x1a00
	s_addc_u32 s21, s21, 0
	v_fma_f32 v50, v16, v216, v32
	v_fma_f32 v51, v16, v236, v32
	v_fmac_f32_e32 v50, v17, v217
	v_fmac_f32_e32 v51, v17, v237
	v_fmac_f32_e32 v50, v18, v218
	v_fmac_f32_e32 v51, v18, v238
	v_fmac_f32_e32 v50, v19, v219
	v_fmac_f32_e32 v51, v19, v239
	v_fmac_f32_e32 v50, v20, v220
	v_fmac_f32_e32 v51, v20, v240
	v_fmac_f32_e32 v50, v21, v221
	v_fmac_f32_e32 v51, v21, v241
	v_fmac_f32_e32 v50, v22, v222
	v_fmac_f32_e32 v51, v22, v242
	v_fmac_f32_e32 v50, v23, v223
	v_fmac_f32_e32 v51, v23, v243
	v_fmac_f32_e32 v50, v24, v224
	v_fmac_f32_e32 v51, v24, v244
	v_fmac_f32_e32 v50, v25, v225
	v_fmac_f32_e32 v51, v25, v245
	v_fmac_f32_e32 v50, v26, v226
	v_fmac_f32_e32 v51, v26, v246
	v_fmac_f32_e32 v50, v27, v227
	v_fmac_f32_e32 v51, v27, v247
	v_fmac_f32_e32 v50, v28, v232
	v_fmac_f32_e32 v51, v28, v248
	v_fmac_f32_e32 v50, v29, v233
	v_fmac_f32_e32 v51, v29, v249
	v_fmac_f32_e32 v50, v30, v234
	v_fmac_f32_e32 v51, v30, v250
	v_fmac_f32_e32 v50, v31, v235
	v_fmac_f32_e32 v51, v31, v251
	v_mul_f32_e64 v52, |v50|, s7
	v_mul_f32_e64 v53, |v51|, s7
	v_exp_f32_e32 v52, v52
	v_exp_f32_e32 v53, v53
	v_min_f32_e32 v50, 0, v50
	v_add_f32_e32 v52, 1.0, v52
	v_add_f32_e32 v53, 1.0, v53
	v_log_f32_e32 v52, v52
	v_log_f32_e32 v53, v53
	v_min_f32_e32 v51, 0, v51
	v_mul_f32_e32 v54, 0x3f317217, v52
	v_mul_f32_e32 v55, 0x3f317217, v53
	v_fma_f32 v56, v52, s9, -v54
	v_fma_f32 v57, v53, s9, -v55
	v_fmac_f32_e32 v56, 0x3377d1cf, v52
	v_fmac_f32_e32 v57, 0x3377d1cf, v53
	v_add_f32_e32 v54, v54, v56
	v_add_f32_e32 v55, v55, v57
	v_sub_f32_e32 v50, v50, v54
	v_sub_f32_e32 v51, v51, v55
	v_fmamk_f32 v66, v50, 0x3d800000, v65
	v_fmamk_f32 v67, v51, 0x3d800000, v66
	s_waitcnt lgkmcnt(0)
	ds_read_b128 v[216:219], v3 offset:384
	ds_read_b128 v[220:223], v3 offset:400
	ds_read_b128 v[224:227], v3 offset:416
	ds_read_b128 v[232:235], v3 offset:432
	ds_read_b128 v[236:239], v3 offset:448
	ds_read_b128 v[240:243], v3 offset:464
	ds_read_b128 v[244:247], v3 offset:480
	ds_read_b128 v[248:251], v3 offset:496
	global_load_ushort v144, v1, s[20:21]
	global_load_ushort v145, v1, s[20:21] offset:1024
	s_add_u32 s20, s20, 0x1a00
	s_addc_u32 s21, s21, 0
	global_load_ushort v146, v1, s[20:21]
	global_load_ushort v147, v1, s[20:21] offset:1024
	s_add_u32 s20, s20, 0x1a00
	s_addc_u32 s21, s21, 0
	v_fma_f32 v50, v16, v34, v32
	v_fma_f32 v51, v16, v200, v32
	v_fmac_f32_e32 v50, v17, v35
	v_fmac_f32_e32 v51, v17, v201
	v_fmac_f32_e32 v50, v18, v36
	v_fmac_f32_e32 v51, v18, v202
	v_fmac_f32_e32 v50, v19, v37
	v_fmac_f32_e32 v51, v19, v203
	v_fmac_f32_e32 v50, v20, v38
	v_fmac_f32_e32 v51, v20, v204
	v_fmac_f32_e32 v50, v21, v39
	v_fmac_f32_e32 v51, v21, v205
	v_fmac_f32_e32 v50, v22, v40
	v_fmac_f32_e32 v51, v22, v206
	v_fmac_f32_e32 v50, v23, v41
	v_fmac_f32_e32 v51, v23, v207
	v_fmac_f32_e32 v50, v24, v42
	v_fmac_f32_e32 v51, v24, v208
	v_fmac_f32_e32 v50, v25, v43
	v_fmac_f32_e32 v51, v25, v209
	v_fmac_f32_e32 v50, v26, v44
	v_fmac_f32_e32 v51, v26, v210
	v_fmac_f32_e32 v50, v27, v45
	v_fmac_f32_e32 v51, v27, v211
	v_fmac_f32_e32 v50, v28, v46
	v_fmac_f32_e32 v51, v28, v212
	v_fmac_f32_e32 v50, v29, v47
	v_fmac_f32_e32 v51, v29, v213
	v_fmac_f32_e32 v50, v30, v48
	v_fmac_f32_e32 v51, v30, v214
	v_fmac_f32_e32 v50, v31, v49
	v_fmac_f32_e32 v51, v31, v215
	v_mul_f32_e64 v52, |v50|, s7
	v_mul_f32_e64 v53, |v51|, s7
	v_exp_f32_e32 v52, v52
	v_exp_f32_e32 v53, v53
	v_min_f32_e32 v50, 0, v50
	v_add_f32_e32 v52, 1.0, v52
	v_add_f32_e32 v53, 1.0, v53
	v_log_f32_e32 v52, v52
	v_log_f32_e32 v53, v53
	v_min_f32_e32 v51, 0, v51
	v_mul_f32_e32 v54, 0x3f317217, v52
	v_mul_f32_e32 v55, 0x3f317217, v53
	v_fma_f32 v56, v52, s9, -v54
	v_fma_f32 v57, v53, s9, -v55
	v_fmac_f32_e32 v56, 0x3377d1cf, v52
	v_fmac_f32_e32 v57, 0x3377d1cf, v53
	v_add_f32_e32 v54, v54, v56
	v_add_f32_e32 v55, v55, v57
	v_sub_f32_e32 v50, v50, v54
	v_sub_f32_e32 v51, v51, v55
	v_fmamk_f32 v68, v50, 0x3d800000, v67
	v_fmamk_f32 v69, v51, 0x3d800000, v68
	s_waitcnt lgkmcnt(0)
	ds_read_b128 v[34:37], v3 offset:512
	ds_read_b128 v[38:41], v3 offset:528
	ds_read_b128 v[42:45], v3 offset:544
	ds_read_b128 v[46:49], v3 offset:560
	ds_read_b128 v[200:203], v3 offset:576
	ds_read_b128 v[204:207], v3 offset:592
	ds_read_b128 v[208:211], v3 offset:608
	ds_read_b128 v[212:215], v3 offset:624
	global_load_ushort v148, v1, s[20:21]
	global_load_ushort v149, v1, s[20:21] offset:1024
	s_add_u32 s20, s20, 0x1a00
	s_addc_u32 s21, s21, 0
	global_load_ushort v150, v1, s[20:21]
	global_load_ushort v151, v1, s[20:21] offset:1024
	s_add_u32 s20, s20, 0x1a00
	s_addc_u32 s21, s21, 0
	v_fma_f32 v50, v16, v216, v32
	v_fma_f32 v51, v16, v236, v32
	v_fmac_f32_e32 v50, v17, v217
	v_fmac_f32_e32 v51, v17, v237
	v_fmac_f32_e32 v50, v18, v218
	v_fmac_f32_e32 v51, v18, v238
	v_fmac_f32_e32 v50, v19, v219
	v_fmac_f32_e32 v51, v19, v239
	v_fmac_f32_e32 v50, v20, v220
	v_fmac_f32_e32 v51, v20, v240
	v_fmac_f32_e32 v50, v21, v221
	v_fmac_f32_e32 v51, v21, v241
	v_fmac_f32_e32 v50, v22, v222
	v_fmac_f32_e32 v51, v22, v242
	v_fmac_f32_e32 v50, v23, v223
	v_fmac_f32_e32 v51, v23, v243
	v_fmac_f32_e32 v50, v24, v224
	v_fmac_f32_e32 v51, v24, v244
	v_fmac_f32_e32 v50, v25, v225
	v_fmac_f32_e32 v51, v25, v245
	v_fmac_f32_e32 v50, v26, v226
	v_fmac_f32_e32 v51, v26, v246
	v_fmac_f32_e32 v50, v27, v227
	v_fmac_f32_e32 v51, v27, v247
	v_fmac_f32_e32 v50, v28, v232
	v_fmac_f32_e32 v51, v28, v248
	v_fmac_f32_e32 v50, v29, v233
	v_fmac_f32_e32 v51, v29, v249
	v_fmac_f32_e32 v50, v30, v234
	v_fmac_f32_e32 v51, v30, v250
	v_fmac_f32_e32 v50, v31, v235
	v_fmac_f32_e32 v51, v31, v251
	v_mul_f32_e64 v52, |v50|, s7
	v_mul_f32_e64 v53, |v51|, s7
	v_exp_f32_e32 v52, v52
	v_exp_f32_e32 v53, v53
	v_min_f32_e32 v50, 0, v50
	v_add_f32_e32 v52, 1.0, v52
	v_add_f32_e32 v53, 1.0, v53
	v_log_f32_e32 v52, v52
	v_log_f32_e32 v53, v53
	v_min_f32_e32 v51, 0, v51
	v_mul_f32_e32 v54, 0x3f317217, v52
	v_mul_f32_e32 v55, 0x3f317217, v53
	v_fma_f32 v56, v52, s9, -v54
	v_fma_f32 v57, v53, s9, -v55
	v_fmac_f32_e32 v56, 0x3377d1cf, v52
	v_fmac_f32_e32 v57, 0x3377d1cf, v53
	v_add_f32_e32 v54, v54, v56
	v_add_f32_e32 v55, v55, v57
	v_sub_f32_e32 v50, v50, v54
	v_sub_f32_e32 v51, v51, v55
	v_fmamk_f32 v70, v50, 0x3d800000, v69
	v_fmamk_f32 v71, v51, 0x3d800000, v70
	s_waitcnt lgkmcnt(0)
	ds_read_b128 v[216:219], v3 offset:640
	ds_read_b128 v[220:223], v3 offset:656
	ds_read_b128 v[224:227], v3 offset:672
	ds_read_b128 v[232:235], v3 offset:688
	ds_read_b128 v[236:239], v3 offset:704
	ds_read_b128 v[240:243], v3 offset:720
	ds_read_b128 v[244:247], v3 offset:736
	ds_read_b128 v[248:251], v3 offset:752
	global_load_ushort v152, v1, s[20:21]
	global_load_ushort v153, v1, s[20:21] offset:1024
	s_add_u32 s20, s20, 0x1a00
	s_addc_u32 s21, s21, 0
	global_load_ushort v154, v1, s[20:21]
	global_load_ushort v155, v1, s[20:21] offset:1024
	s_add_u32 s20, s20, 0x1a00
	s_addc_u32 s21, s21, 0
	v_fma_f32 v50, v16, v34, v32
	v_fma_f32 v51, v16, v200, v32
	v_fmac_f32_e32 v50, v17, v35
	v_fmac_f32_e32 v51, v17, v201
	v_fmac_f32_e32 v50, v18, v36
	v_fmac_f32_e32 v51, v18, v202
	v_fmac_f32_e32 v50, v19, v37
	v_fmac_f32_e32 v51, v19, v203
	v_fmac_f32_e32 v50, v20, v38
	v_fmac_f32_e32 v51, v20, v204
	v_fmac_f32_e32 v50, v21, v39
	v_fmac_f32_e32 v51, v21, v205
	v_fmac_f32_e32 v50, v22, v40
	v_fmac_f32_e32 v51, v22, v206
	v_fmac_f32_e32 v50, v23, v41
	v_fmac_f32_e32 v51, v23, v207
	v_fmac_f32_e32 v50, v24, v42
	v_fmac_f32_e32 v51, v24, v208
	v_fmac_f32_e32 v50, v25, v43
	v_fmac_f32_e32 v51, v25, v209
	v_fmac_f32_e32 v50, v26, v44
	v_fmac_f32_e32 v51, v26, v210
	v_fmac_f32_e32 v50, v27, v45
	v_fmac_f32_e32 v51, v27, v211
	v_fmac_f32_e32 v50, v28, v46
	v_fmac_f32_e32 v51, v28, v212
	v_fmac_f32_e32 v50, v29, v47
	v_fmac_f32_e32 v51, v29, v213
	v_fmac_f32_e32 v50, v30, v48
	v_fmac_f32_e32 v51, v30, v214
	v_fmac_f32_e32 v50, v31, v49
	v_fmac_f32_e32 v51, v31, v215
	v_mul_f32_e64 v52, |v50|, s7
	v_mul_f32_e64 v53, |v51|, s7
	v_exp_f32_e32 v52, v52
	v_exp_f32_e32 v53, v53
	v_min_f32_e32 v50, 0, v50
	v_add_f32_e32 v52, 1.0, v52
	v_add_f32_e32 v53, 1.0, v53
	v_log_f32_e32 v52, v52
	v_log_f32_e32 v53, v53
	v_min_f32_e32 v51, 0, v51
	v_mul_f32_e32 v54, 0x3f317217, v52
	v_mul_f32_e32 v55, 0x3f317217, v53
	v_fma_f32 v56, v52, s9, -v54
	v_fma_f32 v57, v53, s9, -v55
	v_fmac_f32_e32 v56, 0x3377d1cf, v52
	v_fmac_f32_e32 v57, 0x3377d1cf, v53
	v_add_f32_e32 v54, v54, v56
	v_add_f32_e32 v55, v55, v57
	v_sub_f32_e32 v50, v50, v54
	v_sub_f32_e32 v51, v51, v55
	v_fmamk_f32 v72, v50, 0x3d800000, v71
	v_fmamk_f32 v73, v51, 0x3d800000, v72
	s_waitcnt lgkmcnt(0)
	ds_read_b128 v[34:37], v3 offset:768
	ds_read_b128 v[38:41], v3 offset:784
	ds_read_b128 v[42:45], v3 offset:800
	ds_read_b128 v[46:49], v3 offset:816
	ds_read_b128 v[200:203], v3 offset:832
	ds_read_b128 v[204:207], v3 offset:848
	ds_read_b128 v[208:211], v3 offset:864
	ds_read_b128 v[212:215], v3 offset:880
	global_load_ushort v156, v1, s[20:21]
	global_load_ushort v157, v1, s[20:21] offset:1024
	s_add_u32 s20, s20, 0x1a00
	s_addc_u32 s21, s21, 0
	global_load_ushort v158, v1, s[20:21]
	global_load_ushort v159, v1, s[20:21] offset:1024
	s_add_u32 s20, s20, 0x1a00
	s_addc_u32 s21, s21, 0
	v_fma_f32 v50, v16, v216, v32
	v_fma_f32 v51, v16, v236, v32
	v_fmac_f32_e32 v50, v17, v217
	v_fmac_f32_e32 v51, v17, v237
	v_fmac_f32_e32 v50, v18, v218
	v_fmac_f32_e32 v51, v18, v238
	v_fmac_f32_e32 v50, v19, v219
	v_fmac_f32_e32 v51, v19, v239
	v_fmac_f32_e32 v50, v20, v220
	v_fmac_f32_e32 v51, v20, v240
	v_fmac_f32_e32 v50, v21, v221
	v_fmac_f32_e32 v51, v21, v241
	v_fmac_f32_e32 v50, v22, v222
	v_fmac_f32_e32 v51, v22, v242
	v_fmac_f32_e32 v50, v23, v223
	v_fmac_f32_e32 v51, v23, v243
	v_fmac_f32_e32 v50, v24, v224
	v_fmac_f32_e32 v51, v24, v244
	v_fmac_f32_e32 v50, v25, v225
	v_fmac_f32_e32 v51, v25, v245
	v_fmac_f32_e32 v50, v26, v226
	v_fmac_f32_e32 v51, v26, v246
	v_fmac_f32_e32 v50, v27, v227
	v_fmac_f32_e32 v51, v27, v247
	v_fmac_f32_e32 v50, v28, v232
	v_fmac_f32_e32 v51, v28, v248
	v_fmac_f32_e32 v50, v29, v233
	v_fmac_f32_e32 v51, v29, v249
	v_fmac_f32_e32 v50, v30, v234
	v_fmac_f32_e32 v51, v30, v250
	v_fmac_f32_e32 v50, v31, v235
	v_fmac_f32_e32 v51, v31, v251
	v_mul_f32_e64 v52, |v50|, s7
	v_mul_f32_e64 v53, |v51|, s7
	v_exp_f32_e32 v52, v52
	v_exp_f32_e32 v53, v53
	v_min_f32_e32 v50, 0, v50
	v_add_f32_e32 v52, 1.0, v52
	v_add_f32_e32 v53, 1.0, v53
	v_log_f32_e32 v52, v52
	v_log_f32_e32 v53, v53
	v_min_f32_e32 v51, 0, v51
	v_mul_f32_e32 v54, 0x3f317217, v52
	v_mul_f32_e32 v55, 0x3f317217, v53
	v_fma_f32 v56, v52, s9, -v54
	v_fma_f32 v57, v53, s9, -v55
	v_fmac_f32_e32 v56, 0x3377d1cf, v52
	v_fmac_f32_e32 v57, 0x3377d1cf, v53
	v_add_f32_e32 v54, v54, v56
	v_add_f32_e32 v55, v55, v57
	v_sub_f32_e32 v50, v50, v54
	v_sub_f32_e32 v51, v51, v55
	v_fmamk_f32 v74, v50, 0x3d800000, v73
	v_fmamk_f32 v75, v51, 0x3d800000, v74
	s_waitcnt lgkmcnt(0)
	ds_read_b128 v[216:219], v3 offset:896
	ds_read_b128 v[220:223], v3 offset:912
	ds_read_b128 v[224:227], v3 offset:928
	ds_read_b128 v[232:235], v3 offset:944
	ds_read_b128 v[236:239], v3 offset:960
	ds_read_b128 v[240:243], v3 offset:976
	ds_read_b128 v[244:247], v3 offset:992
	ds_read_b128 v[248:251], v3 offset:1008
	global_load_ushort v160, v1, s[20:21]
	global_load_ushort v161, v1, s[20:21] offset:1024
	s_add_u32 s20, s20, 0x1a00
	s_addc_u32 s21, s21, 0
	global_load_ushort v162, v1, s[20:21]
	global_load_ushort v163, v1, s[20:21] offset:1024
	s_add_u32 s20, s20, 0x1a00
	s_addc_u32 s21, s21, 0
	v_fma_f32 v50, v16, v34, v32
	v_fma_f32 v51, v16, v200, v32
	v_fmac_f32_e32 v50, v17, v35
	v_fmac_f32_e32 v51, v17, v201
	v_fmac_f32_e32 v50, v18, v36
	v_fmac_f32_e32 v51, v18, v202
	v_fmac_f32_e32 v50, v19, v37
	v_fmac_f32_e32 v51, v19, v203
	v_fmac_f32_e32 v50, v20, v38
	v_fmac_f32_e32 v51, v20, v204
	v_fmac_f32_e32 v50, v21, v39
	v_fmac_f32_e32 v51, v21, v205
	v_fmac_f32_e32 v50, v22, v40
	v_fmac_f32_e32 v51, v22, v206
	v_fmac_f32_e32 v50, v23, v41
	v_fmac_f32_e32 v51, v23, v207
	v_fmac_f32_e32 v50, v24, v42
	v_fmac_f32_e32 v51, v24, v208
	v_fmac_f32_e32 v50, v25, v43
	v_fmac_f32_e32 v51, v25, v209
	v_fmac_f32_e32 v50, v26, v44
	v_fmac_f32_e32 v51, v26, v210
	v_fmac_f32_e32 v50, v27, v45
	v_fmac_f32_e32 v51, v27, v211
	v_fmac_f32_e32 v50, v28, v46
	v_fmac_f32_e32 v51, v28, v212
	v_fmac_f32_e32 v50, v29, v47
	v_fmac_f32_e32 v51, v29, v213
	v_fmac_f32_e32 v50, v30, v48
	v_fmac_f32_e32 v51, v30, v214
	v_fmac_f32_e32 v50, v31, v49
	v_fmac_f32_e32 v51, v31, v215
	v_mul_f32_e64 v52, |v50|, s7
	v_mul_f32_e64 v53, |v51|, s7
	v_exp_f32_e32 v52, v52
	v_exp_f32_e32 v53, v53
	v_min_f32_e32 v50, 0, v50
	v_add_f32_e32 v52, 1.0, v52
	v_add_f32_e32 v53, 1.0, v53
	v_log_f32_e32 v52, v52
	v_log_f32_e32 v53, v53
	v_min_f32_e32 v51, 0, v51
	v_mul_f32_e32 v54, 0x3f317217, v52
	v_mul_f32_e32 v55, 0x3f317217, v53
	v_fma_f32 v56, v52, s9, -v54
	v_fma_f32 v57, v53, s9, -v55
	v_fmac_f32_e32 v56, 0x3377d1cf, v52
	v_fmac_f32_e32 v57, 0x3377d1cf, v53
	v_add_f32_e32 v54, v54, v56
	v_add_f32_e32 v55, v55, v57
	v_sub_f32_e32 v50, v50, v54
	v_sub_f32_e32 v51, v51, v55
	v_fmamk_f32 v76, v50, 0x3d800000, v75
	v_fmamk_f32 v77, v51, 0x3d800000, v76
	s_waitcnt lgkmcnt(0)
	ds_read_b128 v[34:37], v3 offset:1024
	ds_read_b128 v[38:41], v3 offset:1040
	ds_read_b128 v[42:45], v3 offset:1056
	ds_read_b128 v[46:49], v3 offset:1072
	ds_read_b128 v[200:203], v3 offset:1088
	ds_read_b128 v[204:207], v3 offset:1104
	ds_read_b128 v[208:211], v3 offset:1120
	ds_read_b128 v[212:215], v3 offset:1136
	global_load_ushort v164, v1, s[20:21]
	global_load_ushort v165, v1, s[20:21] offset:1024
	s_add_u32 s20, s20, 0x1a00
	s_addc_u32 s21, s21, 0
	global_load_ushort v166, v1, s[20:21]
	global_load_ushort v167, v1, s[20:21] offset:1024
	s_add_u32 s20, s20, 0x1a00
	s_addc_u32 s21, s21, 0
	v_fma_f32 v50, v16, v216, v32
	v_fma_f32 v51, v16, v236, v32
	v_fmac_f32_e32 v50, v17, v217
	v_fmac_f32_e32 v51, v17, v237
	v_fmac_f32_e32 v50, v18, v218
	v_fmac_f32_e32 v51, v18, v238
	v_fmac_f32_e32 v50, v19, v219
	v_fmac_f32_e32 v51, v19, v239
	v_fmac_f32_e32 v50, v20, v220
	v_fmac_f32_e32 v51, v20, v240
	v_fmac_f32_e32 v50, v21, v221
	v_fmac_f32_e32 v51, v21, v241
	v_fmac_f32_e32 v50, v22, v222
	v_fmac_f32_e32 v51, v22, v242
	v_fmac_f32_e32 v50, v23, v223
	v_fmac_f32_e32 v51, v23, v243
	v_fmac_f32_e32 v50, v24, v224
	v_fmac_f32_e32 v51, v24, v244
	v_fmac_f32_e32 v50, v25, v225
	v_fmac_f32_e32 v51, v25, v245
	v_fmac_f32_e32 v50, v26, v226
	v_fmac_f32_e32 v51, v26, v246
	v_fmac_f32_e32 v50, v27, v227
	v_fmac_f32_e32 v51, v27, v247
	v_fmac_f32_e32 v50, v28, v232
	v_fmac_f32_e32 v51, v28, v248
	v_fmac_f32_e32 v50, v29, v233
	v_fmac_f32_e32 v51, v29, v249
	v_fmac_f32_e32 v50, v30, v234
	v_fmac_f32_e32 v51, v30, v250
	v_fmac_f32_e32 v50, v31, v235
	v_fmac_f32_e32 v51, v31, v251
	v_mul_f32_e64 v52, |v50|, s7
	v_mul_f32_e64 v53, |v51|, s7
	v_exp_f32_e32 v52, v52
	v_exp_f32_e32 v53, v53
	v_min_f32_e32 v50, 0, v50
	v_add_f32_e32 v52, 1.0, v52
	v_add_f32_e32 v53, 1.0, v53
	v_log_f32_e32 v52, v52
	v_log_f32_e32 v53, v53
	v_min_f32_e32 v51, 0, v51
	v_mul_f32_e32 v54, 0x3f317217, v52
	v_mul_f32_e32 v55, 0x3f317217, v53
	v_fma_f32 v56, v52, s9, -v54
	v_fma_f32 v57, v53, s9, -v55
	v_fmac_f32_e32 v56, 0x3377d1cf, v52
	v_fmac_f32_e32 v57, 0x3377d1cf, v53
	v_add_f32_e32 v54, v54, v56
	v_add_f32_e32 v55, v55, v57
	v_sub_f32_e32 v50, v50, v54
	v_sub_f32_e32 v51, v51, v55
	v_fmamk_f32 v78, v50, 0x3d800000, v77
	v_fmamk_f32 v79, v51, 0x3d800000, v78
	s_waitcnt lgkmcnt(0)
	ds_read_b128 v[216:219], v3 offset:1152
	ds_read_b128 v[220:223], v3 offset:1168
	ds_read_b128 v[224:227], v3 offset:1184
	ds_read_b128 v[232:235], v3 offset:1200
	ds_read_b128 v[236:239], v3 offset:1216
	ds_read_b128 v[240:243], v3 offset:1232
	ds_read_b128 v[244:247], v3 offset:1248
	ds_read_b128 v[248:251], v3 offset:1264
	global_load_ushort v168, v1, s[20:21]
	global_load_ushort v169, v1, s[20:21] offset:1024
	s_add_u32 s20, s20, 0x1a00
	s_addc_u32 s21, s21, 0
	global_load_ushort v170, v1, s[20:21]
	global_load_ushort v171, v1, s[20:21] offset:1024
	s_add_u32 s20, s20, 0x1a00
	s_addc_u32 s21, s21, 0
	v_fma_f32 v50, v16, v34, v32
	v_fma_f32 v51, v16, v200, v32
	v_fmac_f32_e32 v50, v17, v35
	v_fmac_f32_e32 v51, v17, v201
	v_fmac_f32_e32 v50, v18, v36
	v_fmac_f32_e32 v51, v18, v202
	v_fmac_f32_e32 v50, v19, v37
	v_fmac_f32_e32 v51, v19, v203
	v_fmac_f32_e32 v50, v20, v38
	v_fmac_f32_e32 v51, v20, v204
	v_fmac_f32_e32 v50, v21, v39
	v_fmac_f32_e32 v51, v21, v205
	v_fmac_f32_e32 v50, v22, v40
	v_fmac_f32_e32 v51, v22, v206
	v_fmac_f32_e32 v50, v23, v41
	v_fmac_f32_e32 v51, v23, v207
	v_fmac_f32_e32 v50, v24, v42
	v_fmac_f32_e32 v51, v24, v208
	v_fmac_f32_e32 v50, v25, v43
	v_fmac_f32_e32 v51, v25, v209
	v_fmac_f32_e32 v50, v26, v44
	v_fmac_f32_e32 v51, v26, v210
	v_fmac_f32_e32 v50, v27, v45
	v_fmac_f32_e32 v51, v27, v211
	v_fmac_f32_e32 v50, v28, v46
	v_fmac_f32_e32 v51, v28, v212
	v_fmac_f32_e32 v50, v29, v47
	v_fmac_f32_e32 v51, v29, v213
	v_fmac_f32_e32 v50, v30, v48
	v_fmac_f32_e32 v51, v30, v214
	v_fmac_f32_e32 v50, v31, v49
	v_fmac_f32_e32 v51, v31, v215
	v_mul_f32_e64 v52, |v50|, s7
	v_mul_f32_e64 v53, |v51|, s7
	v_exp_f32_e32 v52, v52
	v_exp_f32_e32 v53, v53
	v_min_f32_e32 v50, 0, v50
	v_add_f32_e32 v52, 1.0, v52
	v_add_f32_e32 v53, 1.0, v53
	v_log_f32_e32 v52, v52
	v_log_f32_e32 v53, v53
	v_min_f32_e32 v51, 0, v51
	v_mul_f32_e32 v54, 0x3f317217, v52
	v_mul_f32_e32 v55, 0x3f317217, v53
	v_fma_f32 v56, v52, s9, -v54
	v_fma_f32 v57, v53, s9, -v55
	v_fmac_f32_e32 v56, 0x3377d1cf, v52
	v_fmac_f32_e32 v57, 0x3377d1cf, v53
	v_add_f32_e32 v54, v54, v56
	v_add_f32_e32 v55, v55, v57
	v_sub_f32_e32 v50, v50, v54
	v_sub_f32_e32 v51, v51, v55
	v_fmamk_f32 v80, v50, 0x3d800000, v79
	v_fmamk_f32 v81, v51, 0x3d800000, v80
	s_waitcnt lgkmcnt(0)
	ds_read_b128 v[34:37], v3 offset:1280
	ds_read_b128 v[38:41], v3 offset:1296
	ds_read_b128 v[42:45], v3 offset:1312
	ds_read_b128 v[46:49], v3 offset:1328
	ds_read_b128 v[200:203], v3 offset:1344
	ds_read_b128 v[204:207], v3 offset:1360
	ds_read_b128 v[208:211], v3 offset:1376
	ds_read_b128 v[212:215], v3 offset:1392
	global_load_ushort v172, v1, s[20:21]
	global_load_ushort v173, v1, s[20:21] offset:1024
	s_add_u32 s20, s20, 0x1a00
	s_addc_u32 s21, s21, 0
	global_load_ushort v174, v1, s[20:21]
	global_load_ushort v175, v1, s[20:21] offset:1024
	s_add_u32 s20, s20, 0x1a00
	s_addc_u32 s21, s21, 0
	v_fma_f32 v50, v16, v216, v32
	v_fma_f32 v51, v16, v236, v32
	v_fmac_f32_e32 v50, v17, v217
	v_fmac_f32_e32 v51, v17, v237
	v_fmac_f32_e32 v50, v18, v218
	v_fmac_f32_e32 v51, v18, v238
	v_fmac_f32_e32 v50, v19, v219
	v_fmac_f32_e32 v51, v19, v239
	v_fmac_f32_e32 v50, v20, v220
	v_fmac_f32_e32 v51, v20, v240
	v_fmac_f32_e32 v50, v21, v221
	v_fmac_f32_e32 v51, v21, v241
	v_fmac_f32_e32 v50, v22, v222
	v_fmac_f32_e32 v51, v22, v242
	v_fmac_f32_e32 v50, v23, v223
	v_fmac_f32_e32 v51, v23, v243
	v_fmac_f32_e32 v50, v24, v224
	v_fmac_f32_e32 v51, v24, v244
	v_fmac_f32_e32 v50, v25, v225
	v_fmac_f32_e32 v51, v25, v245
	v_fmac_f32_e32 v50, v26, v226
	v_fmac_f32_e32 v51, v26, v246
	v_fmac_f32_e32 v50, v27, v227
	v_fmac_f32_e32 v51, v27, v247
	v_fmac_f32_e32 v50, v28, v232
	v_fmac_f32_e32 v51, v28, v248
	v_fmac_f32_e32 v50, v29, v233
	v_fmac_f32_e32 v51, v29, v249
	v_fmac_f32_e32 v50, v30, v234
	v_fmac_f32_e32 v51, v30, v250
	v_fmac_f32_e32 v50, v31, v235
	v_fmac_f32_e32 v51, v31, v251
	v_mul_f32_e64 v52, |v50|, s7
	v_mul_f32_e64 v53, |v51|, s7
	v_exp_f32_e32 v52, v52
	v_exp_f32_e32 v53, v53
	v_min_f32_e32 v50, 0, v50
	v_add_f32_e32 v52, 1.0, v52
	v_add_f32_e32 v53, 1.0, v53
	v_log_f32_e32 v52, v52
	v_log_f32_e32 v53, v53
	v_min_f32_e32 v51, 0, v51
	v_mul_f32_e32 v54, 0x3f317217, v52
	v_mul_f32_e32 v55, 0x3f317217, v53
	v_fma_f32 v56, v52, s9, -v54
	v_fma_f32 v57, v53, s9, -v55
	v_fmac_f32_e32 v56, 0x3377d1cf, v52
	v_fmac_f32_e32 v57, 0x3377d1cf, v53
	v_add_f32_e32 v54, v54, v56
	v_add_f32_e32 v55, v55, v57
	v_sub_f32_e32 v50, v50, v54
	v_sub_f32_e32 v51, v51, v55
	v_fmamk_f32 v82, v50, 0x3d800000, v81
	v_fmamk_f32 v83, v51, 0x3d800000, v82
	s_waitcnt lgkmcnt(0)
	ds_read_b128 v[216:219], v3 offset:1408
	ds_read_b128 v[220:223], v3 offset:1424
	ds_read_b128 v[224:227], v3 offset:1440
	ds_read_b128 v[232:235], v3 offset:1456
	ds_read_b128 v[236:239], v3 offset:1472
	ds_read_b128 v[240:243], v3 offset:1488
	ds_read_b128 v[244:247], v3 offset:1504
	ds_read_b128 v[248:251], v3 offset:1520
	global_load_ushort v176, v1, s[20:21]
	global_load_ushort v177, v1, s[20:21] offset:1024
	s_add_u32 s20, s20, 0x1a00
	s_addc_u32 s21, s21, 0
	global_load_ushort v178, v1, s[20:21]
	global_load_ushort v179, v1, s[20:21] offset:1024
	s_add_u32 s20, s20, 0x1a00
	s_addc_u32 s21, s21, 0
	v_fma_f32 v50, v16, v34, v32
	v_fma_f32 v51, v16, v200, v32
	v_fmac_f32_e32 v50, v17, v35
	v_fmac_f32_e32 v51, v17, v201
	v_fmac_f32_e32 v50, v18, v36
	v_fmac_f32_e32 v51, v18, v202
	v_fmac_f32_e32 v50, v19, v37
	v_fmac_f32_e32 v51, v19, v203
	v_fmac_f32_e32 v50, v20, v38
	v_fmac_f32_e32 v51, v20, v204
	v_fmac_f32_e32 v50, v21, v39
	v_fmac_f32_e32 v51, v21, v205
	v_fmac_f32_e32 v50, v22, v40
	v_fmac_f32_e32 v51, v22, v206
	v_fmac_f32_e32 v50, v23, v41
	v_fmac_f32_e32 v51, v23, v207
	v_fmac_f32_e32 v50, v24, v42
	v_fmac_f32_e32 v51, v24, v208
	v_fmac_f32_e32 v50, v25, v43
	v_fmac_f32_e32 v51, v25, v209
	v_fmac_f32_e32 v50, v26, v44
	v_fmac_f32_e32 v51, v26, v210
	v_fmac_f32_e32 v50, v27, v45
	v_fmac_f32_e32 v51, v27, v211
	v_fmac_f32_e32 v50, v28, v46
	v_fmac_f32_e32 v51, v28, v212
	v_fmac_f32_e32 v50, v29, v47
	v_fmac_f32_e32 v51, v29, v213
	v_fmac_f32_e32 v50, v30, v48
	v_fmac_f32_e32 v51, v30, v214
	v_fmac_f32_e32 v50, v31, v49
	v_fmac_f32_e32 v51, v31, v215
	v_mul_f32_e64 v52, |v50|, s7
	v_mul_f32_e64 v53, |v51|, s7
	v_exp_f32_e32 v52, v52
	v_exp_f32_e32 v53, v53
	v_min_f32_e32 v50, 0, v50
	v_add_f32_e32 v52, 1.0, v52
	v_add_f32_e32 v53, 1.0, v53
	v_log_f32_e32 v52, v52
	v_log_f32_e32 v53, v53
	v_min_f32_e32 v51, 0, v51
	v_mul_f32_e32 v54, 0x3f317217, v52
	v_mul_f32_e32 v55, 0x3f317217, v53
	v_fma_f32 v56, v52, s9, -v54
	v_fma_f32 v57, v53, s9, -v55
	v_fmac_f32_e32 v56, 0x3377d1cf, v52
	v_fmac_f32_e32 v57, 0x3377d1cf, v53
	v_add_f32_e32 v54, v54, v56
	v_add_f32_e32 v55, v55, v57
	v_sub_f32_e32 v50, v50, v54
	v_sub_f32_e32 v51, v51, v55
	v_fmamk_f32 v84, v50, 0x3d800000, v83
	v_fmamk_f32 v85, v51, 0x3d800000, v84
	s_waitcnt lgkmcnt(0)
	ds_read_b128 v[34:37], v3 offset:1536
	ds_read_b128 v[38:41], v3 offset:1552
	ds_read_b128 v[42:45], v3 offset:1568
	ds_read_b128 v[46:49], v3 offset:1584
	ds_read_b128 v[200:203], v3 offset:1600
	ds_read_b128 v[204:207], v3 offset:1616
	ds_read_b128 v[208:211], v3 offset:1632
	ds_read_b128 v[212:215], v3 offset:1648
	global_load_ushort v180, v1, s[20:21]
	global_load_ushort v181, v1, s[20:21] offset:1024
	s_add_u32 s20, s20, 0x1a00
	s_addc_u32 s21, s21, 0
	global_load_ushort v182, v1, s[20:21]
	global_load_ushort v183, v1, s[20:21] offset:1024
	s_add_u32 s20, s20, 0x1a00
	s_addc_u32 s21, s21, 0
	v_fma_f32 v50, v16, v216, v32
	v_fma_f32 v51, v16, v236, v32
	v_fmac_f32_e32 v50, v17, v217
	v_fmac_f32_e32 v51, v17, v237
	v_fmac_f32_e32 v50, v18, v218
	v_fmac_f32_e32 v51, v18, v238
	v_fmac_f32_e32 v50, v19, v219
	v_fmac_f32_e32 v51, v19, v239
	v_fmac_f32_e32 v50, v20, v220
	v_fmac_f32_e32 v51, v20, v240
	v_fmac_f32_e32 v50, v21, v221
	v_fmac_f32_e32 v51, v21, v241
	v_fmac_f32_e32 v50, v22, v222
	v_fmac_f32_e32 v51, v22, v242
	v_fmac_f32_e32 v50, v23, v223
	v_fmac_f32_e32 v51, v23, v243
	v_fmac_f32_e32 v50, v24, v224
	v_fmac_f32_e32 v51, v24, v244
	v_fmac_f32_e32 v50, v25, v225
	v_fmac_f32_e32 v51, v25, v245
	v_fmac_f32_e32 v50, v26, v226
	v_fmac_f32_e32 v51, v26, v246
	v_fmac_f32_e32 v50, v27, v227
	v_fmac_f32_e32 v51, v27, v247
	v_fmac_f32_e32 v50, v28, v232
	v_fmac_f32_e32 v51, v28, v248
	v_fmac_f32_e32 v50, v29, v233
	v_fmac_f32_e32 v51, v29, v249
	v_fmac_f32_e32 v50, v30, v234
	v_fmac_f32_e32 v51, v30, v250
	v_fmac_f32_e32 v50, v31, v235
	v_fmac_f32_e32 v51, v31, v251
	v_mul_f32_e64 v52, |v50|, s7
	v_mul_f32_e64 v53, |v51|, s7
	v_exp_f32_e32 v52, v52
	v_exp_f32_e32 v53, v53
	v_min_f32_e32 v50, 0, v50
	v_add_f32_e32 v52, 1.0, v52
	v_add_f32_e32 v53, 1.0, v53
	v_log_f32_e32 v52, v52
	v_log_f32_e32 v53, v53
	v_min_f32_e32 v51, 0, v51
	v_mul_f32_e32 v54, 0x3f317217, v52
	v_mul_f32_e32 v55, 0x3f317217, v53
	v_fma_f32 v56, v52, s9, -v54
	v_fma_f32 v57, v53, s9, -v55
	v_fmac_f32_e32 v56, 0x3377d1cf, v52
	v_fmac_f32_e32 v57, 0x3377d1cf, v53
	v_add_f32_e32 v54, v54, v56
	v_add_f32_e32 v55, v55, v57
	v_sub_f32_e32 v50, v50, v54
	v_sub_f32_e32 v51, v51, v55
	v_fmamk_f32 v86, v50, 0x3d800000, v85
	v_fmamk_f32 v87, v51, 0x3d800000, v86
	s_waitcnt lgkmcnt(0)
	ds_read_b128 v[216:219], v3 offset:1664
	ds_read_b128 v[220:223], v3 offset:1680
	ds_read_b128 v[224:227], v3 offset:1696
	ds_read_b128 v[232:235], v3 offset:1712
	ds_read_b128 v[236:239], v3 offset:1728
	ds_read_b128 v[240:243], v3 offset:1744
	ds_read_b128 v[244:247], v3 offset:1760
	ds_read_b128 v[248:251], v3 offset:1776
	global_load_ushort v184, v1, s[20:21]
	global_load_ushort v185, v1, s[20:21] offset:1024
	s_add_u32 s20, s20, 0x1a00
	s_addc_u32 s21, s21, 0
	global_load_ushort v186, v1, s[20:21]
	global_load_ushort v187, v1, s[20:21] offset:1024
	s_add_u32 s20, s20, 0x1a00
	s_addc_u32 s21, s21, 0
	v_fma_f32 v50, v16, v34, v32
	v_fma_f32 v51, v16, v200, v32
	v_fmac_f32_e32 v50, v17, v35
	v_fmac_f32_e32 v51, v17, v201
	v_fmac_f32_e32 v50, v18, v36
	v_fmac_f32_e32 v51, v18, v202
	v_fmac_f32_e32 v50, v19, v37
	v_fmac_f32_e32 v51, v19, v203
	v_fmac_f32_e32 v50, v20, v38
	v_fmac_f32_e32 v51, v20, v204
	v_fmac_f32_e32 v50, v21, v39
	v_fmac_f32_e32 v51, v21, v205
	v_fmac_f32_e32 v50, v22, v40
	v_fmac_f32_e32 v51, v22, v206
	v_fmac_f32_e32 v50, v23, v41
	v_fmac_f32_e32 v51, v23, v207
	v_fmac_f32_e32 v50, v24, v42
	v_fmac_f32_e32 v51, v24, v208
	v_fmac_f32_e32 v50, v25, v43
	v_fmac_f32_e32 v51, v25, v209
	v_fmac_f32_e32 v50, v26, v44
	v_fmac_f32_e32 v51, v26, v210
	v_fmac_f32_e32 v50, v27, v45
	v_fmac_f32_e32 v51, v27, v211
	v_fmac_f32_e32 v50, v28, v46
	v_fmac_f32_e32 v51, v28, v212
	v_fmac_f32_e32 v50, v29, v47
	v_fmac_f32_e32 v51, v29, v213
	v_fmac_f32_e32 v50, v30, v48
	v_fmac_f32_e32 v51, v30, v214
	v_fmac_f32_e32 v50, v31, v49
	v_fmac_f32_e32 v51, v31, v215
	v_mul_f32_e64 v52, |v50|, s7
	v_mul_f32_e64 v53, |v51|, s7
	v_exp_f32_e32 v52, v52
	v_exp_f32_e32 v53, v53
	v_min_f32_e32 v50, 0, v50
	v_add_f32_e32 v52, 1.0, v52
	v_add_f32_e32 v53, 1.0, v53
	v_log_f32_e32 v52, v52
	v_log_f32_e32 v53, v53
	v_min_f32_e32 v51, 0, v51
	v_mul_f32_e32 v54, 0x3f317217, v52
	v_mul_f32_e32 v55, 0x3f317217, v53
	v_fma_f32 v56, v52, s9, -v54
	v_fma_f32 v57, v53, s9, -v55
	v_fmac_f32_e32 v56, 0x3377d1cf, v52
	v_fmac_f32_e32 v57, 0x3377d1cf, v53
	v_add_f32_e32 v54, v54, v56
	v_add_f32_e32 v55, v55, v57
	v_sub_f32_e32 v50, v50, v54
	v_sub_f32_e32 v51, v51, v55
	v_fmamk_f32 v88, v50, 0x3d800000, v87
	v_fmamk_f32 v89, v51, 0x3d800000, v88
	s_waitcnt lgkmcnt(0)
	ds_read_b128 v[34:37], v3 offset:1792
	ds_read_b128 v[38:41], v3 offset:1808
	ds_read_b128 v[42:45], v3 offset:1824
	ds_read_b128 v[46:49], v3 offset:1840
	ds_read_b128 v[200:203], v3 offset:1856
	ds_read_b128 v[204:207], v3 offset:1872
	ds_read_b128 v[208:211], v3 offset:1888
	ds_read_b128 v[212:215], v3 offset:1904
	global_load_ushort v188, v1, s[20:21]
	global_load_ushort v189, v1, s[20:21] offset:1024
	s_add_u32 s20, s20, 0x1a00
	s_addc_u32 s21, s21, 0
	global_load_ushort v190, v1, s[20:21]
	global_load_ushort v191, v1, s[20:21] offset:1024
	s_add_u32 s20, s20, 0x1a00
	s_addc_u32 s21, s21, 0
	v_fma_f32 v50, v16, v216, v32
	v_fma_f32 v51, v16, v236, v32
	v_fmac_f32_e32 v50, v17, v217
	v_fmac_f32_e32 v51, v17, v237
	v_fmac_f32_e32 v50, v18, v218
	v_fmac_f32_e32 v51, v18, v238
	v_fmac_f32_e32 v50, v19, v219
	v_fmac_f32_e32 v51, v19, v239
	v_fmac_f32_e32 v50, v20, v220
	v_fmac_f32_e32 v51, v20, v240
	v_fmac_f32_e32 v50, v21, v221
	v_fmac_f32_e32 v51, v21, v241
	v_fmac_f32_e32 v50, v22, v222
	v_fmac_f32_e32 v51, v22, v242
	v_fmac_f32_e32 v50, v23, v223
	v_fmac_f32_e32 v51, v23, v243
	v_fmac_f32_e32 v50, v24, v224
	v_fmac_f32_e32 v51, v24, v244
	v_fmac_f32_e32 v50, v25, v225
	v_fmac_f32_e32 v51, v25, v245
	v_fmac_f32_e32 v50, v26, v226
	v_fmac_f32_e32 v51, v26, v246
	v_fmac_f32_e32 v50, v27, v227
	v_fmac_f32_e32 v51, v27, v247
	v_fmac_f32_e32 v50, v28, v232
	v_fmac_f32_e32 v51, v28, v248
	v_fmac_f32_e32 v50, v29, v233
	v_fmac_f32_e32 v51, v29, v249
	v_fmac_f32_e32 v50, v30, v234
	v_fmac_f32_e32 v51, v30, v250
	v_fmac_f32_e32 v50, v31, v235
	v_fmac_f32_e32 v51, v31, v251
	v_mul_f32_e64 v52, |v50|, s7
	v_mul_f32_e64 v53, |v51|, s7
	v_exp_f32_e32 v52, v52
	v_exp_f32_e32 v53, v53
	v_min_f32_e32 v50, 0, v50
	v_add_f32_e32 v52, 1.0, v52
	v_add_f32_e32 v53, 1.0, v53
	v_log_f32_e32 v52, v52
	v_log_f32_e32 v53, v53
	v_min_f32_e32 v51, 0, v51
	v_mul_f32_e32 v54, 0x3f317217, v52
	v_mul_f32_e32 v55, 0x3f317217, v53
	v_fma_f32 v56, v52, s9, -v54
	v_fma_f32 v57, v53, s9, -v55
	v_fmac_f32_e32 v56, 0x3377d1cf, v52
	v_fmac_f32_e32 v57, 0x3377d1cf, v53
	v_add_f32_e32 v54, v54, v56
	v_add_f32_e32 v55, v55, v57
	v_sub_f32_e32 v50, v50, v54
	v_sub_f32_e32 v51, v51, v55
	v_fmamk_f32 v90, v50, 0x3d800000, v89
	v_fmamk_f32 v91, v51, 0x3d800000, v90
	s_waitcnt lgkmcnt(0)
	ds_read_b128 v[216:219], v3 offset:1920
	ds_read_b128 v[220:223], v3 offset:1936
	ds_read_b128 v[224:227], v3 offset:1952
	ds_read_b128 v[232:235], v3 offset:1968
	ds_read_b128 v[236:239], v3 offset:1984
	ds_read_b128 v[240:243], v3 offset:2000
	ds_read_b128 v[244:247], v3 offset:2016
	ds_read_b128 v[248:251], v3 offset:2032
	s_waitcnt vmcnt(56)
	global_load_ushort v192, v1, s[20:21]
	global_load_ushort v193, v1, s[20:21] offset:1024
	s_add_u32 s20, s20, 0x1a00
	s_addc_u32 s21, s21, 0
	global_load_ushort v194, v1, s[20:21]
	global_load_ushort v195, v1, s[20:21] offset:1024
	s_add_u32 s20, s20, 0x1a00
	s_addc_u32 s21, s21, 0
	v_fma_f32 v50, v16, v34, v32
	v_fma_f32 v51, v16, v200, v32
	v_fmac_f32_e32 v50, v17, v35
	v_fmac_f32_e32 v51, v17, v201
	v_fmac_f32_e32 v50, v18, v36
	v_fmac_f32_e32 v51, v18, v202
	v_fmac_f32_e32 v50, v19, v37
	v_fmac_f32_e32 v51, v19, v203
	v_fmac_f32_e32 v50, v20, v38
	v_fmac_f32_e32 v51, v20, v204
	v_fmac_f32_e32 v50, v21, v39
	v_fmac_f32_e32 v51, v21, v205
	v_fmac_f32_e32 v50, v22, v40
	v_fmac_f32_e32 v51, v22, v206
	v_fmac_f32_e32 v50, v23, v41
	v_fmac_f32_e32 v51, v23, v207
	v_fmac_f32_e32 v50, v24, v42
	v_fmac_f32_e32 v51, v24, v208
	v_fmac_f32_e32 v50, v25, v43
	v_fmac_f32_e32 v51, v25, v209
	v_fmac_f32_e32 v50, v26, v44
	v_fmac_f32_e32 v51, v26, v210
	v_fmac_f32_e32 v50, v27, v45
	v_fmac_f32_e32 v51, v27, v211
	v_fmac_f32_e32 v50, v28, v46
	v_fmac_f32_e32 v51, v28, v212
	v_fmac_f32_e32 v50, v29, v47
	v_fmac_f32_e32 v51, v29, v213
	v_fmac_f32_e32 v50, v30, v48
	v_fmac_f32_e32 v51, v30, v214
	v_fmac_f32_e32 v50, v31, v49
	v_fmac_f32_e32 v51, v31, v215
	v_mul_f32_e64 v52, |v50|, s7
	v_mul_f32_e64 v53, |v51|, s7
	v_exp_f32_e32 v52, v52
	v_exp_f32_e32 v53, v53
	v_min_f32_e32 v50, 0, v50
	v_add_f32_e32 v52, 1.0, v52
	v_add_f32_e32 v53, 1.0, v53
	v_log_f32_e32 v52, v52
	v_log_f32_e32 v53, v53
	v_min_f32_e32 v51, 0, v51
	v_mul_f32_e32 v54, 0x3f317217, v52
	v_mul_f32_e32 v55, 0x3f317217, v53
	v_fma_f32 v56, v52, s9, -v54
	v_fma_f32 v57, v53, s9, -v55
	v_fmac_f32_e32 v56, 0x3377d1cf, v52
	v_fmac_f32_e32 v57, 0x3377d1cf, v53
	v_add_f32_e32 v54, v54, v56
	v_add_f32_e32 v55, v55, v57
	v_sub_f32_e32 v50, v50, v54
	v_sub_f32_e32 v51, v51, v55
	v_fmamk_f32 v92, v50, 0x3d800000, v91
	v_fmamk_f32 v93, v51, 0x3d800000, v92
	s_waitcnt lgkmcnt(0)
	ds_read_b128 v[34:37], v3 offset:2048
	ds_read_b128 v[38:41], v3 offset:2064
	ds_read_b128 v[42:45], v3 offset:2080
	ds_read_b128 v[46:49], v3 offset:2096
	ds_read_b128 v[200:203], v3 offset:2112
	ds_read_b128 v[204:207], v3 offset:2128
	ds_read_b128 v[208:211], v3 offset:2144
	ds_read_b128 v[212:215], v3 offset:2160
	s_waitcnt vmcnt(56)
	global_load_ushort v196, v1, s[20:21]
	global_load_ushort v197, v1, s[20:21] offset:1024
	s_add_u32 s20, s20, 0x1a00
	s_addc_u32 s21, s21, 0
	global_load_ushort v198, v1, s[20:21]
	global_load_ushort v199, v1, s[20:21] offset:1024
	s_add_u32 s20, s20, 0x1a00
	s_addc_u32 s21, s21, 0
	v_fma_f32 v50, v16, v216, v32
	v_fma_f32 v51, v16, v236, v32
	v_fmac_f32_e32 v50, v17, v217
	v_fmac_f32_e32 v51, v17, v237
	v_fmac_f32_e32 v50, v18, v218
	v_fmac_f32_e32 v51, v18, v238
	v_fmac_f32_e32 v50, v19, v219
	v_fmac_f32_e32 v51, v19, v239
	v_fmac_f32_e32 v50, v20, v220
	v_fmac_f32_e32 v51, v20, v240
	v_fmac_f32_e32 v50, v21, v221
	v_fmac_f32_e32 v51, v21, v241
	v_fmac_f32_e32 v50, v22, v222
	v_fmac_f32_e32 v51, v22, v242
	v_fmac_f32_e32 v50, v23, v223
	v_fmac_f32_e32 v51, v23, v243
	v_fmac_f32_e32 v50, v24, v224
	v_fmac_f32_e32 v51, v24, v244
	v_fmac_f32_e32 v50, v25, v225
	v_fmac_f32_e32 v51, v25, v245
	v_fmac_f32_e32 v50, v26, v226
	v_fmac_f32_e32 v51, v26, v246
	v_fmac_f32_e32 v50, v27, v227
	v_fmac_f32_e32 v51, v27, v247
	v_fmac_f32_e32 v50, v28, v232
	v_fmac_f32_e32 v51, v28, v248
	v_fmac_f32_e32 v50, v29, v233
	v_fmac_f32_e32 v51, v29, v249
	v_fmac_f32_e32 v50, v30, v234
	v_fmac_f32_e32 v51, v30, v250
	v_fmac_f32_e32 v50, v31, v235
	v_fmac_f32_e32 v51, v31, v251
	v_mul_f32_e64 v52, |v50|, s7
	v_mul_f32_e64 v53, |v51|, s7
	v_exp_f32_e32 v52, v52
	v_exp_f32_e32 v53, v53
	v_min_f32_e32 v50, 0, v50
	v_add_f32_e32 v52, 1.0, v52
	v_add_f32_e32 v53, 1.0, v53
	v_log_f32_e32 v52, v52
	v_log_f32_e32 v53, v53
	v_min_f32_e32 v51, 0, v51
	v_mul_f32_e32 v54, 0x3f317217, v52
	v_mul_f32_e32 v55, 0x3f317217, v53
	v_fma_f32 v56, v52, s9, -v54
	v_fma_f32 v57, v53, s9, -v55
	v_fmac_f32_e32 v56, 0x3377d1cf, v52
	v_fmac_f32_e32 v57, 0x3377d1cf, v53
	v_add_f32_e32 v54, v54, v56
	v_add_f32_e32 v55, v55, v57
	v_sub_f32_e32 v50, v50, v54
	v_sub_f32_e32 v51, v51, v55
	v_fmamk_f32 v94, v50, 0x3d800000, v93
	v_fmamk_f32 v95, v51, 0x3d800000, v94
	s_waitcnt lgkmcnt(0)
	ds_read_b128 v[216:219], v3 offset:2176
	ds_read_b128 v[220:223], v3 offset:2192
	ds_read_b128 v[224:227], v3 offset:2208
	ds_read_b128 v[232:235], v3 offset:2224
	ds_read_b128 v[236:239], v3 offset:2240
	ds_read_b128 v[240:243], v3 offset:2256
	ds_read_b128 v[244:247], v3 offset:2272
	ds_read_b128 v[248:251], v3 offset:2288
	v_fma_f32 v50, v16, v34, v32
	v_fma_f32 v51, v16, v200, v32
	v_fmac_f32_e32 v50, v17, v35
	v_fmac_f32_e32 v51, v17, v201
	v_fmac_f32_e32 v50, v18, v36
	v_fmac_f32_e32 v51, v18, v202
	v_fmac_f32_e32 v50, v19, v37
	v_fmac_f32_e32 v51, v19, v203
	v_fmac_f32_e32 v50, v20, v38
	v_fmac_f32_e32 v51, v20, v204
	v_fmac_f32_e32 v50, v21, v39
	v_fmac_f32_e32 v51, v21, v205
	v_fmac_f32_e32 v50, v22, v40
	v_fmac_f32_e32 v51, v22, v206
	v_fmac_f32_e32 v50, v23, v41
	v_fmac_f32_e32 v51, v23, v207
	v_fmac_f32_e32 v50, v24, v42
	v_fmac_f32_e32 v51, v24, v208
	v_fmac_f32_e32 v50, v25, v43
	v_fmac_f32_e32 v51, v25, v209
	v_fmac_f32_e32 v50, v26, v44
	v_fmac_f32_e32 v51, v26, v210
	v_fmac_f32_e32 v50, v27, v45
	v_fmac_f32_e32 v51, v27, v211
	v_fmac_f32_e32 v50, v28, v46
	v_fmac_f32_e32 v51, v28, v212
	v_fmac_f32_e32 v50, v29, v47
	v_fmac_f32_e32 v51, v29, v213
	v_fmac_f32_e32 v50, v30, v48
	v_fmac_f32_e32 v51, v30, v214
	v_fmac_f32_e32 v50, v31, v49
	v_fmac_f32_e32 v51, v31, v215
	v_mul_f32_e64 v52, |v50|, s7
	v_mul_f32_e64 v53, |v51|, s7
	v_exp_f32_e32 v52, v52
	v_exp_f32_e32 v53, v53
	v_min_f32_e32 v50, 0, v50
	v_add_f32_e32 v52, 1.0, v52
	v_add_f32_e32 v53, 1.0, v53
	v_log_f32_e32 v52, v52
	v_log_f32_e32 v53, v53
	v_min_f32_e32 v51, 0, v51
	v_mul_f32_e32 v54, 0x3f317217, v52
	v_mul_f32_e32 v55, 0x3f317217, v53
	v_fma_f32 v56, v52, s9, -v54
	v_fma_f32 v57, v53, s9, -v55
	v_fmac_f32_e32 v56, 0x3377d1cf, v52
	v_fmac_f32_e32 v57, 0x3377d1cf, v53
	v_add_f32_e32 v54, v54, v56
	v_add_f32_e32 v55, v55, v57
	v_sub_f32_e32 v50, v50, v54
	v_sub_f32_e32 v51, v51, v55
	v_fmamk_f32 v96, v50, 0x3d800000, v95
	v_fmamk_f32 v97, v51, 0x3d800000, v96
	s_waitcnt vmcnt(0)
	v_sub_f32_e32 v52, v64, v96
	v_lshlrev_b32_e32 v50, 16, v136
	v_mul_f32_e32 v52, 0x3fb8aa3b, v52
	v_lshlrev_b32_e32 v51, 16, v137
	v_exp_f32_e32 v53, v52
	v_exp_f32_e64 v54, -v52
	v_mul_f32_e32 v50, 0x3db504f3, v50
	s_nop 0
	v_mul_f32_e32 v50, v53, v50
	v_mul_f32_e32 v8, v54, v51
	v_cvt_pk_bf16_f32 v50, v50, v8
	global_store_short v1, v50, s[22:23]
	global_store_short_d16_hi v1, v50, s[22:23] offset:1024
	s_add_u32 s22, s22, 0x1a00
	s_addc_u32 s23, s23, 0
	global_load_ushort v136, v1, s[20:21]
	global_load_ushort v137, v1, s[20:21] offset:1024
	s_add_u32 s20, s20, 0x1a00
	s_addc_u32 s21, s21, 0
	v_sub_f32_e32 v52, v65, v96
	v_lshlrev_b32_e32 v50, 16, v138
	v_mul_f32_e32 v52, 0x3fb8aa3b, v52
	v_lshlrev_b32_e32 v51, 16, v139
	v_exp_f32_e32 v53, v52
	v_exp_f32_e64 v54, -v52
	v_mul_f32_e32 v50, 0x3db504f3, v50
	s_nop 0
	v_mul_f32_e32 v50, v53, v50
	v_mul_f32_e32 v9, v54, v51
	v_cvt_pk_bf16_f32 v50, v50, v9
	global_store_short v1, v50, s[22:23]
	global_store_short_d16_hi v1, v50, s[22:23] offset:1024
	s_add_u32 s22, s22, 0x1a00
	s_addc_u32 s23, s23, 0
	global_load_ushort v138, v1, s[20:21]
	global_load_ushort v139, v1, s[20:21] offset:1024
	s_add_u32 s20, s20, 0x1a00
	s_addc_u32 s21, s21, 0
	v_sub_f32_e32 v52, v66, v96
	v_lshlrev_b32_e32 v50, 16, v140
	v_mul_f32_e32 v52, 0x3fb8aa3b, v52
	v_lshlrev_b32_e32 v51, 16, v141
	v_exp_f32_e32 v53, v52
	v_exp_f32_e64 v54, -v52
	v_mul_f32_e32 v50, 0x3db504f3, v50
	s_nop 0
	v_mul_f32_e32 v50, v53, v50
	v_mul_f32_e32 v10, v54, v51
	v_cvt_pk_bf16_f32 v50, v50, v10
	global_store_short v1, v50, s[22:23]
	global_store_short_d16_hi v1, v50, s[22:23] offset:1024
	s_add_u32 s22, s22, 0x1a00
	s_addc_u32 s23, s23, 0
	global_load_ushort v140, v1, s[20:21]
	global_load_ushort v141, v1, s[20:21] offset:1024
	s_add_u32 s20, s20, 0x1a00
	s_addc_u32 s21, s21, 0
	v_sub_f32_e32 v52, v67, v96
	v_lshlrev_b32_e32 v50, 16, v142
	v_mul_f32_e32 v52, 0x3fb8aa3b, v52
	v_lshlrev_b32_e32 v51, 16, v143
	v_exp_f32_e32 v53, v52
	v_exp_f32_e64 v54, -v52
	v_mul_f32_e32 v50, 0x3db504f3, v50
	s_nop 0
	v_mul_f32_e32 v50, v53, v50
	v_mul_f32_e32 v11, v54, v51
	v_cvt_pk_bf16_f32 v50, v50, v11
	global_store_short v1, v50, s[22:23]
	global_store_short_d16_hi v1, v50, s[22:23] offset:1024
	s_add_u32 s22, s22, 0x1a00
	s_addc_u32 s23, s23, 0
	global_load_ushort v142, v1, s[20:21]
	global_load_ushort v143, v1, s[20:21] offset:1024
	s_add_u32 s20, s20, 0x1a00
	s_addc_u32 s21, s21, 0
	v_sub_f32_e32 v52, v68, v96
	v_lshlrev_b32_e32 v50, 16, v144
	v_mul_f32_e32 v52, 0x3fb8aa3b, v52
	v_lshlrev_b32_e32 v51, 16, v145
	v_exp_f32_e32 v53, v52
	v_exp_f32_e64 v54, -v52
	v_mul_f32_e32 v50, 0x3db504f3, v50
	s_nop 0
	v_mul_f32_e32 v50, v53, v50
	v_mul_f32_e32 v12, v54, v51
	v_cvt_pk_bf16_f32 v50, v50, v12
	global_store_short v1, v50, s[22:23]
	global_store_short_d16_hi v1, v50, s[22:23] offset:1024
	s_add_u32 s22, s22, 0x1a00
	s_addc_u32 s23, s23, 0
	global_load_ushort v144, v1, s[20:21]
	global_load_ushort v145, v1, s[20:21] offset:1024
	s_add_u32 s20, s20, 0x1a00
	s_addc_u32 s21, s21, 0
	v_sub_f32_e32 v52, v69, v96
	v_lshlrev_b32_e32 v50, 16, v146
	v_mul_f32_e32 v52, 0x3fb8aa3b, v52
	v_lshlrev_b32_e32 v51, 16, v147
	v_exp_f32_e32 v53, v52
	v_exp_f32_e64 v54, -v52
	v_mul_f32_e32 v50, 0x3db504f3, v50
	s_nop 0
	v_mul_f32_e32 v50, v53, v50
	v_mul_f32_e32 v13, v54, v51
	v_cvt_pk_bf16_f32 v50, v50, v13
	global_store_short v1, v50, s[22:23]
	global_store_short_d16_hi v1, v50, s[22:23] offset:1024
	s_add_u32 s22, s22, 0x1a00
	s_addc_u32 s23, s23, 0
	global_load_ushort v146, v1, s[20:21]
	global_load_ushort v147, v1, s[20:21] offset:1024
	s_add_u32 s20, s20, 0x1a00
	s_addc_u32 s21, s21, 0
	v_sub_f32_e32 v52, v70, v96
	v_lshlrev_b32_e32 v50, 16, v148
	v_mul_f32_e32 v52, 0x3fb8aa3b, v52
	v_lshlrev_b32_e32 v51, 16, v149
	v_exp_f32_e32 v53, v52
	v_exp_f32_e64 v54, -v52
	v_mul_f32_e32 v50, 0x3db504f3, v50
	s_nop 0
	v_mul_f32_e32 v50, v53, v50
	v_mul_f32_e32 v14, v54, v51
	v_cvt_pk_bf16_f32 v50, v50, v14
	global_store_short v1, v50, s[22:23]
	global_store_short_d16_hi v1, v50, s[22:23] offset:1024
	s_add_u32 s22, s22, 0x1a00
	s_addc_u32 s23, s23, 0
	global_load_ushort v148, v1, s[20:21]
	global_load_ushort v149, v1, s[20:21] offset:1024
	s_add_u32 s20, s20, 0x1a00
	s_addc_u32 s21, s21, 0
	v_sub_f32_e32 v52, v71, v96
	v_lshlrev_b32_e32 v50, 16, v150
	v_mul_f32_e32 v52, 0x3fb8aa3b, v52
	v_lshlrev_b32_e32 v51, 16, v151
	v_exp_f32_e32 v53, v52
	v_exp_f32_e64 v54, -v52
	v_mul_f32_e32 v50, 0x3db504f3, v50
	s_nop 0
	v_mul_f32_e32 v50, v53, v50
	v_mul_f32_e32 v15, v54, v51
	v_cvt_pk_bf16_f32 v50, v50, v15
	global_store_short v1, v50, s[22:23]
	global_store_short_d16_hi v1, v50, s[22:23] offset:1024
	s_add_u32 s22, s22, 0x1a00
	s_addc_u32 s23, s23, 0
	v_cvt_pk_bf16_f32 v4, v8, v9
	v_cvt_pk_bf16_f32 v5, v10, v11
	v_cvt_pk_bf16_f32 v6, v12, v13
	v_cvt_pk_bf16_f32 v7, v14, v15
	global_store_dwordx4 v2, v[4:7], s[26:27] offset:0 sc1
	global_load_ushort v150, v1, s[20:21]
	global_load_ushort v151, v1, s[20:21] offset:1024
	s_add_u32 s20, s20, 0x1a00
	s_addc_u32 s21, s21, 0
	v_sub_f32_e32 v52, v72, v96
	v_lshlrev_b32_e32 v50, 16, v152
	v_mul_f32_e32 v52, 0x3fb8aa3b, v52
	v_lshlrev_b32_e32 v51, 16, v153
	v_exp_f32_e32 v53, v52
	v_exp_f32_e64 v54, -v52
	v_mul_f32_e32 v50, 0x3db504f3, v50
	s_nop 0
	v_mul_f32_e32 v50, v53, v50
	v_mul_f32_e32 v8, v54, v51
	v_cvt_pk_bf16_f32 v50, v50, v8
	global_store_short v1, v50, s[22:23]
	global_store_short_d16_hi v1, v50, s[22:23] offset:1024
	s_add_u32 s22, s22, 0x1a00
	s_addc_u32 s23, s23, 0
	global_load_ushort v152, v1, s[20:21]
	global_load_ushort v153, v1, s[20:21] offset:1024
	s_add_u32 s20, s20, 0x1a00
	s_addc_u32 s21, s21, 0
	v_sub_f32_e32 v52, v73, v96
	v_lshlrev_b32_e32 v50, 16, v154
	v_mul_f32_e32 v52, 0x3fb8aa3b, v52
	v_lshlrev_b32_e32 v51, 16, v155
	v_exp_f32_e32 v53, v52
	v_exp_f32_e64 v54, -v52
	v_mul_f32_e32 v50, 0x3db504f3, v50
	s_nop 0
	v_mul_f32_e32 v50, v53, v50
	v_mul_f32_e32 v9, v54, v51
	v_cvt_pk_bf16_f32 v50, v50, v9
	global_store_short v1, v50, s[22:23]
	global_store_short_d16_hi v1, v50, s[22:23] offset:1024
	s_add_u32 s22, s22, 0x1a00
	s_addc_u32 s23, s23, 0
	global_load_ushort v154, v1, s[20:21]
	global_load_ushort v155, v1, s[20:21] offset:1024
	s_add_u32 s20, s20, 0x1a00
	s_addc_u32 s21, s21, 0
	v_sub_f32_e32 v52, v74, v96
	v_lshlrev_b32_e32 v50, 16, v156
	v_mul_f32_e32 v52, 0x3fb8aa3b, v52
	v_lshlrev_b32_e32 v51, 16, v157
	v_exp_f32_e32 v53, v52
	v_exp_f32_e64 v54, -v52
	v_mul_f32_e32 v50, 0x3db504f3, v50
	s_nop 0
	v_mul_f32_e32 v50, v53, v50
	v_mul_f32_e32 v10, v54, v51
	v_cvt_pk_bf16_f32 v50, v50, v10
	global_store_short v1, v50, s[22:23]
	global_store_short_d16_hi v1, v50, s[22:23] offset:1024
	s_add_u32 s22, s22, 0x1a00
	s_addc_u32 s23, s23, 0
	global_load_ushort v156, v1, s[20:21]
	global_load_ushort v157, v1, s[20:21] offset:1024
	s_add_u32 s20, s20, 0x1a00
	s_addc_u32 s21, s21, 0
	v_sub_f32_e32 v52, v75, v96
	v_lshlrev_b32_e32 v50, 16, v158
	v_mul_f32_e32 v52, 0x3fb8aa3b, v52
	v_lshlrev_b32_e32 v51, 16, v159
	v_exp_f32_e32 v53, v52
	v_exp_f32_e64 v54, -v52
	v_mul_f32_e32 v50, 0x3db504f3, v50
	s_nop 0
	v_mul_f32_e32 v50, v53, v50
	v_mul_f32_e32 v11, v54, v51
	v_cvt_pk_bf16_f32 v50, v50, v11
	global_store_short v1, v50, s[22:23]
	global_store_short_d16_hi v1, v50, s[22:23] offset:1024
	s_add_u32 s22, s22, 0x1a00
	s_addc_u32 s23, s23, 0
	global_load_ushort v158, v1, s[20:21]
	global_load_ushort v159, v1, s[20:21] offset:1024
	s_add_u32 s20, s20, 0x1a00
	s_addc_u32 s21, s21, 0
	s_waitcnt vmcnt(52)
	v_sub_f32_e32 v52, v76, v96
	v_lshlrev_b32_e32 v50, 16, v160
	v_mul_f32_e32 v52, 0x3fb8aa3b, v52
	v_lshlrev_b32_e32 v51, 16, v161
	v_exp_f32_e32 v53, v52
	v_exp_f32_e64 v54, -v52
	v_mul_f32_e32 v50, 0x3db504f3, v50
	s_nop 0
	v_mul_f32_e32 v50, v53, v50
	v_mul_f32_e32 v12, v54, v51
	v_cvt_pk_bf16_f32 v50, v50, v12
	global_store_short v1, v50, s[22:23]
	global_store_short_d16_hi v1, v50, s[22:23] offset:1024
	s_add_u32 s22, s22, 0x1a00
	s_addc_u32 s23, s23, 0
	global_load_ushort v160, v1, s[20:21]
	global_load_ushort v161, v1, s[20:21] offset:1024
	s_add_u32 s20, s20, 0x1a00
	s_addc_u32 s21, s21, 0
	s_waitcnt vmcnt(52)
	v_sub_f32_e32 v52, v77, v96
	v_lshlrev_b32_e32 v50, 16, v162
	v_mul_f32_e32 v52, 0x3fb8aa3b, v52
	v_lshlrev_b32_e32 v51, 16, v163
	v_exp_f32_e32 v53, v52
	v_exp_f32_e64 v54, -v52
	v_mul_f32_e32 v50, 0x3db504f3, v50
	s_nop 0
	v_mul_f32_e32 v50, v53, v50
	v_mul_f32_e32 v13, v54, v51
	v_cvt_pk_bf16_f32 v50, v50, v13
	global_store_short v1, v50, s[22:23]
	global_store_short_d16_hi v1, v50, s[22:23] offset:1024
	s_add_u32 s22, s22, 0x1a00
	s_addc_u32 s23, s23, 0
	global_load_ushort v162, v1, s[20:21]
	global_load_ushort v163, v1, s[20:21] offset:1024
	s_add_u32 s20, s20, 0x1a00
	s_addc_u32 s21, s21, 0
	s_waitcnt vmcnt(52)
	v_sub_f32_e32 v52, v78, v96
	v_lshlrev_b32_e32 v50, 16, v164
	v_mul_f32_e32 v52, 0x3fb8aa3b, v52
	v_lshlrev_b32_e32 v51, 16, v165
	v_exp_f32_e32 v53, v52
	v_exp_f32_e64 v54, -v52
	v_mul_f32_e32 v50, 0x3db504f3, v50
	s_nop 0
	v_mul_f32_e32 v50, v53, v50
	v_mul_f32_e32 v14, v54, v51
	v_cvt_pk_bf16_f32 v50, v50, v14
	global_store_short v1, v50, s[22:23]
	global_store_short_d16_hi v1, v50, s[22:23] offset:1024
	s_add_u32 s22, s22, 0x1a00
	s_addc_u32 s23, s23, 0
	global_load_ushort v164, v1, s[20:21]
	global_load_ushort v165, v1, s[20:21] offset:1024
	s_add_u32 s20, s20, 0x1a00
	s_addc_u32 s21, s21, 0
	s_waitcnt vmcnt(52)
	v_sub_f32_e32 v52, v79, v96
	v_lshlrev_b32_e32 v50, 16, v166
	v_mul_f32_e32 v52, 0x3fb8aa3b, v52
	v_lshlrev_b32_e32 v51, 16, v167
	v_exp_f32_e32 v53, v52
	v_exp_f32_e64 v54, -v52
	v_mul_f32_e32 v50, 0x3db504f3, v50
	s_nop 0
	v_mul_f32_e32 v50, v53, v50
	v_mul_f32_e32 v15, v54, v51
	v_cvt_pk_bf16_f32 v50, v50, v15
	global_store_short v1, v50, s[22:23]
	global_store_short_d16_hi v1, v50, s[22:23] offset:1024
	s_add_u32 s22, s22, 0x1a00
	s_addc_u32 s23, s23, 0
	v_cvt_pk_bf16_f32 v4, v8, v9
	v_cvt_pk_bf16_f32 v5, v10, v11
	v_cvt_pk_bf16_f32 v6, v12, v13
	v_cvt_pk_bf16_f32 v7, v14, v15
	global_store_dwordx4 v2, v[4:7], s[26:27] offset:16 sc1
	global_load_ushort v166, v1, s[20:21]
	global_load_ushort v167, v1, s[20:21] offset:1024
	s_add_u32 s20, s20, 0x1a00
	s_addc_u32 s21, s21, 0
	s_waitcnt vmcnt(52)
	v_sub_f32_e32 v52, v80, v96
	v_lshlrev_b32_e32 v50, 16, v168
	v_mul_f32_e32 v52, 0x3fb8aa3b, v52
	v_lshlrev_b32_e32 v51, 16, v169
	v_exp_f32_e32 v53, v52
	v_exp_f32_e64 v54, -v52
	v_mul_f32_e32 v50, 0x3db504f3, v50
	s_nop 0
	v_mul_f32_e32 v50, v53, v50
	v_mul_f32_e32 v8, v54, v51
	v_cvt_pk_bf16_f32 v50, v50, v8
	global_store_short v1, v50, s[22:23]
	global_store_short_d16_hi v1, v50, s[22:23] offset:1024
	s_add_u32 s22, s22, 0x1a00
	s_addc_u32 s23, s23, 0
	global_load_ushort v168, v1, s[20:21]
	global_load_ushort v169, v1, s[20:21] offset:1024
	s_add_u32 s20, s20, 0x1a00
	s_addc_u32 s21, s21, 0
	s_waitcnt vmcnt(52)
	v_sub_f32_e32 v52, v81, v96
	v_lshlrev_b32_e32 v50, 16, v170
	v_mul_f32_e32 v52, 0x3fb8aa3b, v52
	v_lshlrev_b32_e32 v51, 16, v171
	v_exp_f32_e32 v53, v52
	v_exp_f32_e64 v54, -v52
	v_mul_f32_e32 v50, 0x3db504f3, v50
	s_nop 0
	v_mul_f32_e32 v50, v53, v50
	v_mul_f32_e32 v9, v54, v51
	v_cvt_pk_bf16_f32 v50, v50, v9
	global_store_short v1, v50, s[22:23]
	global_store_short_d16_hi v1, v50, s[22:23] offset:1024
	s_add_u32 s22, s22, 0x1a00
	s_addc_u32 s23, s23, 0
	global_load_ushort v170, v1, s[20:21]
	global_load_ushort v171, v1, s[20:21] offset:1024
	s_add_u32 s20, s20, 0x1a00
	s_addc_u32 s21, s21, 0
	s_waitcnt vmcnt(52)
	v_sub_f32_e32 v52, v82, v96
	v_lshlrev_b32_e32 v50, 16, v172
	v_mul_f32_e32 v52, 0x3fb8aa3b, v52
	v_lshlrev_b32_e32 v51, 16, v173
	v_exp_f32_e32 v53, v52
	v_exp_f32_e64 v54, -v52
	v_mul_f32_e32 v50, 0x3db504f3, v50
	s_nop 0
	v_mul_f32_e32 v50, v53, v50
	v_mul_f32_e32 v10, v54, v51
	v_cvt_pk_bf16_f32 v50, v50, v10
	global_store_short v1, v50, s[22:23]
	global_store_short_d16_hi v1, v50, s[22:23] offset:1024
	s_add_u32 s22, s22, 0x1a00
	s_addc_u32 s23, s23, 0
	global_load_ushort v172, v1, s[20:21]
	global_load_ushort v173, v1, s[20:21] offset:1024
	s_add_u32 s20, s20, 0x1a00
	s_addc_u32 s21, s21, 0
	s_waitcnt vmcnt(52)
	v_sub_f32_e32 v52, v83, v96
	v_lshlrev_b32_e32 v50, 16, v174
	v_mul_f32_e32 v52, 0x3fb8aa3b, v52
	v_lshlrev_b32_e32 v51, 16, v175
	v_exp_f32_e32 v53, v52
	v_exp_f32_e64 v54, -v52
	v_mul_f32_e32 v50, 0x3db504f3, v50
	s_nop 0
	v_mul_f32_e32 v50, v53, v50
	v_mul_f32_e32 v11, v54, v51
	v_cvt_pk_bf16_f32 v50, v50, v11
	global_store_short v1, v50, s[22:23]
	global_store_short_d16_hi v1, v50, s[22:23] offset:1024
	s_add_u32 s22, s22, 0x1a00
	s_addc_u32 s23, s23, 0
	global_load_ushort v174, v1, s[20:21]
	global_load_ushort v175, v1, s[20:21] offset:1024
	s_add_u32 s20, s20, 0x1a00
	s_addc_u32 s21, s21, 0
	s_waitcnt vmcnt(52)
	v_sub_f32_e32 v52, v84, v96
	v_lshlrev_b32_e32 v50, 16, v176
	v_mul_f32_e32 v52, 0x3fb8aa3b, v52
	v_lshlrev_b32_e32 v51, 16, v177
	v_exp_f32_e32 v53, v52
	v_exp_f32_e64 v54, -v52
	v_mul_f32_e32 v50, 0x3db504f3, v50
	s_nop 0
	v_mul_f32_e32 v50, v53, v50
	v_mul_f32_e32 v12, v54, v51
	v_cvt_pk_bf16_f32 v50, v50, v12
	global_store_short v1, v50, s[22:23]
	global_store_short_d16_hi v1, v50, s[22:23] offset:1024
	s_add_u32 s22, s22, 0x1a00
	s_addc_u32 s23, s23, 0
	global_load_ushort v176, v1, s[20:21]
	global_load_ushort v177, v1, s[20:21] offset:1024
	s_add_u32 s20, s20, 0x1a00
	s_addc_u32 s21, s21, 0
	s_waitcnt vmcnt(52)
	v_sub_f32_e32 v52, v85, v96
	v_lshlrev_b32_e32 v50, 16, v178
	v_mul_f32_e32 v52, 0x3fb8aa3b, v52
	v_lshlrev_b32_e32 v51, 16, v179
	v_exp_f32_e32 v53, v52
	v_exp_f32_e64 v54, -v52
	v_mul_f32_e32 v50, 0x3db504f3, v50
	s_nop 0
	v_mul_f32_e32 v50, v53, v50
	v_mul_f32_e32 v13, v54, v51
	v_cvt_pk_bf16_f32 v50, v50, v13
	global_store_short v1, v50, s[22:23]
	global_store_short_d16_hi v1, v50, s[22:23] offset:1024
	s_add_u32 s22, s22, 0x1a00
	s_addc_u32 s23, s23, 0
	global_load_ushort v178, v1, s[20:21]
	global_load_ushort v179, v1, s[20:21] offset:1024
	s_add_u32 s20, s20, 0x1a00
	s_addc_u32 s21, s21, 0
	s_waitcnt vmcnt(52)
	v_sub_f32_e32 v52, v86, v96
	v_lshlrev_b32_e32 v50, 16, v180
	v_mul_f32_e32 v52, 0x3fb8aa3b, v52
	v_lshlrev_b32_e32 v51, 16, v181
	v_exp_f32_e32 v53, v52
	v_exp_f32_e64 v54, -v52
	v_mul_f32_e32 v50, 0x3db504f3, v50
	s_nop 0
	v_mul_f32_e32 v50, v53, v50
	v_mul_f32_e32 v14, v54, v51
	v_cvt_pk_bf16_f32 v50, v50, v14
	global_store_short v1, v50, s[22:23]
	global_store_short_d16_hi v1, v50, s[22:23] offset:1024
	s_add_u32 s22, s22, 0x1a00
	s_addc_u32 s23, s23, 0
	global_load_ushort v180, v1, s[20:21]
	global_load_ushort v181, v1, s[20:21] offset:1024
	s_add_u32 s20, s20, 0x1a00
	s_addc_u32 s21, s21, 0
	s_waitcnt vmcnt(52)
	v_sub_f32_e32 v52, v87, v96
	v_lshlrev_b32_e32 v50, 16, v182
	v_mul_f32_e32 v52, 0x3fb8aa3b, v52
	v_lshlrev_b32_e32 v51, 16, v183
	v_exp_f32_e32 v53, v52
	v_exp_f32_e64 v54, -v52
	v_mul_f32_e32 v50, 0x3db504f3, v50
	s_nop 0
	v_mul_f32_e32 v50, v53, v50
	v_mul_f32_e32 v15, v54, v51
	v_cvt_pk_bf16_f32 v50, v50, v15
	global_store_short v1, v50, s[22:23]
	global_store_short_d16_hi v1, v50, s[22:23] offset:1024
	s_add_u32 s22, s22, 0x1a00
	s_addc_u32 s23, s23, 0
	v_cvt_pk_bf16_f32 v4, v8, v9
	v_cvt_pk_bf16_f32 v5, v10, v11
	v_cvt_pk_bf16_f32 v6, v12, v13
	v_cvt_pk_bf16_f32 v7, v14, v15
	global_store_dwordx4 v2, v[4:7], s[26:27] offset:32 sc1
	global_load_ushort v182, v1, s[20:21]
	global_load_ushort v183, v1, s[20:21] offset:1024
	s_add_u32 s20, s20, 0x1a00
	s_addc_u32 s21, s21, 0
	s_waitcnt vmcnt(52)
	v_sub_f32_e32 v52, v88, v96
	v_lshlrev_b32_e32 v50, 16, v184
	v_mul_f32_e32 v52, 0x3fb8aa3b, v52
	v_lshlrev_b32_e32 v51, 16, v185
	v_exp_f32_e32 v53, v52
	v_exp_f32_e64 v54, -v52
	v_mul_f32_e32 v50, 0x3db504f3, v50
	s_nop 0
	v_mul_f32_e32 v50, v53, v50
	v_mul_f32_e32 v8, v54, v51
	v_cvt_pk_bf16_f32 v50, v50, v8
	global_store_short v1, v50, s[22:23]
	global_store_short_d16_hi v1, v50, s[22:23] offset:1024
	s_add_u32 s22, s22, 0x1a00
	s_addc_u32 s23, s23, 0
	global_load_ushort v184, v1, s[20:21]
	global_load_ushort v185, v1, s[20:21] offset:1024
	s_add_u32 s20, s20, 0x1a00
	s_addc_u32 s21, s21, 0
	s_waitcnt vmcnt(52)
	v_sub_f32_e32 v52, v89, v96
	v_lshlrev_b32_e32 v50, 16, v186
	v_mul_f32_e32 v52, 0x3fb8aa3b, v52
	v_lshlrev_b32_e32 v51, 16, v187
	v_exp_f32_e32 v53, v52
	v_exp_f32_e64 v54, -v52
	v_mul_f32_e32 v50, 0x3db504f3, v50
	s_nop 0
	v_mul_f32_e32 v50, v53, v50
	v_mul_f32_e32 v9, v54, v51
	v_cvt_pk_bf16_f32 v50, v50, v9
	global_store_short v1, v50, s[22:23]
	global_store_short_d16_hi v1, v50, s[22:23] offset:1024
	s_add_u32 s22, s22, 0x1a00
	s_addc_u32 s23, s23, 0
	global_load_ushort v186, v1, s[20:21]
	global_load_ushort v187, v1, s[20:21] offset:1024
	s_add_u32 s20, s20, 0x1a00
	s_addc_u32 s21, s21, 0
	s_waitcnt vmcnt(52)
	v_sub_f32_e32 v52, v90, v96
	v_lshlrev_b32_e32 v50, 16, v188
	v_mul_f32_e32 v52, 0x3fb8aa3b, v52
	v_lshlrev_b32_e32 v51, 16, v189
	v_exp_f32_e32 v53, v52
	v_exp_f32_e64 v54, -v52
	v_mul_f32_e32 v50, 0x3db504f3, v50
	s_nop 0
	v_mul_f32_e32 v50, v53, v50
	v_mul_f32_e32 v10, v54, v51
	v_cvt_pk_bf16_f32 v50, v50, v10
	global_store_short v1, v50, s[22:23]
	global_store_short_d16_hi v1, v50, s[22:23] offset:1024
	s_add_u32 s22, s22, 0x1a00
	s_addc_u32 s23, s23, 0
	global_load_ushort v188, v1, s[20:21]
	global_load_ushort v189, v1, s[20:21] offset:1024
	s_add_u32 s20, s20, 0x1a00
	s_addc_u32 s21, s21, 0
	s_waitcnt vmcnt(52)
	v_sub_f32_e32 v52, v91, v96
	v_lshlrev_b32_e32 v50, 16, v190
	v_mul_f32_e32 v52, 0x3fb8aa3b, v52
	v_lshlrev_b32_e32 v51, 16, v191
	v_exp_f32_e32 v53, v52
	v_exp_f32_e64 v54, -v52
	v_mul_f32_e32 v50, 0x3db504f3, v50
	s_nop 0
	v_mul_f32_e32 v50, v53, v50
	v_mul_f32_e32 v11, v54, v51
	v_cvt_pk_bf16_f32 v50, v50, v11
	global_store_short v1, v50, s[22:23]
	global_store_short_d16_hi v1, v50, s[22:23] offset:1024
	s_add_u32 s22, s22, 0x1a00
	s_addc_u32 s23, s23, 0
	global_load_ushort v190, v1, s[20:21]
	global_load_ushort v191, v1, s[20:21] offset:1024
	s_add_u32 s20, s20, 0x1a00
	s_addc_u32 s21, s21, 0
	s_waitcnt vmcnt(52)
	v_sub_f32_e32 v52, v92, v96
	v_lshlrev_b32_e32 v50, 16, v192
	v_mul_f32_e32 v52, 0x3fb8aa3b, v52
	v_lshlrev_b32_e32 v51, 16, v193
	v_exp_f32_e32 v53, v52
	v_exp_f32_e64 v54, -v52
	v_mul_f32_e32 v50, 0x3db504f3, v50
	s_nop 0
	v_mul_f32_e32 v50, v53, v50
	v_mul_f32_e32 v12, v54, v51
	v_cvt_pk_bf16_f32 v50, v50, v12
	global_store_short v1, v50, s[22:23]
	global_store_short_d16_hi v1, v50, s[22:23] offset:1024
	s_add_u32 s22, s22, 0x1a00
	s_addc_u32 s23, s23, 0
	global_load_ushort v192, v1, s[20:21]
	global_load_ushort v193, v1, s[20:21] offset:1024
	s_add_u32 s20, s20, 0x1a00
	s_addc_u32 s21, s21, 0
	s_waitcnt vmcnt(52)
	v_sub_f32_e32 v52, v93, v96
	v_lshlrev_b32_e32 v50, 16, v194
	v_mul_f32_e32 v52, 0x3fb8aa3b, v52
	v_lshlrev_b32_e32 v51, 16, v195
	v_exp_f32_e32 v53, v52
	v_exp_f32_e64 v54, -v52
	v_mul_f32_e32 v50, 0x3db504f3, v50
	s_nop 0
	v_mul_f32_e32 v50, v53, v50
	v_mul_f32_e32 v13, v54, v51
	v_cvt_pk_bf16_f32 v50, v50, v13
	global_store_short v1, v50, s[22:23]
	global_store_short_d16_hi v1, v50, s[22:23] offset:1024
	s_add_u32 s22, s22, 0x1a00
	s_addc_u32 s23, s23, 0
	global_load_ushort v194, v1, s[20:21]
	global_load_ushort v195, v1, s[20:21] offset:1024
	s_add_u32 s20, s20, 0x1a00
	s_addc_u32 s21, s21, 0
	s_waitcnt vmcnt(52)
	v_sub_f32_e32 v52, v94, v96
	v_lshlrev_b32_e32 v50, 16, v196
	v_mul_f32_e32 v52, 0x3fb8aa3b, v52
	v_lshlrev_b32_e32 v51, 16, v197
	v_exp_f32_e32 v53, v52
	v_exp_f32_e64 v54, -v52
	v_mul_f32_e32 v50, 0x3db504f3, v50
	s_nop 0
	v_mul_f32_e32 v50, v53, v50
	v_mul_f32_e32 v14, v54, v51
	v_cvt_pk_bf16_f32 v50, v50, v14
	global_store_short v1, v50, s[22:23]
	global_store_short_d16_hi v1, v50, s[22:23] offset:1024
	s_add_u32 s22, s22, 0x1a00
	s_addc_u32 s23, s23, 0
	global_load_ushort v196, v1, s[20:21]
	global_load_ushort v197, v1, s[20:21] offset:1024
	s_add_u32 s20, s20, 0x1a00
	s_addc_u32 s21, s21, 0
	s_waitcnt vmcnt(52)
	v_sub_f32_e32 v52, v95, v96
	v_lshlrev_b32_e32 v50, 16, v198
	v_mul_f32_e32 v52, 0x3fb8aa3b, v52
	v_lshlrev_b32_e32 v51, 16, v199
	v_exp_f32_e32 v53, v52
	v_exp_f32_e64 v54, -v52
	v_mul_f32_e32 v50, 0x3db504f3, v50
	s_nop 0
	v_mul_f32_e32 v50, v53, v50
	v_mul_f32_e32 v15, v54, v51
	v_cvt_pk_bf16_f32 v50, v50, v15
	global_store_short v1, v50, s[22:23]
	global_store_short_d16_hi v1, v50, s[22:23] offset:1024
	s_add_u32 s22, s22, 0x1a00
	s_addc_u32 s23, s23, 0
	v_cvt_pk_bf16_f32 v4, v8, v9
	v_cvt_pk_bf16_f32 v5, v10, v11
	v_cvt_pk_bf16_f32 v6, v12, v13
	v_cvt_pk_bf16_f32 v7, v14, v15
	global_store_dwordx4 v2, v[4:7], s[26:27] offset:48 sc1
	global_load_ushort v198, v1, s[20:21]
	global_load_ushort v199, v1, s[20:21] offset:1024
	s_add_u32 s20, s20, 0x1a00
	s_addc_u32 s21, s21, 0
	s_waitcnt lgkmcnt(0)
	ds_read_b128 v[34:37], v3 offset:2304
	ds_read_b128 v[38:41], v3 offset:2320
	ds_read_b128 v[42:45], v3 offset:2336
	ds_read_b128 v[46:49], v3 offset:2352
	ds_read_b128 v[200:203], v3 offset:2368
	ds_read_b128 v[204:207], v3 offset:2384
	ds_read_b128 v[208:211], v3 offset:2400
	ds_read_b128 v[212:215], v3 offset:2416
	v_fma_f32 v50, v16, v216, v32
	v_fma_f32 v51, v16, v236, v32
	v_fmac_f32_e32 v50, v17, v217
	v_fmac_f32_e32 v51, v17, v237
	v_fmac_f32_e32 v50, v18, v218
	v_fmac_f32_e32 v51, v18, v238
	v_fmac_f32_e32 v50, v19, v219
	v_fmac_f32_e32 v51, v19, v239
	v_fmac_f32_e32 v50, v20, v220
	v_fmac_f32_e32 v51, v20, v240
	v_fmac_f32_e32 v50, v21, v221
	v_fmac_f32_e32 v51, v21, v241
	v_fmac_f32_e32 v50, v22, v222
	v_fmac_f32_e32 v51, v22, v242
	v_fmac_f32_e32 v50, v23, v223
	v_fmac_f32_e32 v51, v23, v243
	v_fmac_f32_e32 v50, v24, v224
	v_fmac_f32_e32 v51, v24, v244
	v_fmac_f32_e32 v50, v25, v225
	v_fmac_f32_e32 v51, v25, v245
	v_fmac_f32_e32 v50, v26, v226
	v_fmac_f32_e32 v51, v26, v246
	v_fmac_f32_e32 v50, v27, v227
	v_fmac_f32_e32 v51, v27, v247
	v_fmac_f32_e32 v50, v28, v232
	v_fmac_f32_e32 v51, v28, v248
	v_fmac_f32_e32 v50, v29, v233
	v_fmac_f32_e32 v51, v29, v249
	v_fmac_f32_e32 v50, v30, v234
	v_fmac_f32_e32 v51, v30, v250
	v_fmac_f32_e32 v50, v31, v235
	v_fmac_f32_e32 v51, v31, v251
	v_mul_f32_e64 v52, |v50|, s7
	v_mul_f32_e64 v53, |v51|, s7
	v_exp_f32_e32 v52, v52
	v_exp_f32_e32 v53, v53
	v_min_f32_e32 v50, 0, v50
	v_add_f32_e32 v52, 1.0, v52
	v_add_f32_e32 v53, 1.0, v53
	v_log_f32_e32 v52, v52
	v_log_f32_e32 v53, v53
	v_min_f32_e32 v51, 0, v51
	v_mul_f32_e32 v54, 0x3f317217, v52
	v_mul_f32_e32 v55, 0x3f317217, v53
	v_fma_f32 v56, v52, s9, -v54
	v_fma_f32 v57, v53, s9, -v55
	v_fmac_f32_e32 v56, 0x3377d1cf, v52
	v_fmac_f32_e32 v57, 0x3377d1cf, v53
	v_add_f32_e32 v54, v54, v56
	v_add_f32_e32 v55, v55, v57
	v_sub_f32_e32 v50, v50, v54
	v_sub_f32_e32 v51, v51, v55
	v_fmamk_f32 v98, v50, 0x3d800000, v97
	v_fmamk_f32 v99, v51, 0x3d800000, v98
	s_waitcnt lgkmcnt(0)
	ds_read_b128 v[216:219], v3 offset:2432
	ds_read_b128 v[220:223], v3 offset:2448
	ds_read_b128 v[224:227], v3 offset:2464
	ds_read_b128 v[232:235], v3 offset:2480
	ds_read_b128 v[236:239], v3 offset:2496
	ds_read_b128 v[240:243], v3 offset:2512
	ds_read_b128 v[244:247], v3 offset:2528
	ds_read_b128 v[248:251], v3 offset:2544
	v_fma_f32 v50, v16, v34, v32
	v_fma_f32 v51, v16, v200, v32
	v_fmac_f32_e32 v50, v17, v35
	v_fmac_f32_e32 v51, v17, v201
	v_fmac_f32_e32 v50, v18, v36
	v_fmac_f32_e32 v51, v18, v202
	v_fmac_f32_e32 v50, v19, v37
	v_fmac_f32_e32 v51, v19, v203
	v_fmac_f32_e32 v50, v20, v38
	v_fmac_f32_e32 v51, v20, v204
	v_fmac_f32_e32 v50, v21, v39
	v_fmac_f32_e32 v51, v21, v205
	v_fmac_f32_e32 v50, v22, v40
	v_fmac_f32_e32 v51, v22, v206
	v_fmac_f32_e32 v50, v23, v41
	v_fmac_f32_e32 v51, v23, v207
	v_fmac_f32_e32 v50, v24, v42
	v_fmac_f32_e32 v51, v24, v208
	v_fmac_f32_e32 v50, v25, v43
	v_fmac_f32_e32 v51, v25, v209
	v_fmac_f32_e32 v50, v26, v44
	v_fmac_f32_e32 v51, v26, v210
	v_fmac_f32_e32 v50, v27, v45
	v_fmac_f32_e32 v51, v27, v211
	v_fmac_f32_e32 v50, v28, v46
	v_fmac_f32_e32 v51, v28, v212
	v_fmac_f32_e32 v50, v29, v47
	v_fmac_f32_e32 v51, v29, v213
	v_fmac_f32_e32 v50, v30, v48
	v_fmac_f32_e32 v51, v30, v214
	v_fmac_f32_e32 v50, v31, v49
	v_fmac_f32_e32 v51, v31, v215
	v_mul_f32_e64 v52, |v50|, s7
	v_mul_f32_e64 v53, |v51|, s7
	v_exp_f32_e32 v52, v52
	v_exp_f32_e32 v53, v53
	v_min_f32_e32 v50, 0, v50
	v_add_f32_e32 v52, 1.0, v52
	v_add_f32_e32 v53, 1.0, v53
	v_log_f32_e32 v52, v52
	v_log_f32_e32 v53, v53
	v_min_f32_e32 v51, 0, v51
	v_mul_f32_e32 v54, 0x3f317217, v52
	v_mul_f32_e32 v55, 0x3f317217, v53
	v_fma_f32 v56, v52, s9, -v54
	v_fma_f32 v57, v53, s9, -v55
	v_fmac_f32_e32 v56, 0x3377d1cf, v52
	v_fmac_f32_e32 v57, 0x3377d1cf, v53
	v_add_f32_e32 v54, v54, v56
	v_add_f32_e32 v55, v55, v57
	v_sub_f32_e32 v50, v50, v54
	v_sub_f32_e32 v51, v51, v55
	v_fmamk_f32 v100, v50, 0x3d800000, v99
	v_fmamk_f32 v101, v51, 0x3d800000, v100
	s_waitcnt lgkmcnt(0)
	ds_read_b128 v[34:37], v3 offset:2560
	ds_read_b128 v[38:41], v3 offset:2576
	ds_read_b128 v[42:45], v3 offset:2592
	ds_read_b128 v[46:49], v3 offset:2608
	ds_read_b128 v[200:203], v3 offset:2624
	ds_read_b128 v[204:207], v3 offset:2640
	ds_read_b128 v[208:211], v3 offset:2656
	ds_read_b128 v[212:215], v3 offset:2672
	v_fma_f32 v50, v16, v216, v32
	v_fma_f32 v51, v16, v236, v32
	v_fmac_f32_e32 v50, v17, v217
	v_fmac_f32_e32 v51, v17, v237
	v_fmac_f32_e32 v50, v18, v218
	v_fmac_f32_e32 v51, v18, v238
	v_fmac_f32_e32 v50, v19, v219
	v_fmac_f32_e32 v51, v19, v239
	v_fmac_f32_e32 v50, v20, v220
	v_fmac_f32_e32 v51, v20, v240
	v_fmac_f32_e32 v50, v21, v221
	v_fmac_f32_e32 v51, v21, v241
	v_fmac_f32_e32 v50, v22, v222
	v_fmac_f32_e32 v51, v22, v242
	v_fmac_f32_e32 v50, v23, v223
	v_fmac_f32_e32 v51, v23, v243
	v_fmac_f32_e32 v50, v24, v224
	v_fmac_f32_e32 v51, v24, v244
	v_fmac_f32_e32 v50, v25, v225
	v_fmac_f32_e32 v51, v25, v245
	v_fmac_f32_e32 v50, v26, v226
	v_fmac_f32_e32 v51, v26, v246
	v_fmac_f32_e32 v50, v27, v227
	v_fmac_f32_e32 v51, v27, v247
	v_fmac_f32_e32 v50, v28, v232
	v_fmac_f32_e32 v51, v28, v248
	v_fmac_f32_e32 v50, v29, v233
	v_fmac_f32_e32 v51, v29, v249
	v_fmac_f32_e32 v50, v30, v234
	v_fmac_f32_e32 v51, v30, v250
	v_fmac_f32_e32 v50, v31, v235
	v_fmac_f32_e32 v51, v31, v251
	v_mul_f32_e64 v52, |v50|, s7
	v_mul_f32_e64 v53, |v51|, s7
	v_exp_f32_e32 v52, v52
	v_exp_f32_e32 v53, v53
	v_min_f32_e32 v50, 0, v50
	v_add_f32_e32 v52, 1.0, v52
	v_add_f32_e32 v53, 1.0, v53
	v_log_f32_e32 v52, v52
	v_log_f32_e32 v53, v53
	v_min_f32_e32 v51, 0, v51
	v_mul_f32_e32 v54, 0x3f317217, v52
	v_mul_f32_e32 v55, 0x3f317217, v53
	v_fma_f32 v56, v52, s9, -v54
	v_fma_f32 v57, v53, s9, -v55
	v_fmac_f32_e32 v56, 0x3377d1cf, v52
	v_fmac_f32_e32 v57, 0x3377d1cf, v53
	v_add_f32_e32 v54, v54, v56
	v_add_f32_e32 v55, v55, v57
	v_sub_f32_e32 v50, v50, v54
	v_sub_f32_e32 v51, v51, v55
	v_fmamk_f32 v102, v50, 0x3d800000, v101
	v_fmamk_f32 v103, v51, 0x3d800000, v102
	s_waitcnt lgkmcnt(0)
	ds_read_b128 v[216:219], v3 offset:2688
	ds_read_b128 v[220:223], v3 offset:2704
	ds_read_b128 v[224:227], v3 offset:2720
	ds_read_b128 v[232:235], v3 offset:2736
	ds_read_b128 v[236:239], v3 offset:2752
	ds_read_b128 v[240:243], v3 offset:2768
	ds_read_b128 v[244:247], v3 offset:2784
	ds_read_b128 v[248:251], v3 offset:2800
	v_fma_f32 v50, v16, v34, v32
	v_fma_f32 v51, v16, v200, v32
	v_fmac_f32_e32 v50, v17, v35
	v_fmac_f32_e32 v51, v17, v201
	v_fmac_f32_e32 v50, v18, v36
	v_fmac_f32_e32 v51, v18, v202
	v_fmac_f32_e32 v50, v19, v37
	v_fmac_f32_e32 v51, v19, v203
	v_fmac_f32_e32 v50, v20, v38
	v_fmac_f32_e32 v51, v20, v204
	v_fmac_f32_e32 v50, v21, v39
	v_fmac_f32_e32 v51, v21, v205
	v_fmac_f32_e32 v50, v22, v40
	v_fmac_f32_e32 v51, v22, v206
	v_fmac_f32_e32 v50, v23, v41
	v_fmac_f32_e32 v51, v23, v207
	v_fmac_f32_e32 v50, v24, v42
	v_fmac_f32_e32 v51, v24, v208
	v_fmac_f32_e32 v50, v25, v43
	v_fmac_f32_e32 v51, v25, v209
	v_fmac_f32_e32 v50, v26, v44
	v_fmac_f32_e32 v51, v26, v210
	v_fmac_f32_e32 v50, v27, v45
	v_fmac_f32_e32 v51, v27, v211
	v_fmac_f32_e32 v50, v28, v46
	v_fmac_f32_e32 v51, v28, v212
	v_fmac_f32_e32 v50, v29, v47
	v_fmac_f32_e32 v51, v29, v213
	v_fmac_f32_e32 v50, v30, v48
	v_fmac_f32_e32 v51, v30, v214
	v_fmac_f32_e32 v50, v31, v49
	v_fmac_f32_e32 v51, v31, v215
	v_mul_f32_e64 v52, |v50|, s7
	v_mul_f32_e64 v53, |v51|, s7
	v_exp_f32_e32 v52, v52
	v_exp_f32_e32 v53, v53
	v_min_f32_e32 v50, 0, v50
	v_add_f32_e32 v52, 1.0, v52
	v_add_f32_e32 v53, 1.0, v53
	v_log_f32_e32 v52, v52
	v_log_f32_e32 v53, v53
	v_min_f32_e32 v51, 0, v51
	v_mul_f32_e32 v54, 0x3f317217, v52
	v_mul_f32_e32 v55, 0x3f317217, v53
	v_fma_f32 v56, v52, s9, -v54
	v_fma_f32 v57, v53, s9, -v55
	v_fmac_f32_e32 v56, 0x3377d1cf, v52
	v_fmac_f32_e32 v57, 0x3377d1cf, v53
	v_add_f32_e32 v54, v54, v56
	v_add_f32_e32 v55, v55, v57
	v_sub_f32_e32 v50, v50, v54
	v_sub_f32_e32 v51, v51, v55
	v_fmamk_f32 v104, v50, 0x3d800000, v103
	v_fmamk_f32 v105, v51, 0x3d800000, v104
	s_waitcnt lgkmcnt(0)
	ds_read_b128 v[34:37], v3 offset:2816
	ds_read_b128 v[38:41], v3 offset:2832
	ds_read_b128 v[42:45], v3 offset:2848
	ds_read_b128 v[46:49], v3 offset:2864
	ds_read_b128 v[200:203], v3 offset:2880
	ds_read_b128 v[204:207], v3 offset:2896
	ds_read_b128 v[208:211], v3 offset:2912
	ds_read_b128 v[212:215], v3 offset:2928
	v_fma_f32 v50, v16, v216, v32
	v_fma_f32 v51, v16, v236, v32
	v_fmac_f32_e32 v50, v17, v217
	v_fmac_f32_e32 v51, v17, v237
	v_fmac_f32_e32 v50, v18, v218
	v_fmac_f32_e32 v51, v18, v238
	v_fmac_f32_e32 v50, v19, v219
	v_fmac_f32_e32 v51, v19, v239
	v_fmac_f32_e32 v50, v20, v220
	v_fmac_f32_e32 v51, v20, v240
	v_fmac_f32_e32 v50, v21, v221
	v_fmac_f32_e32 v51, v21, v241
	v_fmac_f32_e32 v50, v22, v222
	v_fmac_f32_e32 v51, v22, v242
	v_fmac_f32_e32 v50, v23, v223
	v_fmac_f32_e32 v51, v23, v243
	v_fmac_f32_e32 v50, v24, v224
	v_fmac_f32_e32 v51, v24, v244
	v_fmac_f32_e32 v50, v25, v225
	v_fmac_f32_e32 v51, v25, v245
	v_fmac_f32_e32 v50, v26, v226
	v_fmac_f32_e32 v51, v26, v246
	v_fmac_f32_e32 v50, v27, v227
	v_fmac_f32_e32 v51, v27, v247
	v_fmac_f32_e32 v50, v28, v232
	v_fmac_f32_e32 v51, v28, v248
	v_fmac_f32_e32 v50, v29, v233
	v_fmac_f32_e32 v51, v29, v249
	v_fmac_f32_e32 v50, v30, v234
	v_fmac_f32_e32 v51, v30, v250
	v_fmac_f32_e32 v50, v31, v235
	v_fmac_f32_e32 v51, v31, v251
	v_mul_f32_e64 v52, |v50|, s7
	v_mul_f32_e64 v53, |v51|, s7
	v_exp_f32_e32 v52, v52
	v_exp_f32_e32 v53, v53
	v_min_f32_e32 v50, 0, v50
	v_add_f32_e32 v52, 1.0, v52
	v_add_f32_e32 v53, 1.0, v53
	v_log_f32_e32 v52, v52
	v_log_f32_e32 v53, v53
	v_min_f32_e32 v51, 0, v51
	v_mul_f32_e32 v54, 0x3f317217, v52
	v_mul_f32_e32 v55, 0x3f317217, v53
	v_fma_f32 v56, v52, s9, -v54
	v_fma_f32 v57, v53, s9, -v55
	v_fmac_f32_e32 v56, 0x3377d1cf, v52
	v_fmac_f32_e32 v57, 0x3377d1cf, v53
	v_add_f32_e32 v54, v54, v56
	v_add_f32_e32 v55, v55, v57
	v_sub_f32_e32 v50, v50, v54
	v_sub_f32_e32 v51, v51, v55
	v_fmamk_f32 v106, v50, 0x3d800000, v105
	v_fmamk_f32 v107, v51, 0x3d800000, v106
	s_waitcnt lgkmcnt(0)
	ds_read_b128 v[216:219], v3 offset:2944
	ds_read_b128 v[220:223], v3 offset:2960
	ds_read_b128 v[224:227], v3 offset:2976
	ds_read_b128 v[232:235], v3 offset:2992
	ds_read_b128 v[236:239], v3 offset:3008
	ds_read_b128 v[240:243], v3 offset:3024
	ds_read_b128 v[244:247], v3 offset:3040
	ds_read_b128 v[248:251], v3 offset:3056
	v_fma_f32 v50, v16, v34, v32
	v_fma_f32 v51, v16, v200, v32
	v_fmac_f32_e32 v50, v17, v35
	v_fmac_f32_e32 v51, v17, v201
	v_fmac_f32_e32 v50, v18, v36
	v_fmac_f32_e32 v51, v18, v202
	v_fmac_f32_e32 v50, v19, v37
	v_fmac_f32_e32 v51, v19, v203
	v_fmac_f32_e32 v50, v20, v38
	v_fmac_f32_e32 v51, v20, v204
	v_fmac_f32_e32 v50, v21, v39
	v_fmac_f32_e32 v51, v21, v205
	v_fmac_f32_e32 v50, v22, v40
	v_fmac_f32_e32 v51, v22, v206
	v_fmac_f32_e32 v50, v23, v41
	v_fmac_f32_e32 v51, v23, v207
	v_fmac_f32_e32 v50, v24, v42
	v_fmac_f32_e32 v51, v24, v208
	v_fmac_f32_e32 v50, v25, v43
	v_fmac_f32_e32 v51, v25, v209
	v_fmac_f32_e32 v50, v26, v44
	v_fmac_f32_e32 v51, v26, v210
	v_fmac_f32_e32 v50, v27, v45
	v_fmac_f32_e32 v51, v27, v211
	v_fmac_f32_e32 v50, v28, v46
	v_fmac_f32_e32 v51, v28, v212
	v_fmac_f32_e32 v50, v29, v47
	v_fmac_f32_e32 v51, v29, v213
	v_fmac_f32_e32 v50, v30, v48
	v_fmac_f32_e32 v51, v30, v214
	v_fmac_f32_e32 v50, v31, v49
	v_fmac_f32_e32 v51, v31, v215
	v_mul_f32_e64 v52, |v50|, s7
	v_mul_f32_e64 v53, |v51|, s7
	v_exp_f32_e32 v52, v52
	v_exp_f32_e32 v53, v53
	v_min_f32_e32 v50, 0, v50
	v_add_f32_e32 v52, 1.0, v52
	v_add_f32_e32 v53, 1.0, v53
	v_log_f32_e32 v52, v52
	v_log_f32_e32 v53, v53
	v_min_f32_e32 v51, 0, v51
	v_mul_f32_e32 v54, 0x3f317217, v52
	v_mul_f32_e32 v55, 0x3f317217, v53
	v_fma_f32 v56, v52, s9, -v54
	v_fma_f32 v57, v53, s9, -v55
	v_fmac_f32_e32 v56, 0x3377d1cf, v52
	v_fmac_f32_e32 v57, 0x3377d1cf, v53
	v_add_f32_e32 v54, v54, v56
	v_add_f32_e32 v55, v55, v57
	v_sub_f32_e32 v50, v50, v54
	v_sub_f32_e32 v51, v51, v55
	v_fmamk_f32 v108, v50, 0x3d800000, v107
	v_fmamk_f32 v109, v51, 0x3d800000, v108
	s_waitcnt lgkmcnt(0)
	ds_read_b128 v[34:37], v3 offset:3072
	ds_read_b128 v[38:41], v3 offset:3088
	ds_read_b128 v[42:45], v3 offset:3104
	ds_read_b128 v[46:49], v3 offset:3120
	ds_read_b128 v[200:203], v3 offset:3136
	ds_read_b128 v[204:207], v3 offset:3152
	ds_read_b128 v[208:211], v3 offset:3168
	ds_read_b128 v[212:215], v3 offset:3184
	v_fma_f32 v50, v16, v216, v32
	v_fma_f32 v51, v16, v236, v32
	v_fmac_f32_e32 v50, v17, v217
	v_fmac_f32_e32 v51, v17, v237
	v_fmac_f32_e32 v50, v18, v218
	v_fmac_f32_e32 v51, v18, v238
	v_fmac_f32_e32 v50, v19, v219
	v_fmac_f32_e32 v51, v19, v239
	v_fmac_f32_e32 v50, v20, v220
	v_fmac_f32_e32 v51, v20, v240
	v_fmac_f32_e32 v50, v21, v221
	v_fmac_f32_e32 v51, v21, v241
	v_fmac_f32_e32 v50, v22, v222
	v_fmac_f32_e32 v51, v22, v242
	v_fmac_f32_e32 v50, v23, v223
	v_fmac_f32_e32 v51, v23, v243
	v_fmac_f32_e32 v50, v24, v224
	v_fmac_f32_e32 v51, v24, v244
	v_fmac_f32_e32 v50, v25, v225
	v_fmac_f32_e32 v51, v25, v245
	v_fmac_f32_e32 v50, v26, v226
	v_fmac_f32_e32 v51, v26, v246
	v_fmac_f32_e32 v50, v27, v227
	v_fmac_f32_e32 v51, v27, v247
	v_fmac_f32_e32 v50, v28, v232
	v_fmac_f32_e32 v51, v28, v248
	v_fmac_f32_e32 v50, v29, v233
	v_fmac_f32_e32 v51, v29, v249
	v_fmac_f32_e32 v50, v30, v234
	v_fmac_f32_e32 v51, v30, v250
	v_fmac_f32_e32 v50, v31, v235
	v_fmac_f32_e32 v51, v31, v251
	v_mul_f32_e64 v52, |v50|, s7
	v_mul_f32_e64 v53, |v51|, s7
	v_exp_f32_e32 v52, v52
	v_exp_f32_e32 v53, v53
	v_min_f32_e32 v50, 0, v50
	v_add_f32_e32 v52, 1.0, v52
	v_add_f32_e32 v53, 1.0, v53
	v_log_f32_e32 v52, v52
	v_log_f32_e32 v53, v53
	v_min_f32_e32 v51, 0, v51
	v_mul_f32_e32 v54, 0x3f317217, v52
	v_mul_f32_e32 v55, 0x3f317217, v53
	v_fma_f32 v56, v52, s9, -v54
	v_fma_f32 v57, v53, s9, -v55
	v_fmac_f32_e32 v56, 0x3377d1cf, v52
	v_fmac_f32_e32 v57, 0x3377d1cf, v53
	v_add_f32_e32 v54, v54, v56
	v_add_f32_e32 v55, v55, v57
	v_sub_f32_e32 v50, v50, v54
	v_sub_f32_e32 v51, v51, v55
	v_fmamk_f32 v110, v50, 0x3d800000, v109
	v_fmamk_f32 v111, v51, 0x3d800000, v110
	s_waitcnt lgkmcnt(0)
	ds_read_b128 v[216:219], v3 offset:3200
	ds_read_b128 v[220:223], v3 offset:3216
	ds_read_b128 v[224:227], v3 offset:3232
	ds_read_b128 v[232:235], v3 offset:3248
	ds_read_b128 v[236:239], v3 offset:3264
	ds_read_b128 v[240:243], v3 offset:3280
	ds_read_b128 v[244:247], v3 offset:3296
	ds_read_b128 v[248:251], v3 offset:3312
	v_fma_f32 v50, v16, v34, v32
	v_fma_f32 v51, v16, v200, v32
	v_fmac_f32_e32 v50, v17, v35
	v_fmac_f32_e32 v51, v17, v201
	v_fmac_f32_e32 v50, v18, v36
	v_fmac_f32_e32 v51, v18, v202
	v_fmac_f32_e32 v50, v19, v37
	v_fmac_f32_e32 v51, v19, v203
	v_fmac_f32_e32 v50, v20, v38
	v_fmac_f32_e32 v51, v20, v204
	v_fmac_f32_e32 v50, v21, v39
	v_fmac_f32_e32 v51, v21, v205
	v_fmac_f32_e32 v50, v22, v40
	v_fmac_f32_e32 v51, v22, v206
	v_fmac_f32_e32 v50, v23, v41
	v_fmac_f32_e32 v51, v23, v207
	v_fmac_f32_e32 v50, v24, v42
	v_fmac_f32_e32 v51, v24, v208
	v_fmac_f32_e32 v50, v25, v43
	v_fmac_f32_e32 v51, v25, v209
	v_fmac_f32_e32 v50, v26, v44
	v_fmac_f32_e32 v51, v26, v210
	v_fmac_f32_e32 v50, v27, v45
	v_fmac_f32_e32 v51, v27, v211
	v_fmac_f32_e32 v50, v28, v46
	v_fmac_f32_e32 v51, v28, v212
	v_fmac_f32_e32 v50, v29, v47
	v_fmac_f32_e32 v51, v29, v213
	v_fmac_f32_e32 v50, v30, v48
	v_fmac_f32_e32 v51, v30, v214
	v_fmac_f32_e32 v50, v31, v49
	v_fmac_f32_e32 v51, v31, v215
	v_mul_f32_e64 v52, |v50|, s7
	v_mul_f32_e64 v53, |v51|, s7
	v_exp_f32_e32 v52, v52
	v_exp_f32_e32 v53, v53
	v_min_f32_e32 v50, 0, v50
	v_add_f32_e32 v52, 1.0, v52
	v_add_f32_e32 v53, 1.0, v53
	v_log_f32_e32 v52, v52
	v_log_f32_e32 v53, v53
	v_min_f32_e32 v51, 0, v51
	v_mul_f32_e32 v54, 0x3f317217, v52
	v_mul_f32_e32 v55, 0x3f317217, v53
	v_fma_f32 v56, v52, s9, -v54
	v_fma_f32 v57, v53, s9, -v55
	v_fmac_f32_e32 v56, 0x3377d1cf, v52
	v_fmac_f32_e32 v57, 0x3377d1cf, v53
	v_add_f32_e32 v54, v54, v56
	v_add_f32_e32 v55, v55, v57
	v_sub_f32_e32 v50, v50, v54
	v_sub_f32_e32 v51, v51, v55
	v_fmamk_f32 v112, v50, 0x3d800000, v111
	v_fmamk_f32 v113, v51, 0x3d800000, v112
	s_waitcnt lgkmcnt(0)
	ds_read_b128 v[34:37], v3 offset:3328
	ds_read_b128 v[38:41], v3 offset:3344
	ds_read_b128 v[42:45], v3 offset:3360
	ds_read_b128 v[46:49], v3 offset:3376
	ds_read_b128 v[200:203], v3 offset:3392
	ds_read_b128 v[204:207], v3 offset:3408
	ds_read_b128 v[208:211], v3 offset:3424
	ds_read_b128 v[212:215], v3 offset:3440
	v_fma_f32 v50, v16, v216, v32
	v_fma_f32 v51, v16, v236, v32
	v_fmac_f32_e32 v50, v17, v217
	v_fmac_f32_e32 v51, v17, v237
	v_fmac_f32_e32 v50, v18, v218
	v_fmac_f32_e32 v51, v18, v238
	v_fmac_f32_e32 v50, v19, v219
	v_fmac_f32_e32 v51, v19, v239
	v_fmac_f32_e32 v50, v20, v220
	v_fmac_f32_e32 v51, v20, v240
	v_fmac_f32_e32 v50, v21, v221
	v_fmac_f32_e32 v51, v21, v241
	v_fmac_f32_e32 v50, v22, v222
	v_fmac_f32_e32 v51, v22, v242
	v_fmac_f32_e32 v50, v23, v223
	v_fmac_f32_e32 v51, v23, v243
	v_fmac_f32_e32 v50, v24, v224
	v_fmac_f32_e32 v51, v24, v244
	v_fmac_f32_e32 v50, v25, v225
	v_fmac_f32_e32 v51, v25, v245
	v_fmac_f32_e32 v50, v26, v226
	v_fmac_f32_e32 v51, v26, v246
	v_fmac_f32_e32 v50, v27, v227
	v_fmac_f32_e32 v51, v27, v247
	v_fmac_f32_e32 v50, v28, v232
	v_fmac_f32_e32 v51, v28, v248
	v_fmac_f32_e32 v50, v29, v233
	v_fmac_f32_e32 v51, v29, v249
	v_fmac_f32_e32 v50, v30, v234
	v_fmac_f32_e32 v51, v30, v250
	v_fmac_f32_e32 v50, v31, v235
	v_fmac_f32_e32 v51, v31, v251
	v_mul_f32_e64 v52, |v50|, s7
	v_mul_f32_e64 v53, |v51|, s7
	v_exp_f32_e32 v52, v52
	v_exp_f32_e32 v53, v53
	v_min_f32_e32 v50, 0, v50
	v_add_f32_e32 v52, 1.0, v52
	v_add_f32_e32 v53, 1.0, v53
	v_log_f32_e32 v52, v52
	v_log_f32_e32 v53, v53
	v_min_f32_e32 v51, 0, v51
	v_mul_f32_e32 v54, 0x3f317217, v52
	v_mul_f32_e32 v55, 0x3f317217, v53
	v_fma_f32 v56, v52, s9, -v54
	v_fma_f32 v57, v53, s9, -v55
	v_fmac_f32_e32 v56, 0x3377d1cf, v52
	v_fmac_f32_e32 v57, 0x3377d1cf, v53
	v_add_f32_e32 v54, v54, v56
	v_add_f32_e32 v55, v55, v57
	v_sub_f32_e32 v50, v50, v54
	v_sub_f32_e32 v51, v51, v55
	v_fmamk_f32 v114, v50, 0x3d800000, v113
	v_fmamk_f32 v115, v51, 0x3d800000, v114
	s_waitcnt lgkmcnt(0)
	ds_read_b128 v[216:219], v3 offset:3456
	ds_read_b128 v[220:223], v3 offset:3472
	ds_read_b128 v[224:227], v3 offset:3488
	ds_read_b128 v[232:235], v3 offset:3504
	ds_read_b128 v[236:239], v3 offset:3520
	ds_read_b128 v[240:243], v3 offset:3536
	ds_read_b128 v[244:247], v3 offset:3552
	ds_read_b128 v[248:251], v3 offset:3568
	v_fma_f32 v50, v16, v34, v32
	v_fma_f32 v51, v16, v200, v32
	v_fmac_f32_e32 v50, v17, v35
	v_fmac_f32_e32 v51, v17, v201
	v_fmac_f32_e32 v50, v18, v36
	v_fmac_f32_e32 v51, v18, v202
	v_fmac_f32_e32 v50, v19, v37
	v_fmac_f32_e32 v51, v19, v203
	v_fmac_f32_e32 v50, v20, v38
	v_fmac_f32_e32 v51, v20, v204
	v_fmac_f32_e32 v50, v21, v39
	v_fmac_f32_e32 v51, v21, v205
	v_fmac_f32_e32 v50, v22, v40
	v_fmac_f32_e32 v51, v22, v206
	v_fmac_f32_e32 v50, v23, v41
	v_fmac_f32_e32 v51, v23, v207
	v_fmac_f32_e32 v50, v24, v42
	v_fmac_f32_e32 v51, v24, v208
	v_fmac_f32_e32 v50, v25, v43
	v_fmac_f32_e32 v51, v25, v209
	v_fmac_f32_e32 v50, v26, v44
	v_fmac_f32_e32 v51, v26, v210
	v_fmac_f32_e32 v50, v27, v45
	v_fmac_f32_e32 v51, v27, v211
	v_fmac_f32_e32 v50, v28, v46
	v_fmac_f32_e32 v51, v28, v212
	v_fmac_f32_e32 v50, v29, v47
	v_fmac_f32_e32 v51, v29, v213
	v_fmac_f32_e32 v50, v30, v48
	v_fmac_f32_e32 v51, v30, v214
	v_fmac_f32_e32 v50, v31, v49
	v_fmac_f32_e32 v51, v31, v215
	v_mul_f32_e64 v52, |v50|, s7
	v_mul_f32_e64 v53, |v51|, s7
	v_exp_f32_e32 v52, v52
	v_exp_f32_e32 v53, v53
	v_min_f32_e32 v50, 0, v50
	v_add_f32_e32 v52, 1.0, v52
	v_add_f32_e32 v53, 1.0, v53
	v_log_f32_e32 v52, v52
	v_log_f32_e32 v53, v53
	v_min_f32_e32 v51, 0, v51
	v_mul_f32_e32 v54, 0x3f317217, v52
	v_mul_f32_e32 v55, 0x3f317217, v53
	v_fma_f32 v56, v52, s9, -v54
	v_fma_f32 v57, v53, s9, -v55
	v_fmac_f32_e32 v56, 0x3377d1cf, v52
	v_fmac_f32_e32 v57, 0x3377d1cf, v53
	v_add_f32_e32 v54, v54, v56
	v_add_f32_e32 v55, v55, v57
	v_sub_f32_e32 v50, v50, v54
	v_sub_f32_e32 v51, v51, v55
	v_fmamk_f32 v116, v50, 0x3d800000, v115
	v_fmamk_f32 v117, v51, 0x3d800000, v116
	s_waitcnt lgkmcnt(0)
	ds_read_b128 v[34:37], v3 offset:3584
	ds_read_b128 v[38:41], v3 offset:3600
	ds_read_b128 v[42:45], v3 offset:3616
	ds_read_b128 v[46:49], v3 offset:3632
	ds_read_b128 v[200:203], v3 offset:3648
	ds_read_b128 v[204:207], v3 offset:3664
	ds_read_b128 v[208:211], v3 offset:3680
	ds_read_b128 v[212:215], v3 offset:3696
	v_fma_f32 v50, v16, v216, v32
	v_fma_f32 v51, v16, v236, v32
	v_fmac_f32_e32 v50, v17, v217
	v_fmac_f32_e32 v51, v17, v237
	v_fmac_f32_e32 v50, v18, v218
	v_fmac_f32_e32 v51, v18, v238
	v_fmac_f32_e32 v50, v19, v219
	v_fmac_f32_e32 v51, v19, v239
	v_fmac_f32_e32 v50, v20, v220
	v_fmac_f32_e32 v51, v20, v240
	v_fmac_f32_e32 v50, v21, v221
	v_fmac_f32_e32 v51, v21, v241
	v_fmac_f32_e32 v50, v22, v222
	v_fmac_f32_e32 v51, v22, v242
	v_fmac_f32_e32 v50, v23, v223
	v_fmac_f32_e32 v51, v23, v243
	v_fmac_f32_e32 v50, v24, v224
	v_fmac_f32_e32 v51, v24, v244
	v_fmac_f32_e32 v50, v25, v225
	v_fmac_f32_e32 v51, v25, v245
	v_fmac_f32_e32 v50, v26, v226
	v_fmac_f32_e32 v51, v26, v246
	v_fmac_f32_e32 v50, v27, v227
	v_fmac_f32_e32 v51, v27, v247
	v_fmac_f32_e32 v50, v28, v232
	v_fmac_f32_e32 v51, v28, v248
	v_fmac_f32_e32 v50, v29, v233
	v_fmac_f32_e32 v51, v29, v249
	v_fmac_f32_e32 v50, v30, v234
	v_fmac_f32_e32 v51, v30, v250
	v_fmac_f32_e32 v50, v31, v235
	v_fmac_f32_e32 v51, v31, v251
	v_mul_f32_e64 v52, |v50|, s7
	v_mul_f32_e64 v53, |v51|, s7
	v_exp_f32_e32 v52, v52
	v_exp_f32_e32 v53, v53
	v_min_f32_e32 v50, 0, v50
	v_add_f32_e32 v52, 1.0, v52
	v_add_f32_e32 v53, 1.0, v53
	v_log_f32_e32 v52, v52
	v_log_f32_e32 v53, v53
	v_min_f32_e32 v51, 0, v51
	v_mul_f32_e32 v54, 0x3f317217, v52
	v_mul_f32_e32 v55, 0x3f317217, v53
	v_fma_f32 v56, v52, s9, -v54
	v_fma_f32 v57, v53, s9, -v55
	v_fmac_f32_e32 v56, 0x3377d1cf, v52
	v_fmac_f32_e32 v57, 0x3377d1cf, v53
	v_add_f32_e32 v54, v54, v56
	v_add_f32_e32 v55, v55, v57
	v_sub_f32_e32 v50, v50, v54
	v_sub_f32_e32 v51, v51, v55
	v_fmamk_f32 v118, v50, 0x3d800000, v117
	v_fmamk_f32 v119, v51, 0x3d800000, v118
	s_waitcnt lgkmcnt(0)
	ds_read_b128 v[216:219], v3 offset:3712
	ds_read_b128 v[220:223], v3 offset:3728
	ds_read_b128 v[224:227], v3 offset:3744
	ds_read_b128 v[232:235], v3 offset:3760
	ds_read_b128 v[236:239], v3 offset:3776
	ds_read_b128 v[240:243], v3 offset:3792
	ds_read_b128 v[244:247], v3 offset:3808
	ds_read_b128 v[248:251], v3 offset:3824
	v_fma_f32 v50, v16, v34, v32
	v_fma_f32 v51, v16, v200, v32
	v_fmac_f32_e32 v50, v17, v35
	v_fmac_f32_e32 v51, v17, v201
	v_fmac_f32_e32 v50, v18, v36
	v_fmac_f32_e32 v51, v18, v202
	v_fmac_f32_e32 v50, v19, v37
	v_fmac_f32_e32 v51, v19, v203
	v_fmac_f32_e32 v50, v20, v38
	v_fmac_f32_e32 v51, v20, v204
	v_fmac_f32_e32 v50, v21, v39
	v_fmac_f32_e32 v51, v21, v205
	v_fmac_f32_e32 v50, v22, v40
	v_fmac_f32_e32 v51, v22, v206
	v_fmac_f32_e32 v50, v23, v41
	v_fmac_f32_e32 v51, v23, v207
	v_fmac_f32_e32 v50, v24, v42
	v_fmac_f32_e32 v51, v24, v208
	v_fmac_f32_e32 v50, v25, v43
	v_fmac_f32_e32 v51, v25, v209
	v_fmac_f32_e32 v50, v26, v44
	v_fmac_f32_e32 v51, v26, v210
	v_fmac_f32_e32 v50, v27, v45
	v_fmac_f32_e32 v51, v27, v211
	v_fmac_f32_e32 v50, v28, v46
	v_fmac_f32_e32 v51, v28, v212
	v_fmac_f32_e32 v50, v29, v47
	v_fmac_f32_e32 v51, v29, v213
	v_fmac_f32_e32 v50, v30, v48
	v_fmac_f32_e32 v51, v30, v214
	v_fmac_f32_e32 v50, v31, v49
	v_fmac_f32_e32 v51, v31, v215
	v_mul_f32_e64 v52, |v50|, s7
	v_mul_f32_e64 v53, |v51|, s7
	v_exp_f32_e32 v52, v52
	v_exp_f32_e32 v53, v53
	v_min_f32_e32 v50, 0, v50
	v_add_f32_e32 v52, 1.0, v52
	v_add_f32_e32 v53, 1.0, v53
	v_log_f32_e32 v52, v52
	v_log_f32_e32 v53, v53
	v_min_f32_e32 v51, 0, v51
	v_mul_f32_e32 v54, 0x3f317217, v52
	v_mul_f32_e32 v55, 0x3f317217, v53
	v_fma_f32 v56, v52, s9, -v54
	v_fma_f32 v57, v53, s9, -v55
	v_fmac_f32_e32 v56, 0x3377d1cf, v52
	v_fmac_f32_e32 v57, 0x3377d1cf, v53
	v_add_f32_e32 v54, v54, v56
	v_add_f32_e32 v55, v55, v57
	v_sub_f32_e32 v50, v50, v54
	v_sub_f32_e32 v51, v51, v55
	v_fmamk_f32 v120, v50, 0x3d800000, v119
	v_fmamk_f32 v121, v51, 0x3d800000, v120
	s_waitcnt lgkmcnt(0)
	ds_read_b128 v[34:37], v3 offset:3840
	ds_read_b128 v[38:41], v3 offset:3856
	ds_read_b128 v[42:45], v3 offset:3872
	ds_read_b128 v[46:49], v3 offset:3888
	ds_read_b128 v[200:203], v3 offset:3904
	ds_read_b128 v[204:207], v3 offset:3920
	ds_read_b128 v[208:211], v3 offset:3936
	ds_read_b128 v[212:215], v3 offset:3952
	v_fma_f32 v50, v16, v216, v32
	v_fma_f32 v51, v16, v236, v32
	v_fmac_f32_e32 v50, v17, v217
	v_fmac_f32_e32 v51, v17, v237
	v_fmac_f32_e32 v50, v18, v218
	v_fmac_f32_e32 v51, v18, v238
	v_fmac_f32_e32 v50, v19, v219
	v_fmac_f32_e32 v51, v19, v239
	v_fmac_f32_e32 v50, v20, v220
	v_fmac_f32_e32 v51, v20, v240
	v_fmac_f32_e32 v50, v21, v221
	v_fmac_f32_e32 v51, v21, v241
	v_fmac_f32_e32 v50, v22, v222
	v_fmac_f32_e32 v51, v22, v242
	v_fmac_f32_e32 v50, v23, v223
	v_fmac_f32_e32 v51, v23, v243
	v_fmac_f32_e32 v50, v24, v224
	v_fmac_f32_e32 v51, v24, v244
	v_fmac_f32_e32 v50, v25, v225
	v_fmac_f32_e32 v51, v25, v245
	v_fmac_f32_e32 v50, v26, v226
	v_fmac_f32_e32 v51, v26, v246
	v_fmac_f32_e32 v50, v27, v227
	v_fmac_f32_e32 v51, v27, v247
	v_fmac_f32_e32 v50, v28, v232
	v_fmac_f32_e32 v51, v28, v248
	v_fmac_f32_e32 v50, v29, v233
	v_fmac_f32_e32 v51, v29, v249
	v_fmac_f32_e32 v50, v30, v234
	v_fmac_f32_e32 v51, v30, v250
	v_fmac_f32_e32 v50, v31, v235
	v_fmac_f32_e32 v51, v31, v251
	v_mul_f32_e64 v52, |v50|, s7
	v_mul_f32_e64 v53, |v51|, s7
	v_exp_f32_e32 v52, v52
	v_exp_f32_e32 v53, v53
	v_min_f32_e32 v50, 0, v50
	v_add_f32_e32 v52, 1.0, v52
	v_add_f32_e32 v53, 1.0, v53
	v_log_f32_e32 v52, v52
	v_log_f32_e32 v53, v53
	v_min_f32_e32 v51, 0, v51
	v_mul_f32_e32 v54, 0x3f317217, v52
	v_mul_f32_e32 v55, 0x3f317217, v53
	v_fma_f32 v56, v52, s9, -v54
	v_fma_f32 v57, v53, s9, -v55
	v_fmac_f32_e32 v56, 0x3377d1cf, v52
	v_fmac_f32_e32 v57, 0x3377d1cf, v53
	v_add_f32_e32 v54, v54, v56
	v_add_f32_e32 v55, v55, v57
	v_sub_f32_e32 v50, v50, v54
	v_sub_f32_e32 v51, v51, v55
	v_fmamk_f32 v122, v50, 0x3d800000, v121
	v_fmamk_f32 v123, v51, 0x3d800000, v122
	s_waitcnt lgkmcnt(0)
	ds_read_b128 v[216:219], v3 offset:3968
	ds_read_b128 v[220:223], v3 offset:3984
	ds_read_b128 v[224:227], v3 offset:4000
	ds_read_b128 v[232:235], v3 offset:4016
	ds_read_b128 v[236:239], v3 offset:4032
	ds_read_b128 v[240:243], v3 offset:4048
	ds_read_b128 v[244:247], v3 offset:4064
	ds_read_b128 v[248:251], v3 offset:4080
	v_fma_f32 v50, v16, v34, v32
	v_fma_f32 v51, v16, v200, v32
	v_fmac_f32_e32 v50, v17, v35
	v_fmac_f32_e32 v51, v17, v201
	v_fmac_f32_e32 v50, v18, v36
	v_fmac_f32_e32 v51, v18, v202
	v_fmac_f32_e32 v50, v19, v37
	v_fmac_f32_e32 v51, v19, v203
	v_fmac_f32_e32 v50, v20, v38
	v_fmac_f32_e32 v51, v20, v204
	v_fmac_f32_e32 v50, v21, v39
	v_fmac_f32_e32 v51, v21, v205
	v_fmac_f32_e32 v50, v22, v40
	v_fmac_f32_e32 v51, v22, v206
	v_fmac_f32_e32 v50, v23, v41
	v_fmac_f32_e32 v51, v23, v207
	v_fmac_f32_e32 v50, v24, v42
	v_fmac_f32_e32 v51, v24, v208
	v_fmac_f32_e32 v50, v25, v43
	v_fmac_f32_e32 v51, v25, v209
	v_fmac_f32_e32 v50, v26, v44
	v_fmac_f32_e32 v51, v26, v210
	v_fmac_f32_e32 v50, v27, v45
	v_fmac_f32_e32 v51, v27, v211
	v_fmac_f32_e32 v50, v28, v46
	v_fmac_f32_e32 v51, v28, v212
	v_fmac_f32_e32 v50, v29, v47
	v_fmac_f32_e32 v51, v29, v213
	v_fmac_f32_e32 v50, v30, v48
	v_fmac_f32_e32 v51, v30, v214
	v_fmac_f32_e32 v50, v31, v49
	v_fmac_f32_e32 v51, v31, v215
	v_mul_f32_e64 v52, |v50|, s7
	v_mul_f32_e64 v53, |v51|, s7
	v_exp_f32_e32 v52, v52
	v_exp_f32_e32 v53, v53
	v_min_f32_e32 v50, 0, v50
	v_add_f32_e32 v52, 1.0, v52
	v_add_f32_e32 v53, 1.0, v53
	v_log_f32_e32 v52, v52
	v_log_f32_e32 v53, v53
	v_min_f32_e32 v51, 0, v51
	v_mul_f32_e32 v54, 0x3f317217, v52
	v_mul_f32_e32 v55, 0x3f317217, v53
	v_fma_f32 v56, v52, s9, -v54
	v_fma_f32 v57, v53, s9, -v55
	v_fmac_f32_e32 v56, 0x3377d1cf, v52
	v_fmac_f32_e32 v57, 0x3377d1cf, v53
	v_add_f32_e32 v54, v54, v56
	v_add_f32_e32 v55, v55, v57
	v_sub_f32_e32 v50, v50, v54
	v_sub_f32_e32 v51, v51, v55
	v_fmamk_f32 v124, v50, 0x3d800000, v123
	v_fmamk_f32 v125, v51, 0x3d800000, v124
	s_waitcnt lgkmcnt(0)
	v_fma_f32 v50, v16, v216, v32
	v_fma_f32 v51, v16, v236, v32
	v_fmac_f32_e32 v50, v17, v217
	v_fmac_f32_e32 v51, v17, v237
	v_fmac_f32_e32 v50, v18, v218
	v_fmac_f32_e32 v51, v18, v238
	v_fmac_f32_e32 v50, v19, v219
	v_fmac_f32_e32 v51, v19, v239
	v_fmac_f32_e32 v50, v20, v220
	v_fmac_f32_e32 v51, v20, v240
	v_fmac_f32_e32 v50, v21, v221
	v_fmac_f32_e32 v51, v21, v241
	v_fmac_f32_e32 v50, v22, v222
	v_fmac_f32_e32 v51, v22, v242
	v_fmac_f32_e32 v50, v23, v223
	v_fmac_f32_e32 v51, v23, v243
	v_fmac_f32_e32 v50, v24, v224
	v_fmac_f32_e32 v51, v24, v244
	v_fmac_f32_e32 v50, v25, v225
	v_fmac_f32_e32 v51, v25, v245
	v_fmac_f32_e32 v50, v26, v226
	v_fmac_f32_e32 v51, v26, v246
	v_fmac_f32_e32 v50, v27, v227
	v_fmac_f32_e32 v51, v27, v247
	v_fmac_f32_e32 v50, v28, v232
	v_fmac_f32_e32 v51, v28, v248
	v_fmac_f32_e32 v50, v29, v233
	v_fmac_f32_e32 v51, v29, v249
	v_fmac_f32_e32 v50, v30, v234
	v_fmac_f32_e32 v51, v30, v250
	v_fmac_f32_e32 v50, v31, v235
	v_fmac_f32_e32 v51, v31, v251
	v_mul_f32_e64 v52, |v50|, s7
	v_mul_f32_e64 v53, |v51|, s7
	v_exp_f32_e32 v52, v52
	v_exp_f32_e32 v53, v53
	v_min_f32_e32 v50, 0, v50
	v_add_f32_e32 v52, 1.0, v52
	v_add_f32_e32 v53, 1.0, v53
	v_log_f32_e32 v52, v52
	v_log_f32_e32 v53, v53
	v_min_f32_e32 v51, 0, v51
	v_mul_f32_e32 v54, 0x3f317217, v52
	v_mul_f32_e32 v55, 0x3f317217, v53
	v_fma_f32 v56, v52, s9, -v54
	v_fma_f32 v57, v53, s9, -v55
	v_fmac_f32_e32 v56, 0x3377d1cf, v52
	v_fmac_f32_e32 v57, 0x3377d1cf, v53
	v_add_f32_e32 v54, v54, v56
	v_add_f32_e32 v55, v55, v57
	v_sub_f32_e32 v50, v50, v54
	v_sub_f32_e32 v51, v51, v55
	v_fmamk_f32 v126, v50, 0x3d800000, v125
	v_fmamk_f32 v127, v51, 0x3d800000, v126
	s_waitcnt vmcnt(0)
	v_sub_f32_e32 v52, v96, v96
	v_lshlrev_b32_e32 v50, 16, v136
	v_mul_f32_e32 v52, 0x3fb8aa3b, v52
	v_lshlrev_b32_e32 v51, 16, v137
	v_exp_f32_e32 v53, v52
	v_exp_f32_e64 v54, -v52
	v_mul_f32_e32 v50, 0x3db504f3, v50
	s_nop 0
	v_mul_f32_e32 v50, v53, v50
	v_mul_f32_e32 v8, v54, v51
	v_cvt_pk_bf16_f32 v50, v50, v8
	global_store_short v1, v50, s[22:23]
	global_store_short_d16_hi v1, v50, s[22:23] offset:1024
	s_add_u32 s22, s22, 0x1a00
	s_addc_u32 s23, s23, 0
	v_sub_f32_e32 v52, v97, v96
	v_lshlrev_b32_e32 v50, 16, v138
	v_mul_f32_e32 v52, 0x3fb8aa3b, v52
	v_lshlrev_b32_e32 v51, 16, v139
	v_exp_f32_e32 v53, v52
	v_exp_f32_e64 v54, -v52
	v_mul_f32_e32 v50, 0x3db504f3, v50
	s_nop 0
	v_mul_f32_e32 v50, v53, v50
	v_mul_f32_e32 v9, v54, v51
	v_cvt_pk_bf16_f32 v50, v50, v9
	global_store_short v1, v50, s[22:23]
	global_store_short_d16_hi v1, v50, s[22:23] offset:1024
	s_add_u32 s22, s22, 0x1a00
	s_addc_u32 s23, s23, 0
	v_sub_f32_e32 v52, v98, v96
	v_lshlrev_b32_e32 v50, 16, v140
	v_mul_f32_e32 v52, 0x3fb8aa3b, v52
	v_lshlrev_b32_e32 v51, 16, v141
	v_exp_f32_e32 v53, v52
	v_exp_f32_e64 v54, -v52
	v_mul_f32_e32 v50, 0x3db504f3, v50
	s_nop 0
	v_mul_f32_e32 v50, v53, v50
	v_mul_f32_e32 v10, v54, v51
	v_cvt_pk_bf16_f32 v50, v50, v10
	global_store_short v1, v50, s[22:23]
	global_store_short_d16_hi v1, v50, s[22:23] offset:1024
	s_add_u32 s22, s22, 0x1a00
	s_addc_u32 s23, s23, 0
	v_sub_f32_e32 v52, v99, v96
	v_lshlrev_b32_e32 v50, 16, v142
	v_mul_f32_e32 v52, 0x3fb8aa3b, v52
	v_lshlrev_b32_e32 v51, 16, v143
	v_exp_f32_e32 v53, v52
	v_exp_f32_e64 v54, -v52
	v_mul_f32_e32 v50, 0x3db504f3, v50
	s_nop 0
	v_mul_f32_e32 v50, v53, v50
	v_mul_f32_e32 v11, v54, v51
	v_cvt_pk_bf16_f32 v50, v50, v11
	global_store_short v1, v50, s[22:23]
	global_store_short_d16_hi v1, v50, s[22:23] offset:1024
	s_add_u32 s22, s22, 0x1a00
	s_addc_u32 s23, s23, 0
	v_sub_f32_e32 v52, v100, v96
	v_lshlrev_b32_e32 v50, 16, v144
	v_mul_f32_e32 v52, 0x3fb8aa3b, v52
	v_lshlrev_b32_e32 v51, 16, v145
	v_exp_f32_e32 v53, v52
	v_exp_f32_e64 v54, -v52
	v_mul_f32_e32 v50, 0x3db504f3, v50
	s_nop 0
	v_mul_f32_e32 v50, v53, v50
	v_mul_f32_e32 v12, v54, v51
	v_cvt_pk_bf16_f32 v50, v50, v12
	global_store_short v1, v50, s[22:23]
	global_store_short_d16_hi v1, v50, s[22:23] offset:1024
	s_add_u32 s22, s22, 0x1a00
	s_addc_u32 s23, s23, 0
	v_sub_f32_e32 v52, v101, v96
	v_lshlrev_b32_e32 v50, 16, v146
	v_mul_f32_e32 v52, 0x3fb8aa3b, v52
	v_lshlrev_b32_e32 v51, 16, v147
	v_exp_f32_e32 v53, v52
	v_exp_f32_e64 v54, -v52
	v_mul_f32_e32 v50, 0x3db504f3, v50
	s_nop 0
	v_mul_f32_e32 v50, v53, v50
	v_mul_f32_e32 v13, v54, v51
	v_cvt_pk_bf16_f32 v50, v50, v13
	global_store_short v1, v50, s[22:23]
	global_store_short_d16_hi v1, v50, s[22:23] offset:1024
	s_add_u32 s22, s22, 0x1a00
	s_addc_u32 s23, s23, 0
	v_sub_f32_e32 v52, v102, v96
	v_lshlrev_b32_e32 v50, 16, v148
	v_mul_f32_e32 v52, 0x3fb8aa3b, v52
	v_lshlrev_b32_e32 v51, 16, v149
	v_exp_f32_e32 v53, v52
	v_exp_f32_e64 v54, -v52
	v_mul_f32_e32 v50, 0x3db504f3, v50
	s_nop 0
	v_mul_f32_e32 v50, v53, v50
	v_mul_f32_e32 v14, v54, v51
	v_cvt_pk_bf16_f32 v50, v50, v14
	global_store_short v1, v50, s[22:23]
	global_store_short_d16_hi v1, v50, s[22:23] offset:1024
	s_add_u32 s22, s22, 0x1a00
	s_addc_u32 s23, s23, 0
	v_sub_f32_e32 v52, v103, v96
	v_lshlrev_b32_e32 v50, 16, v150
	v_mul_f32_e32 v52, 0x3fb8aa3b, v52
	v_lshlrev_b32_e32 v51, 16, v151
	v_exp_f32_e32 v53, v52
	v_exp_f32_e64 v54, -v52
	v_mul_f32_e32 v50, 0x3db504f3, v50
	s_nop 0
	v_mul_f32_e32 v50, v53, v50
	v_mul_f32_e32 v15, v54, v51
	v_cvt_pk_bf16_f32 v50, v50, v15
	global_store_short v1, v50, s[22:23]
	global_store_short_d16_hi v1, v50, s[22:23] offset:1024
	s_add_u32 s22, s22, 0x1a00
	s_addc_u32 s23, s23, 0
	v_cvt_pk_bf16_f32 v4, v8, v9
	v_cvt_pk_bf16_f32 v5, v10, v11
	v_cvt_pk_bf16_f32 v6, v12, v13
	v_cvt_pk_bf16_f32 v7, v14, v15
	global_store_dwordx4 v2, v[4:7], s[26:27] offset:64 sc1
	v_sub_f32_e32 v52, v104, v96
	v_lshlrev_b32_e32 v50, 16, v152
	v_mul_f32_e32 v52, 0x3fb8aa3b, v52
	v_lshlrev_b32_e32 v51, 16, v153
	v_exp_f32_e32 v53, v52
	v_exp_f32_e64 v54, -v52
	v_mul_f32_e32 v50, 0x3db504f3, v50
	s_nop 0
	v_mul_f32_e32 v50, v53, v50
	v_mul_f32_e32 v8, v54, v51
	v_cvt_pk_bf16_f32 v50, v50, v8
	global_store_short v1, v50, s[22:23]
	global_store_short_d16_hi v1, v50, s[22:23] offset:1024
	s_add_u32 s22, s22, 0x1a00
	s_addc_u32 s23, s23, 0
	v_sub_f32_e32 v52, v105, v96
	v_lshlrev_b32_e32 v50, 16, v154
	v_mul_f32_e32 v52, 0x3fb8aa3b, v52
	v_lshlrev_b32_e32 v51, 16, v155
	v_exp_f32_e32 v53, v52
	v_exp_f32_e64 v54, -v52
	v_mul_f32_e32 v50, 0x3db504f3, v50
	s_nop 0
	v_mul_f32_e32 v50, v53, v50
	v_mul_f32_e32 v9, v54, v51
	v_cvt_pk_bf16_f32 v50, v50, v9
	global_store_short v1, v50, s[22:23]
	global_store_short_d16_hi v1, v50, s[22:23] offset:1024
	s_add_u32 s22, s22, 0x1a00
	s_addc_u32 s23, s23, 0
	v_sub_f32_e32 v52, v106, v96
	v_lshlrev_b32_e32 v50, 16, v156
	v_mul_f32_e32 v52, 0x3fb8aa3b, v52
	v_lshlrev_b32_e32 v51, 16, v157
	v_exp_f32_e32 v53, v52
	v_exp_f32_e64 v54, -v52
	v_mul_f32_e32 v50, 0x3db504f3, v50
	s_nop 0
	v_mul_f32_e32 v50, v53, v50
	v_mul_f32_e32 v10, v54, v51
	v_cvt_pk_bf16_f32 v50, v50, v10
	global_store_short v1, v50, s[22:23]
	global_store_short_d16_hi v1, v50, s[22:23] offset:1024
	s_add_u32 s22, s22, 0x1a00
	s_addc_u32 s23, s23, 0
	v_sub_f32_e32 v52, v107, v96
	v_lshlrev_b32_e32 v50, 16, v158
	v_mul_f32_e32 v52, 0x3fb8aa3b, v52
	v_lshlrev_b32_e32 v51, 16, v159
	v_exp_f32_e32 v53, v52
	v_exp_f32_e64 v54, -v52
	v_mul_f32_e32 v50, 0x3db504f3, v50
	s_nop 0
	v_mul_f32_e32 v50, v53, v50
	v_mul_f32_e32 v11, v54, v51
	v_cvt_pk_bf16_f32 v50, v50, v11
	global_store_short v1, v50, s[22:23]
	global_store_short_d16_hi v1, v50, s[22:23] offset:1024
	s_add_u32 s22, s22, 0x1a00
	s_addc_u32 s23, s23, 0
	v_sub_f32_e32 v52, v108, v96
	v_lshlrev_b32_e32 v50, 16, v160
	v_mul_f32_e32 v52, 0x3fb8aa3b, v52
	v_lshlrev_b32_e32 v51, 16, v161
	v_exp_f32_e32 v53, v52
	v_exp_f32_e64 v54, -v52
	v_mul_f32_e32 v50, 0x3db504f3, v50
	s_nop 0
	v_mul_f32_e32 v50, v53, v50
	v_mul_f32_e32 v12, v54, v51
	v_cvt_pk_bf16_f32 v50, v50, v12
	global_store_short v1, v50, s[22:23]
	global_store_short_d16_hi v1, v50, s[22:23] offset:1024
	s_add_u32 s22, s22, 0x1a00
	s_addc_u32 s23, s23, 0
	v_sub_f32_e32 v52, v109, v96
	v_lshlrev_b32_e32 v50, 16, v162
	v_mul_f32_e32 v52, 0x3fb8aa3b, v52
	v_lshlrev_b32_e32 v51, 16, v163
	v_exp_f32_e32 v53, v52
	v_exp_f32_e64 v54, -v52
	v_mul_f32_e32 v50, 0x3db504f3, v50
	s_nop 0
	v_mul_f32_e32 v50, v53, v50
	v_mul_f32_e32 v13, v54, v51
	v_cvt_pk_bf16_f32 v50, v50, v13
	global_store_short v1, v50, s[22:23]
	global_store_short_d16_hi v1, v50, s[22:23] offset:1024
	s_add_u32 s22, s22, 0x1a00
	s_addc_u32 s23, s23, 0
	v_sub_f32_e32 v52, v110, v96
	v_lshlrev_b32_e32 v50, 16, v164
	v_mul_f32_e32 v52, 0x3fb8aa3b, v52
	v_lshlrev_b32_e32 v51, 16, v165
	v_exp_f32_e32 v53, v52
	v_exp_f32_e64 v54, -v52
	v_mul_f32_e32 v50, 0x3db504f3, v50
	s_nop 0
	v_mul_f32_e32 v50, v53, v50
	v_mul_f32_e32 v14, v54, v51
	v_cvt_pk_bf16_f32 v50, v50, v14
	global_store_short v1, v50, s[22:23]
	global_store_short_d16_hi v1, v50, s[22:23] offset:1024
	s_add_u32 s22, s22, 0x1a00
	s_addc_u32 s23, s23, 0
	v_sub_f32_e32 v52, v111, v96
	v_lshlrev_b32_e32 v50, 16, v166
	v_mul_f32_e32 v52, 0x3fb8aa3b, v52
	v_lshlrev_b32_e32 v51, 16, v167
	v_exp_f32_e32 v53, v52
	v_exp_f32_e64 v54, -v52
	v_mul_f32_e32 v50, 0x3db504f3, v50
	s_nop 0
	v_mul_f32_e32 v50, v53, v50
	v_mul_f32_e32 v15, v54, v51
	v_cvt_pk_bf16_f32 v50, v50, v15
	global_store_short v1, v50, s[22:23]
	global_store_short_d16_hi v1, v50, s[22:23] offset:1024
	s_add_u32 s22, s22, 0x1a00
	s_addc_u32 s23, s23, 0
	v_cvt_pk_bf16_f32 v4, v8, v9
	v_cvt_pk_bf16_f32 v5, v10, v11
	v_cvt_pk_bf16_f32 v6, v12, v13
	v_cvt_pk_bf16_f32 v7, v14, v15
	global_store_dwordx4 v2, v[4:7], s[26:27] offset:80 sc1
	v_sub_f32_e32 v52, v112, v96
	v_lshlrev_b32_e32 v50, 16, v168
	v_mul_f32_e32 v52, 0x3fb8aa3b, v52
	v_lshlrev_b32_e32 v51, 16, v169
	v_exp_f32_e32 v53, v52
	v_exp_f32_e64 v54, -v52
	v_mul_f32_e32 v50, 0x3db504f3, v50
	s_nop 0
	v_mul_f32_e32 v50, v53, v50
	v_mul_f32_e32 v8, v54, v51
	v_cvt_pk_bf16_f32 v50, v50, v8
	global_store_short v1, v50, s[22:23]
	global_store_short_d16_hi v1, v50, s[22:23] offset:1024
	s_add_u32 s22, s22, 0x1a00
	s_addc_u32 s23, s23, 0
	v_sub_f32_e32 v52, v113, v96
	v_lshlrev_b32_e32 v50, 16, v170
	v_mul_f32_e32 v52, 0x3fb8aa3b, v52
	v_lshlrev_b32_e32 v51, 16, v171
	v_exp_f32_e32 v53, v52
	v_exp_f32_e64 v54, -v52
	v_mul_f32_e32 v50, 0x3db504f3, v50
	s_nop 0
	v_mul_f32_e32 v50, v53, v50
	v_mul_f32_e32 v9, v54, v51
	v_cvt_pk_bf16_f32 v50, v50, v9
	global_store_short v1, v50, s[22:23]
	global_store_short_d16_hi v1, v50, s[22:23] offset:1024
	s_add_u32 s22, s22, 0x1a00
	s_addc_u32 s23, s23, 0
	v_sub_f32_e32 v52, v114, v96
	v_lshlrev_b32_e32 v50, 16, v172
	v_mul_f32_e32 v52, 0x3fb8aa3b, v52
	v_lshlrev_b32_e32 v51, 16, v173
	v_exp_f32_e32 v53, v52
	v_exp_f32_e64 v54, -v52
	v_mul_f32_e32 v50, 0x3db504f3, v50
	s_nop 0
	v_mul_f32_e32 v50, v53, v50
	v_mul_f32_e32 v10, v54, v51
	v_cvt_pk_bf16_f32 v50, v50, v10
	global_store_short v1, v50, s[22:23]
	global_store_short_d16_hi v1, v50, s[22:23] offset:1024
	s_add_u32 s22, s22, 0x1a00
	s_addc_u32 s23, s23, 0
	v_sub_f32_e32 v52, v115, v96
	v_lshlrev_b32_e32 v50, 16, v174
	v_mul_f32_e32 v52, 0x3fb8aa3b, v52
	v_lshlrev_b32_e32 v51, 16, v175
	v_exp_f32_e32 v53, v52
	v_exp_f32_e64 v54, -v52
	v_mul_f32_e32 v50, 0x3db504f3, v50
	s_nop 0
	v_mul_f32_e32 v50, v53, v50
	v_mul_f32_e32 v11, v54, v51
	v_cvt_pk_bf16_f32 v50, v50, v11
	global_store_short v1, v50, s[22:23]
	global_store_short_d16_hi v1, v50, s[22:23] offset:1024
	s_add_u32 s22, s22, 0x1a00
	s_addc_u32 s23, s23, 0
	v_sub_f32_e32 v52, v116, v96
	v_lshlrev_b32_e32 v50, 16, v176
	v_mul_f32_e32 v52, 0x3fb8aa3b, v52
	v_lshlrev_b32_e32 v51, 16, v177
	v_exp_f32_e32 v53, v52
	v_exp_f32_e64 v54, -v52
	v_mul_f32_e32 v50, 0x3db504f3, v50
	s_nop 0
	v_mul_f32_e32 v50, v53, v50
	v_mul_f32_e32 v12, v54, v51
	v_cvt_pk_bf16_f32 v50, v50, v12
	global_store_short v1, v50, s[22:23]
	global_store_short_d16_hi v1, v50, s[22:23] offset:1024
	s_add_u32 s22, s22, 0x1a00
	s_addc_u32 s23, s23, 0
	v_sub_f32_e32 v52, v117, v96
	v_lshlrev_b32_e32 v50, 16, v178
	v_mul_f32_e32 v52, 0x3fb8aa3b, v52
	v_lshlrev_b32_e32 v51, 16, v179
	v_exp_f32_e32 v53, v52
	v_exp_f32_e64 v54, -v52
	v_mul_f32_e32 v50, 0x3db504f3, v50
	s_nop 0
	v_mul_f32_e32 v50, v53, v50
	v_mul_f32_e32 v13, v54, v51
	v_cvt_pk_bf16_f32 v50, v50, v13
	global_store_short v1, v50, s[22:23]
	global_store_short_d16_hi v1, v50, s[22:23] offset:1024
	s_add_u32 s22, s22, 0x1a00
	s_addc_u32 s23, s23, 0
	v_sub_f32_e32 v52, v118, v96
	v_lshlrev_b32_e32 v50, 16, v180
	v_mul_f32_e32 v52, 0x3fb8aa3b, v52
	v_lshlrev_b32_e32 v51, 16, v181
	v_exp_f32_e32 v53, v52
	v_exp_f32_e64 v54, -v52
	v_mul_f32_e32 v50, 0x3db504f3, v50
	s_nop 0
	v_mul_f32_e32 v50, v53, v50
	v_mul_f32_e32 v14, v54, v51
	v_cvt_pk_bf16_f32 v50, v50, v14
	global_store_short v1, v50, s[22:23]
	global_store_short_d16_hi v1, v50, s[22:23] offset:1024
	s_add_u32 s22, s22, 0x1a00
	s_addc_u32 s23, s23, 0
	v_sub_f32_e32 v52, v119, v96
	v_lshlrev_b32_e32 v50, 16, v182
	v_mul_f32_e32 v52, 0x3fb8aa3b, v52
	v_lshlrev_b32_e32 v51, 16, v183
	v_exp_f32_e32 v53, v52
	v_exp_f32_e64 v54, -v52
	v_mul_f32_e32 v50, 0x3db504f3, v50
	s_nop 0
	v_mul_f32_e32 v50, v53, v50
	v_mul_f32_e32 v15, v54, v51
	v_cvt_pk_bf16_f32 v50, v50, v15
	global_store_short v1, v50, s[22:23]
	global_store_short_d16_hi v1, v50, s[22:23] offset:1024
	s_add_u32 s22, s22, 0x1a00
	s_addc_u32 s23, s23, 0
	v_cvt_pk_bf16_f32 v4, v8, v9
	v_cvt_pk_bf16_f32 v5, v10, v11
	v_cvt_pk_bf16_f32 v6, v12, v13
	v_cvt_pk_bf16_f32 v7, v14, v15
	global_store_dwordx4 v2, v[4:7], s[26:27] offset:96 sc1
	s_waitcnt vmcnt(52)
	v_sub_f32_e32 v52, v120, v96
	v_lshlrev_b32_e32 v50, 16, v184
	v_mul_f32_e32 v52, 0x3fb8aa3b, v52
	v_lshlrev_b32_e32 v51, 16, v185
	v_exp_f32_e32 v53, v52
	v_exp_f32_e64 v54, -v52
	v_mul_f32_e32 v50, 0x3db504f3, v50
	s_nop 0
	v_mul_f32_e32 v50, v53, v50
	v_mul_f32_e32 v8, v54, v51
	v_cvt_pk_bf16_f32 v50, v50, v8
	global_store_short v1, v50, s[22:23]
	global_store_short_d16_hi v1, v50, s[22:23] offset:1024
	s_add_u32 s22, s22, 0x1a00
	s_addc_u32 s23, s23, 0
	s_waitcnt vmcnt(52)
	v_sub_f32_e32 v52, v121, v96
	v_lshlrev_b32_e32 v50, 16, v186
	v_mul_f32_e32 v52, 0x3fb8aa3b, v52
	v_lshlrev_b32_e32 v51, 16, v187
	v_exp_f32_e32 v53, v52
	v_exp_f32_e64 v54, -v52
	v_mul_f32_e32 v50, 0x3db504f3, v50
	s_nop 0
	v_mul_f32_e32 v50, v53, v50
	v_mul_f32_e32 v9, v54, v51
	v_cvt_pk_bf16_f32 v50, v50, v9
	global_store_short v1, v50, s[22:23]
	global_store_short_d16_hi v1, v50, s[22:23] offset:1024
	s_add_u32 s22, s22, 0x1a00
	s_addc_u32 s23, s23, 0
	s_waitcnt vmcnt(52)
	v_sub_f32_e32 v52, v122, v96
	v_lshlrev_b32_e32 v50, 16, v188
	v_mul_f32_e32 v52, 0x3fb8aa3b, v52
	v_lshlrev_b32_e32 v51, 16, v189
	v_exp_f32_e32 v53, v52
	v_exp_f32_e64 v54, -v52
	v_mul_f32_e32 v50, 0x3db504f3, v50
	s_nop 0
	v_mul_f32_e32 v50, v53, v50
	v_mul_f32_e32 v10, v54, v51
	v_cvt_pk_bf16_f32 v50, v50, v10
	global_store_short v1, v50, s[22:23]
	global_store_short_d16_hi v1, v50, s[22:23] offset:1024
	s_add_u32 s22, s22, 0x1a00
	s_addc_u32 s23, s23, 0
	s_waitcnt vmcnt(52)
	v_sub_f32_e32 v52, v123, v96
	v_lshlrev_b32_e32 v50, 16, v190
	v_mul_f32_e32 v52, 0x3fb8aa3b, v52
	v_lshlrev_b32_e32 v51, 16, v191
	v_exp_f32_e32 v53, v52
	v_exp_f32_e64 v54, -v52
	v_mul_f32_e32 v50, 0x3db504f3, v50
	s_nop 0
	v_mul_f32_e32 v50, v53, v50
	v_mul_f32_e32 v11, v54, v51
	v_cvt_pk_bf16_f32 v50, v50, v11
	global_store_short v1, v50, s[22:23]
	global_store_short_d16_hi v1, v50, s[22:23] offset:1024
	s_add_u32 s22, s22, 0x1a00
	s_addc_u32 s23, s23, 0
	s_waitcnt vmcnt(52)
	v_sub_f32_e32 v52, v124, v96
	v_lshlrev_b32_e32 v50, 16, v192
	v_mul_f32_e32 v52, 0x3fb8aa3b, v52
	v_lshlrev_b32_e32 v51, 16, v193
	v_exp_f32_e32 v53, v52
	v_exp_f32_e64 v54, -v52
	v_mul_f32_e32 v50, 0x3db504f3, v50
	s_nop 0
	v_mul_f32_e32 v50, v53, v50
	v_mul_f32_e32 v12, v54, v51
	v_cvt_pk_bf16_f32 v50, v50, v12
	global_store_short v1, v50, s[22:23]
	global_store_short_d16_hi v1, v50, s[22:23] offset:1024
	s_add_u32 s22, s22, 0x1a00
	s_addc_u32 s23, s23, 0
	s_waitcnt vmcnt(52)
	v_sub_f32_e32 v52, v125, v96
	v_lshlrev_b32_e32 v50, 16, v194
	v_mul_f32_e32 v52, 0x3fb8aa3b, v52
	v_lshlrev_b32_e32 v51, 16, v195
	v_exp_f32_e32 v53, v52
	v_exp_f32_e64 v54, -v52
	v_mul_f32_e32 v50, 0x3db504f3, v50
	s_nop 0
	v_mul_f32_e32 v50, v53, v50
	v_mul_f32_e32 v13, v54, v51
	v_cvt_pk_bf16_f32 v50, v50, v13
	global_store_short v1, v50, s[22:23]
	global_store_short_d16_hi v1, v50, s[22:23] offset:1024
	s_add_u32 s22, s22, 0x1a00
	s_addc_u32 s23, s23, 0
	s_waitcnt vmcnt(52)
	v_sub_f32_e32 v52, v126, v96
	v_lshlrev_b32_e32 v50, 16, v196
	v_mul_f32_e32 v52, 0x3fb8aa3b, v52
	v_lshlrev_b32_e32 v51, 16, v197
	v_exp_f32_e32 v53, v52
	v_exp_f32_e64 v54, -v52
	v_mul_f32_e32 v50, 0x3db504f3, v50
	s_nop 0
	v_mul_f32_e32 v50, v53, v50
	v_mul_f32_e32 v14, v54, v51
	v_cvt_pk_bf16_f32 v50, v50, v14
	global_store_short v1, v50, s[22:23]
	global_store_short_d16_hi v1, v50, s[22:23] offset:1024
	s_add_u32 s22, s22, 0x1a00
	s_addc_u32 s23, s23, 0
	s_waitcnt vmcnt(52)
	v_sub_f32_e32 v52, v127, v96
	v_lshlrev_b32_e32 v50, 16, v198
	v_mul_f32_e32 v52, 0x3fb8aa3b, v52
	v_lshlrev_b32_e32 v51, 16, v199
	v_exp_f32_e32 v53, v52
	v_exp_f32_e64 v54, -v52
	v_mul_f32_e32 v50, 0x3db504f3, v50
	s_nop 0
	v_mul_f32_e32 v50, v53, v50
	v_mul_f32_e32 v15, v54, v51
	v_cvt_pk_bf16_f32 v50, v50, v15
	global_store_short v1, v50, s[22:23]
	global_store_short_d16_hi v1, v50, s[22:23] offset:1024
	s_add_u32 s22, s22, 0x1a00
	s_addc_u32 s23, s23, 0
	v_cvt_pk_bf16_f32 v4, v8, v9
	v_cvt_pk_bf16_f32 v5, v10, v11
	v_cvt_pk_bf16_f32 v6, v12, v13
	v_cvt_pk_bf16_f32 v7, v14, v15
	global_store_dwordx4 v2, v[4:7], s[26:27] offset:112 sc1
	v_mul_f32_e32 v50, 0x3fb8aa3b, v96
	v_sub_f32_e32 v51, v127, v96
	v_mul_f32_e32 v52, 0x3fb8aa3b, v127
	v_mul_f32_e32 v51, 0x3fb8aa3b, v51
	v_exp_f32_e32 v50, v50
	v_exp_f32_e32 v51, v51
	v_exp_f32_e32 v52, v52
	s_nop 0
	global_store_dword v0, v50, s[28:29]
	global_store_dword v0, v51, s[28:29] offset:2048
	s_add_u32 s28, s28, 0x1000
	s_addc_u32 s29, s29, 0
	global_store_dword v0, v52, s[28:29]
	s_add_i32 s82, s82, s3
	s_cmpk_lt_i32 s82, 0x100
	s_cbranch_scc1 .Lprep_item

.LBB0_486:
	ds_read_b128 v[154:157], v151
	ds_read_b128 v[158:161], v151 offset:1024
	ds_read_b128 v[162:165], v151 offset:2048
	ds_read_b128 v[166:169], v151 offset:3072
	s_add_u32 s30, s28, 0xfffc0080
	s_addc_u32 s31, s29, -1
	s_cmp_eq_u32 s84, 12
	s_cselect_b32 s35, s19, s31
	s_cselect_b32 s34, s80, s30
	s_cselect_b32 s31, s17, s83
	s_cselect_b32 s30, s81, s82
	v_lshl_add_u64 v[202:203], s[28:29], 0, v[138:139]
	s_add_i32 m0, s15, 0xc000
	ds_read_b128 v[170:173], v152
	ds_read_b128 v[174:177], v152 offset:1024
	ds_read_b128 v[178:181], v152 offset:2048
	ds_read_b128 v[182:185], v152 offset:3072
	ds_read_b128 v[186:189], v152 offset:4096
	ds_read_b128 v[190:193], v152 offset:5120
	ds_read_b128 v[194:197], v152 offset:6144
	ds_read_b128 v[198:201], v152 offset:7168
	global_load_lds_dwordx4 v[202:203], off
	v_lshl_add_u64 v[202:203], s[28:29], 0, v[140:141]
	s_add_i32 m0, s15, 0xe000
	s_nop 0
	global_load_lds_dwordx4 v[202:203], off
	s_waitcnt lgkmcnt(8)
	s_barrier
	s_waitcnt lgkmcnt(0)
	s_setprio 1
	s_waitcnt lgkmcnt(0)
	v_mfma_f32_16x16x32_bf16 v[124:127], v[154:157], v[170:173], v[124:127]
	v_mfma_f32_16x16x32_bf16 v[120:123], v[162:165], v[170:173], v[120:123]
	v_mfma_f32_16x16x32_bf16 v[116:119], v[154:157], v[178:181], v[116:119]
	v_mfma_f32_16x16x32_bf16 v[112:115], v[162:165], v[178:181], v[112:115]
	v_mfma_f32_16x16x32_bf16 v[100:103], v[154:157], v[186:189], v[100:103]
	v_mfma_f32_16x16x32_bf16 v[96:99], v[162:165], v[186:189], v[96:99]
	v_mfma_f32_16x16x32_bf16 v[84:87], v[154:157], v[194:197], v[84:87]
	v_mfma_f32_16x16x32_bf16 v[80:83], v[162:165], v[194:197], v[80:83]
	v_mfma_f32_16x16x32_bf16 v[124:127], v[158:161], v[174:177], v[124:127]
	v_mfma_f32_16x16x32_bf16 v[120:123], v[166:169], v[174:177], v[120:123]
	v_mfma_f32_16x16x32_bf16 v[116:119], v[158:161], v[182:185], v[116:119]
	v_mfma_f32_16x16x32_bf16 v[112:115], v[166:169], v[182:185], v[112:115]
	v_mfma_f32_16x16x32_bf16 v[100:103], v[158:161], v[190:193], v[100:103]
	v_mfma_f32_16x16x32_bf16 v[96:99], v[166:169], v[190:193], v[96:99]
	v_mfma_f32_16x16x32_bf16 v[84:87], v[158:161], v[198:201], v[84:87]
	v_mfma_f32_16x16x32_bf16 v[80:83], v[166:169], v[198:201], v[80:83]
	s_setprio 0
	s_barrier
	s_add_i32 s85, s74, s55
	v_lshl_add_u64 v[218:219], s[30:31], 0, v[134:135]
	s_mov_b32 m0, s85
	ds_read_b128 v[202:205], v153
	ds_read_b128 v[206:209], v153 offset:1024
	ds_read_b128 v[210:213], v153 offset:2048
	ds_read_b128 v[214:217], v153 offset:3072
	global_load_lds_dwordx4 v[218:219], off
	v_lshl_add_u64 v[220:221], s[30:31], 0, v[130:131]
	s_add_i32 m0, s85, 0x2000
	s_nop 0
	global_load_lds_dwordx4 v[220:221], off
	s_barrier
	s_waitcnt lgkmcnt(0)
	s_setprio 1
	s_waitcnt lgkmcnt(0)
	v_mfma_f32_16x16x32_bf16 v[108:111], v[202:205], v[170:173], v[108:111]
	v_mfma_f32_16x16x32_bf16 v[104:107], v[210:213], v[170:173], v[104:107]
	v_mfma_f32_16x16x32_bf16 v[92:95], v[202:205], v[178:181], v[92:95]
	v_mfma_f32_16x16x32_bf16 v[88:91], v[210:213], v[178:181], v[88:91]
	v_mfma_f32_16x16x32_bf16 v[76:79], v[202:205], v[186:189], v[76:79]
	v_mfma_f32_16x16x32_bf16 v[72:75], v[210:213], v[186:189], v[72:75]
	v_mfma_f32_16x16x32_bf16 v[68:71], v[202:205], v[194:197], v[68:71]
	v_mfma_f32_16x16x32_bf16 v[64:67], v[210:213], v[194:197], v[64:67]
	v_mfma_f32_16x16x32_bf16 v[108:111], v[206:209], v[174:177], v[108:111]
	v_mfma_f32_16x16x32_bf16 v[104:107], v[214:217], v[174:177], v[104:107]
	v_mfma_f32_16x16x32_bf16 v[92:95], v[206:209], v[182:185], v[92:95]
	v_mfma_f32_16x16x32_bf16 v[88:91], v[214:217], v[182:185], v[88:91]
	v_mfma_f32_16x16x32_bf16 v[76:79], v[206:209], v[190:193], v[76:79]
	v_mfma_f32_16x16x32_bf16 v[72:75], v[214:217], v[190:193], v[72:75]
	v_mfma_f32_16x16x32_bf16 v[68:71], v[206:209], v[198:201], v[68:71]
	v_mfma_f32_16x16x32_bf16 v[64:67], v[214:217], v[198:201], v[64:67]
	s_setprio 0
	s_mov_b32 m0, s15
	v_lshl_add_u64 v[222:223], s[34:35], 0, v[136:137]
	s_barrier
	ds_read_b128 v[170:173], v152 offset:16384
	ds_read_b128 v[174:177], v152 offset:17408
	ds_read_b128 v[178:181], v152 offset:18432
	ds_read_b128 v[182:185], v152 offset:19456
	ds_read_b128 v[186:189], v152 offset:20480
	ds_read_b128 v[190:193], v152 offset:21504
	ds_read_b128 v[194:197], v152 offset:22528
	ds_read_b128 v[198:201], v152 offset:23552
	global_load_lds_dwordx4 v[222:223], off
	v_lshl_add_u64 v[224:225], s[34:35], 0, v[132:133]
	s_mov_b32 m0, s57
	s_nop 0
	global_load_lds_dwordx4 v[224:225], off
	s_barrier
	s_waitcnt lgkmcnt(0)
	s_setprio 1
	s_waitcnt lgkmcnt(0)
	v_mfma_f32_16x16x32_bf16 v[60:63], v[154:157], v[170:173], v[60:63]
	v_mfma_f32_16x16x32_bf16 v[56:59], v[162:165], v[170:173], v[56:59]
	v_mfma_f32_16x16x32_bf16 v[52:55], v[154:157], v[178:181], v[52:55]
	v_mfma_f32_16x16x32_bf16 v[48:51], v[162:165], v[178:181], v[48:51]
	v_mfma_f32_16x16x32_bf16 v[36:39], v[154:157], v[186:189], v[36:39]
	v_mfma_f32_16x16x32_bf16 v[32:35], v[162:165], v[186:189], v[32:35]
	v_mfma_f32_16x16x32_bf16 v[20:23], v[154:157], v[194:197], v[20:23]
	v_mfma_f32_16x16x32_bf16 v[16:19], v[162:165], v[194:197], v[16:19]
	v_mfma_f32_16x16x32_bf16 v[60:63], v[158:161], v[174:177], v[60:63]
	v_mfma_f32_16x16x32_bf16 v[56:59], v[166:169], v[174:177], v[56:59]
	v_mfma_f32_16x16x32_bf16 v[52:55], v[158:161], v[182:185], v[52:55]
	v_mfma_f32_16x16x32_bf16 v[48:51], v[166:169], v[182:185], v[48:51]
	v_mfma_f32_16x16x32_bf16 v[36:39], v[158:161], v[190:193], v[36:39]
	v_mfma_f32_16x16x32_bf16 v[32:35], v[166:169], v[190:193], v[32:35]
	v_mfma_f32_16x16x32_bf16 v[20:23], v[158:161], v[198:201], v[20:23]
	v_mfma_f32_16x16x32_bf16 v[16:19], v[166:169], v[198:201], v[16:19]
	s_setprio 0
	s_barrier
	s_add_u32 s86, s30, 0x40000
	s_addc_u32 s87, s31, 0
	s_add_i32 s85, s75, s55
	v_lshl_add_u64 v[154:155], s[86:87], 0, v[134:135]
	s_mov_b32 m0, s85
	s_nop 0
	global_load_lds_dwordx4 v[154:155], off
	v_lshl_add_u64 v[154:155], s[86:87], 0, v[130:131]
	s_add_i32 m0, s85, 0x2000
	s_nop 0
	global_load_lds_dwordx4 v[154:155], off
	s_waitcnt vmcnt(6)
	s_barrier
	s_setprio 1
	v_mfma_f32_16x16x32_bf16 v[44:47], v[202:205], v[170:173], v[44:47]
	v_mfma_f32_16x16x32_bf16 v[40:43], v[210:213], v[170:173], v[40:43]
	v_mfma_f32_16x16x32_bf16 v[28:31], v[202:205], v[178:181], v[28:31]
	v_mfma_f32_16x16x32_bf16 v[24:27], v[210:213], v[178:181], v[24:27]
	v_mfma_f32_16x16x32_bf16 v[12:15], v[202:205], v[186:189], v[12:15]
	v_mfma_f32_16x16x32_bf16 v[8:11], v[210:213], v[186:189], v[8:11]
	v_mfma_f32_16x16x32_bf16 v[4:7], v[202:205], v[194:197], v[4:7]
	v_mfma_f32_16x16x32_bf16 v[0:3], v[210:213], v[194:197], v[0:3]
	v_mfma_f32_16x16x32_bf16 v[44:47], v[206:209], v[174:177], v[44:47]
	v_mfma_f32_16x16x32_bf16 v[40:43], v[214:217], v[174:177], v[40:43]
	v_mfma_f32_16x16x32_bf16 v[28:31], v[206:209], v[182:185], v[28:31]
	v_mfma_f32_16x16x32_bf16 v[24:27], v[214:217], v[182:185], v[24:27]
	v_mfma_f32_16x16x32_bf16 v[12:15], v[206:209], v[190:193], v[12:15]
	v_mfma_f32_16x16x32_bf16 v[8:11], v[214:217], v[190:193], v[8:11]
	v_mfma_f32_16x16x32_bf16 v[4:7], v[206:209], v[198:201], v[4:7]
	v_mfma_f32_16x16x32_bf16 v[0:3], v[214:217], v[198:201], v[0:3]
	s_setprio 0
	s_add_i32 s85, 0, 0x18000
	v_add_u32_e32 v166, s85, v149
	s_barrier
	ds_read_b128 v[154:157], v166
	ds_read_b128 v[158:161], v166 offset:1024
	ds_read_b128 v[162:165], v166 offset:2048
	ds_read_b128 v[166:169], v166 offset:3072
	s_add_u32 s34, s34, 0x40000
	s_addc_u32 s35, s35, 0
	s_mov_b32 m0, s60
	v_lshl_add_u64 v[202:203], s[34:35], 0, v[136:137]
	ds_read_b128 v[170:173], v152 offset:32768
	ds_read_b128 v[174:177], v152 offset:33792
	ds_read_b128 v[178:181], v152 offset:34816
	ds_read_b128 v[182:185], v152 offset:35840
	ds_read_b128 v[186:189], v152 offset:36864
	ds_read_b128 v[190:193], v152 offset:37888
	ds_read_b128 v[194:197], v152 offset:38912
	ds_read_b128 v[198:201], v152 offset:39936
	global_load_lds_dwordx4 v[202:203], off
	v_lshl_add_u64 v[202:203], s[34:35], 0, v[132:133]
	s_mov_b32 m0, s61
	s_nop 0
	global_load_lds_dwordx4 v[202:203], off
	s_waitcnt lgkmcnt(8)
	s_barrier
	s_waitcnt lgkmcnt(0)
	s_setprio 1
	s_waitcnt lgkmcnt(0)
	v_mfma_f32_16x16x32_bf16 v[124:127], v[154:157], v[170:173], v[124:127]
	v_mfma_f32_16x16x32_bf16 v[120:123], v[162:165], v[170:173], v[120:123]
	v_mfma_f32_16x16x32_bf16 v[116:119], v[154:157], v[178:181], v[116:119]
	v_mfma_f32_16x16x32_bf16 v[112:115], v[162:165], v[178:181], v[112:115]
	v_mfma_f32_16x16x32_bf16 v[100:103], v[154:157], v[186:189], v[100:103]
	v_mfma_f32_16x16x32_bf16 v[96:99], v[162:165], v[186:189], v[96:99]
	v_mfma_f32_16x16x32_bf16 v[84:87], v[154:157], v[194:197], v[84:87]
	v_mfma_f32_16x16x32_bf16 v[80:83], v[162:165], v[194:197], v[80:83]
	v_mfma_f32_16x16x32_bf16 v[124:127], v[158:161], v[174:177], v[124:127]
	v_mfma_f32_16x16x32_bf16 v[120:123], v[166:169], v[174:177], v[120:123]
	v_mfma_f32_16x16x32_bf16 v[116:119], v[158:161], v[182:185], v[116:119]
	v_mfma_f32_16x16x32_bf16 v[112:115], v[166:169], v[182:185], v[112:115]
	v_mfma_f32_16x16x32_bf16 v[100:103], v[158:161], v[190:193], v[100:103]
	v_mfma_f32_16x16x32_bf16 v[96:99], v[166:169], v[190:193], v[96:99]
	v_mfma_f32_16x16x32_bf16 v[84:87], v[158:161], v[198:201], v[84:87]
	v_mfma_f32_16x16x32_bf16 v[80:83], v[166:169], v[198:201], v[80:83]
	s_setprio 0
	s_barrier
	s_add_i32 s34, 0, 0x1c000
	s_add_i32 s35, s85, s55
	v_add_u32_e32 v214, s34, v149
	v_lshl_add_u64 v[218:219], v[218:219], 0, s[8:9]
	s_mov_b32 m0, s35
	ds_read_b128 v[202:205], v214
	ds_read_b128 v[206:209], v214 offset:1024
	ds_read_b128 v[210:213], v214 offset:2048
	ds_read_b128 v[214:217], v214 offset:3072
	global_load_lds_dwordx4 v[218:219], off
	v_lshl_add_u64 v[218:219], v[220:221], 0, s[8:9]
	s_add_i32 m0, s35, 0x2000
	s_nop 0
	global_load_lds_dwordx4 v[218:219], off
	s_barrier
	s_waitcnt lgkmcnt(0)
	s_setprio 1
	s_waitcnt lgkmcnt(0)
	v_mfma_f32_16x16x32_bf16 v[108:111], v[202:205], v[170:173], v[108:111]
	v_mfma_f32_16x16x32_bf16 v[104:107], v[210:213], v[170:173], v[104:107]
	v_mfma_f32_16x16x32_bf16 v[92:95], v[202:205], v[178:181], v[92:95]
	v_mfma_f32_16x16x32_bf16 v[88:91], v[210:213], v[178:181], v[88:91]
	v_mfma_f32_16x16x32_bf16 v[76:79], v[202:205], v[186:189], v[76:79]
	v_mfma_f32_16x16x32_bf16 v[72:75], v[210:213], v[186:189], v[72:75]
	v_mfma_f32_16x16x32_bf16 v[68:71], v[202:205], v[194:197], v[68:71]
	v_mfma_f32_16x16x32_bf16 v[64:67], v[210:213], v[194:197], v[64:67]
	v_mfma_f32_16x16x32_bf16 v[108:111], v[206:209], v[174:177], v[108:111]
	v_mfma_f32_16x16x32_bf16 v[104:107], v[214:217], v[174:177], v[104:107]
	v_mfma_f32_16x16x32_bf16 v[92:95], v[206:209], v[182:185], v[92:95]
	v_mfma_f32_16x16x32_bf16 v[88:91], v[214:217], v[182:185], v[88:91]
	v_mfma_f32_16x16x32_bf16 v[76:79], v[206:209], v[190:193], v[76:79]
	v_mfma_f32_16x16x32_bf16 v[72:75], v[214:217], v[190:193], v[72:75]
	v_mfma_f32_16x16x32_bf16 v[68:71], v[206:209], v[198:201], v[68:71]
	v_mfma_f32_16x16x32_bf16 v[64:67], v[214:217], v[198:201], v[64:67]
	s_setprio 0
	s_mov_b32 m0, s71
	v_lshl_add_u64 v[218:219], v[222:223], 0, s[8:9]
	s_barrier
	ds_read_b128 v[170:173], v152 offset:49152
	ds_read_b128 v[174:177], v152 offset:50176
	ds_read_b128 v[178:181], v152 offset:51200
	ds_read_b128 v[182:185], v152 offset:52224
	ds_read_b128 v[186:189], v152 offset:53248
	ds_read_b128 v[190:193], v152 offset:54272
	ds_read_b128 v[194:197], v152 offset:55296
	ds_read_b128 v[198:201], v152 offset:56320
	global_load_lds_dwordx4 v[218:219], off
	v_lshl_add_u64 v[218:219], v[224:225], 0, s[8:9]
	s_mov_b32 m0, s72
	s_nop 0
	global_load_lds_dwordx4 v[218:219], off
	s_barrier
	s_waitcnt lgkmcnt(0)
	s_setprio 1
	s_waitcnt lgkmcnt(0)
	v_mfma_f32_16x16x32_bf16 v[60:63], v[154:157], v[170:173], v[60:63]
	v_mfma_f32_16x16x32_bf16 v[56:59], v[162:165], v[170:173], v[56:59]
	v_mfma_f32_16x16x32_bf16 v[52:55], v[154:157], v[178:181], v[52:55]
	v_mfma_f32_16x16x32_bf16 v[48:51], v[162:165], v[178:181], v[48:51]
	v_mfma_f32_16x16x32_bf16 v[36:39], v[154:157], v[186:189], v[36:39]
	v_mfma_f32_16x16x32_bf16 v[32:35], v[162:165], v[186:189], v[32:35]
	v_mfma_f32_16x16x32_bf16 v[20:23], v[154:157], v[194:197], v[20:23]
	v_mfma_f32_16x16x32_bf16 v[16:19], v[162:165], v[194:197], v[16:19]
	v_mfma_f32_16x16x32_bf16 v[60:63], v[158:161], v[174:177], v[60:63]
	v_mfma_f32_16x16x32_bf16 v[56:59], v[166:169], v[174:177], v[56:59]
	v_mfma_f32_16x16x32_bf16 v[52:55], v[158:161], v[182:185], v[52:55]
	v_mfma_f32_16x16x32_bf16 v[48:51], v[166:169], v[182:185], v[48:51]
	v_mfma_f32_16x16x32_bf16 v[36:39], v[158:161], v[190:193], v[36:39]
	v_mfma_f32_16x16x32_bf16 v[32:35], v[166:169], v[190:193], v[32:35]
	v_mfma_f32_16x16x32_bf16 v[20:23], v[158:161], v[198:201], v[20:23]
	v_mfma_f32_16x16x32_bf16 v[16:19], v[166:169], v[198:201], v[16:19]
	s_setprio 0
	s_barrier
	s_add_u32 s30, s30, 0x40080
	s_addc_u32 s31, s31, 0
	s_add_i32 s34, s34, s55
	v_lshl_add_u64 v[154:155], s[30:31], 0, v[134:135]
	s_mov_b32 m0, s34
	s_nop 0
	global_load_lds_dwordx4 v[154:155], off
	v_lshl_add_u64 v[154:155], s[30:31], 0, v[130:131]
	s_add_i32 m0, s34, 0x2000
	s_nop 0
	global_load_lds_dwordx4 v[154:155], off
	s_waitcnt vmcnt(6)
	s_barrier
	s_setprio 1
	v_mfma_f32_16x16x32_bf16 v[44:47], v[202:205], v[170:173], v[44:47]
	v_mfma_f32_16x16x32_bf16 v[40:43], v[210:213], v[170:173], v[40:43]
	v_mfma_f32_16x16x32_bf16 v[28:31], v[202:205], v[178:181], v[28:31]
	v_mfma_f32_16x16x32_bf16 v[24:27], v[210:213], v[178:181], v[24:27]
	v_mfma_f32_16x16x32_bf16 v[12:15], v[202:205], v[186:189], v[12:15]
	v_mfma_f32_16x16x32_bf16 v[8:11], v[210:213], v[186:189], v[8:11]
	v_mfma_f32_16x16x32_bf16 v[4:7], v[202:205], v[194:197], v[4:7]
	v_mfma_f32_16x16x32_bf16 v[0:3], v[210:213], v[194:197], v[0:3]
	v_mfma_f32_16x16x32_bf16 v[44:47], v[206:209], v[174:177], v[44:47]
	v_mfma_f32_16x16x32_bf16 v[40:43], v[214:217], v[174:177], v[40:43]
	v_mfma_f32_16x16x32_bf16 v[28:31], v[206:209], v[182:185], v[28:31]
	v_mfma_f32_16x16x32_bf16 v[24:27], v[214:217], v[182:185], v[24:27]
	v_mfma_f32_16x16x32_bf16 v[12:15], v[206:209], v[190:193], v[12:15]
	v_mfma_f32_16x16x32_bf16 v[8:11], v[214:217], v[190:193], v[8:11]
	v_mfma_f32_16x16x32_bf16 v[4:7], v[206:209], v[198:201], v[4:7]
	v_mfma_f32_16x16x32_bf16 v[0:3], v[214:217], v[198:201], v[0:3]
	s_setprio 0
	s_add_i32 s84, s84, 2
	s_add_u32 s28, s28, 0x100
	s_addc_u32 s29, s29, 0
	s_add_u32 s82, s82, 0x100
	s_addc_u32 s83, s83, 0
	s_cmp_gt_u32 s84, 13
	s_barrier
	s_cbranch_scc0 .LBB0_486
	v_lshl_add_u32 v154, s14, 8, v148
	v_lshl_or_b32 v156, s79, 8, v150
	v_ashrrev_i32_e32 v155, 31, v154
	v_lshlrev_b64 v[158:159], 11, v[154:155]
	v_ashrrev_i32_e32 v157, 31, v156
	v_lshl_add_u64 v[158:159], s[46:47], 0, v[158:159]
	v_cvt_pk_bf16_f32 v124, v124, v125
	v_cvt_pk_bf16_f32 v125, v126, v127
	v_cvt_pk_bf16_f32 v126, v120, v121
	v_lshlrev_b64 v[120:121], 1, v[156:157]
	v_cvt_pk_bf16_f32 v127, v122, v123
	v_lshl_add_u64 v[122:123], v[158:159], 0, v[120:121]
	s_mov_b32 s14, 0x40000
	v_cvt_pk_bf16_f32 v108, v108, v109
	v_cvt_pk_bf16_f32 v109, v110, v111
	v_cvt_pk_bf16_f32 v110, v104, v105
	v_or_b32_e32 v104, 16, v154
	v_cvt_pk_bf16_f32 v60, v60, v61
	v_cvt_pk_bf16_f32 v61, v62, v63
	v_cvt_pk_bf16_f32 v63, v58, v59
	s_mov_b64 s[28:29], 0x40000
	v_add_co_u32_e32 v58, vcc, s14, v122
	v_ashrrev_i32_e32 v105, 31, v104
	v_cvt_pk_bf16_f32 v62, v56, v57
	v_lshl_add_u64 v[56:57], v[122:123], 0, s[28:29]
	v_addc_co_u32_e32 v59, vcc, 0, v123, vcc
	v_cvt_pk_bf16_f32 v44, v44, v45
	v_cvt_pk_bf16_f32 v45, v46, v47
	v_cvt_pk_bf16_f32 v46, v40, v41
	v_cvt_pk_bf16_f32 v47, v42, v43
	v_cvt_pk_bf16_f32 v111, v106, v107
	v_lshlrev_b64 v[104:105], 11, v[104:105]
	v_cvt_pk_bf16_f32 v92, v92, v93
	v_cvt_pk_bf16_f32 v93, v94, v95
	v_cvt_pk_bf16_f32 v94, v88, v89
	v_or_b32_e32 v88, 32, v154
	global_store_dwordx4 v[56:57], v[44:47], off offset:256 sc1
	s_mov_b64 s[28:29], 0x48000
	global_store_dwordx4 v[122:123], v[108:111], off offset:256 sc1
	v_add_co_u32_e32 v46, vcc, s76, v122
	s_nop 0
	v_lshl_add_u64 v[108:109], s[46:47], 0, v[104:105]
	v_ashrrev_i32_e32 v89, 31, v88
	v_lshl_add_u64 v[44:45], v[122:123], 0, s[28:29]
	v_addc_co_u32_e32 v47, vcc, 0, v123, vcc
	v_cvt_pk_bf16_f32 v28, v28, v29
	v_cvt_pk_bf16_f32 v29, v30, v31
	v_cvt_pk_bf16_f32 v30, v24, v25
	v_cvt_pk_bf16_f32 v31, v26, v27
	v_lshl_add_u64 v[108:109], v[108:109], 0, v[120:121]
	v_cvt_pk_bf16_f32 v95, v90, v91
	v_lshlrev_b64 v[88:89], 11, v[88:89]
	v_cvt_pk_bf16_f32 v76, v76, v77
	v_cvt_pk_bf16_f32 v77, v78, v79
	v_cvt_pk_bf16_f32 v78, v72, v73
	v_or_b32_e32 v72, 48, v154
	global_store_dwordx4 v[44:45], v[28:31], off offset:256 sc1
	global_store_dwordx4 v[108:109], v[92:95], off offset:256 sc1
	v_ashrrev_i32_e32 v73, 31, v72
	v_add_co_u32_e32 v30, vcc, s77, v122
	v_lshl_add_u64 v[92:93], s[46:47], 0, v[88:89]
	v_lshl_add_u64 v[28:29], v[122:123], 0, s[10:11]
	v_addc_co_u32_e32 v31, vcc, 0, v123, vcc
	v_cvt_pk_bf16_f32 v12, v12, v13
	v_cvt_pk_bf16_f32 v13, v14, v15
	v_cvt_pk_bf16_f32 v14, v8, v9
	v_cvt_pk_bf16_f32 v15, v10, v11
	v_lshl_add_u64 v[92:93], v[92:93], 0, v[120:121]
	v_cvt_pk_bf16_f32 v79, v74, v75
	v_lshlrev_b64 v[72:73], 11, v[72:73]
	global_store_dwordx4 v[28:29], v[12:15], off offset:256 sc1
	global_store_dwordx4 v[92:93], v[76:79], off offset:256 sc1
	v_cvt_pk_bf16_f32 v104, v116, v117
	v_add_co_u32_e32 v14, vcc, s78, v122
	v_lshl_add_u64 v[76:77], s[46:47], 0, v[72:73]
	s_nop 0
	v_addc_co_u32_e32 v15, vcc, 0, v123, vcc
	v_cvt_pk_bf16_f32 v105, v118, v119
	v_cvt_pk_bf16_f32 v106, v112, v113
	v_cvt_pk_bf16_f32 v107, v114, v115
	v_cvt_pk_bf16_f32 v88, v100, v101
	v_cvt_pk_bf16_f32 v89, v102, v103
	v_cvt_pk_bf16_f32 v90, v96, v97
	v_cvt_pk_bf16_f32 v91, v98, v99
	v_cvt_pk_bf16_f32 v72, v84, v85
	v_cvt_pk_bf16_f32 v73, v86, v87
	v_cvt_pk_bf16_f32 v74, v80, v81
	v_cvt_pk_bf16_f32 v75, v82, v83
	v_lshl_add_u64 v[76:77], v[76:77], 0, v[120:121]
	v_cvt_pk_bf16_f32 v68, v68, v69
	v_cvt_pk_bf16_f32 v69, v70, v71
	v_cvt_pk_bf16_f32 v70, v64, v65
	v_cvt_pk_bf16_f32 v71, v66, v67
	v_cvt_pk_bf16_f32 v40, v52, v53
	v_cvt_pk_bf16_f32 v41, v54, v55
	v_cvt_pk_bf16_f32 v42, v48, v49
	v_cvt_pk_bf16_f32 v43, v50, v51
	v_cvt_pk_bf16_f32 v24, v36, v37
	v_cvt_pk_bf16_f32 v25, v38, v39
	v_cvt_pk_bf16_f32 v26, v32, v33
	v_cvt_pk_bf16_f32 v27, v34, v35
	v_cvt_pk_bf16_f32 v8, v20, v21
	v_cvt_pk_bf16_f32 v9, v22, v23
	v_cvt_pk_bf16_f32 v10, v16, v17
	v_cvt_pk_bf16_f32 v11, v18, v19
	v_lshl_add_u64 v[12:13], v[122:123], 0, s[12:13]
	v_cvt_pk_bf16_f32 v4, v4, v5
	v_cvt_pk_bf16_f32 v5, v6, v7
	v_cvt_pk_bf16_f32 v6, v0, v1
	v_cvt_pk_bf16_f32 v7, v2, v3
	s_and_b64 vcc, exec, s[4:5]
	s_mov_b32 s79, s16
	s_mov_b32 s14, s18
	s_mov_b64 s[30:31], s[26:27]
	s_mov_b64 s[28:29], s[20:21]
	global_store_dwordx4 v[122:123], v[124:127], off sc1
	global_store_dwordx4 v[108:109], v[104:107], off sc1
	global_store_dwordx4 v[92:93], v[88:91], off sc1
	global_store_dwordx4 v[76:77], v[72:75], off sc1
	global_store_dwordx4 v[76:77], v[68:71], off offset:256 sc1
	global_store_dwordx4 v[58:59], v[60:63], off sc1
	global_store_dwordx4 v[46:47], v[40:43], off sc1
	global_store_dwordx4 v[30:31], v[24:27], off sc1
	global_store_dwordx4 v[14:15], v[8:11], off sc1
	global_store_dwordx4 v[12:13], v[4:7], off offset:256 sc1
	s_cbranch_vccz .LBB0_483
	s_waitcnt vmcnt(0)
	s_cmpk_gt_u32 s54, 0xff
	s_cbranch_scc1 .LBB0_490
	s_barrier

.LBB0_566:
	global_store_dwordx4 v[98:99], v[32:35], off sc1

.LBB0_569:
	global_store_dwordx4 v[98:99], v[36:39], off offset:1024 sc1

.LBB0_572:
	global_store_dwordx4 v[98:99], v[40:43], off offset:2048 sc1

.LBB0_575:
	global_store_dwordx4 v[98:99], v[44:47], off offset:3072 sc1

.LBB0_581:
	global_store_dwordx4 v[88:89], v[32:35], off sc1

.LBB0_584:
	global_store_dwordx4 v[88:89], v[36:39], off offset:1024 sc1

.LBB0_587:
	global_store_dwordx4 v[88:89], v[40:43], off offset:2048 sc1

.LBB0_590:
	global_store_dwordx4 v[88:89], v[44:47], off offset:3072 sc1

.LBB0_683:
	ds_read_b128 v[154:157], v151
	ds_read_b128 v[158:161], v151 offset:1024
	ds_read_b128 v[162:165], v151 offset:2048
	ds_read_b128 v[166:169], v151 offset:3072
	s_add_u32 s34, s30, 0xfffc0080
	s_addc_u32 s35, s31, -1
	s_cmp_eq_u32 s85, 12
	s_cselect_b32 s55, s19, s35
	s_cselect_b32 s54, s81, s34
	s_cselect_b32 s35, s17, s84
	s_cselect_b32 s34, s82, s83
	v_lshl_add_u64 v[202:203], s[30:31], 0, v[138:139]
	s_add_i32 m0, s29, 0xc000
	ds_read_b128 v[170:173], v152
	ds_read_b128 v[174:177], v152 offset:1024
	ds_read_b128 v[178:181], v152 offset:2048
	ds_read_b128 v[182:185], v152 offset:3072
	ds_read_b128 v[186:189], v152 offset:4096
	ds_read_b128 v[190:193], v152 offset:5120
	ds_read_b128 v[194:197], v152 offset:6144
	ds_read_b128 v[198:201], v152 offset:7168
	global_load_lds_dwordx4 v[202:203], off
	v_lshl_add_u64 v[202:203], s[30:31], 0, v[140:141]
	s_add_i32 m0, s29, 0xe000
	s_nop 0
	global_load_lds_dwordx4 v[202:203], off
	s_waitcnt lgkmcnt(8)
	s_barrier
	s_waitcnt lgkmcnt(0)
	s_setprio 1
	s_waitcnt lgkmcnt(0)
	v_mfma_f32_16x16x32_bf16 v[124:127], v[154:157], v[170:173], v[124:127]
	v_mfma_f32_16x16x32_bf16 v[120:123], v[162:165], v[170:173], v[120:123]
	v_mfma_f32_16x16x32_bf16 v[108:111], v[154:157], v[178:181], v[108:111]
	v_mfma_f32_16x16x32_bf16 v[104:107], v[162:165], v[178:181], v[104:107]
	v_mfma_f32_16x16x32_bf16 v[92:95], v[154:157], v[186:189], v[92:95]
	v_mfma_f32_16x16x32_bf16 v[88:91], v[162:165], v[186:189], v[88:91]
	v_mfma_f32_16x16x32_bf16 v[76:79], v[154:157], v[194:197], v[76:79]
	v_mfma_f32_16x16x32_bf16 v[72:75], v[162:165], v[194:197], v[72:75]
	v_mfma_f32_16x16x32_bf16 v[124:127], v[158:161], v[174:177], v[124:127]
	v_mfma_f32_16x16x32_bf16 v[120:123], v[166:169], v[174:177], v[120:123]
	v_mfma_f32_16x16x32_bf16 v[108:111], v[158:161], v[182:185], v[108:111]
	v_mfma_f32_16x16x32_bf16 v[104:107], v[166:169], v[182:185], v[104:107]
	v_mfma_f32_16x16x32_bf16 v[92:95], v[158:161], v[190:193], v[92:95]
	v_mfma_f32_16x16x32_bf16 v[88:91], v[166:169], v[190:193], v[88:91]
	v_mfma_f32_16x16x32_bf16 v[76:79], v[158:161], v[198:201], v[76:79]
	v_mfma_f32_16x16x32_bf16 v[72:75], v[166:169], v[198:201], v[72:75]
	s_setprio 0
	s_barrier
	s_add_i32 s86, s74, s60
	v_lshl_add_u64 v[218:219], s[34:35], 0, v[132:133]
	s_mov_b32 m0, s86
	ds_read_b128 v[202:205], v153
	ds_read_b128 v[206:209], v153 offset:1024
	ds_read_b128 v[210:213], v153 offset:2048
	ds_read_b128 v[214:217], v153 offset:3072
	global_load_lds_dwordx4 v[218:219], off
	v_lshl_add_u64 v[220:221], s[34:35], 0, v[136:137]
	s_add_i32 m0, s86, 0x2000
	s_nop 0
	global_load_lds_dwordx4 v[220:221], off
	s_barrier
	s_waitcnt lgkmcnt(0)
	s_setprio 1
	s_waitcnt lgkmcnt(0)
	v_mfma_f32_16x16x32_bf16 v[116:119], v[202:205], v[170:173], v[116:119]
	v_mfma_f32_16x16x32_bf16 v[112:115], v[210:213], v[170:173], v[112:115]
	v_mfma_f32_16x16x32_bf16 v[100:103], v[202:205], v[178:181], v[100:103]
	v_mfma_f32_16x16x32_bf16 v[96:99], v[210:213], v[178:181], v[96:99]
	v_mfma_f32_16x16x32_bf16 v[84:87], v[202:205], v[186:189], v[84:87]
	v_mfma_f32_16x16x32_bf16 v[80:83], v[210:213], v[186:189], v[80:83]
	v_mfma_f32_16x16x32_bf16 v[68:71], v[202:205], v[194:197], v[68:71]
	v_mfma_f32_16x16x32_bf16 v[64:67], v[210:213], v[194:197], v[64:67]
	v_mfma_f32_16x16x32_bf16 v[116:119], v[206:209], v[174:177], v[116:119]
	v_mfma_f32_16x16x32_bf16 v[112:115], v[214:217], v[174:177], v[112:115]
	v_mfma_f32_16x16x32_bf16 v[100:103], v[206:209], v[182:185], v[100:103]
	v_mfma_f32_16x16x32_bf16 v[96:99], v[214:217], v[182:185], v[96:99]
	v_mfma_f32_16x16x32_bf16 v[84:87], v[206:209], v[190:193], v[84:87]
	v_mfma_f32_16x16x32_bf16 v[80:83], v[214:217], v[190:193], v[80:83]
	v_mfma_f32_16x16x32_bf16 v[68:71], v[206:209], v[198:201], v[68:71]
	v_mfma_f32_16x16x32_bf16 v[64:67], v[214:217], v[198:201], v[64:67]
	s_setprio 0
	s_mov_b32 m0, s29
	v_lshl_add_u64 v[222:223], s[54:55], 0, v[130:131]
	s_barrier
	ds_read_b128 v[170:173], v152 offset:16384
	ds_read_b128 v[174:177], v152 offset:17408
	ds_read_b128 v[178:181], v152 offset:18432
	ds_read_b128 v[182:185], v152 offset:19456
	ds_read_b128 v[186:189], v152 offset:20480
	ds_read_b128 v[190:193], v152 offset:21504
	ds_read_b128 v[194:197], v152 offset:22528
	ds_read_b128 v[198:201], v152 offset:23552
	global_load_lds_dwordx4 v[222:223], off
	v_lshl_add_u64 v[224:225], s[54:55], 0, v[134:135]
	s_mov_b32 m0, s61
	s_nop 0
	global_load_lds_dwordx4 v[224:225], off
	s_barrier
	s_waitcnt lgkmcnt(0)
	s_setprio 1
	s_waitcnt lgkmcnt(0)
	v_mfma_f32_16x16x32_bf16 v[60:63], v[154:157], v[170:173], v[60:63]
	v_mfma_f32_16x16x32_bf16 v[56:59], v[162:165], v[170:173], v[56:59]
	v_mfma_f32_16x16x32_bf16 v[44:47], v[154:157], v[178:181], v[44:47]
	v_mfma_f32_16x16x32_bf16 v[40:43], v[162:165], v[178:181], v[40:43]
	v_mfma_f32_16x16x32_bf16 v[28:31], v[154:157], v[186:189], v[28:31]
	v_mfma_f32_16x16x32_bf16 v[24:27], v[162:165], v[186:189], v[24:27]
	v_mfma_f32_16x16x32_bf16 v[12:15], v[154:157], v[194:197], v[12:15]
	v_mfma_f32_16x16x32_bf16 v[8:11], v[162:165], v[194:197], v[8:11]
	v_mfma_f32_16x16x32_bf16 v[60:63], v[158:161], v[174:177], v[60:63]
	v_mfma_f32_16x16x32_bf16 v[56:59], v[166:169], v[174:177], v[56:59]
	v_mfma_f32_16x16x32_bf16 v[44:47], v[158:161], v[182:185], v[44:47]
	v_mfma_f32_16x16x32_bf16 v[40:43], v[166:169], v[182:185], v[40:43]
	v_mfma_f32_16x16x32_bf16 v[28:31], v[158:161], v[190:193], v[28:31]
	v_mfma_f32_16x16x32_bf16 v[24:27], v[166:169], v[190:193], v[24:27]
	v_mfma_f32_16x16x32_bf16 v[12:15], v[158:161], v[198:201], v[12:15]
	v_mfma_f32_16x16x32_bf16 v[8:11], v[166:169], v[198:201], v[8:11]
	s_setprio 0
	s_barrier
	s_add_u32 s86, s34, 0x40000
	s_addc_u32 s87, s35, 0
	s_add_i32 s88, s75, s60
	v_lshl_add_u64 v[154:155], s[86:87], 0, v[132:133]
	s_mov_b32 m0, s88
	s_nop 0
	global_load_lds_dwordx4 v[154:155], off
	v_lshl_add_u64 v[154:155], s[86:87], 0, v[136:137]
	s_add_i32 m0, s88, 0x2000
	s_nop 0
	global_load_lds_dwordx4 v[154:155], off
	s_waitcnt vmcnt(6)
	s_barrier
	s_setprio 1
	v_mfma_f32_16x16x32_bf16 v[52:55], v[202:205], v[170:173], v[52:55]
	v_mfma_f32_16x16x32_bf16 v[48:51], v[210:213], v[170:173], v[48:51]
	v_mfma_f32_16x16x32_bf16 v[36:39], v[202:205], v[178:181], v[36:39]
	v_mfma_f32_16x16x32_bf16 v[32:35], v[210:213], v[178:181], v[32:35]
	v_mfma_f32_16x16x32_bf16 v[20:23], v[202:205], v[186:189], v[20:23]
	v_mfma_f32_16x16x32_bf16 v[16:19], v[210:213], v[186:189], v[16:19]
	v_mfma_f32_16x16x32_bf16 v[4:7], v[202:205], v[194:197], v[4:7]
	v_mfma_f32_16x16x32_bf16 v[0:3], v[210:213], v[194:197], v[0:3]
	v_mfma_f32_16x16x32_bf16 v[52:55], v[206:209], v[174:177], v[52:55]
	v_mfma_f32_16x16x32_bf16 v[48:51], v[214:217], v[174:177], v[48:51]
	v_mfma_f32_16x16x32_bf16 v[36:39], v[206:209], v[182:185], v[36:39]
	v_mfma_f32_16x16x32_bf16 v[32:35], v[214:217], v[182:185], v[32:35]
	v_mfma_f32_16x16x32_bf16 v[20:23], v[206:209], v[190:193], v[20:23]
	v_mfma_f32_16x16x32_bf16 v[16:19], v[214:217], v[190:193], v[16:19]
	v_mfma_f32_16x16x32_bf16 v[4:7], v[206:209], v[198:201], v[4:7]
	v_mfma_f32_16x16x32_bf16 v[0:3], v[214:217], v[198:201], v[0:3]
	s_setprio 0
	s_add_i32 s86, 0, 0x18000
	v_add_u32_e32 v166, s86, v149
	s_barrier
	ds_read_b128 v[154:157], v166
	ds_read_b128 v[158:161], v166 offset:1024
	ds_read_b128 v[162:165], v166 offset:2048
	ds_read_b128 v[166:169], v166 offset:3072
	s_add_u32 s54, s54, 0x40000
	s_addc_u32 s55, s55, 0
	s_mov_b32 m0, s62
	v_lshl_add_u64 v[202:203], s[54:55], 0, v[130:131]
	ds_read_b128 v[170:173], v152 offset:32768
	ds_read_b128 v[174:177], v152 offset:33792
	ds_read_b128 v[178:181], v152 offset:34816
	ds_read_b128 v[182:185], v152 offset:35840
	ds_read_b128 v[186:189], v152 offset:36864
	ds_read_b128 v[190:193], v152 offset:37888
	ds_read_b128 v[194:197], v152 offset:38912
	ds_read_b128 v[198:201], v152 offset:39936
	global_load_lds_dwordx4 v[202:203], off
	v_lshl_add_u64 v[202:203], s[54:55], 0, v[134:135]
	s_mov_b32 m0, s63
	s_nop 0
	global_load_lds_dwordx4 v[202:203], off
	s_waitcnt lgkmcnt(8)
	s_barrier
	s_waitcnt lgkmcnt(0)
	s_setprio 1
	s_waitcnt lgkmcnt(0)
	v_mfma_f32_16x16x32_bf16 v[124:127], v[154:157], v[170:173], v[124:127]
	v_mfma_f32_16x16x32_bf16 v[120:123], v[162:165], v[170:173], v[120:123]
	v_mfma_f32_16x16x32_bf16 v[108:111], v[154:157], v[178:181], v[108:111]
	v_mfma_f32_16x16x32_bf16 v[104:107], v[162:165], v[178:181], v[104:107]
	v_mfma_f32_16x16x32_bf16 v[92:95], v[154:157], v[186:189], v[92:95]
	v_mfma_f32_16x16x32_bf16 v[88:91], v[162:165], v[186:189], v[88:91]
	v_mfma_f32_16x16x32_bf16 v[76:79], v[154:157], v[194:197], v[76:79]
	v_mfma_f32_16x16x32_bf16 v[72:75], v[162:165], v[194:197], v[72:75]
	v_mfma_f32_16x16x32_bf16 v[124:127], v[158:161], v[174:177], v[124:127]
	v_mfma_f32_16x16x32_bf16 v[120:123], v[166:169], v[174:177], v[120:123]
	v_mfma_f32_16x16x32_bf16 v[108:111], v[158:161], v[182:185], v[108:111]
	v_mfma_f32_16x16x32_bf16 v[104:107], v[166:169], v[182:185], v[104:107]
	v_mfma_f32_16x16x32_bf16 v[92:95], v[158:161], v[190:193], v[92:95]
	v_mfma_f32_16x16x32_bf16 v[88:91], v[166:169], v[190:193], v[88:91]
	v_mfma_f32_16x16x32_bf16 v[76:79], v[158:161], v[198:201], v[76:79]
	v_mfma_f32_16x16x32_bf16 v[72:75], v[166:169], v[198:201], v[72:75]
	s_setprio 0
	s_barrier
	s_add_i32 s54, 0, 0x1c000
	s_add_i32 s55, s86, s60
	v_add_u32_e32 v214, s54, v149
	v_lshl_add_u64 v[218:219], v[218:219], 0, s[8:9]
	s_mov_b32 m0, s55
	ds_read_b128 v[202:205], v214
	ds_read_b128 v[206:209], v214 offset:1024
	ds_read_b128 v[210:213], v214 offset:2048
	ds_read_b128 v[214:217], v214 offset:3072
	global_load_lds_dwordx4 v[218:219], off
	v_lshl_add_u64 v[218:219], v[220:221], 0, s[8:9]
	s_add_i32 m0, s55, 0x2000
	s_nop 0
	global_load_lds_dwordx4 v[218:219], off
	s_barrier
	s_waitcnt lgkmcnt(0)
	s_setprio 1
	s_waitcnt lgkmcnt(0)
	v_mfma_f32_16x16x32_bf16 v[116:119], v[202:205], v[170:173], v[116:119]
	v_mfma_f32_16x16x32_bf16 v[112:115], v[210:213], v[170:173], v[112:115]
	v_mfma_f32_16x16x32_bf16 v[100:103], v[202:205], v[178:181], v[100:103]
	v_mfma_f32_16x16x32_bf16 v[96:99], v[210:213], v[178:181], v[96:99]
	v_mfma_f32_16x16x32_bf16 v[84:87], v[202:205], v[186:189], v[84:87]
	v_mfma_f32_16x16x32_bf16 v[80:83], v[210:213], v[186:189], v[80:83]
	v_mfma_f32_16x16x32_bf16 v[68:71], v[202:205], v[194:197], v[68:71]
	v_mfma_f32_16x16x32_bf16 v[64:67], v[210:213], v[194:197], v[64:67]
	v_mfma_f32_16x16x32_bf16 v[116:119], v[206:209], v[174:177], v[116:119]
	v_mfma_f32_16x16x32_bf16 v[112:115], v[214:217], v[174:177], v[112:115]
	v_mfma_f32_16x16x32_bf16 v[100:103], v[206:209], v[182:185], v[100:103]
	v_mfma_f32_16x16x32_bf16 v[96:99], v[214:217], v[182:185], v[96:99]
	v_mfma_f32_16x16x32_bf16 v[84:87], v[206:209], v[190:193], v[84:87]
	v_mfma_f32_16x16x32_bf16 v[80:83], v[214:217], v[190:193], v[80:83]
	v_mfma_f32_16x16x32_bf16 v[68:71], v[206:209], v[198:201], v[68:71]
	v_mfma_f32_16x16x32_bf16 v[64:67], v[214:217], v[198:201], v[64:67]
	s_setprio 0
	s_mov_b32 m0, s71
	v_lshl_add_u64 v[218:219], v[222:223], 0, s[8:9]
	s_barrier
	ds_read_b128 v[170:173], v152 offset:49152
	ds_read_b128 v[174:177], v152 offset:50176
	ds_read_b128 v[178:181], v152 offset:51200
	ds_read_b128 v[182:185], v152 offset:52224
	ds_read_b128 v[186:189], v152 offset:53248
	ds_read_b128 v[190:193], v152 offset:54272
	ds_read_b128 v[194:197], v152 offset:55296
	ds_read_b128 v[198:201], v152 offset:56320
	global_load_lds_dwordx4 v[218:219], off
	v_lshl_add_u64 v[218:219], v[224:225], 0, s[8:9]
	s_mov_b32 m0, s72
	s_nop 0
	global_load_lds_dwordx4 v[218:219], off
	s_barrier
	s_waitcnt lgkmcnt(0)
	s_setprio 1
	s_waitcnt lgkmcnt(0)
	v_mfma_f32_16x16x32_bf16 v[60:63], v[154:157], v[170:173], v[60:63]
	v_mfma_f32_16x16x32_bf16 v[56:59], v[162:165], v[170:173], v[56:59]
	v_mfma_f32_16x16x32_bf16 v[44:47], v[154:157], v[178:181], v[44:47]
	v_mfma_f32_16x16x32_bf16 v[40:43], v[162:165], v[178:181], v[40:43]
	v_mfma_f32_16x16x32_bf16 v[28:31], v[154:157], v[186:189], v[28:31]
	v_mfma_f32_16x16x32_bf16 v[24:27], v[162:165], v[186:189], v[24:27]
	v_mfma_f32_16x16x32_bf16 v[12:15], v[154:157], v[194:197], v[12:15]
	v_mfma_f32_16x16x32_bf16 v[8:11], v[162:165], v[194:197], v[8:11]
	v_mfma_f32_16x16x32_bf16 v[60:63], v[158:161], v[174:177], v[60:63]
	v_mfma_f32_16x16x32_bf16 v[56:59], v[166:169], v[174:177], v[56:59]
	v_mfma_f32_16x16x32_bf16 v[44:47], v[158:161], v[182:185], v[44:47]
	v_mfma_f32_16x16x32_bf16 v[40:43], v[166:169], v[182:185], v[40:43]
	v_mfma_f32_16x16x32_bf16 v[28:31], v[158:161], v[190:193], v[28:31]
	v_mfma_f32_16x16x32_bf16 v[24:27], v[166:169], v[190:193], v[24:27]
	v_mfma_f32_16x16x32_bf16 v[12:15], v[158:161], v[198:201], v[12:15]
	v_mfma_f32_16x16x32_bf16 v[8:11], v[166:169], v[198:201], v[8:11]
	s_setprio 0
	s_barrier
	s_add_u32 s34, s34, 0x40080
	s_addc_u32 s35, s35, 0
	s_add_i32 s54, s54, s60
	v_lshl_add_u64 v[154:155], s[34:35], 0, v[132:133]
	s_mov_b32 m0, s54
	s_nop 0
	global_load_lds_dwordx4 v[154:155], off
	v_lshl_add_u64 v[154:155], s[34:35], 0, v[136:137]
	s_add_i32 m0, s54, 0x2000
	s_nop 0
	global_load_lds_dwordx4 v[154:155], off
	s_waitcnt vmcnt(6)
	s_barrier
	s_setprio 1
	v_mfma_f32_16x16x32_bf16 v[52:55], v[202:205], v[170:173], v[52:55]
	v_mfma_f32_16x16x32_bf16 v[48:51], v[210:213], v[170:173], v[48:51]
	v_mfma_f32_16x16x32_bf16 v[36:39], v[202:205], v[178:181], v[36:39]
	v_mfma_f32_16x16x32_bf16 v[32:35], v[210:213], v[178:181], v[32:35]
	v_mfma_f32_16x16x32_bf16 v[20:23], v[202:205], v[186:189], v[20:23]
	v_mfma_f32_16x16x32_bf16 v[16:19], v[210:213], v[186:189], v[16:19]
	v_mfma_f32_16x16x32_bf16 v[4:7], v[202:205], v[194:197], v[4:7]
	v_mfma_f32_16x16x32_bf16 v[0:3], v[210:213], v[194:197], v[0:3]
	v_mfma_f32_16x16x32_bf16 v[52:55], v[206:209], v[174:177], v[52:55]
	v_mfma_f32_16x16x32_bf16 v[48:51], v[214:217], v[174:177], v[48:51]
	v_mfma_f32_16x16x32_bf16 v[36:39], v[206:209], v[182:185], v[36:39]
	v_mfma_f32_16x16x32_bf16 v[32:35], v[214:217], v[182:185], v[32:35]
	v_mfma_f32_16x16x32_bf16 v[20:23], v[206:209], v[190:193], v[20:23]
	v_mfma_f32_16x16x32_bf16 v[16:19], v[214:217], v[190:193], v[16:19]
	v_mfma_f32_16x16x32_bf16 v[4:7], v[206:209], v[198:201], v[4:7]
	v_mfma_f32_16x16x32_bf16 v[0:3], v[214:217], v[198:201], v[0:3]
	s_setprio 0
	s_add_i32 s85, s85, 2
	s_add_u32 s30, s30, 0x100
	s_addc_u32 s31, s31, 0
	s_add_u32 s83, s83, 0x100
	s_addc_u32 s84, s84, 0
	s_cmp_gt_u32 s85, 13
	s_barrier
	s_cbranch_scc0 .LBB0_683
	v_lshl_add_u32 v154, s28, 8, v148
	v_max_f32_e32 v126, v126, v126
	v_max_f32_e32 v127, v127, v127
	v_lshl_or_b32 v156, s80, 8, v150
	v_ashrrev_i32_e32 v155, 31, v154
	v_max_f32_e32 v124, v124, v124
	v_max_f32_e32 v120, v120, v120
	v_max_f32_e32 v125, v125, v125
	v_max_f32_e32 v121, v121, v121
	v_max_f32_e32 v126, 0, v126
	v_max_f32_e32 v122, v122, v122
	v_max_f32_e32 v127, 0, v127
	v_max_f32_e32 v123, v123, v123
	v_lshlrev_b64 v[158:159], 13, v[154:155]
	v_max_f32_e32 v124, 0, v124
	v_max_f32_e32 v120, 0, v120
	v_max_f32_e32 v125, 0, v125
	v_max_f32_e32 v121, 0, v121
	v_max_f32_e32 v122, 0, v122
	v_max_f32_e32 v123, 0, v123
	v_pk_mul_f32 v[126:127], v[126:127], v[126:127]
	v_ashrrev_i32_e32 v157, 31, v156
	v_lshl_add_u64 v[158:159], s[46:47], 0, v[158:159]
	v_pk_mul_f32 v[124:125], v[124:125], v[124:125]
	v_pk_mul_f32 v[120:121], v[120:121], v[120:121]
	v_pk_mul_f32 v[160:161], v[122:123], v[122:123]
	v_cvt_pk_bf16_f32 v123, v126, v127
	v_lshlrev_b64 v[126:127], 1, v[156:157]
	v_max_f32_e32 v112, v112, v112
	v_max_f32_e32 v113, v113, v113
	v_cvt_pk_bf16_f32 v122, v124, v125
	v_cvt_pk_bf16_f32 v124, v120, v121
	v_cvt_pk_bf16_f32 v125, v160, v161
	v_lshl_add_u64 v[120:121], v[158:159], 0, v[126:127]
	v_max_f32_e32 v112, 0, v112
	v_max_f32_e32 v113, 0, v113
	global_store_dwordx4 v[120:121], v[122:125], off sc1
	v_max_f32_e32 v116, v116, v116
	v_max_f32_e32 v117, v117, v117
	v_pk_mul_f32 v[122:123], v[112:113], v[112:113]
	v_max_f32_e32 v113, v114, v114
	v_max_f32_e32 v112, v118, v118
	v_max_f32_e32 v114, 0, v113
	v_max_f32_e32 v113, v119, v119
	v_max_f32_e32 v115, v115, v115
	v_max_f32_e32 v116, 0, v116
	v_max_f32_e32 v117, 0, v117
	v_max_f32_e32 v112, 0, v112
	v_max_f32_e32 v113, 0, v113
	v_max_f32_e32 v115, 0, v115
	v_pk_mul_f32 v[116:117], v[116:117], v[116:117]
	v_pk_mul_f32 v[118:119], v[112:113], v[112:113]
	v_pk_mul_f32 v[124:125], v[114:115], v[114:115]
	v_max_f32_e32 v104, v104, v104
	v_max_f32_e32 v105, v105, v105
	v_cvt_pk_bf16_f32 v112, v116, v117
	v_cvt_pk_bf16_f32 v113, v118, v119
	v_cvt_pk_bf16_f32 v114, v122, v123
	v_cvt_pk_bf16_f32 v115, v124, v125
	v_max_f32_e32 v104, 0, v104
	v_max_f32_e32 v105, 0, v105
	global_store_dwordx4 v[120:121], v[112:115], off offset:256 sc1
	v_max_f32_e32 v108, v108, v108
	v_max_f32_e32 v109, v109, v109
	v_or_b32_e32 v112, 16, v154
	v_pk_mul_f32 v[114:115], v[104:105], v[104:105]
	v_max_f32_e32 v105, v106, v106
	v_ashrrev_i32_e32 v113, 31, v112
	v_max_f32_e32 v104, v110, v110
	v_max_f32_e32 v106, 0, v105
	v_max_f32_e32 v105, v111, v111
	v_max_f32_e32 v107, v107, v107
	v_lshlrev_b64 v[112:113], 13, v[112:113]
	v_max_f32_e32 v108, 0, v108
	v_max_f32_e32 v109, 0, v109
	v_max_f32_e32 v104, 0, v104
	v_max_f32_e32 v105, 0, v105
	v_max_f32_e32 v107, 0, v107
	v_lshl_add_u64 v[112:113], s[46:47], 0, v[112:113]
	v_pk_mul_f32 v[108:109], v[108:109], v[108:109]
	v_pk_mul_f32 v[110:111], v[104:105], v[104:105]
	v_pk_mul_f32 v[116:117], v[106:107], v[106:107]
	v_max_f32_e32 v96, v96, v96
	v_max_f32_e32 v97, v97, v97
	v_cvt_pk_bf16_f32 v104, v108, v109
	v_cvt_pk_bf16_f32 v105, v110, v111
	v_cvt_pk_bf16_f32 v106, v114, v115
	v_cvt_pk_bf16_f32 v107, v116, v117
	v_lshl_add_u64 v[108:109], v[112:113], 0, v[126:127]
	v_max_f32_e32 v96, 0, v96
	v_max_f32_e32 v97, 0, v97
	global_store_dwordx4 v[108:109], v[104:107], off sc1
	v_max_f32_e32 v100, v100, v100
	v_max_f32_e32 v101, v101, v101
	v_pk_mul_f32 v[104:105], v[96:97], v[96:97]
	v_max_f32_e32 v97, v98, v98
	v_max_f32_e32 v96, v102, v102
	v_max_f32_e32 v98, 0, v97
	v_max_f32_e32 v97, v103, v103
	v_max_f32_e32 v99, v99, v99
	v_max_f32_e32 v100, 0, v100
	v_max_f32_e32 v101, 0, v101
	v_max_f32_e32 v96, 0, v96
	v_max_f32_e32 v97, 0, v97
	v_max_f32_e32 v99, 0, v99
	v_pk_mul_f32 v[100:101], v[100:101], v[100:101]
	v_pk_mul_f32 v[102:103], v[96:97], v[96:97]
	v_pk_mul_f32 v[106:107], v[98:99], v[98:99]
	v_max_f32_e32 v88, v88, v88
	v_max_f32_e32 v89, v89, v89
	v_cvt_pk_bf16_f32 v96, v100, v101
	v_cvt_pk_bf16_f32 v97, v102, v103
	v_cvt_pk_bf16_f32 v98, v104, v105
	v_cvt_pk_bf16_f32 v99, v106, v107
	v_max_f32_e32 v88, 0, v88
	v_max_f32_e32 v89, 0, v89
	global_store_dwordx4 v[108:109], v[96:99], off offset:256 sc1
	v_max_f32_e32 v92, v92, v92
	v_max_f32_e32 v93, v93, v93
	v_or_b32_e32 v96, 32, v154
	v_pk_mul_f32 v[98:99], v[88:89], v[88:89]
	v_max_f32_e32 v89, v90, v90
	v_ashrrev_i32_e32 v97, 31, v96
	v_max_f32_e32 v88, v94, v94
	v_max_f32_e32 v90, 0, v89
	v_max_f32_e32 v89, v95, v95
	v_max_f32_e32 v91, v91, v91
	v_lshlrev_b64 v[96:97], 13, v[96:97]
	v_max_f32_e32 v92, 0, v92
	v_max_f32_e32 v93, 0, v93
	v_max_f32_e32 v88, 0, v88
	v_max_f32_e32 v89, 0, v89
	v_max_f32_e32 v91, 0, v91
	v_lshl_add_u64 v[96:97], s[46:47], 0, v[96:97]
	v_pk_mul_f32 v[92:93], v[92:93], v[92:93]
	v_pk_mul_f32 v[94:95], v[88:89], v[88:89]
	v_pk_mul_f32 v[100:101], v[90:91], v[90:91]
	v_max_f32_e32 v80, v80, v80
	v_max_f32_e32 v81, v81, v81
	v_cvt_pk_bf16_f32 v88, v92, v93
	v_cvt_pk_bf16_f32 v89, v94, v95
	v_cvt_pk_bf16_f32 v90, v98, v99
	v_cvt_pk_bf16_f32 v91, v100, v101
	v_lshl_add_u64 v[92:93], v[96:97], 0, v[126:127]
	v_max_f32_e32 v80, 0, v80
	v_max_f32_e32 v81, 0, v81
	global_store_dwordx4 v[92:93], v[88:91], off sc1
	v_max_f32_e32 v84, v84, v84
	v_max_f32_e32 v85, v85, v85
	v_pk_mul_f32 v[88:89], v[80:81], v[80:81]
	v_max_f32_e32 v81, v82, v82
	v_max_f32_e32 v80, v86, v86
	v_max_f32_e32 v82, 0, v81
	v_max_f32_e32 v81, v87, v87
	v_max_f32_e32 v83, v83, v83
	v_max_f32_e32 v84, 0, v84
	v_max_f32_e32 v85, 0, v85
	v_max_f32_e32 v80, 0, v80
	v_max_f32_e32 v81, 0, v81
	v_max_f32_e32 v83, 0, v83
	v_pk_mul_f32 v[84:85], v[84:85], v[84:85]
	v_pk_mul_f32 v[86:87], v[80:81], v[80:81]
	v_pk_mul_f32 v[90:91], v[82:83], v[82:83]
	v_max_f32_e32 v72, v72, v72
	v_max_f32_e32 v73, v73, v73
	v_cvt_pk_bf16_f32 v80, v84, v85
	v_cvt_pk_bf16_f32 v81, v86, v87
	v_cvt_pk_bf16_f32 v82, v88, v89
	v_cvt_pk_bf16_f32 v83, v90, v91
	v_max_f32_e32 v72, 0, v72
	v_max_f32_e32 v73, 0, v73
	global_store_dwordx4 v[92:93], v[80:83], off offset:256 sc1
	v_max_f32_e32 v76, v76, v76
	v_max_f32_e32 v77, v77, v77
	v_or_b32_e32 v80, 48, v154
	v_pk_mul_f32 v[82:83], v[72:73], v[72:73]
	v_max_f32_e32 v73, v74, v74
	v_ashrrev_i32_e32 v81, 31, v80
	v_max_f32_e32 v72, v78, v78
	v_max_f32_e32 v74, 0, v73
	v_max_f32_e32 v73, v79, v79
	v_max_f32_e32 v75, v75, v75
	v_lshlrev_b64 v[80:81], 13, v[80:81]
	v_max_f32_e32 v76, 0, v76
	v_max_f32_e32 v77, 0, v77
	v_max_f32_e32 v72, 0, v72
	v_max_f32_e32 v73, 0, v73
	v_max_f32_e32 v75, 0, v75
	v_lshl_add_u64 v[80:81], s[46:47], 0, v[80:81]
	v_pk_mul_f32 v[76:77], v[76:77], v[76:77]
	v_pk_mul_f32 v[78:79], v[72:73], v[72:73]
	v_pk_mul_f32 v[84:85], v[74:75], v[74:75]
	v_max_f32_e32 v64, v64, v64
	v_max_f32_e32 v65, v65, v65
	v_cvt_pk_bf16_f32 v72, v76, v77
	v_cvt_pk_bf16_f32 v73, v78, v79
	v_cvt_pk_bf16_f32 v74, v82, v83
	v_cvt_pk_bf16_f32 v75, v84, v85
	v_lshl_add_u64 v[76:77], v[80:81], 0, v[126:127]
	v_max_f32_e32 v64, 0, v64
	v_max_f32_e32 v65, 0, v65
	global_store_dwordx4 v[76:77], v[72:75], off sc1
	v_max_f32_e32 v68, v68, v68
	v_max_f32_e32 v69, v69, v69
	v_pk_mul_f32 v[72:73], v[64:65], v[64:65]
	v_max_f32_e32 v65, v66, v66
	v_max_f32_e32 v64, v70, v70
	v_max_f32_e32 v66, 0, v65
	v_max_f32_e32 v65, v71, v71
	v_max_f32_e32 v67, v67, v67
	v_max_f32_e32 v68, 0, v68
	v_max_f32_e32 v69, 0, v69
	v_max_f32_e32 v64, 0, v64
	v_max_f32_e32 v65, 0, v65
	v_max_f32_e32 v67, 0, v67
	v_pk_mul_f32 v[68:69], v[68:69], v[68:69]
	v_pk_mul_f32 v[70:71], v[64:65], v[64:65]
	v_pk_mul_f32 v[74:75], v[66:67], v[66:67]
	v_max_f32_e32 v56, v56, v56
	v_max_f32_e32 v57, v57, v57
	v_cvt_pk_bf16_f32 v64, v68, v69
	v_cvt_pk_bf16_f32 v65, v70, v71
	v_cvt_pk_bf16_f32 v66, v72, v73
	v_cvt_pk_bf16_f32 v67, v74, v75
	v_max_f32_e32 v56, 0, v56
	v_max_f32_e32 v57, 0, v57
	global_store_dwordx4 v[76:77], v[64:67], off offset:256 sc1
	v_max_f32_e32 v60, v60, v60
	v_max_f32_e32 v61, v61, v61
	v_pk_mul_f32 v[64:65], v[56:57], v[56:57]
	v_max_f32_e32 v57, v58, v58
	v_max_f32_e32 v56, v62, v62
	v_max_f32_e32 v58, 0, v57
	v_max_f32_e32 v57, v63, v63
	v_max_f32_e32 v56, 0, v56
	v_max_f32_e32 v57, 0, v57
	v_max_f32_e32 v59, v59, v59
	v_max_f32_e32 v60, 0, v60
	v_max_f32_e32 v61, 0, v61
	v_max_f32_e32 v59, 0, v59
	v_pk_mul_f32 v[62:63], v[56:57], v[56:57]
	v_pk_mul_f32 v[60:61], v[60:61], v[60:61]
	v_pk_mul_f32 v[66:67], v[58:59], v[58:59]
	v_cvt_pk_bf16_f32 v57, v62, v63
	v_add_co_u32_e32 v62, vcc, s76, v120
	v_max_f32_e32 v48, v48, v48
	v_max_f32_e32 v49, v49, v49
	v_cvt_pk_bf16_f32 v56, v60, v61
	v_cvt_pk_bf16_f32 v58, v64, v65
	v_cvt_pk_bf16_f32 v59, v66, v67
	v_addc_co_u32_e32 v63, vcc, 0, v121, vcc
	v_max_f32_e32 v48, 0, v48
	v_max_f32_e32 v49, 0, v49
	global_store_dwordx4 v[62:63], v[56:59], off sc1
	v_max_f32_e32 v52, v52, v52
	v_max_f32_e32 v53, v53, v53
	v_pk_mul_f32 v[56:57], v[48:49], v[48:49]
	v_max_f32_e32 v49, v50, v50
	v_max_f32_e32 v48, v54, v54
	v_max_f32_e32 v50, 0, v49
	v_max_f32_e32 v49, v55, v55
	v_max_f32_e32 v51, v51, v51
	v_max_f32_e32 v52, 0, v52
	v_max_f32_e32 v53, 0, v53
	v_max_f32_e32 v48, 0, v48
	v_max_f32_e32 v49, 0, v49
	v_max_f32_e32 v51, 0, v51
	s_mov_b64 s[30:31], 0x100000
	v_pk_mul_f32 v[52:53], v[52:53], v[52:53]
	v_pk_mul_f32 v[54:55], v[48:49], v[48:49]
	v_pk_mul_f32 v[58:59], v[50:51], v[50:51]
	v_max_f32_e32 v40, v40, v40
	v_max_f32_e32 v41, v41, v41
	v_lshl_add_u64 v[60:61], v[120:121], 0, s[30:31]
	v_cvt_pk_bf16_f32 v48, v52, v53
	v_cvt_pk_bf16_f32 v49, v54, v55
	v_cvt_pk_bf16_f32 v50, v56, v57
	v_cvt_pk_bf16_f32 v51, v58, v59
	v_max_f32_e32 v40, 0, v40
	v_max_f32_e32 v41, 0, v41
	global_store_dwordx4 v[60:61], v[48:51], off offset:256 sc1
	v_max_f32_e32 v44, v44, v44
	v_max_f32_e32 v45, v45, v45
	v_pk_mul_f32 v[48:49], v[40:41], v[40:41]
	v_max_f32_e32 v41, v42, v42
	v_max_f32_e32 v40, v46, v46
	v_max_f32_e32 v42, 0, v41
	v_max_f32_e32 v41, v47, v47
	v_max_f32_e32 v40, 0, v40
	v_max_f32_e32 v41, 0, v41
	v_max_f32_e32 v43, v43, v43
	v_max_f32_e32 v44, 0, v44
	v_max_f32_e32 v45, 0, v45
	v_max_f32_e32 v43, 0, v43
	v_pk_mul_f32 v[46:47], v[40:41], v[40:41]
	v_pk_mul_f32 v[44:45], v[44:45], v[44:45]
	v_pk_mul_f32 v[50:51], v[42:43], v[42:43]
	v_cvt_pk_bf16_f32 v41, v46, v47
	v_add_co_u32_e32 v46, vcc, s77, v120
	v_max_f32_e32 v32, v32, v32
	v_max_f32_e32 v33, v33, v33
	v_cvt_pk_bf16_f32 v40, v44, v45
	v_cvt_pk_bf16_f32 v42, v48, v49
	v_cvt_pk_bf16_f32 v43, v50, v51
	v_addc_co_u32_e32 v47, vcc, 0, v121, vcc
	v_max_f32_e32 v32, 0, v32
	v_max_f32_e32 v33, 0, v33
	global_store_dwordx4 v[46:47], v[40:43], off sc1
	v_max_f32_e32 v36, v36, v36
	v_max_f32_e32 v37, v37, v37
	v_pk_mul_f32 v[40:41], v[32:33], v[32:33]
	v_max_f32_e32 v33, v34, v34
	v_max_f32_e32 v32, v38, v38
	v_max_f32_e32 v34, 0, v33
	v_max_f32_e32 v33, v39, v39
	v_max_f32_e32 v35, v35, v35
	v_max_f32_e32 v36, 0, v36
	v_max_f32_e32 v37, 0, v37
	v_max_f32_e32 v32, 0, v32
	v_max_f32_e32 v33, 0, v33
	v_max_f32_e32 v35, 0, v35
	v_pk_mul_f32 v[36:37], v[36:37], v[36:37]
	v_pk_mul_f32 v[38:39], v[32:33], v[32:33]
	v_pk_mul_f32 v[42:43], v[34:35], v[34:35]
	v_max_f32_e32 v24, v24, v24
	v_max_f32_e32 v25, v25, v25
	v_lshl_add_u64 v[44:45], v[120:121], 0, s[10:11]
	v_cvt_pk_bf16_f32 v32, v36, v37
	v_cvt_pk_bf16_f32 v33, v38, v39
	v_cvt_pk_bf16_f32 v34, v40, v41
	v_cvt_pk_bf16_f32 v35, v42, v43
	v_max_f32_e32 v24, 0, v24
	v_max_f32_e32 v25, 0, v25
	global_store_dwordx4 v[44:45], v[32:35], off offset:256 sc1
	v_max_f32_e32 v28, v28, v28
	v_max_f32_e32 v29, v29, v29
	v_pk_mul_f32 v[32:33], v[24:25], v[24:25]
	v_max_f32_e32 v25, v26, v26
	v_max_f32_e32 v24, v30, v30
	v_max_f32_e32 v26, 0, v25
	v_max_f32_e32 v25, v31, v31
	v_max_f32_e32 v24, 0, v24
	v_max_f32_e32 v25, 0, v25
	v_max_f32_e32 v27, v27, v27
	v_max_f32_e32 v28, 0, v28
	v_max_f32_e32 v29, 0, v29
	v_max_f32_e32 v27, 0, v27
	v_pk_mul_f32 v[30:31], v[24:25], v[24:25]
	v_pk_mul_f32 v[28:29], v[28:29], v[28:29]
	v_pk_mul_f32 v[34:35], v[26:27], v[26:27]
	v_cvt_pk_bf16_f32 v25, v30, v31
	v_add_co_u32_e32 v30, vcc, s78, v120
	v_max_f32_e32 v16, v16, v16
	v_max_f32_e32 v17, v17, v17
	v_cvt_pk_bf16_f32 v24, v28, v29
	v_cvt_pk_bf16_f32 v26, v32, v33
	v_cvt_pk_bf16_f32 v27, v34, v35
	v_addc_co_u32_e32 v31, vcc, 0, v121, vcc
	v_max_f32_e32 v16, 0, v16
	v_max_f32_e32 v17, 0, v17
	global_store_dwordx4 v[30:31], v[24:27], off sc1
	v_max_f32_e32 v20, v20, v20
	v_max_f32_e32 v21, v21, v21
	v_pk_mul_f32 v[24:25], v[16:17], v[16:17]
	v_max_f32_e32 v17, v18, v18
	v_max_f32_e32 v16, v22, v22
	v_max_f32_e32 v18, 0, v17
	v_max_f32_e32 v17, v23, v23
	v_max_f32_e32 v19, v19, v19
	v_max_f32_e32 v20, 0, v20
	v_max_f32_e32 v21, 0, v21
	v_max_f32_e32 v16, 0, v16
	v_max_f32_e32 v17, 0, v17
	v_max_f32_e32 v19, 0, v19
	v_pk_mul_f32 v[20:21], v[20:21], v[20:21]
	v_pk_mul_f32 v[22:23], v[16:17], v[16:17]
	v_pk_mul_f32 v[26:27], v[18:19], v[18:19]
	v_max_f32_e32 v8, v8, v8
	v_max_f32_e32 v9, v9, v9
	v_lshl_add_u64 v[28:29], v[120:121], 0, s[12:13]
	v_cvt_pk_bf16_f32 v16, v20, v21
	v_cvt_pk_bf16_f32 v17, v22, v23
	v_cvt_pk_bf16_f32 v18, v24, v25
	v_cvt_pk_bf16_f32 v19, v26, v27
	v_max_f32_e32 v8, 0, v8
	v_max_f32_e32 v9, 0, v9
	global_store_dwordx4 v[28:29], v[16:19], off offset:256 sc1
	v_max_f32_e32 v12, v12, v12
	v_max_f32_e32 v13, v13, v13
	v_pk_mul_f32 v[16:17], v[8:9], v[8:9]
	v_max_f32_e32 v9, v10, v10
	v_max_f32_e32 v8, v14, v14
	v_max_f32_e32 v10, 0, v9
	v_max_f32_e32 v9, v15, v15
	v_max_f32_e32 v8, 0, v8
	v_max_f32_e32 v9, 0, v9
	v_max_f32_e32 v11, v11, v11
	v_max_f32_e32 v12, 0, v12
	v_max_f32_e32 v13, 0, v13
	v_max_f32_e32 v11, 0, v11
	v_pk_mul_f32 v[14:15], v[8:9], v[8:9]
	v_pk_mul_f32 v[12:13], v[12:13], v[12:13]
	v_pk_mul_f32 v[18:19], v[10:11], v[10:11]
	v_cvt_pk_bf16_f32 v9, v14, v15
	v_add_co_u32_e32 v14, vcc, s79, v120
	v_max_f32_e32 v0, v0, v0
	v_max_f32_e32 v1, v1, v1
	v_cvt_pk_bf16_f32 v8, v12, v13
	v_cvt_pk_bf16_f32 v10, v16, v17
	v_cvt_pk_bf16_f32 v11, v18, v19
	v_addc_co_u32_e32 v15, vcc, 0, v121, vcc
	v_max_f32_e32 v0, 0, v0
	v_max_f32_e32 v1, 0, v1
	global_store_dwordx4 v[14:15], v[8:11], off sc1
	v_max_f32_e32 v4, v4, v4
	v_max_f32_e32 v5, v5, v5
	v_pk_mul_f32 v[8:9], v[0:1], v[0:1]
	v_max_f32_e32 v1, v2, v2
	v_max_f32_e32 v0, v6, v6
	v_max_f32_e32 v2, 0, v1
	v_max_f32_e32 v1, v7, v7
	v_max_f32_e32 v3, v3, v3
	v_max_f32_e32 v4, 0, v4
	v_max_f32_e32 v5, 0, v5
	v_max_f32_e32 v0, 0, v0
	v_max_f32_e32 v1, 0, v1
	v_max_f32_e32 v3, 0, v3
	v_pk_mul_f32 v[4:5], v[4:5], v[4:5]
	v_pk_mul_f32 v[6:7], v[0:1], v[0:1]
	v_pk_mul_f32 v[10:11], v[2:3], v[2:3]
	v_lshl_add_u64 v[12:13], v[120:121], 0, s[14:15]
	v_cvt_pk_bf16_f32 v0, v4, v5
	v_cvt_pk_bf16_f32 v1, v6, v7
	v_cvt_pk_bf16_f32 v2, v8, v9
	v_cvt_pk_bf16_f32 v3, v10, v11
	s_and_b64 vcc, exec, s[4:5]
	s_mov_b32 s80, s16
	s_mov_b32 s28, s18
	s_mov_b64 s[34:35], s[26:27]
	s_mov_b64 s[30:31], s[20:21]
	global_store_dwordx4 v[12:13], v[0:3], off offset:256 sc1
	s_cbranch_vccz .LBB0_676
	s_waitcnt vmcnt(0)
	s_cmpk_gt_u32 s56, 0xff
	s_cbranch_scc1 .LBB0_687
	s_barrier

.LBB0_776:
	ds_read_b128 v[156:159], v152
	ds_read_b128 v[160:163], v152 offset:1024
	ds_read_b128 v[164:167], v152 offset:2048
	ds_read_b128 v[168:171], v152 offset:3072
	s_add_u32 s34, s30, 0xfff00080
	s_addc_u32 s35, s31, -1
	s_cmp_eq_u32 s85, 60
	s_cselect_b32 s55, s21, s35
	s_cselect_b32 s54, s81, s34
	s_cselect_b32 s35, s19, s84
	s_cselect_b32 s34, s82, s83
	v_lshl_add_u64 v[204:205], s[30:31], 0, v[138:139]
	s_add_i32 m0, s17, 0xc000
	ds_read_b128 v[172:175], v153
	ds_read_b128 v[176:179], v153 offset:1024
	ds_read_b128 v[180:183], v153 offset:2048
	ds_read_b128 v[184:187], v153 offset:3072
	ds_read_b128 v[188:191], v153 offset:4096
	ds_read_b128 v[192:195], v153 offset:5120
	ds_read_b128 v[196:199], v153 offset:6144
	ds_read_b128 v[200:203], v153 offset:7168
	global_load_lds_dwordx4 v[204:205], off
	v_lshl_add_u64 v[204:205], s[30:31], 0, v[140:141]
	s_add_i32 m0, s17, 0xe000
	s_nop 0
	global_load_lds_dwordx4 v[204:205], off
	s_waitcnt lgkmcnt(8)
	s_barrier
	s_waitcnt lgkmcnt(0)
	s_setprio 1
	s_waitcnt lgkmcnt(0)
	v_mfma_f32_16x16x32_bf16 v[124:127], v[156:159], v[172:175], v[124:127]
	v_mfma_f32_16x16x32_bf16 v[120:123], v[164:167], v[172:175], v[120:123]
	v_mfma_f32_16x16x32_bf16 v[116:119], v[156:159], v[180:183], v[116:119]
	v_mfma_f32_16x16x32_bf16 v[112:115], v[164:167], v[180:183], v[112:115]
	v_mfma_f32_16x16x32_bf16 v[100:103], v[156:159], v[188:191], v[100:103]
	v_mfma_f32_16x16x32_bf16 v[96:99], v[164:167], v[188:191], v[96:99]
	v_mfma_f32_16x16x32_bf16 v[84:87], v[156:159], v[196:199], v[84:87]
	v_mfma_f32_16x16x32_bf16 v[80:83], v[164:167], v[196:199], v[80:83]
	v_mfma_f32_16x16x32_bf16 v[124:127], v[160:163], v[176:179], v[124:127]
	v_mfma_f32_16x16x32_bf16 v[120:123], v[168:171], v[176:179], v[120:123]
	v_mfma_f32_16x16x32_bf16 v[116:119], v[160:163], v[184:187], v[116:119]
	v_mfma_f32_16x16x32_bf16 v[112:115], v[168:171], v[184:187], v[112:115]
	v_mfma_f32_16x16x32_bf16 v[100:103], v[160:163], v[192:195], v[100:103]
	v_mfma_f32_16x16x32_bf16 v[96:99], v[168:171], v[192:195], v[96:99]
	v_mfma_f32_16x16x32_bf16 v[84:87], v[160:163], v[200:203], v[84:87]
	v_mfma_f32_16x16x32_bf16 v[80:83], v[168:171], v[200:203], v[80:83]
	s_setprio 0
	s_barrier
	s_add_i32 s86, s74, s57
	v_lshl_add_u64 v[220:221], s[34:35], 0, v[134:135]
	s_mov_b32 m0, s86
	ds_read_b128 v[204:207], v154
	ds_read_b128 v[208:211], v154 offset:1024
	ds_read_b128 v[212:215], v154 offset:2048
	ds_read_b128 v[216:219], v154 offset:3072
	global_load_lds_dwordx4 v[220:221], off
	v_lshl_add_u64 v[222:223], s[34:35], 0, v[130:131]
	s_add_i32 m0, s86, 0x2000
	s_nop 0
	global_load_lds_dwordx4 v[222:223], off
	s_barrier
	s_waitcnt lgkmcnt(0)
	s_setprio 1
	s_waitcnt lgkmcnt(0)
	v_mfma_f32_16x16x32_bf16 v[108:111], v[204:207], v[172:175], v[108:111]
	v_mfma_f32_16x16x32_bf16 v[104:107], v[212:215], v[172:175], v[104:107]
	v_mfma_f32_16x16x32_bf16 v[92:95], v[204:207], v[180:183], v[92:95]
	v_mfma_f32_16x16x32_bf16 v[88:91], v[212:215], v[180:183], v[88:91]
	v_mfma_f32_16x16x32_bf16 v[76:79], v[204:207], v[188:191], v[76:79]
	v_mfma_f32_16x16x32_bf16 v[72:75], v[212:215], v[188:191], v[72:75]
	v_mfma_f32_16x16x32_bf16 v[68:71], v[204:207], v[196:199], v[68:71]
	v_mfma_f32_16x16x32_bf16 v[64:67], v[212:215], v[196:199], v[64:67]
	v_mfma_f32_16x16x32_bf16 v[108:111], v[208:211], v[176:179], v[108:111]
	v_mfma_f32_16x16x32_bf16 v[104:107], v[216:219], v[176:179], v[104:107]
	v_mfma_f32_16x16x32_bf16 v[92:95], v[208:211], v[184:187], v[92:95]
	v_mfma_f32_16x16x32_bf16 v[88:91], v[216:219], v[184:187], v[88:91]
	v_mfma_f32_16x16x32_bf16 v[76:79], v[208:211], v[192:195], v[76:79]
	v_mfma_f32_16x16x32_bf16 v[72:75], v[216:219], v[192:195], v[72:75]
	v_mfma_f32_16x16x32_bf16 v[68:71], v[208:211], v[200:203], v[68:71]
	v_mfma_f32_16x16x32_bf16 v[64:67], v[216:219], v[200:203], v[64:67]
	s_setprio 0
	s_mov_b32 m0, s17
	v_lshl_add_u64 v[224:225], s[54:55], 0, v[136:137]
	s_barrier
	ds_read_b128 v[172:175], v153 offset:16384
	ds_read_b128 v[176:179], v153 offset:17408
	ds_read_b128 v[180:183], v153 offset:18432
	ds_read_b128 v[184:187], v153 offset:19456
	ds_read_b128 v[188:191], v153 offset:20480
	ds_read_b128 v[192:195], v153 offset:21504
	ds_read_b128 v[196:199], v153 offset:22528
	ds_read_b128 v[200:203], v153 offset:23552
	global_load_lds_dwordx4 v[224:225], off
	v_lshl_add_u64 v[226:227], s[54:55], 0, v[132:133]
	s_mov_b32 m0, s61
	s_nop 0
	global_load_lds_dwordx4 v[226:227], off
	s_barrier
	s_waitcnt lgkmcnt(0)
	s_setprio 1
	s_waitcnt lgkmcnt(0)
	v_mfma_f32_16x16x32_bf16 v[60:63], v[156:159], v[172:175], v[60:63]
	v_mfma_f32_16x16x32_bf16 v[56:59], v[164:167], v[172:175], v[56:59]
	v_mfma_f32_16x16x32_bf16 v[52:55], v[156:159], v[180:183], v[52:55]
	v_mfma_f32_16x16x32_bf16 v[48:51], v[164:167], v[180:183], v[48:51]
	v_mfma_f32_16x16x32_bf16 v[36:39], v[156:159], v[188:191], v[36:39]
	v_mfma_f32_16x16x32_bf16 v[32:35], v[164:167], v[188:191], v[32:35]
	v_mfma_f32_16x16x32_bf16 v[20:23], v[156:159], v[196:199], v[20:23]
	v_mfma_f32_16x16x32_bf16 v[16:19], v[164:167], v[196:199], v[16:19]
	v_mfma_f32_16x16x32_bf16 v[60:63], v[160:163], v[176:179], v[60:63]
	v_mfma_f32_16x16x32_bf16 v[56:59], v[168:171], v[176:179], v[56:59]
	v_mfma_f32_16x16x32_bf16 v[52:55], v[160:163], v[184:187], v[52:55]
	v_mfma_f32_16x16x32_bf16 v[48:51], v[168:171], v[184:187], v[48:51]
	v_mfma_f32_16x16x32_bf16 v[36:39], v[160:163], v[192:195], v[36:39]
	v_mfma_f32_16x16x32_bf16 v[32:35], v[168:171], v[192:195], v[32:35]
	v_mfma_f32_16x16x32_bf16 v[20:23], v[160:163], v[200:203], v[20:23]
	v_mfma_f32_16x16x32_bf16 v[16:19], v[168:171], v[200:203], v[16:19]
	s_setprio 0
	s_barrier
	s_add_u32 s86, s34, 0x100000
	s_addc_u32 s87, s35, 0
	s_add_i32 s88, s75, s57
	v_lshl_add_u64 v[156:157], s[86:87], 0, v[134:135]
	s_mov_b32 m0, s88
	s_nop 0
	global_load_lds_dwordx4 v[156:157], off
	v_lshl_add_u64 v[156:157], s[86:87], 0, v[130:131]
	s_add_i32 m0, s88, 0x2000
	s_nop 0
	global_load_lds_dwordx4 v[156:157], off
	s_waitcnt vmcnt(6)
	s_barrier
	s_setprio 1
	v_mfma_f32_16x16x32_bf16 v[44:47], v[204:207], v[172:175], v[44:47]
	v_mfma_f32_16x16x32_bf16 v[40:43], v[212:215], v[172:175], v[40:43]
	v_mfma_f32_16x16x32_bf16 v[28:31], v[204:207], v[180:183], v[28:31]
	v_mfma_f32_16x16x32_bf16 v[24:27], v[212:215], v[180:183], v[24:27]
	v_mfma_f32_16x16x32_bf16 v[12:15], v[204:207], v[188:191], v[12:15]
	v_mfma_f32_16x16x32_bf16 v[8:11], v[212:215], v[188:191], v[8:11]
	v_mfma_f32_16x16x32_bf16 v[4:7], v[204:207], v[196:199], v[4:7]
	v_mfma_f32_16x16x32_bf16 v[0:3], v[212:215], v[196:199], v[0:3]
	v_mfma_f32_16x16x32_bf16 v[44:47], v[208:211], v[176:179], v[44:47]
	v_mfma_f32_16x16x32_bf16 v[40:43], v[216:219], v[176:179], v[40:43]
	v_mfma_f32_16x16x32_bf16 v[28:31], v[208:211], v[184:187], v[28:31]
	v_mfma_f32_16x16x32_bf16 v[24:27], v[216:219], v[184:187], v[24:27]
	v_mfma_f32_16x16x32_bf16 v[12:15], v[208:211], v[192:195], v[12:15]
	v_mfma_f32_16x16x32_bf16 v[8:11], v[216:219], v[192:195], v[8:11]
	v_mfma_f32_16x16x32_bf16 v[4:7], v[208:211], v[200:203], v[4:7]
	v_mfma_f32_16x16x32_bf16 v[0:3], v[216:219], v[200:203], v[0:3]
	s_setprio 0
	s_add_i32 s86, 0, 0x18000
	v_add_u32_e32 v155, s86, v150
	s_barrier
	ds_read_b128 v[156:159], v155
	ds_read_b128 v[160:163], v155 offset:1024
	ds_read_b128 v[164:167], v155 offset:2048
	ds_read_b128 v[168:171], v155 offset:3072
	s_add_u32 s54, s54, 0x100000
	s_addc_u32 s55, s55, 0
	s_mov_b32 m0, s62
	v_lshl_add_u64 v[204:205], s[54:55], 0, v[136:137]
	ds_read_b128 v[172:175], v153 offset:32768
	ds_read_b128 v[176:179], v153 offset:33792
	ds_read_b128 v[180:183], v153 offset:34816
	ds_read_b128 v[184:187], v153 offset:35840
	ds_read_b128 v[188:191], v153 offset:36864
	ds_read_b128 v[192:195], v153 offset:37888
	ds_read_b128 v[196:199], v153 offset:38912
	ds_read_b128 v[200:203], v153 offset:39936
	global_load_lds_dwordx4 v[204:205], off
	v_lshl_add_u64 v[204:205], s[54:55], 0, v[132:133]
	s_mov_b32 m0, s63
	s_nop 0
	global_load_lds_dwordx4 v[204:205], off
	s_waitcnt lgkmcnt(8)
	s_barrier
	s_waitcnt lgkmcnt(0)
	s_setprio 1
	s_waitcnt lgkmcnt(0)
	v_mfma_f32_16x16x32_bf16 v[124:127], v[156:159], v[172:175], v[124:127]
	v_mfma_f32_16x16x32_bf16 v[120:123], v[164:167], v[172:175], v[120:123]
	v_mfma_f32_16x16x32_bf16 v[116:119], v[156:159], v[180:183], v[116:119]
	v_mfma_f32_16x16x32_bf16 v[112:115], v[164:167], v[180:183], v[112:115]
	v_mfma_f32_16x16x32_bf16 v[100:103], v[156:159], v[188:191], v[100:103]
	v_mfma_f32_16x16x32_bf16 v[96:99], v[164:167], v[188:191], v[96:99]
	v_mfma_f32_16x16x32_bf16 v[84:87], v[156:159], v[196:199], v[84:87]
	v_mfma_f32_16x16x32_bf16 v[80:83], v[164:167], v[196:199], v[80:83]
	v_mfma_f32_16x16x32_bf16 v[124:127], v[160:163], v[176:179], v[124:127]
	v_mfma_f32_16x16x32_bf16 v[120:123], v[168:171], v[176:179], v[120:123]
	v_mfma_f32_16x16x32_bf16 v[116:119], v[160:163], v[184:187], v[116:119]
	v_mfma_f32_16x16x32_bf16 v[112:115], v[168:171], v[184:187], v[112:115]
	v_mfma_f32_16x16x32_bf16 v[100:103], v[160:163], v[192:195], v[100:103]
	v_mfma_f32_16x16x32_bf16 v[96:99], v[168:171], v[192:195], v[96:99]
	v_mfma_f32_16x16x32_bf16 v[84:87], v[160:163], v[200:203], v[84:87]
	v_mfma_f32_16x16x32_bf16 v[80:83], v[168:171], v[200:203], v[80:83]
	s_setprio 0
	s_barrier
	s_add_i32 s54, 0, 0x1c000
	s_add_i32 s55, s86, s57
	v_add_u32_e32 v155, s54, v150
	v_lshl_add_u64 v[220:221], v[220:221], 0, s[8:9]
	s_mov_b32 m0, s55
	ds_read_b128 v[204:207], v155
	ds_read_b128 v[208:211], v155 offset:1024
	ds_read_b128 v[212:215], v155 offset:2048
	ds_read_b128 v[216:219], v155 offset:3072
	global_load_lds_dwordx4 v[220:221], off
	v_lshl_add_u64 v[220:221], v[222:223], 0, s[8:9]
	s_add_i32 m0, s55, 0x2000
	s_nop 0
	global_load_lds_dwordx4 v[220:221], off
	s_barrier
	s_waitcnt lgkmcnt(0)
	s_setprio 1
	s_waitcnt lgkmcnt(0)
	v_mfma_f32_16x16x32_bf16 v[108:111], v[204:207], v[172:175], v[108:111]
	v_mfma_f32_16x16x32_bf16 v[104:107], v[212:215], v[172:175], v[104:107]
	v_mfma_f32_16x16x32_bf16 v[92:95], v[204:207], v[180:183], v[92:95]
	v_mfma_f32_16x16x32_bf16 v[88:91], v[212:215], v[180:183], v[88:91]
	v_mfma_f32_16x16x32_bf16 v[76:79], v[204:207], v[188:191], v[76:79]
	v_mfma_f32_16x16x32_bf16 v[72:75], v[212:215], v[188:191], v[72:75]
	v_mfma_f32_16x16x32_bf16 v[68:71], v[204:207], v[196:199], v[68:71]
	v_mfma_f32_16x16x32_bf16 v[64:67], v[212:215], v[196:199], v[64:67]
	v_mfma_f32_16x16x32_bf16 v[108:111], v[208:211], v[176:179], v[108:111]
	v_mfma_f32_16x16x32_bf16 v[104:107], v[216:219], v[176:179], v[104:107]
	v_mfma_f32_16x16x32_bf16 v[92:95], v[208:211], v[184:187], v[92:95]
	v_mfma_f32_16x16x32_bf16 v[88:91], v[216:219], v[184:187], v[88:91]
	v_mfma_f32_16x16x32_bf16 v[76:79], v[208:211], v[192:195], v[76:79]
	v_mfma_f32_16x16x32_bf16 v[72:75], v[216:219], v[192:195], v[72:75]
	v_mfma_f32_16x16x32_bf16 v[68:71], v[208:211], v[200:203], v[68:71]
	v_mfma_f32_16x16x32_bf16 v[64:67], v[216:219], v[200:203], v[64:67]
	s_setprio 0
	s_mov_b32 m0, s71
	v_lshl_add_u64 v[220:221], v[224:225], 0, s[8:9]
	s_barrier
	ds_read_b128 v[172:175], v153 offset:49152
	ds_read_b128 v[176:179], v153 offset:50176
	ds_read_b128 v[180:183], v153 offset:51200
	ds_read_b128 v[184:187], v153 offset:52224
	ds_read_b128 v[188:191], v153 offset:53248
	ds_read_b128 v[192:195], v153 offset:54272
	ds_read_b128 v[196:199], v153 offset:55296
	ds_read_b128 v[200:203], v153 offset:56320
	global_load_lds_dwordx4 v[220:221], off
	v_lshl_add_u64 v[220:221], v[226:227], 0, s[8:9]
	s_mov_b32 m0, s72
	s_nop 0
	global_load_lds_dwordx4 v[220:221], off
	s_barrier
	s_waitcnt lgkmcnt(0)
	s_setprio 1
	s_waitcnt lgkmcnt(0)
	v_mfma_f32_16x16x32_bf16 v[60:63], v[156:159], v[172:175], v[60:63]
	v_mfma_f32_16x16x32_bf16 v[56:59], v[164:167], v[172:175], v[56:59]
	v_mfma_f32_16x16x32_bf16 v[52:55], v[156:159], v[180:183], v[52:55]
	v_mfma_f32_16x16x32_bf16 v[48:51], v[164:167], v[180:183], v[48:51]
	v_mfma_f32_16x16x32_bf16 v[36:39], v[156:159], v[188:191], v[36:39]
	v_mfma_f32_16x16x32_bf16 v[32:35], v[164:167], v[188:191], v[32:35]
	v_mfma_f32_16x16x32_bf16 v[20:23], v[156:159], v[196:199], v[20:23]
	v_mfma_f32_16x16x32_bf16 v[16:19], v[164:167], v[196:199], v[16:19]
	v_mfma_f32_16x16x32_bf16 v[60:63], v[160:163], v[176:179], v[60:63]
	v_mfma_f32_16x16x32_bf16 v[56:59], v[168:171], v[176:179], v[56:59]
	v_mfma_f32_16x16x32_bf16 v[52:55], v[160:163], v[184:187], v[52:55]
	v_mfma_f32_16x16x32_bf16 v[48:51], v[168:171], v[184:187], v[48:51]
	v_mfma_f32_16x16x32_bf16 v[36:39], v[160:163], v[192:195], v[36:39]
	v_mfma_f32_16x16x32_bf16 v[32:35], v[168:171], v[192:195], v[32:35]
	v_mfma_f32_16x16x32_bf16 v[20:23], v[160:163], v[200:203], v[20:23]
	v_mfma_f32_16x16x32_bf16 v[16:19], v[168:171], v[200:203], v[16:19]
	s_setprio 0
	s_barrier
	s_add_u32 s34, s34, 0x100080
	s_addc_u32 s35, s35, 0
	s_add_i32 s54, s54, s57
	v_lshl_add_u64 v[156:157], s[34:35], 0, v[134:135]
	s_mov_b32 m0, s54
	s_nop 0
	global_load_lds_dwordx4 v[156:157], off
	v_lshl_add_u64 v[156:157], s[34:35], 0, v[130:131]
	s_add_i32 m0, s54, 0x2000
	s_nop 0
	global_load_lds_dwordx4 v[156:157], off
	s_waitcnt vmcnt(6)
	s_barrier
	s_setprio 1
	v_mfma_f32_16x16x32_bf16 v[44:47], v[204:207], v[172:175], v[44:47]
	v_mfma_f32_16x16x32_bf16 v[40:43], v[212:215], v[172:175], v[40:43]
	v_mfma_f32_16x16x32_bf16 v[28:31], v[204:207], v[180:183], v[28:31]
	v_mfma_f32_16x16x32_bf16 v[24:27], v[212:215], v[180:183], v[24:27]
	v_mfma_f32_16x16x32_bf16 v[12:15], v[204:207], v[188:191], v[12:15]
	v_mfma_f32_16x16x32_bf16 v[8:11], v[212:215], v[188:191], v[8:11]
	v_mfma_f32_16x16x32_bf16 v[4:7], v[204:207], v[196:199], v[4:7]
	v_mfma_f32_16x16x32_bf16 v[0:3], v[212:215], v[196:199], v[0:3]
	v_mfma_f32_16x16x32_bf16 v[44:47], v[208:211], v[176:179], v[44:47]
	v_mfma_f32_16x16x32_bf16 v[40:43], v[216:219], v[176:179], v[40:43]
	v_mfma_f32_16x16x32_bf16 v[28:31], v[208:211], v[184:187], v[28:31]
	v_mfma_f32_16x16x32_bf16 v[24:27], v[216:219], v[184:187], v[24:27]
	v_mfma_f32_16x16x32_bf16 v[12:15], v[208:211], v[192:195], v[12:15]
	v_mfma_f32_16x16x32_bf16 v[8:11], v[216:219], v[192:195], v[8:11]
	v_mfma_f32_16x16x32_bf16 v[4:7], v[208:211], v[200:203], v[4:7]
	v_mfma_f32_16x16x32_bf16 v[0:3], v[216:219], v[200:203], v[0:3]
	s_setprio 0
	s_add_i32 s85, s85, 2
	s_add_u32 s30, s30, 0x100
	s_addc_u32 s31, s31, 0
	s_add_u32 s83, s83, 0x100
	s_addc_u32 s84, s84, 0
	s_cmp_gt_u32 s85, 61
	s_barrier
	s_cbranch_scc0 .LBB0_776
	v_lshl_add_u32 v156, s16, 8, v149
	v_lshl_or_b32 v158, s80, 8, v151
	v_ashrrev_i32_e32 v157, 31, v156
	v_lshlrev_b64 v[160:161], 11, v[156:157]
	v_ashrrev_i32_e32 v159, 31, v158
	v_lshl_add_u64 v[160:161], s[44:45], 0, v[160:161]
	v_cvt_pk_bf16_f32 v124, v124, v125
	v_cvt_pk_bf16_f32 v125, v126, v127
	v_cvt_pk_bf16_f32 v126, v120, v121
	v_lshlrev_b64 v[120:121], 1, v[158:159]
	v_cvt_pk_bf16_f32 v127, v122, v123
	v_lshl_add_u64 v[122:123], v[160:161], 0, v[120:121]
	v_cvt_pk_bf16_f32 v108, v108, v109
	v_cvt_pk_bf16_f32 v109, v110, v111
	v_cvt_pk_bf16_f32 v110, v104, v105
	v_or_b32_e32 v104, 16, v156
	v_cvt_pk_bf16_f32 v60, v60, v61
	v_cvt_pk_bf16_f32 v61, v62, v63
	v_cvt_pk_bf16_f32 v63, v58, v59
	s_mov_b64 s[30:31], 0x40000
	v_add_co_u32_e32 v58, vcc, s76, v122
	v_ashrrev_i32_e32 v105, 31, v104
	v_cvt_pk_bf16_f32 v62, v56, v57
	v_lshl_add_u64 v[56:57], v[122:123], 0, s[30:31]
	v_addc_co_u32_e32 v59, vcc, 0, v123, vcc
	v_cvt_pk_bf16_f32 v44, v44, v45
	v_cvt_pk_bf16_f32 v45, v46, v47
	v_cvt_pk_bf16_f32 v46, v40, v41
	v_cvt_pk_bf16_f32 v47, v42, v43
	v_cvt_pk_bf16_f32 v111, v106, v107
	v_lshlrev_b64 v[104:105], 11, v[104:105]
	v_cvt_pk_bf16_f32 v92, v92, v93
	v_cvt_pk_bf16_f32 v93, v94, v95
	v_cvt_pk_bf16_f32 v94, v88, v89
	v_or_b32_e32 v88, 32, v156
	global_store_dwordx4 v[56:57], v[44:47], off offset:256 sc1
	global_store_dwordx4 v[122:123], v[108:111], off offset:256 sc1
	v_ashrrev_i32_e32 v89, 31, v88
	v_add_co_u32_e32 v46, vcc, s77, v122
	v_lshl_add_u64 v[108:109], s[44:45], 0, v[104:105]
	v_lshl_add_u64 v[44:45], v[122:123], 0, s[10:11]
	v_addc_co_u32_e32 v47, vcc, 0, v123, vcc
	v_cvt_pk_bf16_f32 v28, v28, v29
	v_cvt_pk_bf16_f32 v29, v30, v31
	v_cvt_pk_bf16_f32 v30, v24, v25
	v_cvt_pk_bf16_f32 v31, v26, v27
	v_lshl_add_u64 v[108:109], v[108:109], 0, v[120:121]
	v_cvt_pk_bf16_f32 v95, v90, v91
	v_lshlrev_b64 v[88:89], 11, v[88:89]
	v_cvt_pk_bf16_f32 v76, v76, v77
	v_cvt_pk_bf16_f32 v77, v78, v79
	v_cvt_pk_bf16_f32 v78, v72, v73
	v_or_b32_e32 v72, 48, v156
	global_store_dwordx4 v[44:45], v[28:31], off offset:256 sc1
	global_store_dwordx4 v[108:109], v[92:95], off offset:256 sc1
	v_ashrrev_i32_e32 v73, 31, v72
	v_add_co_u32_e32 v30, vcc, s78, v122
	v_lshl_add_u64 v[92:93], s[44:45], 0, v[88:89]
	v_lshl_add_u64 v[28:29], v[122:123], 0, s[12:13]
	v_addc_co_u32_e32 v31, vcc, 0, v123, vcc
	v_cvt_pk_bf16_f32 v12, v12, v13
	v_cvt_pk_bf16_f32 v13, v14, v15
	v_cvt_pk_bf16_f32 v14, v8, v9
	v_cvt_pk_bf16_f32 v15, v10, v11
	v_lshl_add_u64 v[92:93], v[92:93], 0, v[120:121]
	v_cvt_pk_bf16_f32 v79, v74, v75
	v_lshlrev_b64 v[72:73], 11, v[72:73]
	global_store_dwordx4 v[28:29], v[12:15], off offset:256 sc1
	global_store_dwordx4 v[92:93], v[76:79], off offset:256 sc1
	v_cvt_pk_bf16_f32 v104, v116, v117
	v_add_co_u32_e32 v14, vcc, s79, v122
	v_lshl_add_u64 v[76:77], s[44:45], 0, v[72:73]
	s_nop 0
	v_addc_co_u32_e32 v15, vcc, 0, v123, vcc
	v_cvt_pk_bf16_f32 v105, v118, v119
	v_cvt_pk_bf16_f32 v106, v112, v113
	v_cvt_pk_bf16_f32 v107, v114, v115
	v_cvt_pk_bf16_f32 v88, v100, v101
	v_cvt_pk_bf16_f32 v89, v102, v103
	v_cvt_pk_bf16_f32 v90, v96, v97
	v_cvt_pk_bf16_f32 v91, v98, v99
	v_cvt_pk_bf16_f32 v72, v84, v85
	v_cvt_pk_bf16_f32 v73, v86, v87
	v_cvt_pk_bf16_f32 v74, v80, v81
	v_cvt_pk_bf16_f32 v75, v82, v83
	v_lshl_add_u64 v[76:77], v[76:77], 0, v[120:121]
	v_cvt_pk_bf16_f32 v68, v68, v69
	v_cvt_pk_bf16_f32 v69, v70, v71
	v_cvt_pk_bf16_f32 v70, v64, v65
	v_cvt_pk_bf16_f32 v71, v66, v67
	v_cvt_pk_bf16_f32 v40, v52, v53
	v_cvt_pk_bf16_f32 v41, v54, v55
	v_cvt_pk_bf16_f32 v42, v48, v49
	v_cvt_pk_bf16_f32 v43, v50, v51
	v_cvt_pk_bf16_f32 v24, v36, v37
	v_cvt_pk_bf16_f32 v25, v38, v39
	v_cvt_pk_bf16_f32 v26, v32, v33
	v_cvt_pk_bf16_f32 v27, v34, v35
	v_cvt_pk_bf16_f32 v8, v20, v21
	v_cvt_pk_bf16_f32 v9, v22, v23
	v_cvt_pk_bf16_f32 v10, v16, v17
	v_cvt_pk_bf16_f32 v11, v18, v19
	v_lshl_add_u64 v[12:13], v[122:123], 0, s[14:15]
	v_cvt_pk_bf16_f32 v4, v4, v5
	v_cvt_pk_bf16_f32 v5, v6, v7
	v_cvt_pk_bf16_f32 v6, v0, v1
	v_cvt_pk_bf16_f32 v7, v2, v3
	s_and_b64 vcc, exec, s[4:5]
	s_mov_b32 s80, s18
	s_mov_b32 s16, s20
	s_mov_b64 s[34:35], s[28:29]
	s_mov_b64 s[30:31], s[26:27]
	global_store_dwordx4 v[122:123], v[124:127], off sc1
	global_store_dwordx4 v[108:109], v[104:107], off sc1
	global_store_dwordx4 v[92:93], v[88:91], off sc1
	global_store_dwordx4 v[76:77], v[72:75], off sc1
	global_store_dwordx4 v[76:77], v[68:71], off offset:256 sc1
	global_store_dwordx4 v[58:59], v[60:63], off sc1
	global_store_dwordx4 v[46:47], v[40:43], off sc1
	global_store_dwordx4 v[30:31], v[24:27], off sc1
	global_store_dwordx4 v[14:15], v[8:11], off sc1
	global_store_dwordx4 v[12:13], v[4:7], off offset:256 sc1
	s_cbranch_vccz .LBB0_773
	s_waitcnt vmcnt(0)
	s_cmpk_gt_u32 s56, 0xff
	s_cbranch_scc1 .LBB0_780
	s_barrier

.LBB0_912:
	ds_read_b128 v[156:159], v152
	ds_read_b128 v[160:163], v152 offset:1024
	ds_read_b128 v[164:167], v152 offset:2048
	ds_read_b128 v[168:171], v152 offset:3072
	s_add_u32 s54, s34, 0xfffc0080
	s_addc_u32 s55, s35, -1
	s_cmp_eq_u32 s87, 12
	s_cselect_b32 s57, s27, s55
	s_cselect_b32 s56, s83, s54
	s_cselect_b32 s55, s21, s86
	s_cselect_b32 s54, s84, s85
	v_lshl_add_u64 v[204:205], s[34:35], 0, v[138:139]
	s_add_i32 m0, s19, 0xc000
	ds_read_b128 v[172:175], v153
	ds_read_b128 v[176:179], v153 offset:1024
	ds_read_b128 v[180:183], v153 offset:2048
	ds_read_b128 v[184:187], v153 offset:3072
	ds_read_b128 v[188:191], v153 offset:4096
	ds_read_b128 v[192:195], v153 offset:5120
	ds_read_b128 v[196:199], v153 offset:6144
	ds_read_b128 v[200:203], v153 offset:7168
	global_load_lds_dwordx4 v[204:205], off
	v_lshl_add_u64 v[204:205], s[34:35], 0, v[140:141]
	s_add_i32 m0, s19, 0xe000
	s_nop 0
	global_load_lds_dwordx4 v[204:205], off
	s_waitcnt lgkmcnt(8)
	s_barrier
	s_waitcnt lgkmcnt(0)
	s_setprio 1
	s_waitcnt lgkmcnt(0)
	v_mfma_f32_16x16x32_bf16 v[124:127], v[156:159], v[172:175], v[124:127]
	v_mfma_f32_16x16x32_bf16 v[120:123], v[164:167], v[172:175], v[120:123]
	v_mfma_f32_16x16x32_bf16 v[116:119], v[156:159], v[180:183], v[116:119]
	v_mfma_f32_16x16x32_bf16 v[112:115], v[164:167], v[180:183], v[112:115]
	v_mfma_f32_16x16x32_bf16 v[100:103], v[156:159], v[188:191], v[100:103]
	v_mfma_f32_16x16x32_bf16 v[96:99], v[164:167], v[188:191], v[96:99]
	v_mfma_f32_16x16x32_bf16 v[84:87], v[156:159], v[196:199], v[84:87]
	v_mfma_f32_16x16x32_bf16 v[80:83], v[164:167], v[196:199], v[80:83]
	v_mfma_f32_16x16x32_bf16 v[124:127], v[160:163], v[176:179], v[124:127]
	v_mfma_f32_16x16x32_bf16 v[120:123], v[168:171], v[176:179], v[120:123]
	v_mfma_f32_16x16x32_bf16 v[116:119], v[160:163], v[184:187], v[116:119]
	v_mfma_f32_16x16x32_bf16 v[112:115], v[168:171], v[184:187], v[112:115]
	v_mfma_f32_16x16x32_bf16 v[100:103], v[160:163], v[192:195], v[100:103]
	v_mfma_f32_16x16x32_bf16 v[96:99], v[168:171], v[192:195], v[96:99]
	v_mfma_f32_16x16x32_bf16 v[84:87], v[160:163], v[200:203], v[84:87]
	v_mfma_f32_16x16x32_bf16 v[80:83], v[168:171], v[200:203], v[80:83]
	s_setprio 0
	s_barrier
	s_add_i32 s88, s76, s61
	v_lshl_add_u64 v[220:221], s[54:55], 0, v[134:135]
	s_mov_b32 m0, s88
	ds_read_b128 v[204:207], v154
	ds_read_b128 v[208:211], v154 offset:1024
	ds_read_b128 v[212:215], v154 offset:2048
	ds_read_b128 v[216:219], v154 offset:3072
	global_load_lds_dwordx4 v[220:221], off
	v_lshl_add_u64 v[222:223], s[54:55], 0, v[130:131]
	s_add_i32 m0, s88, 0x2000
	s_nop 0
	global_load_lds_dwordx4 v[222:223], off
	s_barrier
	s_waitcnt lgkmcnt(0)
	s_setprio 1
	s_waitcnt lgkmcnt(0)
	v_mfma_f32_16x16x32_bf16 v[108:111], v[204:207], v[172:175], v[108:111]
	v_mfma_f32_16x16x32_bf16 v[104:107], v[212:215], v[172:175], v[104:107]
	v_mfma_f32_16x16x32_bf16 v[92:95], v[204:207], v[180:183], v[92:95]
	v_mfma_f32_16x16x32_bf16 v[88:91], v[212:215], v[180:183], v[88:91]
	v_mfma_f32_16x16x32_bf16 v[76:79], v[204:207], v[188:191], v[76:79]
	v_mfma_f32_16x16x32_bf16 v[72:75], v[212:215], v[188:191], v[72:75]
	v_mfma_f32_16x16x32_bf16 v[68:71], v[204:207], v[196:199], v[68:71]
	v_mfma_f32_16x16x32_bf16 v[64:67], v[212:215], v[196:199], v[64:67]
	v_mfma_f32_16x16x32_bf16 v[108:111], v[208:211], v[176:179], v[108:111]
	v_mfma_f32_16x16x32_bf16 v[104:107], v[216:219], v[176:179], v[104:107]
	v_mfma_f32_16x16x32_bf16 v[92:95], v[208:211], v[184:187], v[92:95]
	v_mfma_f32_16x16x32_bf16 v[88:91], v[216:219], v[184:187], v[88:91]
	v_mfma_f32_16x16x32_bf16 v[76:79], v[208:211], v[192:195], v[76:79]
	v_mfma_f32_16x16x32_bf16 v[72:75], v[216:219], v[192:195], v[72:75]
	v_mfma_f32_16x16x32_bf16 v[68:71], v[208:211], v[200:203], v[68:71]
	v_mfma_f32_16x16x32_bf16 v[64:67], v[216:219], v[200:203], v[64:67]
	s_setprio 0
	s_mov_b32 m0, s19
	v_lshl_add_u64 v[224:225], s[56:57], 0, v[136:137]
	s_barrier
	ds_read_b128 v[172:175], v153 offset:16384
	ds_read_b128 v[176:179], v153 offset:17408
	ds_read_b128 v[180:183], v153 offset:18432
	ds_read_b128 v[184:187], v153 offset:19456
	ds_read_b128 v[188:191], v153 offset:20480
	ds_read_b128 v[192:195], v153 offset:21504
	ds_read_b128 v[196:199], v153 offset:22528
	ds_read_b128 v[200:203], v153 offset:23552
	global_load_lds_dwordx4 v[224:225], off
	v_lshl_add_u64 v[226:227], s[56:57], 0, v[132:133]
	s_mov_b32 m0, s63
	s_nop 0
	global_load_lds_dwordx4 v[226:227], off
	s_barrier
	s_waitcnt lgkmcnt(0)
	s_setprio 1
	s_waitcnt lgkmcnt(0)
	v_mfma_f32_16x16x32_bf16 v[60:63], v[156:159], v[172:175], v[60:63]
	v_mfma_f32_16x16x32_bf16 v[56:59], v[164:167], v[172:175], v[56:59]
	v_mfma_f32_16x16x32_bf16 v[52:55], v[156:159], v[180:183], v[52:55]
	v_mfma_f32_16x16x32_bf16 v[48:51], v[164:167], v[180:183], v[48:51]
	v_mfma_f32_16x16x32_bf16 v[36:39], v[156:159], v[188:191], v[36:39]
	v_mfma_f32_16x16x32_bf16 v[32:35], v[164:167], v[188:191], v[32:35]
	v_mfma_f32_16x16x32_bf16 v[20:23], v[156:159], v[196:199], v[20:23]
	v_mfma_f32_16x16x32_bf16 v[16:19], v[164:167], v[196:199], v[16:19]
	v_mfma_f32_16x16x32_bf16 v[60:63], v[160:163], v[176:179], v[60:63]
	v_mfma_f32_16x16x32_bf16 v[56:59], v[168:171], v[176:179], v[56:59]
	v_mfma_f32_16x16x32_bf16 v[52:55], v[160:163], v[184:187], v[52:55]
	v_mfma_f32_16x16x32_bf16 v[48:51], v[168:171], v[184:187], v[48:51]
	v_mfma_f32_16x16x32_bf16 v[36:39], v[160:163], v[192:195], v[36:39]
	v_mfma_f32_16x16x32_bf16 v[32:35], v[168:171], v[192:195], v[32:35]
	v_mfma_f32_16x16x32_bf16 v[20:23], v[160:163], v[200:203], v[20:23]
	v_mfma_f32_16x16x32_bf16 v[16:19], v[168:171], v[200:203], v[16:19]
	s_setprio 0
	s_barrier
	s_add_u32 s88, s54, 0x40000
	s_addc_u32 s89, s55, 0
	s_add_i32 s90, s77, s61
	v_lshl_add_u64 v[156:157], s[88:89], 0, v[134:135]
	s_mov_b32 m0, s90
	s_nop 0
	global_load_lds_dwordx4 v[156:157], off
	v_lshl_add_u64 v[156:157], s[88:89], 0, v[130:131]
	s_add_i32 m0, s90, 0x2000
	s_nop 0
	global_load_lds_dwordx4 v[156:157], off
	s_waitcnt vmcnt(6)
	s_barrier
	s_setprio 1
	v_mfma_f32_16x16x32_bf16 v[44:47], v[204:207], v[172:175], v[44:47]
	v_mfma_f32_16x16x32_bf16 v[40:43], v[212:215], v[172:175], v[40:43]
	v_mfma_f32_16x16x32_bf16 v[28:31], v[204:207], v[180:183], v[28:31]
	v_mfma_f32_16x16x32_bf16 v[24:27], v[212:215], v[180:183], v[24:27]
	v_mfma_f32_16x16x32_bf16 v[12:15], v[204:207], v[188:191], v[12:15]
	v_mfma_f32_16x16x32_bf16 v[8:11], v[212:215], v[188:191], v[8:11]
	v_mfma_f32_16x16x32_bf16 v[4:7], v[204:207], v[196:199], v[4:7]
	v_mfma_f32_16x16x32_bf16 v[0:3], v[212:215], v[196:199], v[0:3]
	v_mfma_f32_16x16x32_bf16 v[44:47], v[208:211], v[176:179], v[44:47]
	v_mfma_f32_16x16x32_bf16 v[40:43], v[216:219], v[176:179], v[40:43]
	v_mfma_f32_16x16x32_bf16 v[28:31], v[208:211], v[184:187], v[28:31]
	v_mfma_f32_16x16x32_bf16 v[24:27], v[216:219], v[184:187], v[24:27]
	v_mfma_f32_16x16x32_bf16 v[12:15], v[208:211], v[192:195], v[12:15]
	v_mfma_f32_16x16x32_bf16 v[8:11], v[216:219], v[192:195], v[8:11]
	v_mfma_f32_16x16x32_bf16 v[4:7], v[208:211], v[200:203], v[4:7]
	v_mfma_f32_16x16x32_bf16 v[0:3], v[216:219], v[200:203], v[0:3]
	s_setprio 0
	s_add_i32 s88, 0, 0x18000
	v_add_u32_e32 v155, s88, v150
	s_barrier
	ds_read_b128 v[156:159], v155
	ds_read_b128 v[160:163], v155 offset:1024
	ds_read_b128 v[164:167], v155 offset:2048
	ds_read_b128 v[168:171], v155 offset:3072
	s_add_u32 s56, s56, 0x40000
	s_addc_u32 s57, s57, 0
	s_mov_b32 m0, s70
	v_lshl_add_u64 v[204:205], s[56:57], 0, v[136:137]
	ds_read_b128 v[172:175], v153 offset:32768
	ds_read_b128 v[176:179], v153 offset:33792
	ds_read_b128 v[180:183], v153 offset:34816
	ds_read_b128 v[184:187], v153 offset:35840
	ds_read_b128 v[188:191], v153 offset:36864
	ds_read_b128 v[192:195], v153 offset:37888
	ds_read_b128 v[196:199], v153 offset:38912
	ds_read_b128 v[200:203], v153 offset:39936
	global_load_lds_dwordx4 v[204:205], off
	v_lshl_add_u64 v[204:205], s[56:57], 0, v[132:133]
	s_mov_b32 m0, s71
	s_nop 0
	global_load_lds_dwordx4 v[204:205], off
	s_waitcnt lgkmcnt(8)
	s_barrier
	s_waitcnt lgkmcnt(0)
	s_setprio 1
	s_waitcnt lgkmcnt(0)
	v_mfma_f32_16x16x32_bf16 v[124:127], v[156:159], v[172:175], v[124:127]
	v_mfma_f32_16x16x32_bf16 v[120:123], v[164:167], v[172:175], v[120:123]
	v_mfma_f32_16x16x32_bf16 v[116:119], v[156:159], v[180:183], v[116:119]
	v_mfma_f32_16x16x32_bf16 v[112:115], v[164:167], v[180:183], v[112:115]
	v_mfma_f32_16x16x32_bf16 v[100:103], v[156:159], v[188:191], v[100:103]
	v_mfma_f32_16x16x32_bf16 v[96:99], v[164:167], v[188:191], v[96:99]
	v_mfma_f32_16x16x32_bf16 v[84:87], v[156:159], v[196:199], v[84:87]
	v_mfma_f32_16x16x32_bf16 v[80:83], v[164:167], v[196:199], v[80:83]
	v_mfma_f32_16x16x32_bf16 v[124:127], v[160:163], v[176:179], v[124:127]
	v_mfma_f32_16x16x32_bf16 v[120:123], v[168:171], v[176:179], v[120:123]
	v_mfma_f32_16x16x32_bf16 v[116:119], v[160:163], v[184:187], v[116:119]
	v_mfma_f32_16x16x32_bf16 v[112:115], v[168:171], v[184:187], v[112:115]
	v_mfma_f32_16x16x32_bf16 v[100:103], v[160:163], v[192:195], v[100:103]
	v_mfma_f32_16x16x32_bf16 v[96:99], v[168:171], v[192:195], v[96:99]
	v_mfma_f32_16x16x32_bf16 v[84:87], v[160:163], v[200:203], v[84:87]
	v_mfma_f32_16x16x32_bf16 v[80:83], v[168:171], v[200:203], v[80:83]
	s_setprio 0
	s_barrier
	s_add_i32 s56, 0, 0x1c000
	s_add_i32 s57, s88, s61
	v_add_u32_e32 v155, s56, v150
	v_lshl_add_u64 v[220:221], v[220:221], 0, s[10:11]
	s_mov_b32 m0, s57
	ds_read_b128 v[204:207], v155
	ds_read_b128 v[208:211], v155 offset:1024
	ds_read_b128 v[212:215], v155 offset:2048
	ds_read_b128 v[216:219], v155 offset:3072
	global_load_lds_dwordx4 v[220:221], off
	v_lshl_add_u64 v[220:221], v[222:223], 0, s[10:11]
	s_add_i32 m0, s57, 0x2000
	s_nop 0
	global_load_lds_dwordx4 v[220:221], off
	s_barrier
	s_waitcnt lgkmcnt(0)
	s_setprio 1
	s_waitcnt lgkmcnt(0)
	v_mfma_f32_16x16x32_bf16 v[108:111], v[204:207], v[172:175], v[108:111]
	v_mfma_f32_16x16x32_bf16 v[104:107], v[212:215], v[172:175], v[104:107]
	v_mfma_f32_16x16x32_bf16 v[92:95], v[204:207], v[180:183], v[92:95]
	v_mfma_f32_16x16x32_bf16 v[88:91], v[212:215], v[180:183], v[88:91]
	v_mfma_f32_16x16x32_bf16 v[76:79], v[204:207], v[188:191], v[76:79]
	v_mfma_f32_16x16x32_bf16 v[72:75], v[212:215], v[188:191], v[72:75]
	v_mfma_f32_16x16x32_bf16 v[68:71], v[204:207], v[196:199], v[68:71]
	v_mfma_f32_16x16x32_bf16 v[64:67], v[212:215], v[196:199], v[64:67]
	v_mfma_f32_16x16x32_bf16 v[108:111], v[208:211], v[176:179], v[108:111]
	v_mfma_f32_16x16x32_bf16 v[104:107], v[216:219], v[176:179], v[104:107]
	v_mfma_f32_16x16x32_bf16 v[92:95], v[208:211], v[184:187], v[92:95]
	v_mfma_f32_16x16x32_bf16 v[88:91], v[216:219], v[184:187], v[88:91]
	v_mfma_f32_16x16x32_bf16 v[76:79], v[208:211], v[192:195], v[76:79]
	v_mfma_f32_16x16x32_bf16 v[72:75], v[216:219], v[192:195], v[72:75]
	v_mfma_f32_16x16x32_bf16 v[68:71], v[208:211], v[200:203], v[68:71]
	v_mfma_f32_16x16x32_bf16 v[64:67], v[216:219], v[200:203], v[64:67]
	s_setprio 0
	s_mov_b32 m0, s73
	v_lshl_add_u64 v[220:221], v[224:225], 0, s[10:11]
	s_barrier
	ds_read_b128 v[172:175], v153 offset:49152
	ds_read_b128 v[176:179], v153 offset:50176
	ds_read_b128 v[180:183], v153 offset:51200
	ds_read_b128 v[184:187], v153 offset:52224
	ds_read_b128 v[188:191], v153 offset:53248
	ds_read_b128 v[192:195], v153 offset:54272
	ds_read_b128 v[196:199], v153 offset:55296
	ds_read_b128 v[200:203], v153 offset:56320
	global_load_lds_dwordx4 v[220:221], off
	v_lshl_add_u64 v[220:221], v[226:227], 0, s[10:11]
	s_mov_b32 m0, s74
	s_nop 0
	global_load_lds_dwordx4 v[220:221], off
	s_barrier
	s_waitcnt lgkmcnt(0)
	s_setprio 1
	s_waitcnt lgkmcnt(0)
	v_mfma_f32_16x16x32_bf16 v[60:63], v[156:159], v[172:175], v[60:63]
	v_mfma_f32_16x16x32_bf16 v[56:59], v[164:167], v[172:175], v[56:59]
	v_mfma_f32_16x16x32_bf16 v[52:55], v[156:159], v[180:183], v[52:55]
	v_mfma_f32_16x16x32_bf16 v[48:51], v[164:167], v[180:183], v[48:51]
	v_mfma_f32_16x16x32_bf16 v[36:39], v[156:159], v[188:191], v[36:39]
	v_mfma_f32_16x16x32_bf16 v[32:35], v[164:167], v[188:191], v[32:35]
	v_mfma_f32_16x16x32_bf16 v[20:23], v[156:159], v[196:199], v[20:23]
	v_mfma_f32_16x16x32_bf16 v[16:19], v[164:167], v[196:199], v[16:19]
	v_mfma_f32_16x16x32_bf16 v[60:63], v[160:163], v[176:179], v[60:63]
	v_mfma_f32_16x16x32_bf16 v[56:59], v[168:171], v[176:179], v[56:59]
	v_mfma_f32_16x16x32_bf16 v[52:55], v[160:163], v[184:187], v[52:55]
	v_mfma_f32_16x16x32_bf16 v[48:51], v[168:171], v[184:187], v[48:51]
	v_mfma_f32_16x16x32_bf16 v[36:39], v[160:163], v[192:195], v[36:39]
	v_mfma_f32_16x16x32_bf16 v[32:35], v[168:171], v[192:195], v[32:35]
	v_mfma_f32_16x16x32_bf16 v[20:23], v[160:163], v[200:203], v[20:23]
	v_mfma_f32_16x16x32_bf16 v[16:19], v[168:171], v[200:203], v[16:19]
	s_setprio 0
	s_barrier
	s_add_u32 s54, s54, 0x40080
	s_addc_u32 s55, s55, 0
	s_add_i32 s56, s56, s61
	v_lshl_add_u64 v[156:157], s[54:55], 0, v[134:135]
	s_mov_b32 m0, s56
	s_nop 0
	global_load_lds_dwordx4 v[156:157], off
	v_lshl_add_u64 v[156:157], s[54:55], 0, v[130:131]
	s_add_i32 m0, s56, 0x2000
	s_nop 0
	global_load_lds_dwordx4 v[156:157], off
	s_waitcnt vmcnt(6)
	s_barrier
	s_setprio 1
	v_mfma_f32_16x16x32_bf16 v[44:47], v[204:207], v[172:175], v[44:47]
	v_mfma_f32_16x16x32_bf16 v[40:43], v[212:215], v[172:175], v[40:43]
	v_mfma_f32_16x16x32_bf16 v[28:31], v[204:207], v[180:183], v[28:31]
	v_mfma_f32_16x16x32_bf16 v[24:27], v[212:215], v[180:183], v[24:27]
	v_mfma_f32_16x16x32_bf16 v[12:15], v[204:207], v[188:191], v[12:15]
	v_mfma_f32_16x16x32_bf16 v[8:11], v[212:215], v[188:191], v[8:11]
	v_mfma_f32_16x16x32_bf16 v[4:7], v[204:207], v[196:199], v[4:7]
	v_mfma_f32_16x16x32_bf16 v[0:3], v[212:215], v[196:199], v[0:3]
	v_mfma_f32_16x16x32_bf16 v[44:47], v[208:211], v[176:179], v[44:47]
	v_mfma_f32_16x16x32_bf16 v[40:43], v[216:219], v[176:179], v[40:43]
	v_mfma_f32_16x16x32_bf16 v[28:31], v[208:211], v[184:187], v[28:31]
	v_mfma_f32_16x16x32_bf16 v[24:27], v[216:219], v[184:187], v[24:27]
	v_mfma_f32_16x16x32_bf16 v[12:15], v[208:211], v[192:195], v[12:15]
	v_mfma_f32_16x16x32_bf16 v[8:11], v[216:219], v[192:195], v[8:11]
	v_mfma_f32_16x16x32_bf16 v[4:7], v[208:211], v[200:203], v[4:7]
	v_mfma_f32_16x16x32_bf16 v[0:3], v[216:219], v[200:203], v[0:3]
	s_setprio 0
	s_add_i32 s87, s87, 2
	s_add_u32 s34, s34, 0x100
	s_addc_u32 s35, s35, 0
	s_add_u32 s85, s85, 0x100
	s_addc_u32 s86, s86, 0
	s_cmp_gt_u32 s87, 13
	s_barrier
	s_cbranch_scc0 .LBB0_912
	v_lshl_add_u32 v156, s18, 8, v149
	v_lshl_or_b32 v158, s82, 8, v151
	v_ashrrev_i32_e32 v157, 31, v156
	v_lshlrev_b64 v[160:161], 11, v[156:157]
	v_ashrrev_i32_e32 v159, 31, v158
	v_lshl_add_u64 v[160:161], s[46:47], 0, v[160:161]
	v_cvt_pk_bf16_f32 v124, v124, v125
	v_cvt_pk_bf16_f32 v125, v126, v127
	v_cvt_pk_bf16_f32 v126, v120, v121
	v_lshlrev_b64 v[120:121], 1, v[158:159]
	v_cvt_pk_bf16_f32 v127, v122, v123
	v_lshl_add_u64 v[122:123], v[160:161], 0, v[120:121]
	v_cvt_pk_bf16_f32 v108, v108, v109
	v_cvt_pk_bf16_f32 v109, v110, v111
	v_cvt_pk_bf16_f32 v110, v104, v105
	v_or_b32_e32 v104, 16, v156
	v_cvt_pk_bf16_f32 v60, v60, v61
	v_cvt_pk_bf16_f32 v61, v62, v63
	v_cvt_pk_bf16_f32 v63, v58, v59
	v_add_co_u32_e32 v58, vcc, s78, v122
	v_ashrrev_i32_e32 v105, 31, v104
	v_cvt_pk_bf16_f32 v62, v56, v57
	v_lshl_add_u64 v[56:57], v[122:123], 0, s[8:9]
	v_addc_co_u32_e32 v59, vcc, 0, v123, vcc
	v_cvt_pk_bf16_f32 v44, v44, v45
	v_cvt_pk_bf16_f32 v45, v46, v47
	v_cvt_pk_bf16_f32 v46, v40, v41
	v_cvt_pk_bf16_f32 v47, v42, v43
	v_cvt_pk_bf16_f32 v111, v106, v107
	v_lshlrev_b64 v[104:105], 11, v[104:105]
	v_cvt_pk_bf16_f32 v92, v92, v93
	v_cvt_pk_bf16_f32 v93, v94, v95
	v_cvt_pk_bf16_f32 v94, v88, v89
	v_or_b32_e32 v88, 32, v156
	global_store_dwordx4 v[56:57], v[44:47], off offset:256 sc1
	global_store_dwordx4 v[122:123], v[108:111], off offset:256 sc1
	v_ashrrev_i32_e32 v89, 31, v88
	v_add_co_u32_e32 v46, vcc, s79, v122
	v_lshl_add_u64 v[108:109], s[46:47], 0, v[104:105]
	v_lshl_add_u64 v[44:45], v[122:123], 0, s[12:13]
	v_addc_co_u32_e32 v47, vcc, 0, v123, vcc
	v_cvt_pk_bf16_f32 v28, v28, v29
	v_cvt_pk_bf16_f32 v29, v30, v31
	v_cvt_pk_bf16_f32 v30, v24, v25
	v_cvt_pk_bf16_f32 v31, v26, v27
	v_lshl_add_u64 v[108:109], v[108:109], 0, v[120:121]
	v_cvt_pk_bf16_f32 v95, v90, v91
	v_lshlrev_b64 v[88:89], 11, v[88:89]
	v_cvt_pk_bf16_f32 v76, v76, v77
	v_cvt_pk_bf16_f32 v77, v78, v79
	v_cvt_pk_bf16_f32 v78, v72, v73
	v_or_b32_e32 v72, 48, v156
	global_store_dwordx4 v[44:45], v[28:31], off offset:256 sc1
	global_store_dwordx4 v[108:109], v[92:95], off offset:256 sc1
	v_ashrrev_i32_e32 v73, 31, v72
	v_add_co_u32_e32 v30, vcc, s80, v122
	v_lshl_add_u64 v[92:93], s[46:47], 0, v[88:89]
	v_lshl_add_u64 v[28:29], v[122:123], 0, s[14:15]
	v_addc_co_u32_e32 v31, vcc, 0, v123, vcc
	v_cvt_pk_bf16_f32 v12, v12, v13
	v_cvt_pk_bf16_f32 v13, v14, v15
	v_cvt_pk_bf16_f32 v14, v8, v9
	v_cvt_pk_bf16_f32 v15, v10, v11
	v_lshl_add_u64 v[92:93], v[92:93], 0, v[120:121]
	v_cvt_pk_bf16_f32 v79, v74, v75
	v_lshlrev_b64 v[72:73], 11, v[72:73]
	global_store_dwordx4 v[28:29], v[12:15], off offset:256 sc1
	global_store_dwordx4 v[92:93], v[76:79], off offset:256 sc1
	v_cvt_pk_bf16_f32 v104, v116, v117
	v_add_co_u32_e32 v14, vcc, s81, v122
	v_lshl_add_u64 v[76:77], s[46:47], 0, v[72:73]
	s_nop 0
	v_addc_co_u32_e32 v15, vcc, 0, v123, vcc
	v_cvt_pk_bf16_f32 v105, v118, v119
	v_cvt_pk_bf16_f32 v106, v112, v113
	v_cvt_pk_bf16_f32 v107, v114, v115
	v_cvt_pk_bf16_f32 v88, v100, v101
	v_cvt_pk_bf16_f32 v89, v102, v103
	v_cvt_pk_bf16_f32 v90, v96, v97
	v_cvt_pk_bf16_f32 v91, v98, v99
	v_cvt_pk_bf16_f32 v72, v84, v85
	v_cvt_pk_bf16_f32 v73, v86, v87
	v_cvt_pk_bf16_f32 v74, v80, v81
	v_cvt_pk_bf16_f32 v75, v82, v83
	v_lshl_add_u64 v[76:77], v[76:77], 0, v[120:121]
	v_cvt_pk_bf16_f32 v68, v68, v69
	v_cvt_pk_bf16_f32 v69, v70, v71
	v_cvt_pk_bf16_f32 v70, v64, v65
	v_cvt_pk_bf16_f32 v71, v66, v67
	v_cvt_pk_bf16_f32 v40, v52, v53
	v_cvt_pk_bf16_f32 v41, v54, v55
	v_cvt_pk_bf16_f32 v42, v48, v49
	v_cvt_pk_bf16_f32 v43, v50, v51
	v_cvt_pk_bf16_f32 v24, v36, v37
	v_cvt_pk_bf16_f32 v25, v38, v39
	v_cvt_pk_bf16_f32 v26, v32, v33
	v_cvt_pk_bf16_f32 v27, v34, v35
	v_cvt_pk_bf16_f32 v8, v20, v21
	v_cvt_pk_bf16_f32 v9, v22, v23
	v_cvt_pk_bf16_f32 v10, v16, v17
	v_cvt_pk_bf16_f32 v11, v18, v19
	v_lshl_add_u64 v[12:13], v[122:123], 0, s[16:17]
	v_cvt_pk_bf16_f32 v4, v4, v5
	v_cvt_pk_bf16_f32 v5, v6, v7
	v_cvt_pk_bf16_f32 v6, v0, v1
	v_cvt_pk_bf16_f32 v7, v2, v3
	s_and_b64 vcc, exec, s[4:5]
	s_mov_b32 s82, s20
	s_mov_b32 s18, s26
	s_mov_b64 s[54:55], s[30:31]
	s_mov_b64 s[34:35], s[28:29]
	global_store_dwordx4 v[122:123], v[124:127], off sc1
	global_store_dwordx4 v[108:109], v[104:107], off sc1
	global_store_dwordx4 v[92:93], v[88:91], off sc1
	global_store_dwordx4 v[76:77], v[72:75], off sc1
	global_store_dwordx4 v[76:77], v[68:71], off offset:256 sc1
	global_store_dwordx4 v[58:59], v[60:63], off sc1
	global_store_dwordx4 v[46:47], v[40:43], off sc1
	global_store_dwordx4 v[30:31], v[24:27], off sc1
	global_store_dwordx4 v[14:15], v[8:11], off sc1
	global_store_dwordx4 v[12:13], v[4:7], off offset:256 sc1
	s_cbranch_vccz .LBB0_909
	s_waitcnt vmcnt(0)
	s_cmpk_gt_u32 s60, 0xff
	s_cbranch_scc1 .LBB0_916
	s_barrier

.LBB0_1291:
	ds_read_b128 v[154:157], v151
	ds_read_b128 v[158:161], v151 offset:1024
	ds_read_b128 v[162:165], v151 offset:2048
	ds_read_b128 v[166:169], v151 offset:3072
	s_add_u32 s36, s34, 0xfffc0080
	s_addc_u32 s37, s35, -1
	s_cmp_eq_u32 s79, 12
	s_cselect_b32 s39, s21, s37
	s_cselect_b32 s38, s75, s36
	s_cselect_b32 s37, s19, s78
	s_cselect_b32 s36, s76, s77
	v_lshl_add_u64 v[202:203], s[34:35], 0, v[138:139]
	s_add_i32 m0, s31, 0xc000
	ds_read_b128 v[170:173], v152
	ds_read_b128 v[174:177], v152 offset:1024
	ds_read_b128 v[178:181], v152 offset:2048
	ds_read_b128 v[182:185], v152 offset:3072
	ds_read_b128 v[186:189], v152 offset:4096
	ds_read_b128 v[190:193], v152 offset:5120
	ds_read_b128 v[194:197], v152 offset:6144
	ds_read_b128 v[198:201], v152 offset:7168
	global_load_lds_dwordx4 v[202:203], off
	v_lshl_add_u64 v[202:203], s[34:35], 0, v[140:141]
	s_add_i32 m0, s31, 0xe000
	s_nop 0
	global_load_lds_dwordx4 v[202:203], off
	s_waitcnt lgkmcnt(8)
	s_barrier
	s_waitcnt lgkmcnt(0)
	s_setprio 1
	s_waitcnt lgkmcnt(0)
	v_mfma_f32_16x16x32_bf16 v[124:127], v[154:157], v[170:173], v[124:127]
	v_mfma_f32_16x16x32_bf16 v[120:123], v[162:165], v[170:173], v[120:123]
	v_mfma_f32_16x16x32_bf16 v[108:111], v[154:157], v[178:181], v[108:111]
	v_mfma_f32_16x16x32_bf16 v[104:107], v[162:165], v[178:181], v[104:107]
	v_mfma_f32_16x16x32_bf16 v[92:95], v[154:157], v[186:189], v[92:95]
	v_mfma_f32_16x16x32_bf16 v[88:91], v[162:165], v[186:189], v[88:91]
	v_mfma_f32_16x16x32_bf16 v[76:79], v[154:157], v[194:197], v[76:79]
	v_mfma_f32_16x16x32_bf16 v[72:75], v[162:165], v[194:197], v[72:75]
	v_mfma_f32_16x16x32_bf16 v[124:127], v[158:161], v[174:177], v[124:127]
	v_mfma_f32_16x16x32_bf16 v[120:123], v[166:169], v[174:177], v[120:123]
	v_mfma_f32_16x16x32_bf16 v[108:111], v[158:161], v[182:185], v[108:111]
	v_mfma_f32_16x16x32_bf16 v[104:107], v[166:169], v[182:185], v[104:107]
	v_mfma_f32_16x16x32_bf16 v[92:95], v[158:161], v[190:193], v[92:95]
	v_mfma_f32_16x16x32_bf16 v[88:91], v[166:169], v[190:193], v[88:91]
	v_mfma_f32_16x16x32_bf16 v[76:79], v[158:161], v[198:201], v[76:79]
	v_mfma_f32_16x16x32_bf16 v[72:75], v[166:169], v[198:201], v[72:75]
	s_setprio 0
	s_barrier
	s_add_i32 s80, s62, s52
	v_lshl_add_u64 v[218:219], s[36:37], 0, v[132:133]
	s_mov_b32 m0, s80
	ds_read_b128 v[202:205], v153
	ds_read_b128 v[206:209], v153 offset:1024
	ds_read_b128 v[210:213], v153 offset:2048
	ds_read_b128 v[214:217], v153 offset:3072
	global_load_lds_dwordx4 v[218:219], off
	v_lshl_add_u64 v[220:221], s[36:37], 0, v[136:137]
	s_add_i32 m0, s80, 0x2000
	s_nop 0
	global_load_lds_dwordx4 v[220:221], off
	s_barrier
	s_waitcnt lgkmcnt(0)
	s_setprio 1
	s_waitcnt lgkmcnt(0)
	v_mfma_f32_16x16x32_bf16 v[116:119], v[202:205], v[170:173], v[116:119]
	v_mfma_f32_16x16x32_bf16 v[112:115], v[210:213], v[170:173], v[112:115]
	v_mfma_f32_16x16x32_bf16 v[100:103], v[202:205], v[178:181], v[100:103]
	v_mfma_f32_16x16x32_bf16 v[96:99], v[210:213], v[178:181], v[96:99]
	v_mfma_f32_16x16x32_bf16 v[84:87], v[202:205], v[186:189], v[84:87]
	v_mfma_f32_16x16x32_bf16 v[80:83], v[210:213], v[186:189], v[80:83]
	v_mfma_f32_16x16x32_bf16 v[68:71], v[202:205], v[194:197], v[68:71]
	v_mfma_f32_16x16x32_bf16 v[64:67], v[210:213], v[194:197], v[64:67]
	v_mfma_f32_16x16x32_bf16 v[116:119], v[206:209], v[174:177], v[116:119]
	v_mfma_f32_16x16x32_bf16 v[112:115], v[214:217], v[174:177], v[112:115]
	v_mfma_f32_16x16x32_bf16 v[100:103], v[206:209], v[182:185], v[100:103]
	v_mfma_f32_16x16x32_bf16 v[96:99], v[214:217], v[182:185], v[96:99]
	v_mfma_f32_16x16x32_bf16 v[84:87], v[206:209], v[190:193], v[84:87]
	v_mfma_f32_16x16x32_bf16 v[80:83], v[214:217], v[190:193], v[80:83]
	v_mfma_f32_16x16x32_bf16 v[68:71], v[206:209], v[198:201], v[68:71]
	v_mfma_f32_16x16x32_bf16 v[64:67], v[214:217], v[198:201], v[64:67]
	s_setprio 0
	s_mov_b32 m0, s31
	v_lshl_add_u64 v[222:223], s[38:39], 0, v[130:131]
	s_barrier
	ds_read_b128 v[170:173], v152 offset:16384
	ds_read_b128 v[174:177], v152 offset:17408
	ds_read_b128 v[178:181], v152 offset:18432
	ds_read_b128 v[182:185], v152 offset:19456
	ds_read_b128 v[186:189], v152 offset:20480
	ds_read_b128 v[190:193], v152 offset:21504
	ds_read_b128 v[194:197], v152 offset:22528
	ds_read_b128 v[198:201], v152 offset:23552
	global_load_lds_dwordx4 v[222:223], off
	v_lshl_add_u64 v[224:225], s[38:39], 0, v[134:135]
	s_mov_b32 m0, s53
	s_nop 0
	global_load_lds_dwordx4 v[224:225], off
	s_barrier
	s_waitcnt lgkmcnt(0)
	s_setprio 1
	s_waitcnt lgkmcnt(0)
	v_mfma_f32_16x16x32_bf16 v[60:63], v[154:157], v[170:173], v[60:63]
	v_mfma_f32_16x16x32_bf16 v[56:59], v[162:165], v[170:173], v[56:59]
	v_mfma_f32_16x16x32_bf16 v[44:47], v[154:157], v[178:181], v[44:47]
	v_mfma_f32_16x16x32_bf16 v[40:43], v[162:165], v[178:181], v[40:43]
	v_mfma_f32_16x16x32_bf16 v[28:31], v[154:157], v[186:189], v[28:31]
	v_mfma_f32_16x16x32_bf16 v[24:27], v[162:165], v[186:189], v[24:27]
	v_mfma_f32_16x16x32_bf16 v[12:15], v[154:157], v[194:197], v[12:15]
	v_mfma_f32_16x16x32_bf16 v[8:11], v[162:165], v[194:197], v[8:11]
	v_mfma_f32_16x16x32_bf16 v[60:63], v[158:161], v[174:177], v[60:63]
	v_mfma_f32_16x16x32_bf16 v[56:59], v[166:169], v[174:177], v[56:59]
	v_mfma_f32_16x16x32_bf16 v[44:47], v[158:161], v[182:185], v[44:47]
	v_mfma_f32_16x16x32_bf16 v[40:43], v[166:169], v[182:185], v[40:43]
	v_mfma_f32_16x16x32_bf16 v[28:31], v[158:161], v[190:193], v[28:31]
	v_mfma_f32_16x16x32_bf16 v[24:27], v[166:169], v[190:193], v[24:27]
	v_mfma_f32_16x16x32_bf16 v[12:15], v[158:161], v[198:201], v[12:15]
	v_mfma_f32_16x16x32_bf16 v[8:11], v[166:169], v[198:201], v[8:11]
	s_setprio 0
	s_barrier
	s_add_u32 s80, s36, 0x40000
	s_addc_u32 s81, s37, 0
	s_add_i32 s82, s63, s52
	v_lshl_add_u64 v[154:155], s[80:81], 0, v[132:133]
	s_mov_b32 m0, s82
	s_nop 0
	global_load_lds_dwordx4 v[154:155], off
	v_lshl_add_u64 v[154:155], s[80:81], 0, v[136:137]
	s_add_i32 m0, s82, 0x2000
	s_nop 0
	global_load_lds_dwordx4 v[154:155], off
	s_waitcnt vmcnt(6)
	s_barrier
	s_setprio 1
	v_mfma_f32_16x16x32_bf16 v[52:55], v[202:205], v[170:173], v[52:55]
	v_mfma_f32_16x16x32_bf16 v[48:51], v[210:213], v[170:173], v[48:51]
	v_mfma_f32_16x16x32_bf16 v[36:39], v[202:205], v[178:181], v[36:39]
	v_mfma_f32_16x16x32_bf16 v[32:35], v[210:213], v[178:181], v[32:35]
	v_mfma_f32_16x16x32_bf16 v[20:23], v[202:205], v[186:189], v[20:23]
	v_mfma_f32_16x16x32_bf16 v[16:19], v[210:213], v[186:189], v[16:19]
	v_mfma_f32_16x16x32_bf16 v[4:7], v[202:205], v[194:197], v[4:7]
	v_mfma_f32_16x16x32_bf16 v[0:3], v[210:213], v[194:197], v[0:3]
	v_mfma_f32_16x16x32_bf16 v[52:55], v[206:209], v[174:177], v[52:55]
	v_mfma_f32_16x16x32_bf16 v[48:51], v[214:217], v[174:177], v[48:51]
	v_mfma_f32_16x16x32_bf16 v[36:39], v[206:209], v[182:185], v[36:39]
	v_mfma_f32_16x16x32_bf16 v[32:35], v[214:217], v[182:185], v[32:35]
	v_mfma_f32_16x16x32_bf16 v[20:23], v[206:209], v[190:193], v[20:23]
	v_mfma_f32_16x16x32_bf16 v[16:19], v[214:217], v[190:193], v[16:19]
	v_mfma_f32_16x16x32_bf16 v[4:7], v[206:209], v[198:201], v[4:7]
	v_mfma_f32_16x16x32_bf16 v[0:3], v[214:217], v[198:201], v[0:3]
	s_setprio 0
	s_add_i32 s80, 0, 0x18000
	v_add_u32_e32 v166, s80, v149
	s_barrier
	ds_read_b128 v[154:157], v166
	ds_read_b128 v[158:161], v166 offset:1024
	ds_read_b128 v[162:165], v166 offset:2048
	ds_read_b128 v[166:169], v166 offset:3072
	s_add_u32 s38, s38, 0x40000
	s_addc_u32 s39, s39, 0
	s_mov_b32 m0, s54
	v_lshl_add_u64 v[202:203], s[38:39], 0, v[130:131]
	ds_read_b128 v[170:173], v152 offset:32768
	ds_read_b128 v[174:177], v152 offset:33792
	ds_read_b128 v[178:181], v152 offset:34816
	ds_read_b128 v[182:185], v152 offset:35840
	ds_read_b128 v[186:189], v152 offset:36864
	ds_read_b128 v[190:193], v152 offset:37888
	ds_read_b128 v[194:197], v152 offset:38912
	ds_read_b128 v[198:201], v152 offset:39936
	global_load_lds_dwordx4 v[202:203], off
	v_lshl_add_u64 v[202:203], s[38:39], 0, v[134:135]
	s_mov_b32 m0, s55
	s_nop 0
	global_load_lds_dwordx4 v[202:203], off
	s_waitcnt lgkmcnt(8)
	s_barrier
	s_waitcnt lgkmcnt(0)
	s_setprio 1
	s_waitcnt lgkmcnt(0)
	v_mfma_f32_16x16x32_bf16 v[124:127], v[154:157], v[170:173], v[124:127]
	v_mfma_f32_16x16x32_bf16 v[120:123], v[162:165], v[170:173], v[120:123]
	v_mfma_f32_16x16x32_bf16 v[108:111], v[154:157], v[178:181], v[108:111]
	v_mfma_f32_16x16x32_bf16 v[104:107], v[162:165], v[178:181], v[104:107]
	v_mfma_f32_16x16x32_bf16 v[92:95], v[154:157], v[186:189], v[92:95]
	v_mfma_f32_16x16x32_bf16 v[88:91], v[162:165], v[186:189], v[88:91]
	v_mfma_f32_16x16x32_bf16 v[76:79], v[154:157], v[194:197], v[76:79]
	v_mfma_f32_16x16x32_bf16 v[72:75], v[162:165], v[194:197], v[72:75]
	v_mfma_f32_16x16x32_bf16 v[124:127], v[158:161], v[174:177], v[124:127]
	v_mfma_f32_16x16x32_bf16 v[120:123], v[166:169], v[174:177], v[120:123]
	v_mfma_f32_16x16x32_bf16 v[108:111], v[158:161], v[182:185], v[108:111]
	v_mfma_f32_16x16x32_bf16 v[104:107], v[166:169], v[182:185], v[104:107]
	v_mfma_f32_16x16x32_bf16 v[92:95], v[158:161], v[190:193], v[92:95]
	v_mfma_f32_16x16x32_bf16 v[88:91], v[166:169], v[190:193], v[88:91]
	v_mfma_f32_16x16x32_bf16 v[76:79], v[158:161], v[198:201], v[76:79]
	v_mfma_f32_16x16x32_bf16 v[72:75], v[166:169], v[198:201], v[72:75]
	s_setprio 0
	s_barrier
	s_add_i32 s38, 0, 0x1c000
	s_add_i32 s39, s80, s52
	v_add_u32_e32 v214, s38, v149
	v_lshl_add_u64 v[218:219], v[218:219], 0, s[8:9]
	s_mov_b32 m0, s39
	ds_read_b128 v[202:205], v214
	ds_read_b128 v[206:209], v214 offset:1024
	ds_read_b128 v[210:213], v214 offset:2048
	ds_read_b128 v[214:217], v214 offset:3072
	global_load_lds_dwordx4 v[218:219], off
	v_lshl_add_u64 v[218:219], v[220:221], 0, s[8:9]
	s_add_i32 m0, s39, 0x2000
	s_nop 0
	global_load_lds_dwordx4 v[218:219], off
	s_barrier
	s_waitcnt lgkmcnt(0)
	s_setprio 1
	s_waitcnt lgkmcnt(0)
	v_mfma_f32_16x16x32_bf16 v[116:119], v[202:205], v[170:173], v[116:119]
	v_mfma_f32_16x16x32_bf16 v[112:115], v[210:213], v[170:173], v[112:115]
	v_mfma_f32_16x16x32_bf16 v[100:103], v[202:205], v[178:181], v[100:103]
	v_mfma_f32_16x16x32_bf16 v[96:99], v[210:213], v[178:181], v[96:99]
	v_mfma_f32_16x16x32_bf16 v[84:87], v[202:205], v[186:189], v[84:87]
	v_mfma_f32_16x16x32_bf16 v[80:83], v[210:213], v[186:189], v[80:83]
	v_mfma_f32_16x16x32_bf16 v[68:71], v[202:205], v[194:197], v[68:71]
	v_mfma_f32_16x16x32_bf16 v[64:67], v[210:213], v[194:197], v[64:67]
	v_mfma_f32_16x16x32_bf16 v[116:119], v[206:209], v[174:177], v[116:119]
	v_mfma_f32_16x16x32_bf16 v[112:115], v[214:217], v[174:177], v[112:115]
	v_mfma_f32_16x16x32_bf16 v[100:103], v[206:209], v[182:185], v[100:103]
	v_mfma_f32_16x16x32_bf16 v[96:99], v[214:217], v[182:185], v[96:99]
	v_mfma_f32_16x16x32_bf16 v[84:87], v[206:209], v[190:193], v[84:87]
	v_mfma_f32_16x16x32_bf16 v[80:83], v[214:217], v[190:193], v[80:83]
	v_mfma_f32_16x16x32_bf16 v[68:71], v[206:209], v[198:201], v[68:71]
	v_mfma_f32_16x16x32_bf16 v[64:67], v[214:217], v[198:201], v[64:67]
	s_setprio 0
	s_mov_b32 m0, s57
	v_lshl_add_u64 v[218:219], v[222:223], 0, s[8:9]
	s_barrier
	ds_read_b128 v[170:173], v152 offset:49152
	ds_read_b128 v[174:177], v152 offset:50176
	ds_read_b128 v[178:181], v152 offset:51200
	ds_read_b128 v[182:185], v152 offset:52224
	ds_read_b128 v[186:189], v152 offset:53248
	ds_read_b128 v[190:193], v152 offset:54272
	ds_read_b128 v[194:197], v152 offset:55296
	ds_read_b128 v[198:201], v152 offset:56320
	global_load_lds_dwordx4 v[218:219], off
	v_lshl_add_u64 v[218:219], v[224:225], 0, s[8:9]
	s_mov_b32 m0, s60
	s_nop 0
	global_load_lds_dwordx4 v[218:219], off
	s_barrier
	s_waitcnt lgkmcnt(0)
	s_setprio 1
	s_waitcnt lgkmcnt(0)
	v_mfma_f32_16x16x32_bf16 v[60:63], v[154:157], v[170:173], v[60:63]
	v_mfma_f32_16x16x32_bf16 v[56:59], v[162:165], v[170:173], v[56:59]
	v_mfma_f32_16x16x32_bf16 v[44:47], v[154:157], v[178:181], v[44:47]
	v_mfma_f32_16x16x32_bf16 v[40:43], v[162:165], v[178:181], v[40:43]
	v_mfma_f32_16x16x32_bf16 v[28:31], v[154:157], v[186:189], v[28:31]
	v_mfma_f32_16x16x32_bf16 v[24:27], v[162:165], v[186:189], v[24:27]
	v_mfma_f32_16x16x32_bf16 v[12:15], v[154:157], v[194:197], v[12:15]
	v_mfma_f32_16x16x32_bf16 v[8:11], v[162:165], v[194:197], v[8:11]
	v_mfma_f32_16x16x32_bf16 v[60:63], v[158:161], v[174:177], v[60:63]
	v_mfma_f32_16x16x32_bf16 v[56:59], v[166:169], v[174:177], v[56:59]
	v_mfma_f32_16x16x32_bf16 v[44:47], v[158:161], v[182:185], v[44:47]
	v_mfma_f32_16x16x32_bf16 v[40:43], v[166:169], v[182:185], v[40:43]
	v_mfma_f32_16x16x32_bf16 v[28:31], v[158:161], v[190:193], v[28:31]
	v_mfma_f32_16x16x32_bf16 v[24:27], v[166:169], v[190:193], v[24:27]
	v_mfma_f32_16x16x32_bf16 v[12:15], v[158:161], v[198:201], v[12:15]
	v_mfma_f32_16x16x32_bf16 v[8:11], v[166:169], v[198:201], v[8:11]
	s_setprio 0
	s_barrier
	s_add_u32 s36, s36, 0x40080
	s_addc_u32 s37, s37, 0
	s_add_i32 s38, s38, s52
	v_lshl_add_u64 v[154:155], s[36:37], 0, v[132:133]
	s_mov_b32 m0, s38
	s_nop 0
	global_load_lds_dwordx4 v[154:155], off
	v_lshl_add_u64 v[154:155], s[36:37], 0, v[136:137]
	s_add_i32 m0, s38, 0x2000
	s_nop 0
	global_load_lds_dwordx4 v[154:155], off
	s_waitcnt vmcnt(6)
	s_barrier
	s_setprio 1
	v_mfma_f32_16x16x32_bf16 v[52:55], v[202:205], v[170:173], v[52:55]
	v_mfma_f32_16x16x32_bf16 v[48:51], v[210:213], v[170:173], v[48:51]
	v_mfma_f32_16x16x32_bf16 v[36:39], v[202:205], v[178:181], v[36:39]
	v_mfma_f32_16x16x32_bf16 v[32:35], v[210:213], v[178:181], v[32:35]
	v_mfma_f32_16x16x32_bf16 v[20:23], v[202:205], v[186:189], v[20:23]
	v_mfma_f32_16x16x32_bf16 v[16:19], v[210:213], v[186:189], v[16:19]
	v_mfma_f32_16x16x32_bf16 v[4:7], v[202:205], v[194:197], v[4:7]
	v_mfma_f32_16x16x32_bf16 v[0:3], v[210:213], v[194:197], v[0:3]
	v_mfma_f32_16x16x32_bf16 v[52:55], v[206:209], v[174:177], v[52:55]
	v_mfma_f32_16x16x32_bf16 v[48:51], v[214:217], v[174:177], v[48:51]
	v_mfma_f32_16x16x32_bf16 v[36:39], v[206:209], v[182:185], v[36:39]
	v_mfma_f32_16x16x32_bf16 v[32:35], v[214:217], v[182:185], v[32:35]
	v_mfma_f32_16x16x32_bf16 v[20:23], v[206:209], v[190:193], v[20:23]
	v_mfma_f32_16x16x32_bf16 v[16:19], v[214:217], v[190:193], v[16:19]
	v_mfma_f32_16x16x32_bf16 v[4:7], v[206:209], v[198:201], v[4:7]
	v_mfma_f32_16x16x32_bf16 v[0:3], v[214:217], v[198:201], v[0:3]
	s_setprio 0
	s_add_i32 s79, s79, 2
	s_add_u32 s34, s34, 0x100
	s_addc_u32 s35, s35, 0
	s_add_u32 s77, s77, 0x100
	s_addc_u32 s78, s78, 0
	s_cmp_gt_u32 s79, 13
	s_barrier
	s_cbranch_scc0 .LBB0_1291
	v_lshl_add_u32 v154, s30, 8, v148
	v_max_f32_e32 v126, v126, v126
	v_max_f32_e32 v127, v127, v127
	v_lshl_or_b32 v156, s74, 8, v150
	v_ashrrev_i32_e32 v155, 31, v154
	v_max_f32_e32 v124, v124, v124
	v_max_f32_e32 v120, v120, v120
	v_max_f32_e32 v125, v125, v125
	v_max_f32_e32 v121, v121, v121
	v_max_f32_e32 v126, 0, v126
	v_max_f32_e32 v122, v122, v122
	v_max_f32_e32 v127, 0, v127
	v_max_f32_e32 v123, v123, v123
	v_lshlrev_b64 v[158:159], 13, v[154:155]
	v_max_f32_e32 v124, 0, v124
	v_max_f32_e32 v120, 0, v120
	v_max_f32_e32 v125, 0, v125
	v_max_f32_e32 v121, 0, v121
	v_max_f32_e32 v122, 0, v122
	v_max_f32_e32 v123, 0, v123
	v_pk_mul_f32 v[126:127], v[126:127], v[126:127]
	v_ashrrev_i32_e32 v157, 31, v156
	v_lshl_add_u64 v[158:159], s[46:47], 0, v[158:159]
	v_pk_mul_f32 v[124:125], v[124:125], v[124:125]
	v_pk_mul_f32 v[120:121], v[120:121], v[120:121]
	v_pk_mul_f32 v[160:161], v[122:123], v[122:123]
	v_cvt_pk_bf16_f32 v123, v126, v127
	v_lshlrev_b64 v[126:127], 1, v[156:157]
	v_max_f32_e32 v112, v112, v112
	v_max_f32_e32 v113, v113, v113
	v_cvt_pk_bf16_f32 v122, v124, v125
	v_cvt_pk_bf16_f32 v124, v120, v121
	v_cvt_pk_bf16_f32 v125, v160, v161
	v_lshl_add_u64 v[120:121], v[158:159], 0, v[126:127]
	v_max_f32_e32 v112, 0, v112
	v_max_f32_e32 v113, 0, v113
	global_store_dwordx4 v[120:121], v[122:125], off sc1
	v_max_f32_e32 v116, v116, v116
	v_max_f32_e32 v117, v117, v117
	v_pk_mul_f32 v[122:123], v[112:113], v[112:113]
	v_max_f32_e32 v113, v114, v114
	v_max_f32_e32 v112, v118, v118
	v_max_f32_e32 v114, 0, v113
	v_max_f32_e32 v113, v119, v119
	v_max_f32_e32 v115, v115, v115
	v_max_f32_e32 v116, 0, v116
	v_max_f32_e32 v117, 0, v117
	v_max_f32_e32 v112, 0, v112
	v_max_f32_e32 v113, 0, v113
	v_max_f32_e32 v115, 0, v115
	v_pk_mul_f32 v[116:117], v[116:117], v[116:117]
	v_pk_mul_f32 v[118:119], v[112:113], v[112:113]
	v_pk_mul_f32 v[124:125], v[114:115], v[114:115]
	v_max_f32_e32 v104, v104, v104
	v_max_f32_e32 v105, v105, v105
	v_cvt_pk_bf16_f32 v112, v116, v117
	v_cvt_pk_bf16_f32 v113, v118, v119
	v_cvt_pk_bf16_f32 v114, v122, v123
	v_cvt_pk_bf16_f32 v115, v124, v125
	v_max_f32_e32 v104, 0, v104
	v_max_f32_e32 v105, 0, v105
	global_store_dwordx4 v[120:121], v[112:115], off offset:256 sc1
	v_max_f32_e32 v108, v108, v108
	v_max_f32_e32 v109, v109, v109
	v_or_b32_e32 v112, 16, v154
	v_pk_mul_f32 v[114:115], v[104:105], v[104:105]
	v_max_f32_e32 v105, v106, v106
	v_ashrrev_i32_e32 v113, 31, v112
	v_max_f32_e32 v104, v110, v110
	v_max_f32_e32 v106, 0, v105
	v_max_f32_e32 v105, v111, v111
	v_max_f32_e32 v107, v107, v107
	v_lshlrev_b64 v[112:113], 13, v[112:113]
	v_max_f32_e32 v108, 0, v108
	v_max_f32_e32 v109, 0, v109
	v_max_f32_e32 v104, 0, v104
	v_max_f32_e32 v105, 0, v105
	v_max_f32_e32 v107, 0, v107
	v_lshl_add_u64 v[112:113], s[46:47], 0, v[112:113]
	v_pk_mul_f32 v[108:109], v[108:109], v[108:109]
	v_pk_mul_f32 v[110:111], v[104:105], v[104:105]
	v_pk_mul_f32 v[116:117], v[106:107], v[106:107]
	v_max_f32_e32 v96, v96, v96
	v_max_f32_e32 v97, v97, v97
	v_cvt_pk_bf16_f32 v104, v108, v109
	v_cvt_pk_bf16_f32 v105, v110, v111
	v_cvt_pk_bf16_f32 v106, v114, v115
	v_cvt_pk_bf16_f32 v107, v116, v117
	v_lshl_add_u64 v[108:109], v[112:113], 0, v[126:127]
	v_max_f32_e32 v96, 0, v96
	v_max_f32_e32 v97, 0, v97
	global_store_dwordx4 v[108:109], v[104:107], off sc1
	v_max_f32_e32 v100, v100, v100
	v_max_f32_e32 v101, v101, v101
	v_pk_mul_f32 v[104:105], v[96:97], v[96:97]
	v_max_f32_e32 v97, v98, v98
	v_max_f32_e32 v96, v102, v102
	v_max_f32_e32 v98, 0, v97
	v_max_f32_e32 v97, v103, v103
	v_max_f32_e32 v99, v99, v99
	v_max_f32_e32 v100, 0, v100
	v_max_f32_e32 v101, 0, v101
	v_max_f32_e32 v96, 0, v96
	v_max_f32_e32 v97, 0, v97
	v_max_f32_e32 v99, 0, v99
	v_pk_mul_f32 v[100:101], v[100:101], v[100:101]
	v_pk_mul_f32 v[102:103], v[96:97], v[96:97]
	v_pk_mul_f32 v[106:107], v[98:99], v[98:99]
	v_max_f32_e32 v88, v88, v88
	v_max_f32_e32 v89, v89, v89
	v_cvt_pk_bf16_f32 v96, v100, v101
	v_cvt_pk_bf16_f32 v97, v102, v103
	v_cvt_pk_bf16_f32 v98, v104, v105
	v_cvt_pk_bf16_f32 v99, v106, v107
	v_max_f32_e32 v88, 0, v88
	v_max_f32_e32 v89, 0, v89
	global_store_dwordx4 v[108:109], v[96:99], off offset:256 sc1
	v_max_f32_e32 v92, v92, v92
	v_max_f32_e32 v93, v93, v93
	v_or_b32_e32 v96, 32, v154
	v_pk_mul_f32 v[98:99], v[88:89], v[88:89]
	v_max_f32_e32 v89, v90, v90
	v_ashrrev_i32_e32 v97, 31, v96
	v_max_f32_e32 v88, v94, v94
	v_max_f32_e32 v90, 0, v89
	v_max_f32_e32 v89, v95, v95
	v_max_f32_e32 v91, v91, v91
	v_lshlrev_b64 v[96:97], 13, v[96:97]
	v_max_f32_e32 v92, 0, v92
	v_max_f32_e32 v93, 0, v93
	v_max_f32_e32 v88, 0, v88
	v_max_f32_e32 v89, 0, v89
	v_max_f32_e32 v91, 0, v91
	v_lshl_add_u64 v[96:97], s[46:47], 0, v[96:97]
	v_pk_mul_f32 v[92:93], v[92:93], v[92:93]
	v_pk_mul_f32 v[94:95], v[88:89], v[88:89]
	v_pk_mul_f32 v[100:101], v[90:91], v[90:91]
	v_max_f32_e32 v80, v80, v80
	v_max_f32_e32 v81, v81, v81
	v_cvt_pk_bf16_f32 v88, v92, v93
	v_cvt_pk_bf16_f32 v89, v94, v95
	v_cvt_pk_bf16_f32 v90, v98, v99
	v_cvt_pk_bf16_f32 v91, v100, v101
	v_lshl_add_u64 v[92:93], v[96:97], 0, v[126:127]
	v_max_f32_e32 v80, 0, v80
	v_max_f32_e32 v81, 0, v81
	global_store_dwordx4 v[92:93], v[88:91], off sc1
	v_max_f32_e32 v84, v84, v84
	v_max_f32_e32 v85, v85, v85
	v_pk_mul_f32 v[88:89], v[80:81], v[80:81]
	v_max_f32_e32 v81, v82, v82
	v_max_f32_e32 v80, v86, v86
	v_max_f32_e32 v82, 0, v81
	v_max_f32_e32 v81, v87, v87
	v_max_f32_e32 v83, v83, v83
	v_max_f32_e32 v84, 0, v84
	v_max_f32_e32 v85, 0, v85
	v_max_f32_e32 v80, 0, v80
	v_max_f32_e32 v81, 0, v81
	v_max_f32_e32 v83, 0, v83
	v_pk_mul_f32 v[84:85], v[84:85], v[84:85]
	v_pk_mul_f32 v[86:87], v[80:81], v[80:81]
	v_pk_mul_f32 v[90:91], v[82:83], v[82:83]
	v_max_f32_e32 v72, v72, v72
	v_max_f32_e32 v73, v73, v73
	v_cvt_pk_bf16_f32 v80, v84, v85
	v_cvt_pk_bf16_f32 v81, v86, v87
	v_cvt_pk_bf16_f32 v82, v88, v89
	v_cvt_pk_bf16_f32 v83, v90, v91
	v_max_f32_e32 v72, 0, v72
	v_max_f32_e32 v73, 0, v73
	global_store_dwordx4 v[92:93], v[80:83], off offset:256 sc1
	v_max_f32_e32 v76, v76, v76
	v_max_f32_e32 v77, v77, v77
	v_or_b32_e32 v80, 48, v154
	v_pk_mul_f32 v[82:83], v[72:73], v[72:73]
	v_max_f32_e32 v73, v74, v74
	v_ashrrev_i32_e32 v81, 31, v80
	v_max_f32_e32 v72, v78, v78
	v_max_f32_e32 v74, 0, v73
	v_max_f32_e32 v73, v79, v79
	v_max_f32_e32 v75, v75, v75
	v_lshlrev_b64 v[80:81], 13, v[80:81]
	v_max_f32_e32 v76, 0, v76
	v_max_f32_e32 v77, 0, v77
	v_max_f32_e32 v72, 0, v72
	v_max_f32_e32 v73, 0, v73
	v_max_f32_e32 v75, 0, v75
	v_lshl_add_u64 v[80:81], s[46:47], 0, v[80:81]
	v_pk_mul_f32 v[76:77], v[76:77], v[76:77]
	v_pk_mul_f32 v[78:79], v[72:73], v[72:73]
	v_pk_mul_f32 v[84:85], v[74:75], v[74:75]
	v_max_f32_e32 v64, v64, v64
	v_max_f32_e32 v65, v65, v65
	v_cvt_pk_bf16_f32 v72, v76, v77
	v_cvt_pk_bf16_f32 v73, v78, v79
	v_cvt_pk_bf16_f32 v74, v82, v83
	v_cvt_pk_bf16_f32 v75, v84, v85
	v_lshl_add_u64 v[76:77], v[80:81], 0, v[126:127]
	v_max_f32_e32 v64, 0, v64
	v_max_f32_e32 v65, 0, v65
	global_store_dwordx4 v[76:77], v[72:75], off sc1
	v_max_f32_e32 v68, v68, v68
	v_max_f32_e32 v69, v69, v69
	v_pk_mul_f32 v[72:73], v[64:65], v[64:65]
	v_max_f32_e32 v65, v66, v66
	v_max_f32_e32 v64, v70, v70
	v_max_f32_e32 v66, 0, v65
	v_max_f32_e32 v65, v71, v71
	v_max_f32_e32 v67, v67, v67
	v_max_f32_e32 v68, 0, v68
	v_max_f32_e32 v69, 0, v69
	v_max_f32_e32 v64, 0, v64
	v_max_f32_e32 v65, 0, v65
	v_max_f32_e32 v67, 0, v67
	v_pk_mul_f32 v[68:69], v[68:69], v[68:69]
	v_pk_mul_f32 v[70:71], v[64:65], v[64:65]
	v_pk_mul_f32 v[74:75], v[66:67], v[66:67]
	v_max_f32_e32 v56, v56, v56
	v_max_f32_e32 v57, v57, v57
	v_cvt_pk_bf16_f32 v64, v68, v69
	v_cvt_pk_bf16_f32 v65, v70, v71
	v_cvt_pk_bf16_f32 v66, v72, v73
	v_cvt_pk_bf16_f32 v67, v74, v75
	v_max_f32_e32 v56, 0, v56
	v_max_f32_e32 v57, 0, v57
	global_store_dwordx4 v[76:77], v[64:67], off offset:256 sc1
	v_max_f32_e32 v60, v60, v60
	v_max_f32_e32 v61, v61, v61
	v_pk_mul_f32 v[64:65], v[56:57], v[56:57]
	v_max_f32_e32 v57, v58, v58
	v_max_f32_e32 v56, v62, v62
	v_max_f32_e32 v58, 0, v57
	v_max_f32_e32 v57, v63, v63
	v_max_f32_e32 v56, 0, v56
	v_max_f32_e32 v57, 0, v57
	v_max_f32_e32 v59, v59, v59
	v_max_f32_e32 v60, 0, v60
	v_max_f32_e32 v61, 0, v61
	v_max_f32_e32 v59, 0, v59
	v_pk_mul_f32 v[62:63], v[56:57], v[56:57]
	v_pk_mul_f32 v[60:61], v[60:61], v[60:61]
	v_pk_mul_f32 v[66:67], v[58:59], v[58:59]
	v_cvt_pk_bf16_f32 v57, v62, v63
	v_add_co_u32_e32 v62, vcc, s70, v120
	v_max_f32_e32 v48, v48, v48
	v_max_f32_e32 v49, v49, v49
	v_cvt_pk_bf16_f32 v56, v60, v61
	v_cvt_pk_bf16_f32 v58, v64, v65
	v_cvt_pk_bf16_f32 v59, v66, v67
	v_addc_co_u32_e32 v63, vcc, 0, v121, vcc
	v_max_f32_e32 v48, 0, v48
	v_max_f32_e32 v49, 0, v49
	global_store_dwordx4 v[62:63], v[56:59], off sc1
	v_max_f32_e32 v52, v52, v52
	v_max_f32_e32 v53, v53, v53
	v_pk_mul_f32 v[56:57], v[48:49], v[48:49]
	v_max_f32_e32 v49, v50, v50
	v_max_f32_e32 v48, v54, v54
	v_max_f32_e32 v50, 0, v49
	v_max_f32_e32 v49, v55, v55
	v_max_f32_e32 v51, v51, v51
	v_max_f32_e32 v52, 0, v52
	v_max_f32_e32 v53, 0, v53
	v_max_f32_e32 v48, 0, v48
	v_max_f32_e32 v49, 0, v49
	v_max_f32_e32 v51, 0, v51
	v_pk_mul_f32 v[52:53], v[52:53], v[52:53]
	v_pk_mul_f32 v[54:55], v[48:49], v[48:49]
	v_pk_mul_f32 v[58:59], v[50:51], v[50:51]
	v_max_f32_e32 v40, v40, v40
	v_max_f32_e32 v41, v41, v41
	v_lshl_add_u64 v[60:61], v[120:121], 0, s[10:11]
	v_cvt_pk_bf16_f32 v48, v52, v53
	v_cvt_pk_bf16_f32 v49, v54, v55
	v_cvt_pk_bf16_f32 v50, v56, v57
	v_cvt_pk_bf16_f32 v51, v58, v59
	v_max_f32_e32 v40, 0, v40
	v_max_f32_e32 v41, 0, v41
	global_store_dwordx4 v[60:61], v[48:51], off offset:256 sc1
	v_max_f32_e32 v44, v44, v44
	v_max_f32_e32 v45, v45, v45
	v_pk_mul_f32 v[48:49], v[40:41], v[40:41]
	v_max_f32_e32 v41, v42, v42
	v_max_f32_e32 v40, v46, v46
	v_max_f32_e32 v42, 0, v41
	v_max_f32_e32 v41, v47, v47
	v_max_f32_e32 v40, 0, v40
	v_max_f32_e32 v41, 0, v41
	v_max_f32_e32 v43, v43, v43
	v_max_f32_e32 v44, 0, v44
	v_max_f32_e32 v45, 0, v45
	v_max_f32_e32 v43, 0, v43
	v_pk_mul_f32 v[46:47], v[40:41], v[40:41]
	v_pk_mul_f32 v[44:45], v[44:45], v[44:45]
	v_pk_mul_f32 v[50:51], v[42:43], v[42:43]
	v_cvt_pk_bf16_f32 v41, v46, v47
	v_add_co_u32_e32 v46, vcc, s71, v120
	v_max_f32_e32 v32, v32, v32
	v_max_f32_e32 v33, v33, v33
	v_cvt_pk_bf16_f32 v40, v44, v45
	v_cvt_pk_bf16_f32 v42, v48, v49
	v_cvt_pk_bf16_f32 v43, v50, v51
	v_addc_co_u32_e32 v47, vcc, 0, v121, vcc
	v_max_f32_e32 v32, 0, v32
	v_max_f32_e32 v33, 0, v33
	global_store_dwordx4 v[46:47], v[40:43], off sc1
	v_max_f32_e32 v36, v36, v36
	v_max_f32_e32 v37, v37, v37
	v_pk_mul_f32 v[40:41], v[32:33], v[32:33]
	v_max_f32_e32 v33, v34, v34
	v_max_f32_e32 v32, v38, v38
	v_max_f32_e32 v34, 0, v33
	v_max_f32_e32 v33, v39, v39
	v_max_f32_e32 v35, v35, v35
	v_max_f32_e32 v36, 0, v36
	v_max_f32_e32 v37, 0, v37
	v_max_f32_e32 v32, 0, v32
	v_max_f32_e32 v33, 0, v33
	v_max_f32_e32 v35, 0, v35
	v_pk_mul_f32 v[36:37], v[36:37], v[36:37]
	v_pk_mul_f32 v[38:39], v[32:33], v[32:33]
	v_pk_mul_f32 v[42:43], v[34:35], v[34:35]
	v_max_f32_e32 v24, v24, v24
	v_max_f32_e32 v25, v25, v25
	v_lshl_add_u64 v[44:45], v[120:121], 0, s[12:13]
	v_cvt_pk_bf16_f32 v32, v36, v37
	v_cvt_pk_bf16_f32 v33, v38, v39
	v_cvt_pk_bf16_f32 v34, v40, v41
	v_cvt_pk_bf16_f32 v35, v42, v43
	v_max_f32_e32 v24, 0, v24
	v_max_f32_e32 v25, 0, v25
	global_store_dwordx4 v[44:45], v[32:35], off offset:256 sc1
	v_max_f32_e32 v28, v28, v28
	v_max_f32_e32 v29, v29, v29
	v_pk_mul_f32 v[32:33], v[24:25], v[24:25]
	v_max_f32_e32 v25, v26, v26
	v_max_f32_e32 v24, v30, v30
	v_max_f32_e32 v26, 0, v25
	v_max_f32_e32 v25, v31, v31
	v_max_f32_e32 v24, 0, v24
	v_max_f32_e32 v25, 0, v25
	v_max_f32_e32 v27, v27, v27
	v_max_f32_e32 v28, 0, v28
	v_max_f32_e32 v29, 0, v29
	v_max_f32_e32 v27, 0, v27
	v_pk_mul_f32 v[30:31], v[24:25], v[24:25]
	v_pk_mul_f32 v[28:29], v[28:29], v[28:29]
	v_pk_mul_f32 v[34:35], v[26:27], v[26:27]
	v_cvt_pk_bf16_f32 v25, v30, v31
	v_add_co_u32_e32 v30, vcc, s72, v120
	v_max_f32_e32 v16, v16, v16
	v_max_f32_e32 v17, v17, v17
	v_cvt_pk_bf16_f32 v24, v28, v29
	v_cvt_pk_bf16_f32 v26, v32, v33
	v_cvt_pk_bf16_f32 v27, v34, v35
	v_addc_co_u32_e32 v31, vcc, 0, v121, vcc
	v_max_f32_e32 v16, 0, v16
	v_max_f32_e32 v17, 0, v17
	global_store_dwordx4 v[30:31], v[24:27], off sc1
	v_max_f32_e32 v20, v20, v20
	v_max_f32_e32 v21, v21, v21
	v_pk_mul_f32 v[24:25], v[16:17], v[16:17]
	v_max_f32_e32 v17, v18, v18
	v_max_f32_e32 v16, v22, v22
	v_max_f32_e32 v18, 0, v17
	v_max_f32_e32 v17, v23, v23
	v_max_f32_e32 v19, v19, v19
	v_max_f32_e32 v20, 0, v20
	v_max_f32_e32 v21, 0, v21
	v_max_f32_e32 v16, 0, v16
	v_max_f32_e32 v17, 0, v17
	v_max_f32_e32 v19, 0, v19
	v_pk_mul_f32 v[20:21], v[20:21], v[20:21]
	v_pk_mul_f32 v[22:23], v[16:17], v[16:17]
	v_pk_mul_f32 v[26:27], v[18:19], v[18:19]
	v_max_f32_e32 v8, v8, v8
	v_max_f32_e32 v9, v9, v9
	v_lshl_add_u64 v[28:29], v[120:121], 0, s[14:15]
	v_cvt_pk_bf16_f32 v16, v20, v21
	v_cvt_pk_bf16_f32 v17, v22, v23
	v_cvt_pk_bf16_f32 v18, v24, v25
	v_cvt_pk_bf16_f32 v19, v26, v27
	v_max_f32_e32 v8, 0, v8
	v_max_f32_e32 v9, 0, v9
	global_store_dwordx4 v[28:29], v[16:19], off offset:256 sc1
	v_max_f32_e32 v12, v12, v12
	v_max_f32_e32 v13, v13, v13
	v_pk_mul_f32 v[16:17], v[8:9], v[8:9]
	v_max_f32_e32 v9, v10, v10
	v_max_f32_e32 v8, v14, v14
	v_max_f32_e32 v10, 0, v9
	v_max_f32_e32 v9, v15, v15
	v_max_f32_e32 v8, 0, v8
	v_max_f32_e32 v9, 0, v9
	v_max_f32_e32 v11, v11, v11
	v_max_f32_e32 v12, 0, v12
	v_max_f32_e32 v13, 0, v13
	v_max_f32_e32 v11, 0, v11
	v_pk_mul_f32 v[14:15], v[8:9], v[8:9]
	v_pk_mul_f32 v[12:13], v[12:13], v[12:13]
	v_pk_mul_f32 v[18:19], v[10:11], v[10:11]
	v_cvt_pk_bf16_f32 v9, v14, v15
	v_add_co_u32_e32 v14, vcc, s73, v120
	v_max_f32_e32 v0, v0, v0
	v_max_f32_e32 v1, v1, v1
	v_cvt_pk_bf16_f32 v8, v12, v13
	v_cvt_pk_bf16_f32 v10, v16, v17
	v_cvt_pk_bf16_f32 v11, v18, v19
	v_addc_co_u32_e32 v15, vcc, 0, v121, vcc
	v_max_f32_e32 v0, 0, v0
	v_max_f32_e32 v1, 0, v1
	global_store_dwordx4 v[14:15], v[8:11], off sc1
	v_max_f32_e32 v4, v4, v4
	v_max_f32_e32 v5, v5, v5
	v_pk_mul_f32 v[8:9], v[0:1], v[0:1]
	v_max_f32_e32 v1, v2, v2
	v_max_f32_e32 v0, v6, v6
	v_max_f32_e32 v2, 0, v1
	v_max_f32_e32 v1, v7, v7
	v_max_f32_e32 v3, v3, v3
	v_max_f32_e32 v4, 0, v4
	v_max_f32_e32 v5, 0, v5
	v_max_f32_e32 v0, 0, v0
	v_max_f32_e32 v1, 0, v1
	v_max_f32_e32 v3, 0, v3
	v_pk_mul_f32 v[4:5], v[4:5], v[4:5]
	v_pk_mul_f32 v[6:7], v[0:1], v[0:1]
	v_pk_mul_f32 v[10:11], v[2:3], v[2:3]
	v_lshl_add_u64 v[12:13], v[120:121], 0, s[16:17]
	v_cvt_pk_bf16_f32 v0, v4, v5
	v_cvt_pk_bf16_f32 v1, v6, v7
	v_cvt_pk_bf16_f32 v2, v8, v9
	v_cvt_pk_bf16_f32 v3, v10, v11
	s_and_b64 vcc, exec, s[4:5]
	s_mov_b32 s74, s18
	s_mov_b32 s30, s20
	s_mov_b64 s[36:37], s[28:29]
	s_mov_b64 s[34:35], s[26:27]
	global_store_dwordx4 v[12:13], v[0:3], off offset:256 sc1
	s_cbranch_vccz .LBB0_1284
	s_waitcnt vmcnt(0)
	s_cmpk_gt_u32 s40, 0xff
	s_cbranch_scc1 .LBB0_1295
	s_barrier

.LBB0_1310:
	ds_read_b128 v[154:157], v151
	ds_read_b128 v[158:161], v151 offset:1024
	ds_read_b128 v[162:165], v151 offset:2048
	ds_read_b128 v[166:169], v151 offset:3072
	s_add_u32 s38, s36, 0xfffc0080
	s_addc_u32 s39, s37, -1
	s_cmp_eq_u32 s77, 12
	s_cselect_b32 s41, s27, s39
	s_cselect_b32 s40, s73, s38
	s_cselect_b32 s39, s21, s76
	s_cselect_b32 s38, s74, s75
	v_lshl_add_u64 v[202:203], s[36:37], 0, v[138:139]
	s_add_i32 m0, s35, 0xc000
	ds_read_b128 v[170:173], v152
	ds_read_b128 v[174:177], v152 offset:1024
	ds_read_b128 v[178:181], v152 offset:2048
	ds_read_b128 v[182:185], v152 offset:3072
	ds_read_b128 v[186:189], v152 offset:4096
	ds_read_b128 v[190:193], v152 offset:5120
	ds_read_b128 v[194:197], v152 offset:6144
	ds_read_b128 v[198:201], v152 offset:7168
	global_load_lds_dwordx4 v[202:203], off
	v_lshl_add_u64 v[202:203], s[36:37], 0, v[140:141]
	s_add_i32 m0, s35, 0xe000
	s_nop 0
	global_load_lds_dwordx4 v[202:203], off
	s_waitcnt lgkmcnt(8)
	s_barrier
	s_waitcnt lgkmcnt(0)
	s_setprio 1
	s_waitcnt lgkmcnt(0)
	v_mfma_f32_16x16x32_bf16 v[124:127], v[154:157], v[170:173], v[124:127]
	v_mfma_f32_16x16x32_bf16 v[120:123], v[162:165], v[170:173], v[120:123]
	v_mfma_f32_16x16x32_bf16 v[108:111], v[154:157], v[178:181], v[108:111]
	v_mfma_f32_16x16x32_bf16 v[104:107], v[162:165], v[178:181], v[104:107]
	v_mfma_f32_16x16x32_bf16 v[92:95], v[154:157], v[186:189], v[92:95]
	v_mfma_f32_16x16x32_bf16 v[88:91], v[162:165], v[186:189], v[88:91]
	v_mfma_f32_16x16x32_bf16 v[76:79], v[154:157], v[194:197], v[76:79]
	v_mfma_f32_16x16x32_bf16 v[72:75], v[162:165], v[194:197], v[72:75]
	v_mfma_f32_16x16x32_bf16 v[124:127], v[158:161], v[174:177], v[124:127]
	v_mfma_f32_16x16x32_bf16 v[120:123], v[166:169], v[174:177], v[120:123]
	v_mfma_f32_16x16x32_bf16 v[108:111], v[158:161], v[182:185], v[108:111]
	v_mfma_f32_16x16x32_bf16 v[104:107], v[166:169], v[182:185], v[104:107]
	v_mfma_f32_16x16x32_bf16 v[92:95], v[158:161], v[190:193], v[92:95]
	v_mfma_f32_16x16x32_bf16 v[88:91], v[166:169], v[190:193], v[88:91]
	v_mfma_f32_16x16x32_bf16 v[76:79], v[158:161], v[198:201], v[76:79]
	v_mfma_f32_16x16x32_bf16 v[72:75], v[166:169], v[198:201], v[72:75]
	s_setprio 0
	s_barrier
	s_add_i32 s78, s62, s52
	v_lshl_add_u64 v[218:219], s[38:39], 0, v[132:133]
	s_mov_b32 m0, s78
	ds_read_b128 v[202:205], v153
	ds_read_b128 v[206:209], v153 offset:1024
	ds_read_b128 v[210:213], v153 offset:2048
	ds_read_b128 v[214:217], v153 offset:3072
	global_load_lds_dwordx4 v[218:219], off
	v_lshl_add_u64 v[220:221], s[38:39], 0, v[136:137]
	s_add_i32 m0, s78, 0x2000
	s_nop 0
	global_load_lds_dwordx4 v[220:221], off
	s_barrier
	s_waitcnt lgkmcnt(0)
	s_setprio 1
	s_waitcnt lgkmcnt(0)
	v_mfma_f32_16x16x32_bf16 v[116:119], v[202:205], v[170:173], v[116:119]
	v_mfma_f32_16x16x32_bf16 v[112:115], v[210:213], v[170:173], v[112:115]
	v_mfma_f32_16x16x32_bf16 v[100:103], v[202:205], v[178:181], v[100:103]
	v_mfma_f32_16x16x32_bf16 v[96:99], v[210:213], v[178:181], v[96:99]
	v_mfma_f32_16x16x32_bf16 v[84:87], v[202:205], v[186:189], v[84:87]
	v_mfma_f32_16x16x32_bf16 v[80:83], v[210:213], v[186:189], v[80:83]
	v_mfma_f32_16x16x32_bf16 v[68:71], v[202:205], v[194:197], v[68:71]
	v_mfma_f32_16x16x32_bf16 v[64:67], v[210:213], v[194:197], v[64:67]
	v_mfma_f32_16x16x32_bf16 v[116:119], v[206:209], v[174:177], v[116:119]
	v_mfma_f32_16x16x32_bf16 v[112:115], v[214:217], v[174:177], v[112:115]
	v_mfma_f32_16x16x32_bf16 v[100:103], v[206:209], v[182:185], v[100:103]
	v_mfma_f32_16x16x32_bf16 v[96:99], v[214:217], v[182:185], v[96:99]
	v_mfma_f32_16x16x32_bf16 v[84:87], v[206:209], v[190:193], v[84:87]
	v_mfma_f32_16x16x32_bf16 v[80:83], v[214:217], v[190:193], v[80:83]
	v_mfma_f32_16x16x32_bf16 v[68:71], v[206:209], v[198:201], v[68:71]
	v_mfma_f32_16x16x32_bf16 v[64:67], v[214:217], v[198:201], v[64:67]
	s_setprio 0
	s_mov_b32 m0, s35
	v_lshl_add_u64 v[222:223], s[40:41], 0, v[130:131]
	s_barrier
	ds_read_b128 v[170:173], v152 offset:16384
	ds_read_b128 v[174:177], v152 offset:17408
	ds_read_b128 v[178:181], v152 offset:18432
	ds_read_b128 v[182:185], v152 offset:19456
	ds_read_b128 v[186:189], v152 offset:20480
	ds_read_b128 v[190:193], v152 offset:21504
	ds_read_b128 v[194:197], v152 offset:22528
	ds_read_b128 v[198:201], v152 offset:23552
	global_load_lds_dwordx4 v[222:223], off
	v_lshl_add_u64 v[224:225], s[40:41], 0, v[134:135]
	s_mov_b32 m0, s53
	s_nop 0
	global_load_lds_dwordx4 v[224:225], off
	s_barrier
	s_waitcnt lgkmcnt(0)
	s_setprio 1
	s_waitcnt lgkmcnt(0)
	v_mfma_f32_16x16x32_bf16 v[60:63], v[154:157], v[170:173], v[60:63]
	v_mfma_f32_16x16x32_bf16 v[56:59], v[162:165], v[170:173], v[56:59]
	v_mfma_f32_16x16x32_bf16 v[44:47], v[154:157], v[178:181], v[44:47]
	v_mfma_f32_16x16x32_bf16 v[40:43], v[162:165], v[178:181], v[40:43]
	v_mfma_f32_16x16x32_bf16 v[28:31], v[154:157], v[186:189], v[28:31]
	v_mfma_f32_16x16x32_bf16 v[24:27], v[162:165], v[186:189], v[24:27]
	v_mfma_f32_16x16x32_bf16 v[12:15], v[154:157], v[194:197], v[12:15]
	v_mfma_f32_16x16x32_bf16 v[8:11], v[162:165], v[194:197], v[8:11]
	v_mfma_f32_16x16x32_bf16 v[60:63], v[158:161], v[174:177], v[60:63]
	v_mfma_f32_16x16x32_bf16 v[56:59], v[166:169], v[174:177], v[56:59]
	v_mfma_f32_16x16x32_bf16 v[44:47], v[158:161], v[182:185], v[44:47]
	v_mfma_f32_16x16x32_bf16 v[40:43], v[166:169], v[182:185], v[40:43]
	v_mfma_f32_16x16x32_bf16 v[28:31], v[158:161], v[190:193], v[28:31]
	v_mfma_f32_16x16x32_bf16 v[24:27], v[166:169], v[190:193], v[24:27]
	v_mfma_f32_16x16x32_bf16 v[12:15], v[158:161], v[198:201], v[12:15]
	v_mfma_f32_16x16x32_bf16 v[8:11], v[166:169], v[198:201], v[8:11]
	s_setprio 0
	s_barrier
	s_add_u32 s78, s38, 0x40000
	s_addc_u32 s79, s39, 0
	s_add_i32 s80, s63, s52
	v_lshl_add_u64 v[154:155], s[78:79], 0, v[132:133]
	s_mov_b32 m0, s80
	s_nop 0
	global_load_lds_dwordx4 v[154:155], off
	v_lshl_add_u64 v[154:155], s[78:79], 0, v[136:137]
	s_add_i32 m0, s80, 0x2000
	s_nop 0
	global_load_lds_dwordx4 v[154:155], off
	s_waitcnt vmcnt(6)
	s_barrier
	s_setprio 1
	v_mfma_f32_16x16x32_bf16 v[52:55], v[202:205], v[170:173], v[52:55]
	v_mfma_f32_16x16x32_bf16 v[48:51], v[210:213], v[170:173], v[48:51]
	v_mfma_f32_16x16x32_bf16 v[36:39], v[202:205], v[178:181], v[36:39]
	v_mfma_f32_16x16x32_bf16 v[32:35], v[210:213], v[178:181], v[32:35]
	v_mfma_f32_16x16x32_bf16 v[20:23], v[202:205], v[186:189], v[20:23]
	v_mfma_f32_16x16x32_bf16 v[16:19], v[210:213], v[186:189], v[16:19]
	v_mfma_f32_16x16x32_bf16 v[4:7], v[202:205], v[194:197], v[4:7]
	v_mfma_f32_16x16x32_bf16 v[0:3], v[210:213], v[194:197], v[0:3]
	v_mfma_f32_16x16x32_bf16 v[52:55], v[206:209], v[174:177], v[52:55]
	v_mfma_f32_16x16x32_bf16 v[48:51], v[214:217], v[174:177], v[48:51]
	v_mfma_f32_16x16x32_bf16 v[36:39], v[206:209], v[182:185], v[36:39]
	v_mfma_f32_16x16x32_bf16 v[32:35], v[214:217], v[182:185], v[32:35]
	v_mfma_f32_16x16x32_bf16 v[20:23], v[206:209], v[190:193], v[20:23]
	v_mfma_f32_16x16x32_bf16 v[16:19], v[214:217], v[190:193], v[16:19]
	v_mfma_f32_16x16x32_bf16 v[4:7], v[206:209], v[198:201], v[4:7]
	v_mfma_f32_16x16x32_bf16 v[0:3], v[214:217], v[198:201], v[0:3]
	s_setprio 0
	s_add_i32 s78, 0, 0x18000
	v_add_u32_e32 v166, s78, v149
	s_barrier
	ds_read_b128 v[154:157], v166
	ds_read_b128 v[158:161], v166 offset:1024
	ds_read_b128 v[162:165], v166 offset:2048
	ds_read_b128 v[166:169], v166 offset:3072
	s_add_u32 s40, s40, 0x40000
	s_addc_u32 s41, s41, 0
	s_mov_b32 m0, s54
	v_lshl_add_u64 v[202:203], s[40:41], 0, v[130:131]
	ds_read_b128 v[170:173], v152 offset:32768
	ds_read_b128 v[174:177], v152 offset:33792
	ds_read_b128 v[178:181], v152 offset:34816
	ds_read_b128 v[182:185], v152 offset:35840
	ds_read_b128 v[186:189], v152 offset:36864
	ds_read_b128 v[190:193], v152 offset:37888
	ds_read_b128 v[194:197], v152 offset:38912
	ds_read_b128 v[198:201], v152 offset:39936
	global_load_lds_dwordx4 v[202:203], off
	v_lshl_add_u64 v[202:203], s[40:41], 0, v[134:135]
	s_mov_b32 m0, s55
	s_nop 0
	global_load_lds_dwordx4 v[202:203], off
	s_waitcnt lgkmcnt(8)
	s_barrier
	s_waitcnt lgkmcnt(0)
	s_setprio 1
	s_waitcnt lgkmcnt(0)
	v_mfma_f32_16x16x32_bf16 v[124:127], v[154:157], v[170:173], v[124:127]
	v_mfma_f32_16x16x32_bf16 v[120:123], v[162:165], v[170:173], v[120:123]
	v_mfma_f32_16x16x32_bf16 v[108:111], v[154:157], v[178:181], v[108:111]
	v_mfma_f32_16x16x32_bf16 v[104:107], v[162:165], v[178:181], v[104:107]
	v_mfma_f32_16x16x32_bf16 v[92:95], v[154:157], v[186:189], v[92:95]
	v_mfma_f32_16x16x32_bf16 v[88:91], v[162:165], v[186:189], v[88:91]
	v_mfma_f32_16x16x32_bf16 v[76:79], v[154:157], v[194:197], v[76:79]
	v_mfma_f32_16x16x32_bf16 v[72:75], v[162:165], v[194:197], v[72:75]
	v_mfma_f32_16x16x32_bf16 v[124:127], v[158:161], v[174:177], v[124:127]
	v_mfma_f32_16x16x32_bf16 v[120:123], v[166:169], v[174:177], v[120:123]
	v_mfma_f32_16x16x32_bf16 v[108:111], v[158:161], v[182:185], v[108:111]
	v_mfma_f32_16x16x32_bf16 v[104:107], v[166:169], v[182:185], v[104:107]
	v_mfma_f32_16x16x32_bf16 v[92:95], v[158:161], v[190:193], v[92:95]
	v_mfma_f32_16x16x32_bf16 v[88:91], v[166:169], v[190:193], v[88:91]
	v_mfma_f32_16x16x32_bf16 v[76:79], v[158:161], v[198:201], v[76:79]
	v_mfma_f32_16x16x32_bf16 v[72:75], v[166:169], v[198:201], v[72:75]
	s_setprio 0
	s_barrier
	s_add_i32 s40, 0, 0x1c000
	s_add_i32 s41, s78, s52
	v_add_u32_e32 v214, s40, v149
	v_lshl_add_u64 v[218:219], v[218:219], 0, s[10:11]
	s_mov_b32 m0, s41
	ds_read_b128 v[202:205], v214
	ds_read_b128 v[206:209], v214 offset:1024
	ds_read_b128 v[210:213], v214 offset:2048
	ds_read_b128 v[214:217], v214 offset:3072
	global_load_lds_dwordx4 v[218:219], off
	v_lshl_add_u64 v[218:219], v[220:221], 0, s[10:11]
	s_add_i32 m0, s41, 0x2000
	s_nop 0
	global_load_lds_dwordx4 v[218:219], off
	s_barrier
	s_waitcnt lgkmcnt(0)
	s_setprio 1
	s_waitcnt lgkmcnt(0)
	v_mfma_f32_16x16x32_bf16 v[116:119], v[202:205], v[170:173], v[116:119]
	v_mfma_f32_16x16x32_bf16 v[112:115], v[210:213], v[170:173], v[112:115]
	v_mfma_f32_16x16x32_bf16 v[100:103], v[202:205], v[178:181], v[100:103]
	v_mfma_f32_16x16x32_bf16 v[96:99], v[210:213], v[178:181], v[96:99]
	v_mfma_f32_16x16x32_bf16 v[84:87], v[202:205], v[186:189], v[84:87]
	v_mfma_f32_16x16x32_bf16 v[80:83], v[210:213], v[186:189], v[80:83]
	v_mfma_f32_16x16x32_bf16 v[68:71], v[202:205], v[194:197], v[68:71]
	v_mfma_f32_16x16x32_bf16 v[64:67], v[210:213], v[194:197], v[64:67]
	v_mfma_f32_16x16x32_bf16 v[116:119], v[206:209], v[174:177], v[116:119]
	v_mfma_f32_16x16x32_bf16 v[112:115], v[214:217], v[174:177], v[112:115]
	v_mfma_f32_16x16x32_bf16 v[100:103], v[206:209], v[182:185], v[100:103]
	v_mfma_f32_16x16x32_bf16 v[96:99], v[214:217], v[182:185], v[96:99]
	v_mfma_f32_16x16x32_bf16 v[84:87], v[206:209], v[190:193], v[84:87]
	v_mfma_f32_16x16x32_bf16 v[80:83], v[214:217], v[190:193], v[80:83]
	v_mfma_f32_16x16x32_bf16 v[68:71], v[206:209], v[198:201], v[68:71]
	v_mfma_f32_16x16x32_bf16 v[64:67], v[214:217], v[198:201], v[64:67]
	s_setprio 0
	s_mov_b32 m0, s57
	v_lshl_add_u64 v[218:219], v[222:223], 0, s[10:11]
	s_barrier
	ds_read_b128 v[170:173], v152 offset:49152
	ds_read_b128 v[174:177], v152 offset:50176
	ds_read_b128 v[178:181], v152 offset:51200
	ds_read_b128 v[182:185], v152 offset:52224
	ds_read_b128 v[186:189], v152 offset:53248
	ds_read_b128 v[190:193], v152 offset:54272
	ds_read_b128 v[194:197], v152 offset:55296
	ds_read_b128 v[198:201], v152 offset:56320
	global_load_lds_dwordx4 v[218:219], off
	v_lshl_add_u64 v[218:219], v[224:225], 0, s[10:11]
	s_mov_b32 m0, s60
	s_nop 0
	global_load_lds_dwordx4 v[218:219], off
	s_barrier
	s_waitcnt lgkmcnt(0)
	s_setprio 1
	s_waitcnt lgkmcnt(0)
	v_mfma_f32_16x16x32_bf16 v[60:63], v[154:157], v[170:173], v[60:63]
	v_mfma_f32_16x16x32_bf16 v[56:59], v[162:165], v[170:173], v[56:59]
	v_mfma_f32_16x16x32_bf16 v[44:47], v[154:157], v[178:181], v[44:47]
	v_mfma_f32_16x16x32_bf16 v[40:43], v[162:165], v[178:181], v[40:43]
	v_mfma_f32_16x16x32_bf16 v[28:31], v[154:157], v[186:189], v[28:31]
	v_mfma_f32_16x16x32_bf16 v[24:27], v[162:165], v[186:189], v[24:27]
	v_mfma_f32_16x16x32_bf16 v[12:15], v[154:157], v[194:197], v[12:15]
	v_mfma_f32_16x16x32_bf16 v[8:11], v[162:165], v[194:197], v[8:11]
	v_mfma_f32_16x16x32_bf16 v[60:63], v[158:161], v[174:177], v[60:63]
	v_mfma_f32_16x16x32_bf16 v[56:59], v[166:169], v[174:177], v[56:59]
	v_mfma_f32_16x16x32_bf16 v[44:47], v[158:161], v[182:185], v[44:47]
	v_mfma_f32_16x16x32_bf16 v[40:43], v[166:169], v[182:185], v[40:43]
	v_mfma_f32_16x16x32_bf16 v[28:31], v[158:161], v[190:193], v[28:31]
	v_mfma_f32_16x16x32_bf16 v[24:27], v[166:169], v[190:193], v[24:27]
	v_mfma_f32_16x16x32_bf16 v[12:15], v[158:161], v[198:201], v[12:15]
	v_mfma_f32_16x16x32_bf16 v[8:11], v[166:169], v[198:201], v[8:11]
	s_setprio 0
	s_barrier
	s_add_u32 s38, s38, 0x40080
	s_addc_u32 s39, s39, 0
	s_add_i32 s40, s40, s52
	v_lshl_add_u64 v[154:155], s[38:39], 0, v[132:133]
	s_mov_b32 m0, s40
	s_nop 0
	global_load_lds_dwordx4 v[154:155], off
	v_lshl_add_u64 v[154:155], s[38:39], 0, v[136:137]
	s_add_i32 m0, s40, 0x2000
	s_nop 0
	global_load_lds_dwordx4 v[154:155], off
	s_waitcnt vmcnt(6)
	s_barrier
	s_setprio 1
	v_mfma_f32_16x16x32_bf16 v[52:55], v[202:205], v[170:173], v[52:55]
	v_mfma_f32_16x16x32_bf16 v[48:51], v[210:213], v[170:173], v[48:51]
	v_mfma_f32_16x16x32_bf16 v[36:39], v[202:205], v[178:181], v[36:39]
	v_mfma_f32_16x16x32_bf16 v[32:35], v[210:213], v[178:181], v[32:35]
	v_mfma_f32_16x16x32_bf16 v[20:23], v[202:205], v[186:189], v[20:23]
	v_mfma_f32_16x16x32_bf16 v[16:19], v[210:213], v[186:189], v[16:19]
	v_mfma_f32_16x16x32_bf16 v[4:7], v[202:205], v[194:197], v[4:7]
	v_mfma_f32_16x16x32_bf16 v[0:3], v[210:213], v[194:197], v[0:3]
	v_mfma_f32_16x16x32_bf16 v[52:55], v[206:209], v[174:177], v[52:55]
	v_mfma_f32_16x16x32_bf16 v[48:51], v[214:217], v[174:177], v[48:51]
	v_mfma_f32_16x16x32_bf16 v[36:39], v[206:209], v[182:185], v[36:39]
	v_mfma_f32_16x16x32_bf16 v[32:35], v[214:217], v[182:185], v[32:35]
	v_mfma_f32_16x16x32_bf16 v[20:23], v[206:209], v[190:193], v[20:23]
	v_mfma_f32_16x16x32_bf16 v[16:19], v[214:217], v[190:193], v[16:19]
	v_mfma_f32_16x16x32_bf16 v[4:7], v[206:209], v[198:201], v[4:7]
	v_mfma_f32_16x16x32_bf16 v[0:3], v[214:217], v[198:201], v[0:3]
	s_setprio 0
	s_add_i32 s77, s77, 2
	s_add_u32 s36, s36, 0x100
	s_addc_u32 s37, s37, 0
	s_add_u32 s75, s75, 0x100
	s_addc_u32 s76, s76, 0
	s_cmp_gt_u32 s77, 13
	s_barrier
	s_cbranch_scc0 .LBB0_1310
	v_lshl_add_u32 v154, s34, 8, v148
	v_max_f32_e32 v126, v126, v126
	v_max_f32_e32 v127, v127, v127
	v_lshl_or_b32 v156, s72, 8, v150
	v_ashrrev_i32_e32 v155, 31, v154
	v_max_f32_e32 v124, v124, v124
	v_max_f32_e32 v120, v120, v120
	v_max_f32_e32 v125, v125, v125
	v_max_f32_e32 v121, v121, v121
	v_max_f32_e32 v126, 0, v126
	v_max_f32_e32 v122, v122, v122
	v_max_f32_e32 v127, 0, v127
	v_max_f32_e32 v123, v123, v123
	v_lshlrev_b64 v[158:159], 13, v[154:155]
	v_max_f32_e32 v124, 0, v124
	v_max_f32_e32 v120, 0, v120
	v_max_f32_e32 v125, 0, v125
	v_max_f32_e32 v121, 0, v121
	v_max_f32_e32 v122, 0, v122
	v_max_f32_e32 v123, 0, v123
	v_pk_mul_f32 v[126:127], v[126:127], v[126:127]
	v_ashrrev_i32_e32 v157, 31, v156
	v_lshl_add_u64 v[158:159], s[46:47], 0, v[158:159]
	v_pk_mul_f32 v[124:125], v[124:125], v[124:125]
	v_pk_mul_f32 v[120:121], v[120:121], v[120:121]
	v_pk_mul_f32 v[160:161], v[122:123], v[122:123]
	v_cvt_pk_bf16_f32 v123, v126, v127
	v_lshlrev_b64 v[126:127], 1, v[156:157]
	v_max_f32_e32 v112, v112, v112
	v_max_f32_e32 v113, v113, v113
	v_cvt_pk_bf16_f32 v122, v124, v125
	v_cvt_pk_bf16_f32 v124, v120, v121
	v_cvt_pk_bf16_f32 v125, v160, v161
	v_lshl_add_u64 v[120:121], v[158:159], 0, v[126:127]
	v_max_f32_e32 v112, 0, v112
	v_max_f32_e32 v113, 0, v113
	global_store_dwordx4 v[120:121], v[122:125], off sc1
	v_max_f32_e32 v116, v116, v116
	v_max_f32_e32 v117, v117, v117
	v_pk_mul_f32 v[122:123], v[112:113], v[112:113]
	v_max_f32_e32 v113, v114, v114
	v_max_f32_e32 v112, v118, v118
	v_max_f32_e32 v114, 0, v113
	v_max_f32_e32 v113, v119, v119
	v_max_f32_e32 v115, v115, v115
	v_max_f32_e32 v116, 0, v116
	v_max_f32_e32 v117, 0, v117
	v_max_f32_e32 v112, 0, v112
	v_max_f32_e32 v113, 0, v113
	v_max_f32_e32 v115, 0, v115
	v_pk_mul_f32 v[116:117], v[116:117], v[116:117]
	v_pk_mul_f32 v[118:119], v[112:113], v[112:113]
	v_pk_mul_f32 v[124:125], v[114:115], v[114:115]
	v_max_f32_e32 v104, v104, v104
	v_max_f32_e32 v105, v105, v105
	v_cvt_pk_bf16_f32 v112, v116, v117
	v_cvt_pk_bf16_f32 v113, v118, v119
	v_cvt_pk_bf16_f32 v114, v122, v123
	v_cvt_pk_bf16_f32 v115, v124, v125
	v_max_f32_e32 v104, 0, v104
	v_max_f32_e32 v105, 0, v105
	global_store_dwordx4 v[120:121], v[112:115], off offset:256 sc1
	v_max_f32_e32 v108, v108, v108
	v_max_f32_e32 v109, v109, v109
	v_or_b32_e32 v112, 16, v154
	v_pk_mul_f32 v[114:115], v[104:105], v[104:105]
	v_max_f32_e32 v105, v106, v106
	v_ashrrev_i32_e32 v113, 31, v112
	v_max_f32_e32 v104, v110, v110
	v_max_f32_e32 v106, 0, v105
	v_max_f32_e32 v105, v111, v111
	v_max_f32_e32 v107, v107, v107
	v_lshlrev_b64 v[112:113], 13, v[112:113]
	v_max_f32_e32 v108, 0, v108
	v_max_f32_e32 v109, 0, v109
	v_max_f32_e32 v104, 0, v104
	v_max_f32_e32 v105, 0, v105
	v_max_f32_e32 v107, 0, v107
	v_lshl_add_u64 v[112:113], s[46:47], 0, v[112:113]
	v_pk_mul_f32 v[108:109], v[108:109], v[108:109]
	v_pk_mul_f32 v[110:111], v[104:105], v[104:105]
	v_pk_mul_f32 v[116:117], v[106:107], v[106:107]
	v_max_f32_e32 v96, v96, v96
	v_max_f32_e32 v97, v97, v97
	v_cvt_pk_bf16_f32 v104, v108, v109
	v_cvt_pk_bf16_f32 v105, v110, v111
	v_cvt_pk_bf16_f32 v106, v114, v115
	v_cvt_pk_bf16_f32 v107, v116, v117
	v_lshl_add_u64 v[108:109], v[112:113], 0, v[126:127]
	v_max_f32_e32 v96, 0, v96
	v_max_f32_e32 v97, 0, v97
	global_store_dwordx4 v[108:109], v[104:107], off sc1
	v_max_f32_e32 v100, v100, v100
	v_max_f32_e32 v101, v101, v101
	v_pk_mul_f32 v[104:105], v[96:97], v[96:97]
	v_max_f32_e32 v97, v98, v98
	v_max_f32_e32 v96, v102, v102
	v_max_f32_e32 v98, 0, v97
	v_max_f32_e32 v97, v103, v103
	v_max_f32_e32 v99, v99, v99
	v_max_f32_e32 v100, 0, v100
	v_max_f32_e32 v101, 0, v101
	v_max_f32_e32 v96, 0, v96
	v_max_f32_e32 v97, 0, v97
	v_max_f32_e32 v99, 0, v99
	v_pk_mul_f32 v[100:101], v[100:101], v[100:101]
	v_pk_mul_f32 v[102:103], v[96:97], v[96:97]
	v_pk_mul_f32 v[106:107], v[98:99], v[98:99]
	v_max_f32_e32 v88, v88, v88
	v_max_f32_e32 v89, v89, v89
	v_cvt_pk_bf16_f32 v96, v100, v101
	v_cvt_pk_bf16_f32 v97, v102, v103
	v_cvt_pk_bf16_f32 v98, v104, v105
	v_cvt_pk_bf16_f32 v99, v106, v107
	v_max_f32_e32 v88, 0, v88
	v_max_f32_e32 v89, 0, v89
	global_store_dwordx4 v[108:109], v[96:99], off offset:256 sc1
	v_max_f32_e32 v92, v92, v92
	v_max_f32_e32 v93, v93, v93
	v_or_b32_e32 v96, 32, v154
	v_pk_mul_f32 v[98:99], v[88:89], v[88:89]
	v_max_f32_e32 v89, v90, v90
	v_ashrrev_i32_e32 v97, 31, v96
	v_max_f32_e32 v88, v94, v94
	v_max_f32_e32 v90, 0, v89
	v_max_f32_e32 v89, v95, v95
	v_max_f32_e32 v91, v91, v91
	v_lshlrev_b64 v[96:97], 13, v[96:97]
	v_max_f32_e32 v92, 0, v92
	v_max_f32_e32 v93, 0, v93
	v_max_f32_e32 v88, 0, v88
	v_max_f32_e32 v89, 0, v89
	v_max_f32_e32 v91, 0, v91
	v_lshl_add_u64 v[96:97], s[46:47], 0, v[96:97]
	v_pk_mul_f32 v[92:93], v[92:93], v[92:93]
	v_pk_mul_f32 v[94:95], v[88:89], v[88:89]
	v_pk_mul_f32 v[100:101], v[90:91], v[90:91]
	v_max_f32_e32 v80, v80, v80
	v_max_f32_e32 v81, v81, v81
	v_cvt_pk_bf16_f32 v88, v92, v93
	v_cvt_pk_bf16_f32 v89, v94, v95
	v_cvt_pk_bf16_f32 v90, v98, v99
	v_cvt_pk_bf16_f32 v91, v100, v101
	v_lshl_add_u64 v[92:93], v[96:97], 0, v[126:127]
	v_max_f32_e32 v80, 0, v80
	v_max_f32_e32 v81, 0, v81
	global_store_dwordx4 v[92:93], v[88:91], off sc1
	v_max_f32_e32 v84, v84, v84
	v_max_f32_e32 v85, v85, v85
	v_pk_mul_f32 v[88:89], v[80:81], v[80:81]
	v_max_f32_e32 v81, v82, v82
	v_max_f32_e32 v80, v86, v86
	v_max_f32_e32 v82, 0, v81
	v_max_f32_e32 v81, v87, v87
	v_max_f32_e32 v83, v83, v83
	v_max_f32_e32 v84, 0, v84
	v_max_f32_e32 v85, 0, v85
	v_max_f32_e32 v80, 0, v80
	v_max_f32_e32 v81, 0, v81
	v_max_f32_e32 v83, 0, v83
	v_pk_mul_f32 v[84:85], v[84:85], v[84:85]
	v_pk_mul_f32 v[86:87], v[80:81], v[80:81]
	v_pk_mul_f32 v[90:91], v[82:83], v[82:83]
	v_max_f32_e32 v72, v72, v72
	v_max_f32_e32 v73, v73, v73
	v_cvt_pk_bf16_f32 v80, v84, v85
	v_cvt_pk_bf16_f32 v81, v86, v87
	v_cvt_pk_bf16_f32 v82, v88, v89
	v_cvt_pk_bf16_f32 v83, v90, v91
	v_max_f32_e32 v72, 0, v72
	v_max_f32_e32 v73, 0, v73
	global_store_dwordx4 v[92:93], v[80:83], off offset:256 sc1
	v_max_f32_e32 v76, v76, v76
	v_max_f32_e32 v77, v77, v77
	v_or_b32_e32 v80, 48, v154
	v_pk_mul_f32 v[82:83], v[72:73], v[72:73]
	v_max_f32_e32 v73, v74, v74
	v_ashrrev_i32_e32 v81, 31, v80
	v_max_f32_e32 v72, v78, v78
	v_max_f32_e32 v74, 0, v73
	v_max_f32_e32 v73, v79, v79
	v_max_f32_e32 v75, v75, v75
	v_lshlrev_b64 v[80:81], 13, v[80:81]
	v_max_f32_e32 v76, 0, v76
	v_max_f32_e32 v77, 0, v77
	v_max_f32_e32 v72, 0, v72
	v_max_f32_e32 v73, 0, v73
	v_max_f32_e32 v75, 0, v75
	v_lshl_add_u64 v[80:81], s[46:47], 0, v[80:81]
	v_pk_mul_f32 v[76:77], v[76:77], v[76:77]
	v_pk_mul_f32 v[78:79], v[72:73], v[72:73]
	v_pk_mul_f32 v[84:85], v[74:75], v[74:75]
	v_max_f32_e32 v64, v64, v64
	v_max_f32_e32 v65, v65, v65
	v_cvt_pk_bf16_f32 v72, v76, v77
	v_cvt_pk_bf16_f32 v73, v78, v79
	v_cvt_pk_bf16_f32 v74, v82, v83
	v_cvt_pk_bf16_f32 v75, v84, v85
	v_lshl_add_u64 v[76:77], v[80:81], 0, v[126:127]
	v_max_f32_e32 v64, 0, v64
	v_max_f32_e32 v65, 0, v65
	global_store_dwordx4 v[76:77], v[72:75], off sc1
	v_max_f32_e32 v68, v68, v68
	v_max_f32_e32 v69, v69, v69
	v_pk_mul_f32 v[72:73], v[64:65], v[64:65]
	v_max_f32_e32 v65, v66, v66
	v_max_f32_e32 v64, v70, v70
	v_max_f32_e32 v66, 0, v65
	v_max_f32_e32 v65, v71, v71
	v_max_f32_e32 v67, v67, v67
	v_max_f32_e32 v68, 0, v68
	v_max_f32_e32 v69, 0, v69
	v_max_f32_e32 v64, 0, v64
	v_max_f32_e32 v65, 0, v65
	v_max_f32_e32 v67, 0, v67
	v_pk_mul_f32 v[68:69], v[68:69], v[68:69]
	v_pk_mul_f32 v[70:71], v[64:65], v[64:65]
	v_pk_mul_f32 v[74:75], v[66:67], v[66:67]
	v_max_f32_e32 v56, v56, v56
	v_max_f32_e32 v57, v57, v57
	v_cvt_pk_bf16_f32 v64, v68, v69
	v_cvt_pk_bf16_f32 v65, v70, v71
	v_cvt_pk_bf16_f32 v66, v72, v73
	v_cvt_pk_bf16_f32 v67, v74, v75
	v_max_f32_e32 v56, 0, v56
	v_max_f32_e32 v57, 0, v57
	global_store_dwordx4 v[76:77], v[64:67], off offset:256 sc1
	v_max_f32_e32 v60, v60, v60
	v_max_f32_e32 v61, v61, v61
	v_pk_mul_f32 v[64:65], v[56:57], v[56:57]
	v_max_f32_e32 v57, v58, v58
	v_max_f32_e32 v56, v62, v62
	v_max_f32_e32 v58, 0, v57
	v_max_f32_e32 v57, v63, v63
	v_max_f32_e32 v56, 0, v56
	v_max_f32_e32 v57, 0, v57
	v_max_f32_e32 v59, v59, v59
	v_max_f32_e32 v60, 0, v60
	v_max_f32_e32 v61, 0, v61
	v_max_f32_e32 v59, 0, v59
	v_pk_mul_f32 v[62:63], v[56:57], v[56:57]
	v_pk_mul_f32 v[60:61], v[60:61], v[60:61]
	v_pk_mul_f32 v[66:67], v[58:59], v[58:59]
	v_cvt_pk_bf16_f32 v57, v62, v63
	v_add_co_u32_e32 v62, vcc, s64, v120
	v_max_f32_e32 v48, v48, v48
	v_max_f32_e32 v49, v49, v49
	v_cvt_pk_bf16_f32 v56, v60, v61
	v_cvt_pk_bf16_f32 v58, v64, v65
	v_cvt_pk_bf16_f32 v59, v66, v67
	v_addc_co_u32_e32 v63, vcc, 0, v121, vcc
	v_max_f32_e32 v48, 0, v48
	v_max_f32_e32 v49, 0, v49
	global_store_dwordx4 v[62:63], v[56:59], off sc1
	v_max_f32_e32 v52, v52, v52
	v_max_f32_e32 v53, v53, v53
	v_pk_mul_f32 v[56:57], v[48:49], v[48:49]
	v_max_f32_e32 v49, v50, v50
	v_max_f32_e32 v48, v54, v54
	v_max_f32_e32 v50, 0, v49
	v_max_f32_e32 v49, v55, v55
	v_max_f32_e32 v51, v51, v51
	v_max_f32_e32 v52, 0, v52
	v_max_f32_e32 v53, 0, v53
	v_max_f32_e32 v48, 0, v48
	v_max_f32_e32 v49, 0, v49
	v_max_f32_e32 v51, 0, v51
	v_pk_mul_f32 v[52:53], v[52:53], v[52:53]
	v_pk_mul_f32 v[54:55], v[48:49], v[48:49]
	v_pk_mul_f32 v[58:59], v[50:51], v[50:51]
	v_max_f32_e32 v40, v40, v40
	v_max_f32_e32 v41, v41, v41
	v_lshl_add_u64 v[60:61], v[120:121], 0, s[12:13]
	v_cvt_pk_bf16_f32 v48, v52, v53
	v_cvt_pk_bf16_f32 v49, v54, v55
	v_cvt_pk_bf16_f32 v50, v56, v57
	v_cvt_pk_bf16_f32 v51, v58, v59
	v_max_f32_e32 v40, 0, v40
	v_max_f32_e32 v41, 0, v41
	global_store_dwordx4 v[60:61], v[48:51], off offset:256 sc1
	v_max_f32_e32 v44, v44, v44
	v_max_f32_e32 v45, v45, v45
	v_pk_mul_f32 v[48:49], v[40:41], v[40:41]
	v_max_f32_e32 v41, v42, v42
	v_max_f32_e32 v40, v46, v46
	v_max_f32_e32 v42, 0, v41
	v_max_f32_e32 v41, v47, v47
	v_max_f32_e32 v40, 0, v40
	v_max_f32_e32 v41, 0, v41
	v_max_f32_e32 v43, v43, v43
	v_max_f32_e32 v44, 0, v44
	v_max_f32_e32 v45, 0, v45
	v_max_f32_e32 v43, 0, v43
	v_pk_mul_f32 v[46:47], v[40:41], v[40:41]
	v_pk_mul_f32 v[44:45], v[44:45], v[44:45]
	v_pk_mul_f32 v[50:51], v[42:43], v[42:43]
	v_cvt_pk_bf16_f32 v41, v46, v47
	v_add_co_u32_e32 v46, vcc, s65, v120
	v_max_f32_e32 v32, v32, v32
	v_max_f32_e32 v33, v33, v33
	v_cvt_pk_bf16_f32 v40, v44, v45
	v_cvt_pk_bf16_f32 v42, v48, v49
	v_cvt_pk_bf16_f32 v43, v50, v51
	v_addc_co_u32_e32 v47, vcc, 0, v121, vcc
	v_max_f32_e32 v32, 0, v32
	v_max_f32_e32 v33, 0, v33
	global_store_dwordx4 v[46:47], v[40:43], off sc1
	v_max_f32_e32 v36, v36, v36
	v_max_f32_e32 v37, v37, v37
	v_pk_mul_f32 v[40:41], v[32:33], v[32:33]
	v_max_f32_e32 v33, v34, v34
	v_max_f32_e32 v32, v38, v38
	v_max_f32_e32 v34, 0, v33
	v_max_f32_e32 v33, v39, v39
	v_max_f32_e32 v35, v35, v35
	v_max_f32_e32 v36, 0, v36
	v_max_f32_e32 v37, 0, v37
	v_max_f32_e32 v32, 0, v32
	v_max_f32_e32 v33, 0, v33
	v_max_f32_e32 v35, 0, v35
	v_pk_mul_f32 v[36:37], v[36:37], v[36:37]
	v_pk_mul_f32 v[38:39], v[32:33], v[32:33]
	v_pk_mul_f32 v[42:43], v[34:35], v[34:35]
	v_max_f32_e32 v24, v24, v24
	v_max_f32_e32 v25, v25, v25
	v_lshl_add_u64 v[44:45], v[120:121], 0, s[14:15]
	v_cvt_pk_bf16_f32 v32, v36, v37
	v_cvt_pk_bf16_f32 v33, v38, v39
	v_cvt_pk_bf16_f32 v34, v40, v41
	v_cvt_pk_bf16_f32 v35, v42, v43
	v_max_f32_e32 v24, 0, v24
	v_max_f32_e32 v25, 0, v25
	global_store_dwordx4 v[44:45], v[32:35], off offset:256 sc1
	v_max_f32_e32 v28, v28, v28
	v_max_f32_e32 v29, v29, v29
	v_pk_mul_f32 v[32:33], v[24:25], v[24:25]
	v_max_f32_e32 v25, v26, v26
	v_max_f32_e32 v24, v30, v30
	v_max_f32_e32 v26, 0, v25
	v_max_f32_e32 v25, v31, v31
	v_max_f32_e32 v24, 0, v24
	v_max_f32_e32 v25, 0, v25
	v_max_f32_e32 v27, v27, v27
	v_max_f32_e32 v28, 0, v28
	v_max_f32_e32 v29, 0, v29
	v_max_f32_e32 v27, 0, v27
	v_pk_mul_f32 v[30:31], v[24:25], v[24:25]
	v_pk_mul_f32 v[28:29], v[28:29], v[28:29]
	v_pk_mul_f32 v[34:35], v[26:27], v[26:27]
	v_cvt_pk_bf16_f32 v25, v30, v31
	v_add_co_u32_e32 v30, vcc, s70, v120
	v_max_f32_e32 v16, v16, v16
	v_max_f32_e32 v17, v17, v17
	v_cvt_pk_bf16_f32 v24, v28, v29
	v_cvt_pk_bf16_f32 v26, v32, v33
	v_cvt_pk_bf16_f32 v27, v34, v35
	v_addc_co_u32_e32 v31, vcc, 0, v121, vcc
	v_max_f32_e32 v16, 0, v16
	v_max_f32_e32 v17, 0, v17
	global_store_dwordx4 v[30:31], v[24:27], off sc1
	v_max_f32_e32 v20, v20, v20
	v_max_f32_e32 v21, v21, v21
	v_pk_mul_f32 v[24:25], v[16:17], v[16:17]
	v_max_f32_e32 v17, v18, v18
	v_max_f32_e32 v16, v22, v22
	v_max_f32_e32 v18, 0, v17
	v_max_f32_e32 v17, v23, v23
	v_max_f32_e32 v19, v19, v19
	v_max_f32_e32 v20, 0, v20
	v_max_f32_e32 v21, 0, v21
	v_max_f32_e32 v16, 0, v16
	v_max_f32_e32 v17, 0, v17
	v_max_f32_e32 v19, 0, v19
	v_pk_mul_f32 v[20:21], v[20:21], v[20:21]
	v_pk_mul_f32 v[22:23], v[16:17], v[16:17]
	v_pk_mul_f32 v[26:27], v[18:19], v[18:19]
	v_max_f32_e32 v8, v8, v8
	v_max_f32_e32 v9, v9, v9
	v_lshl_add_u64 v[28:29], v[120:121], 0, s[16:17]
	v_cvt_pk_bf16_f32 v16, v20, v21
	v_cvt_pk_bf16_f32 v17, v22, v23
	v_cvt_pk_bf16_f32 v18, v24, v25
	v_cvt_pk_bf16_f32 v19, v26, v27
	v_max_f32_e32 v8, 0, v8
	v_max_f32_e32 v9, 0, v9
	global_store_dwordx4 v[28:29], v[16:19], off offset:256 sc1
	v_max_f32_e32 v12, v12, v12
	v_max_f32_e32 v13, v13, v13
	v_pk_mul_f32 v[16:17], v[8:9], v[8:9]
	v_max_f32_e32 v9, v10, v10
	v_max_f32_e32 v8, v14, v14
	v_max_f32_e32 v10, 0, v9
	v_max_f32_e32 v9, v15, v15
	v_max_f32_e32 v8, 0, v8
	v_max_f32_e32 v9, 0, v9
	v_max_f32_e32 v11, v11, v11
	v_max_f32_e32 v12, 0, v12
	v_max_f32_e32 v13, 0, v13
	v_max_f32_e32 v11, 0, v11
	v_pk_mul_f32 v[14:15], v[8:9], v[8:9]
	v_pk_mul_f32 v[12:13], v[12:13], v[12:13]
	v_pk_mul_f32 v[18:19], v[10:11], v[10:11]
	v_cvt_pk_bf16_f32 v9, v14, v15
	v_add_co_u32_e32 v14, vcc, s71, v120
	v_max_f32_e32 v0, v0, v0
	v_max_f32_e32 v1, v1, v1
	v_cvt_pk_bf16_f32 v8, v12, v13
	v_cvt_pk_bf16_f32 v10, v16, v17
	v_cvt_pk_bf16_f32 v11, v18, v19
	v_addc_co_u32_e32 v15, vcc, 0, v121, vcc
	v_max_f32_e32 v0, 0, v0
	v_max_f32_e32 v1, 0, v1
	global_store_dwordx4 v[14:15], v[8:11], off sc1
	v_max_f32_e32 v4, v4, v4
	v_max_f32_e32 v5, v5, v5
	v_pk_mul_f32 v[8:9], v[0:1], v[0:1]
	v_max_f32_e32 v1, v2, v2
	v_max_f32_e32 v0, v6, v6
	v_max_f32_e32 v2, 0, v1
	v_max_f32_e32 v1, v7, v7
	v_max_f32_e32 v3, v3, v3
	v_max_f32_e32 v4, 0, v4
	v_max_f32_e32 v5, 0, v5
	v_max_f32_e32 v0, 0, v0
	v_max_f32_e32 v1, 0, v1
	v_max_f32_e32 v3, 0, v3
	v_pk_mul_f32 v[4:5], v[4:5], v[4:5]
	v_pk_mul_f32 v[6:7], v[0:1], v[0:1]
	v_pk_mul_f32 v[10:11], v[2:3], v[2:3]
	v_lshl_add_u64 v[12:13], v[120:121], 0, s[18:19]
	v_cvt_pk_bf16_f32 v0, v4, v5
	v_cvt_pk_bf16_f32 v1, v6, v7
	v_cvt_pk_bf16_f32 v2, v8, v9
	v_cvt_pk_bf16_f32 v3, v10, v11
	s_and_b64 vcc, exec, s[4:5]
	s_mov_b32 s72, s20
	s_mov_b32 s34, s26
	s_mov_b64 s[38:39], s[30:31]
	s_mov_b64 s[36:37], s[28:29]
	global_store_dwordx4 v[12:13], v[0:3], off offset:256 sc1
	s_cbranch_vccz .LBB0_1303
	s_waitcnt vmcnt(0)
	s_cmpk_gt_u32 s42, 0xff
	s_cbranch_scc1 .LBB0_1314
	s_barrier

.LBB0_1384:
	ds_read_b128 v[156:159], v153
	ds_read_b128 v[160:163], v153 offset:1024
	ds_read_b128 v[164:167], v153 offset:2048
	ds_read_b128 v[168:171], v153 offset:3072
	s_add_u32 s36, s34, 0xfff00080
	s_addc_u32 s37, s35, -1
	s_cmp_eq_u32 s77, 60
	s_cselect_b32 s39, s27, s37
	s_cselect_b32 s38, s73, s36
	s_cselect_b32 s37, s21, s76
	s_cselect_b32 s36, s74, s75
	v_lshl_add_u64 v[204:205], s[34:35], 0, v[138:139]
	s_add_i32 m0, s19, 0xc000
	ds_read_b128 v[172:175], v154
	ds_read_b128 v[176:179], v154 offset:1024
	ds_read_b128 v[180:183], v154 offset:2048
	ds_read_b128 v[184:187], v154 offset:3072
	ds_read_b128 v[188:191], v154 offset:4096
	ds_read_b128 v[192:195], v154 offset:5120
	ds_read_b128 v[196:199], v154 offset:6144
	ds_read_b128 v[200:203], v154 offset:7168
	global_load_lds_dwordx4 v[204:205], off
	v_lshl_add_u64 v[204:205], s[34:35], 0, v[140:141]
	s_add_i32 m0, s19, 0xe000
	s_nop 0
	global_load_lds_dwordx4 v[204:205], off
	s_waitcnt lgkmcnt(8)
	s_barrier
	s_waitcnt lgkmcnt(0)
	s_setprio 1
	s_waitcnt lgkmcnt(0)
	v_mfma_f32_16x16x32_bf16 v[124:127], v[156:159], v[172:175], v[124:127]
	v_mfma_f32_16x16x32_bf16 v[120:123], v[164:167], v[172:175], v[120:123]
	v_mfma_f32_16x16x32_bf16 v[116:119], v[156:159], v[180:183], v[116:119]
	v_mfma_f32_16x16x32_bf16 v[112:115], v[164:167], v[180:183], v[112:115]
	v_mfma_f32_16x16x32_bf16 v[100:103], v[156:159], v[188:191], v[100:103]
	v_mfma_f32_16x16x32_bf16 v[96:99], v[164:167], v[188:191], v[96:99]
	v_mfma_f32_16x16x32_bf16 v[84:87], v[156:159], v[196:199], v[84:87]
	v_mfma_f32_16x16x32_bf16 v[80:83], v[164:167], v[196:199], v[80:83]
	v_mfma_f32_16x16x32_bf16 v[124:127], v[160:163], v[176:179], v[124:127]
	v_mfma_f32_16x16x32_bf16 v[120:123], v[168:171], v[176:179], v[120:123]
	v_mfma_f32_16x16x32_bf16 v[116:119], v[160:163], v[184:187], v[116:119]
	v_mfma_f32_16x16x32_bf16 v[112:115], v[168:171], v[184:187], v[112:115]
	v_mfma_f32_16x16x32_bf16 v[100:103], v[160:163], v[192:195], v[100:103]
	v_mfma_f32_16x16x32_bf16 v[96:99], v[168:171], v[192:195], v[96:99]
	v_mfma_f32_16x16x32_bf16 v[84:87], v[160:163], v[200:203], v[84:87]
	v_mfma_f32_16x16x32_bf16 v[80:83], v[168:171], v[200:203], v[80:83]
	s_setprio 0
	s_barrier
	s_add_i32 s78, s62, s43
	v_lshl_add_u64 v[220:221], s[36:37], 0, v[134:135]
	s_mov_b32 m0, s78
	ds_read_b128 v[204:207], v155
	ds_read_b128 v[208:211], v155 offset:1024
	ds_read_b128 v[212:215], v155 offset:2048
	ds_read_b128 v[216:219], v155 offset:3072
	global_load_lds_dwordx4 v[220:221], off
	v_lshl_add_u64 v[222:223], s[36:37], 0, v[130:131]
	s_add_i32 m0, s78, 0x2000
	s_nop 0
	global_load_lds_dwordx4 v[222:223], off
	s_barrier
	s_waitcnt lgkmcnt(0)
	s_setprio 1
	s_waitcnt lgkmcnt(0)
	v_mfma_f32_16x16x32_bf16 v[108:111], v[204:207], v[172:175], v[108:111]
	v_mfma_f32_16x16x32_bf16 v[104:107], v[212:215], v[172:175], v[104:107]
	v_mfma_f32_16x16x32_bf16 v[92:95], v[204:207], v[180:183], v[92:95]
	v_mfma_f32_16x16x32_bf16 v[88:91], v[212:215], v[180:183], v[88:91]
	v_mfma_f32_16x16x32_bf16 v[76:79], v[204:207], v[188:191], v[76:79]
	v_mfma_f32_16x16x32_bf16 v[72:75], v[212:215], v[188:191], v[72:75]
	v_mfma_f32_16x16x32_bf16 v[68:71], v[204:207], v[196:199], v[68:71]
	v_mfma_f32_16x16x32_bf16 v[64:67], v[212:215], v[196:199], v[64:67]
	v_mfma_f32_16x16x32_bf16 v[108:111], v[208:211], v[176:179], v[108:111]
	v_mfma_f32_16x16x32_bf16 v[104:107], v[216:219], v[176:179], v[104:107]
	v_mfma_f32_16x16x32_bf16 v[92:95], v[208:211], v[184:187], v[92:95]
	v_mfma_f32_16x16x32_bf16 v[88:91], v[216:219], v[184:187], v[88:91]
	v_mfma_f32_16x16x32_bf16 v[76:79], v[208:211], v[192:195], v[76:79]
	v_mfma_f32_16x16x32_bf16 v[72:75], v[216:219], v[192:195], v[72:75]
	v_mfma_f32_16x16x32_bf16 v[68:71], v[208:211], v[200:203], v[68:71]
	v_mfma_f32_16x16x32_bf16 v[64:67], v[216:219], v[200:203], v[64:67]
	s_setprio 0
	s_mov_b32 m0, s19
	v_lshl_add_u64 v[224:225], s[38:39], 0, v[136:137]
	s_barrier
	ds_read_b128 v[172:175], v154 offset:16384
	ds_read_b128 v[176:179], v154 offset:17408
	ds_read_b128 v[180:183], v154 offset:18432
	ds_read_b128 v[184:187], v154 offset:19456
	ds_read_b128 v[188:191], v154 offset:20480
	ds_read_b128 v[192:195], v154 offset:21504
	ds_read_b128 v[196:199], v154 offset:22528
	ds_read_b128 v[200:203], v154 offset:23552
	global_load_lds_dwordx4 v[224:225], off
	v_lshl_add_u64 v[226:227], s[38:39], 0, v[132:133]
	s_mov_b32 m0, s53
	s_nop 0
	global_load_lds_dwordx4 v[226:227], off
	s_barrier
	s_waitcnt lgkmcnt(0)
	s_setprio 1
	s_waitcnt lgkmcnt(0)
	v_mfma_f32_16x16x32_bf16 v[60:63], v[156:159], v[172:175], v[60:63]
	v_mfma_f32_16x16x32_bf16 v[56:59], v[164:167], v[172:175], v[56:59]
	v_mfma_f32_16x16x32_bf16 v[52:55], v[156:159], v[180:183], v[52:55]
	v_mfma_f32_16x16x32_bf16 v[48:51], v[164:167], v[180:183], v[48:51]
	v_mfma_f32_16x16x32_bf16 v[36:39], v[156:159], v[188:191], v[36:39]
	v_mfma_f32_16x16x32_bf16 v[32:35], v[164:167], v[188:191], v[32:35]
	v_mfma_f32_16x16x32_bf16 v[20:23], v[156:159], v[196:199], v[20:23]
	v_mfma_f32_16x16x32_bf16 v[16:19], v[164:167], v[196:199], v[16:19]
	v_mfma_f32_16x16x32_bf16 v[60:63], v[160:163], v[176:179], v[60:63]
	v_mfma_f32_16x16x32_bf16 v[56:59], v[168:171], v[176:179], v[56:59]
	v_mfma_f32_16x16x32_bf16 v[52:55], v[160:163], v[184:187], v[52:55]
	v_mfma_f32_16x16x32_bf16 v[48:51], v[168:171], v[184:187], v[48:51]
	v_mfma_f32_16x16x32_bf16 v[36:39], v[160:163], v[192:195], v[36:39]
	v_mfma_f32_16x16x32_bf16 v[32:35], v[168:171], v[192:195], v[32:35]
	v_mfma_f32_16x16x32_bf16 v[20:23], v[160:163], v[200:203], v[20:23]
	v_mfma_f32_16x16x32_bf16 v[16:19], v[168:171], v[200:203], v[16:19]
	s_setprio 0
	s_barrier
	s_add_u32 s78, s36, 0x100000
	s_addc_u32 s79, s37, 0
	s_add_i32 s80, s63, s43
	v_lshl_add_u64 v[156:157], s[78:79], 0, v[134:135]
	s_mov_b32 m0, s80
	s_nop 0
	global_load_lds_dwordx4 v[156:157], off
	v_lshl_add_u64 v[156:157], s[78:79], 0, v[130:131]
	s_add_i32 m0, s80, 0x2000
	s_nop 0
	global_load_lds_dwordx4 v[156:157], off
	s_waitcnt vmcnt(6)
	s_barrier
	s_setprio 1
	v_mfma_f32_16x16x32_bf16 v[44:47], v[204:207], v[172:175], v[44:47]
	v_mfma_f32_16x16x32_bf16 v[40:43], v[212:215], v[172:175], v[40:43]
	v_mfma_f32_16x16x32_bf16 v[28:31], v[204:207], v[180:183], v[28:31]
	v_mfma_f32_16x16x32_bf16 v[24:27], v[212:215], v[180:183], v[24:27]
	v_mfma_f32_16x16x32_bf16 v[12:15], v[204:207], v[188:191], v[12:15]
	v_mfma_f32_16x16x32_bf16 v[8:11], v[212:215], v[188:191], v[8:11]
	v_mfma_f32_16x16x32_bf16 v[4:7], v[204:207], v[196:199], v[4:7]
	v_mfma_f32_16x16x32_bf16 v[0:3], v[212:215], v[196:199], v[0:3]
	v_mfma_f32_16x16x32_bf16 v[44:47], v[208:211], v[176:179], v[44:47]
	v_mfma_f32_16x16x32_bf16 v[40:43], v[216:219], v[176:179], v[40:43]
	v_mfma_f32_16x16x32_bf16 v[28:31], v[208:211], v[184:187], v[28:31]
	v_mfma_f32_16x16x32_bf16 v[24:27], v[216:219], v[184:187], v[24:27]
	v_mfma_f32_16x16x32_bf16 v[12:15], v[208:211], v[192:195], v[12:15]
	v_mfma_f32_16x16x32_bf16 v[8:11], v[216:219], v[192:195], v[8:11]
	v_mfma_f32_16x16x32_bf16 v[4:7], v[208:211], v[200:203], v[4:7]
	v_mfma_f32_16x16x32_bf16 v[0:3], v[216:219], v[200:203], v[0:3]
	s_setprio 0
	s_add_i32 s78, 0, 0x18000
	v_add_u32_e32 v168, s78, v151
	s_barrier
	ds_read_b128 v[156:159], v168
	ds_read_b128 v[160:163], v168 offset:1024
	ds_read_b128 v[164:167], v168 offset:2048
	ds_read_b128 v[168:171], v168 offset:3072
	s_add_u32 s38, s38, 0x100000
	s_addc_u32 s39, s39, 0
	s_mov_b32 m0, s54
	v_lshl_add_u64 v[204:205], s[38:39], 0, v[136:137]
	ds_read_b128 v[172:175], v154 offset:32768
	ds_read_b128 v[176:179], v154 offset:33792
	ds_read_b128 v[180:183], v154 offset:34816
	ds_read_b128 v[184:187], v154 offset:35840
	ds_read_b128 v[188:191], v154 offset:36864
	ds_read_b128 v[192:195], v154 offset:37888
	ds_read_b128 v[196:199], v154 offset:38912
	ds_read_b128 v[200:203], v154 offset:39936
	global_load_lds_dwordx4 v[204:205], off
	v_lshl_add_u64 v[204:205], s[38:39], 0, v[132:133]
	s_mov_b32 m0, s55
	s_nop 0
	global_load_lds_dwordx4 v[204:205], off
	s_waitcnt lgkmcnt(8)
	s_barrier
	s_waitcnt lgkmcnt(0)
	s_setprio 1
	s_waitcnt lgkmcnt(0)
	v_mfma_f32_16x16x32_bf16 v[124:127], v[156:159], v[172:175], v[124:127]
	v_mfma_f32_16x16x32_bf16 v[120:123], v[164:167], v[172:175], v[120:123]
	v_mfma_f32_16x16x32_bf16 v[116:119], v[156:159], v[180:183], v[116:119]
	v_mfma_f32_16x16x32_bf16 v[112:115], v[164:167], v[180:183], v[112:115]
	v_mfma_f32_16x16x32_bf16 v[100:103], v[156:159], v[188:191], v[100:103]
	v_mfma_f32_16x16x32_bf16 v[96:99], v[164:167], v[188:191], v[96:99]
	v_mfma_f32_16x16x32_bf16 v[84:87], v[156:159], v[196:199], v[84:87]
	v_mfma_f32_16x16x32_bf16 v[80:83], v[164:167], v[196:199], v[80:83]
	v_mfma_f32_16x16x32_bf16 v[124:127], v[160:163], v[176:179], v[124:127]
	v_mfma_f32_16x16x32_bf16 v[120:123], v[168:171], v[176:179], v[120:123]
	v_mfma_f32_16x16x32_bf16 v[116:119], v[160:163], v[184:187], v[116:119]
	v_mfma_f32_16x16x32_bf16 v[112:115], v[168:171], v[184:187], v[112:115]
	v_mfma_f32_16x16x32_bf16 v[100:103], v[160:163], v[192:195], v[100:103]
	v_mfma_f32_16x16x32_bf16 v[96:99], v[168:171], v[192:195], v[96:99]
	v_mfma_f32_16x16x32_bf16 v[84:87], v[160:163], v[200:203], v[84:87]
	v_mfma_f32_16x16x32_bf16 v[80:83], v[168:171], v[200:203], v[80:83]
	s_setprio 0
	s_barrier
	s_add_i32 s38, 0, 0x1c000
	s_add_i32 s39, s78, s43
	v_add_u32_e32 v216, s38, v151
	v_lshl_add_u64 v[220:221], v[220:221], 0, s[8:9]
	s_mov_b32 m0, s39
	ds_read_b128 v[204:207], v216
	ds_read_b128 v[208:211], v216 offset:1024
	ds_read_b128 v[212:215], v216 offset:2048
	ds_read_b128 v[216:219], v216 offset:3072
	global_load_lds_dwordx4 v[220:221], off
	v_lshl_add_u64 v[220:221], v[222:223], 0, s[8:9]
	s_add_i32 m0, s39, 0x2000
	s_nop 0
	global_load_lds_dwordx4 v[220:221], off
	s_barrier
	s_waitcnt lgkmcnt(0)
	s_setprio 1
	s_waitcnt lgkmcnt(0)
	v_mfma_f32_16x16x32_bf16 v[108:111], v[204:207], v[172:175], v[108:111]
	v_mfma_f32_16x16x32_bf16 v[104:107], v[212:215], v[172:175], v[104:107]
	v_mfma_f32_16x16x32_bf16 v[92:95], v[204:207], v[180:183], v[92:95]
	v_mfma_f32_16x16x32_bf16 v[88:91], v[212:215], v[180:183], v[88:91]
	v_mfma_f32_16x16x32_bf16 v[76:79], v[204:207], v[188:191], v[76:79]
	v_mfma_f32_16x16x32_bf16 v[72:75], v[212:215], v[188:191], v[72:75]
	v_mfma_f32_16x16x32_bf16 v[68:71], v[204:207], v[196:199], v[68:71]
	v_mfma_f32_16x16x32_bf16 v[64:67], v[212:215], v[196:199], v[64:67]
	v_mfma_f32_16x16x32_bf16 v[108:111], v[208:211], v[176:179], v[108:111]
	v_mfma_f32_16x16x32_bf16 v[104:107], v[216:219], v[176:179], v[104:107]
	v_mfma_f32_16x16x32_bf16 v[92:95], v[208:211], v[184:187], v[92:95]
	v_mfma_f32_16x16x32_bf16 v[88:91], v[216:219], v[184:187], v[88:91]
	v_mfma_f32_16x16x32_bf16 v[76:79], v[208:211], v[192:195], v[76:79]
	v_mfma_f32_16x16x32_bf16 v[72:75], v[216:219], v[192:195], v[72:75]
	v_mfma_f32_16x16x32_bf16 v[68:71], v[208:211], v[200:203], v[68:71]
	v_mfma_f32_16x16x32_bf16 v[64:67], v[216:219], v[200:203], v[64:67]
	s_setprio 0
	s_mov_b32 m0, s57
	v_lshl_add_u64 v[220:221], v[224:225], 0, s[8:9]
	s_barrier
	ds_read_b128 v[172:175], v154 offset:49152
	ds_read_b128 v[176:179], v154 offset:50176
	ds_read_b128 v[180:183], v154 offset:51200
	ds_read_b128 v[184:187], v154 offset:52224
	ds_read_b128 v[188:191], v154 offset:53248
	ds_read_b128 v[192:195], v154 offset:54272
	ds_read_b128 v[196:199], v154 offset:55296
	ds_read_b128 v[200:203], v154 offset:56320
	global_load_lds_dwordx4 v[220:221], off
	v_lshl_add_u64 v[220:221], v[226:227], 0, s[8:9]
	s_mov_b32 m0, s60
	s_nop 0
	global_load_lds_dwordx4 v[220:221], off
	s_barrier
	s_waitcnt lgkmcnt(0)
	s_setprio 1
	s_waitcnt lgkmcnt(0)
	v_mfma_f32_16x16x32_bf16 v[60:63], v[156:159], v[172:175], v[60:63]
	v_mfma_f32_16x16x32_bf16 v[56:59], v[164:167], v[172:175], v[56:59]
	v_mfma_f32_16x16x32_bf16 v[52:55], v[156:159], v[180:183], v[52:55]
	v_mfma_f32_16x16x32_bf16 v[48:51], v[164:167], v[180:183], v[48:51]
	v_mfma_f32_16x16x32_bf16 v[36:39], v[156:159], v[188:191], v[36:39]
	v_mfma_f32_16x16x32_bf16 v[32:35], v[164:167], v[188:191], v[32:35]
	v_mfma_f32_16x16x32_bf16 v[20:23], v[156:159], v[196:199], v[20:23]
	v_mfma_f32_16x16x32_bf16 v[16:19], v[164:167], v[196:199], v[16:19]
	v_mfma_f32_16x16x32_bf16 v[60:63], v[160:163], v[176:179], v[60:63]
	v_mfma_f32_16x16x32_bf16 v[56:59], v[168:171], v[176:179], v[56:59]
	v_mfma_f32_16x16x32_bf16 v[52:55], v[160:163], v[184:187], v[52:55]
	v_mfma_f32_16x16x32_bf16 v[48:51], v[168:171], v[184:187], v[48:51]
	v_mfma_f32_16x16x32_bf16 v[36:39], v[160:163], v[192:195], v[36:39]
	v_mfma_f32_16x16x32_bf16 v[32:35], v[168:171], v[192:195], v[32:35]
	v_mfma_f32_16x16x32_bf16 v[20:23], v[160:163], v[200:203], v[20:23]
	v_mfma_f32_16x16x32_bf16 v[16:19], v[168:171], v[200:203], v[16:19]
	s_setprio 0
	s_barrier
	s_add_u32 s36, s36, 0x100080
	s_addc_u32 s37, s37, 0
	s_add_i32 s38, s38, s43
	v_lshl_add_u64 v[156:157], s[36:37], 0, v[134:135]
	s_mov_b32 m0, s38
	s_nop 0
	global_load_lds_dwordx4 v[156:157], off
	v_lshl_add_u64 v[156:157], s[36:37], 0, v[130:131]
	s_add_i32 m0, s38, 0x2000
	s_nop 0
	global_load_lds_dwordx4 v[156:157], off
	s_waitcnt vmcnt(6)
	s_barrier
	s_setprio 1
	v_mfma_f32_16x16x32_bf16 v[44:47], v[204:207], v[172:175], v[44:47]
	v_mfma_f32_16x16x32_bf16 v[40:43], v[212:215], v[172:175], v[40:43]
	v_mfma_f32_16x16x32_bf16 v[28:31], v[204:207], v[180:183], v[28:31]
	v_mfma_f32_16x16x32_bf16 v[24:27], v[212:215], v[180:183], v[24:27]
	v_mfma_f32_16x16x32_bf16 v[12:15], v[204:207], v[188:191], v[12:15]
	v_mfma_f32_16x16x32_bf16 v[8:11], v[212:215], v[188:191], v[8:11]
	v_mfma_f32_16x16x32_bf16 v[4:7], v[204:207], v[196:199], v[4:7]
	v_mfma_f32_16x16x32_bf16 v[0:3], v[212:215], v[196:199], v[0:3]
	v_mfma_f32_16x16x32_bf16 v[44:47], v[208:211], v[176:179], v[44:47]
	v_mfma_f32_16x16x32_bf16 v[40:43], v[216:219], v[176:179], v[40:43]
	v_mfma_f32_16x16x32_bf16 v[28:31], v[208:211], v[184:187], v[28:31]
	v_mfma_f32_16x16x32_bf16 v[24:27], v[216:219], v[184:187], v[24:27]
	v_mfma_f32_16x16x32_bf16 v[12:15], v[208:211], v[192:195], v[12:15]
	v_mfma_f32_16x16x32_bf16 v[8:11], v[216:219], v[192:195], v[8:11]
	v_mfma_f32_16x16x32_bf16 v[4:7], v[208:211], v[200:203], v[4:7]
	v_mfma_f32_16x16x32_bf16 v[0:3], v[216:219], v[200:203], v[0:3]
	s_setprio 0
	s_add_i32 s77, s77, 2
	s_add_u32 s34, s34, 0x100
	s_addc_u32 s35, s35, 0
	s_add_u32 s75, s75, 0x100
	s_addc_u32 s76, s76, 0
	s_cmp_gt_u32 s77, 61
	s_barrier
	s_cbranch_scc0 .LBB0_1384
	v_lshl_add_u32 v156, s18, 8, v150
	v_lshl_or_b32 v158, s72, 8, v152
	v_ashrrev_i32_e32 v157, 31, v156
	v_lshlrev_b64 v[160:161], 11, v[156:157]
	v_ashrrev_i32_e32 v159, 31, v158
	v_lshl_add_u64 v[160:161], s[44:45], 0, v[160:161]
	v_cvt_pk_bf16_f32 v124, v124, v125
	v_cvt_pk_bf16_f32 v125, v126, v127
	v_cvt_pk_bf16_f32 v126, v120, v121
	v_lshlrev_b64 v[120:121], 1, v[158:159]
	v_cvt_pk_bf16_f32 v127, v122, v123
	v_lshl_add_u64 v[122:123], v[160:161], 0, v[120:121]
	v_cvt_pk_bf16_f32 v108, v108, v109
	v_cvt_pk_bf16_f32 v109, v110, v111
	v_cvt_pk_bf16_f32 v110, v104, v105
	v_or_b32_e32 v104, 16, v156
	v_cvt_pk_bf16_f32 v60, v60, v61
	v_cvt_pk_bf16_f32 v61, v62, v63
	v_cvt_pk_bf16_f32 v63, v58, v59
	v_add_co_u32_e32 v58, vcc, s64, v122
	v_ashrrev_i32_e32 v105, 31, v104
	v_cvt_pk_bf16_f32 v62, v56, v57
	v_lshl_add_u64 v[56:57], v[122:123], 0, s[10:11]
	v_addc_co_u32_e32 v59, vcc, 0, v123, vcc
	v_cvt_pk_bf16_f32 v44, v44, v45
	v_cvt_pk_bf16_f32 v45, v46, v47
	v_cvt_pk_bf16_f32 v46, v40, v41
	v_cvt_pk_bf16_f32 v47, v42, v43
	v_cvt_pk_bf16_f32 v111, v106, v107
	v_lshlrev_b64 v[104:105], 11, v[104:105]
	v_cvt_pk_bf16_f32 v92, v92, v93
	v_cvt_pk_bf16_f32 v93, v94, v95
	v_cvt_pk_bf16_f32 v94, v88, v89
	v_or_b32_e32 v88, 32, v156
	global_store_dwordx4 v[56:57], v[44:47], off offset:256 sc1
	global_store_dwordx4 v[122:123], v[108:111], off offset:256 sc1
	v_ashrrev_i32_e32 v89, 31, v88
	v_add_co_u32_e32 v46, vcc, s65, v122
	v_lshl_add_u64 v[108:109], s[44:45], 0, v[104:105]
	v_lshl_add_u64 v[44:45], v[122:123], 0, s[12:13]
	v_addc_co_u32_e32 v47, vcc, 0, v123, vcc
	v_cvt_pk_bf16_f32 v28, v28, v29
	v_cvt_pk_bf16_f32 v29, v30, v31
	v_cvt_pk_bf16_f32 v30, v24, v25
	v_cvt_pk_bf16_f32 v31, v26, v27
	v_lshl_add_u64 v[108:109], v[108:109], 0, v[120:121]
	v_cvt_pk_bf16_f32 v95, v90, v91
	v_lshlrev_b64 v[88:89], 11, v[88:89]
	v_cvt_pk_bf16_f32 v76, v76, v77
	v_cvt_pk_bf16_f32 v77, v78, v79
	v_cvt_pk_bf16_f32 v78, v72, v73
	v_or_b32_e32 v72, 48, v156
	global_store_dwordx4 v[44:45], v[28:31], off offset:256 sc1
	global_store_dwordx4 v[108:109], v[92:95], off offset:256 sc1
	v_ashrrev_i32_e32 v73, 31, v72
	v_add_co_u32_e32 v30, vcc, s70, v122
	v_lshl_add_u64 v[92:93], s[44:45], 0, v[88:89]
	v_lshl_add_u64 v[28:29], v[122:123], 0, s[14:15]
	v_addc_co_u32_e32 v31, vcc, 0, v123, vcc
	v_cvt_pk_bf16_f32 v12, v12, v13
	v_cvt_pk_bf16_f32 v13, v14, v15
	v_cvt_pk_bf16_f32 v14, v8, v9
	v_cvt_pk_bf16_f32 v15, v10, v11
	v_lshl_add_u64 v[92:93], v[92:93], 0, v[120:121]
	v_cvt_pk_bf16_f32 v79, v74, v75
	v_lshlrev_b64 v[72:73], 11, v[72:73]
	global_store_dwordx4 v[28:29], v[12:15], off offset:256 sc1
	global_store_dwordx4 v[92:93], v[76:79], off offset:256 sc1
	v_cvt_pk_bf16_f32 v104, v116, v117
	v_add_co_u32_e32 v14, vcc, s71, v122
	v_lshl_add_u64 v[76:77], s[44:45], 0, v[72:73]
	s_nop 0
	v_addc_co_u32_e32 v15, vcc, 0, v123, vcc
	v_cvt_pk_bf16_f32 v105, v118, v119
	v_cvt_pk_bf16_f32 v106, v112, v113
	v_cvt_pk_bf16_f32 v107, v114, v115
	v_cvt_pk_bf16_f32 v88, v100, v101
	v_cvt_pk_bf16_f32 v89, v102, v103
	v_cvt_pk_bf16_f32 v90, v96, v97
	v_cvt_pk_bf16_f32 v91, v98, v99
	v_cvt_pk_bf16_f32 v72, v84, v85
	v_cvt_pk_bf16_f32 v73, v86, v87
	v_cvt_pk_bf16_f32 v74, v80, v81
	v_cvt_pk_bf16_f32 v75, v82, v83
	v_lshl_add_u64 v[76:77], v[76:77], 0, v[120:121]
	v_cvt_pk_bf16_f32 v68, v68, v69
	v_cvt_pk_bf16_f32 v69, v70, v71
	v_cvt_pk_bf16_f32 v70, v64, v65
	v_cvt_pk_bf16_f32 v71, v66, v67
	v_cvt_pk_bf16_f32 v40, v52, v53
	v_cvt_pk_bf16_f32 v41, v54, v55
	v_cvt_pk_bf16_f32 v42, v48, v49
	v_cvt_pk_bf16_f32 v43, v50, v51
	v_cvt_pk_bf16_f32 v24, v36, v37
	v_cvt_pk_bf16_f32 v25, v38, v39
	v_cvt_pk_bf16_f32 v26, v32, v33
	v_cvt_pk_bf16_f32 v27, v34, v35
	v_cvt_pk_bf16_f32 v8, v20, v21
	v_cvt_pk_bf16_f32 v9, v22, v23
	v_cvt_pk_bf16_f32 v10, v16, v17
	v_cvt_pk_bf16_f32 v11, v18, v19
	v_lshl_add_u64 v[12:13], v[122:123], 0, s[16:17]
	v_cvt_pk_bf16_f32 v4, v4, v5
	v_cvt_pk_bf16_f32 v5, v6, v7
	v_cvt_pk_bf16_f32 v6, v0, v1
	v_cvt_pk_bf16_f32 v7, v2, v3
	s_and_b64 vcc, exec, s[4:5]
	s_mov_b32 s72, s20
	s_mov_b32 s18, s26
	s_mov_b64 s[36:37], s[30:31]
	s_mov_b64 s[34:35], s[28:29]
	global_store_dwordx4 v[122:123], v[124:127], off sc1
	global_store_dwordx4 v[108:109], v[104:107], off sc1
	global_store_dwordx4 v[92:93], v[88:91], off sc1
	global_store_dwordx4 v[76:77], v[72:75], off sc1
	global_store_dwordx4 v[76:77], v[68:71], off offset:256 sc1
	global_store_dwordx4 v[58:59], v[60:63], off sc1
	global_store_dwordx4 v[46:47], v[40:43], off sc1
	global_store_dwordx4 v[30:31], v[24:27], off sc1
	global_store_dwordx4 v[14:15], v[8:11], off sc1
	global_store_dwordx4 v[12:13], v[4:7], off offset:256 sc1
	s_cbranch_vccz .LBB0_1381
	s_waitcnt vmcnt(0)
	s_cmpk_gt_u32 s40, 0xff
	s_cbranch_scc1 .LBB0_1388
	s_barrier

.LBB0_1456:
	s_or_b64 exec, exec, s[0:1]
	s_waitcnt vmcnt(7)
	v_and_b32_e32 v67, 0xffff0000, v56
	s_waitcnt vmcnt(6)
	v_and_b32_e32 v69, 0xffff0000, v54
	v_lshlrev_b32_e32 v66, 16, v56
	v_lshlrev_b32_e32 v68, 16, v54
	v_mov_b32_e32 v72, v67
	v_mov_b32_e32 v73, v69
	v_lshlrev_b32_e32 v56, 16, v57
	v_lshlrev_b32_e32 v54, 16, v55
	v_mov_b32_e32 v70, v66
	v_mov_b32_e32 v71, v68
	v_pk_mul_f32 v[72:73], v[72:73], v[72:73]
	v_and_b32_e32 v57, 0xffff0000, v57
	v_and_b32_e32 v55, 0xffff0000, v55
	v_pk_fma_f32 v[70:71], v[70:71], v[70:71], v[72:73]
	v_mov_b32_e32 v72, v56
	v_mov_b32_e32 v73, v54
	v_mov_b32_e32 v74, v57
	v_mov_b32_e32 v75, v55
	v_pk_fma_f32 v[70:71], v[72:73], v[72:73], v[70:71]
	s_waitcnt vmcnt(5)
	v_and_b32_e32 v73, 0xffff0000, v52
	v_pk_fma_f32 v[70:71], v[74:75], v[74:75], v[70:71]
	s_waitcnt vmcnt(4)
	v_and_b32_e32 v75, 0xffff0000, v50
	v_lshlrev_b32_e32 v72, 16, v52
	v_lshlrev_b32_e32 v74, 16, v50
	v_mov_b32_e32 v78, v73
	v_mov_b32_e32 v79, v75
	v_lshlrev_b32_e32 v52, 16, v53
	v_lshlrev_b32_e32 v50, 16, v51
	v_mov_b32_e32 v76, v72
	v_mov_b32_e32 v77, v74
	v_pk_mul_f32 v[78:79], v[78:79], v[78:79]
	v_and_b32_e32 v53, 0xffff0000, v53
	v_and_b32_e32 v51, 0xffff0000, v51
	v_pk_fma_f32 v[76:77], v[76:77], v[76:77], v[78:79]
	v_mov_b32_e32 v78, v52
	v_mov_b32_e32 v79, v50
	v_mov_b32_e32 v80, v53
	v_mov_b32_e32 v81, v51
	v_pk_fma_f32 v[76:77], v[78:79], v[78:79], v[76:77]
	v_add_f32_e32 v65, v70, v71
	v_pk_fma_f32 v[76:77], v[80:81], v[80:81], v[76:77]
	v_lshlrev_b64 v[40:41], 12, v[40:41]
	v_add_f32_e32 v65, v65, v76
	v_add_f32_e32 v65, v65, v77
	ds_bpermute_b32 v70, v58, v65
	s_waitcnt vmcnt(3)
	v_and_b32_e32 v71, 0xffff0000, v48
	s_waitcnt vmcnt(0)
	v_lshlrev_b32_e32 v82, 16, v42
	v_and_b32_e32 v83, 0xffff0000, v42
	v_lshlrev_b32_e32 v84, 16, v43
	s_waitcnt lgkmcnt(0)
	v_add_f32_e32 v65, v65, v70
	ds_bpermute_b32 v70, v59, v65
	v_and_b32_e32 v85, 0xffff0000, v43
	v_lshlrev_b32_e32 v78, 16, v46
	v_lshlrev_b32_e32 v80, 16, v44
	v_and_b32_e32 v81, 0xffff0000, v44
	s_waitcnt lgkmcnt(0)
	v_add_f32_e32 v65, v65, v70
	ds_bpermute_b32 v76, v60, v65
	v_lshlrev_b32_e32 v70, 16, v48
	v_lshlrev_b32_e32 v48, 16, v49
	v_and_b32_e32 v49, 0xffff0000, v49
	v_lshlrev_b32_e32 v44, 16, v45
	s_waitcnt lgkmcnt(0)
	v_add_f32_e32 v65, v65, v76
	ds_bpermute_b32 v79, v61, v65
	v_lshl_add_u64 v[76:77], v[20:21], 0, v[40:41]
	v_and_b32_e32 v45, 0xffff0000, v45
	s_waitcnt lgkmcnt(0)
	v_add_f32_e32 v40, v65, v79
	ds_bpermute_b32 v41, v62, v40
	v_and_b32_e32 v79, 0xffff0000, v46
	v_lshlrev_b32_e32 v46, 16, v47
	v_and_b32_e32 v47, 0xffff0000, v47
	s_waitcnt lgkmcnt(0)
	v_add_f32_e32 v40, v40, v41
	ds_bpermute_b32 v41, v63, v40
	s_waitcnt lgkmcnt(0)
	v_add_f32_e32 v40, v40, v41
	v_fmamk_f32 v40, v40, 0x3a800000, v64
	v_mul_f32_e32 v41, 0x4b800000, v40
	v_cmp_gt_f32_e64 s[0:1], s11, v40
	s_nop 1
	v_cndmask_b32_e64 v40, v40, v41, s[0:1]
	v_rsq_f32_e32 v40, v40
	s_nop 0
	v_mul_f32_e32 v41, 0x45800000, v40
	v_cndmask_b32_e64 v86, v40, v41, s[0:1]
	v_pk_mul_f32 v[40:41], v[86:87], v[66:67] op_sel_hi:[0,1]
	v_pk_mul_f32 v[42:43], v[86:87], v[56:57] op_sel_hi:[0,1]
	v_pk_fma_f32 v[40:41], v[12:13], v[40:41], v[70:71]
	v_pk_fma_f32 v[42:43], v[14:15], v[42:43], v[48:49]
	global_store_dwordx4 v[76:77], v[40:43], off sc1
	s_nop 1
	v_pk_mul_f32 v[40:41], v[86:87], v[68:69] op_sel_hi:[0,1]
	v_pk_mul_f32 v[42:43], v[86:87], v[54:55] op_sel_hi:[0,1]
	v_pk_fma_f32 v[40:41], v[4:5], v[40:41], v[78:79]
	v_pk_fma_f32 v[42:43], v[6:7], v[42:43], v[46:47]
	global_store_dwordx4 v[76:77], v[40:43], off offset:1024 sc1
	s_nop 1
	v_pk_mul_f32 v[40:41], v[86:87], v[72:73] op_sel_hi:[0,1]
	v_pk_mul_f32 v[42:43], v[86:87], v[52:53] op_sel_hi:[0,1]
	v_pk_fma_f32 v[40:41], v[0:1], v[40:41], v[80:81]
	v_pk_fma_f32 v[42:43], v[2:3], v[42:43], v[44:45]
	global_store_dwordx4 v[76:77], v[40:43], off offset:2048 sc1
	s_nop 1
	v_pk_mul_f32 v[40:41], v[86:87], v[74:75] op_sel_hi:[0,1]
	v_pk_mul_f32 v[42:43], v[86:87], v[50:51] op_sel_hi:[0,1]
	v_pk_fma_f32 v[40:41], v[8:9], v[40:41], v[82:83]
	v_pk_fma_f32 v[42:43], v[10:11], v[42:43], v[84:85]
	global_store_dwordx4 v[76:77], v[40:43], off offset:3072 sc1
	s_and_saveexec_b64 s[0:1], vcc
	s_cbranch_execz .LBB0_1453
	v_and_b32_e32 v41, 0xffff0000, v22
	v_and_b32_e32 v45, 0xffff0000, v24
	v_lshlrev_b32_e32 v40, 16, v22
	v_lshlrev_b32_e32 v44, 16, v24
	v_mov_b32_e32 v50, v45
	v_mov_b32_e32 v51, v41
	v_lshlrev_b32_e32 v42, 16, v23
	v_lshlrev_b32_e32 v46, 16, v25
	v_mov_b32_e32 v48, v44
	v_mov_b32_e32 v49, v40
	v_pk_mul_f32 v[50:51], v[50:51], v[50:51]
	v_and_b32_e32 v43, 0xffff0000, v23
	v_pk_fma_f32 v[48:49], v[48:49], v[48:49], v[50:51]
	v_mov_b32_e32 v50, v46
	v_mov_b32_e32 v51, v42
	v_and_b32_e32 v47, 0xffff0000, v25
	v_pk_fma_f32 v[48:49], v[50:51], v[50:51], v[48:49]
	v_and_b32_e32 v51, 0xffff0000, v26
	v_and_b32_e32 v55, 0xffff0000, v36
	v_mov_b32_e32 v52, v47
	v_mov_b32_e32 v53, v43
	v_lshlrev_b32_e32 v50, 16, v26
	v_lshlrev_b32_e32 v54, 16, v36
	v_mov_b32_e32 v68, v51
	v_mov_b32_e32 v69, v55
	v_pk_fma_f32 v[48:49], v[52:53], v[52:53], v[48:49]
	v_lshlrev_b32_e32 v52, 16, v27
	v_lshlrev_b32_e32 v56, 16, v37
	v_mov_b32_e32 v66, v50
	v_mov_b32_e32 v67, v54
	v_pk_mul_f32 v[68:69], v[68:69], v[68:69]
	v_and_b32_e32 v53, 0xffff0000, v27
	v_and_b32_e32 v57, 0xffff0000, v37
	v_pk_fma_f32 v[66:67], v[66:67], v[66:67], v[68:69]
	v_mov_b32_e32 v68, v52
	v_mov_b32_e32 v69, v56
	v_mov_b32_e32 v70, v53
	v_mov_b32_e32 v71, v57
	v_pk_fma_f32 v[66:67], v[68:69], v[68:69], v[66:67]
	v_add_f32_e32 v48, v48, v49
	v_pk_fma_f32 v[66:67], v[70:71], v[70:71], v[66:67]
	v_and_b32_e32 v69, 0xffff0000, v35
	v_add_f32_e32 v48, v48, v66
	v_add_f32_e32 v48, v48, v67
	ds_bpermute_b32 v49, v58, v48
	v_lshlrev_b32_e32 v66, 16, v34
	v_and_b32_e32 v67, 0xffff0000, v34
	v_lshlrev_b32_e32 v70, 16, v32
	v_and_b32_e32 v71, 0xffff0000, v32
	s_waitcnt lgkmcnt(0)
	v_add_f32_e32 v48, v48, v49
	ds_bpermute_b32 v49, v59, v48
	v_lshlrev_b32_e32 v72, 16, v33
	v_and_b32_e32 v73, 0xffff0000, v33
	v_lshlrev_b32_e32 v74, 16, v30
	v_and_b32_e32 v75, 0xffff0000, v30
	s_waitcnt lgkmcnt(0)
	v_add_f32_e32 v65, v48, v49
	ds_bpermute_b32 v68, v60, v65
	v_lshlrev_b64 v[48:49], 12, v[38:39]
	v_lshl_add_u64 v[48:49], v[20:21], 0, v[48:49]
	v_lshlrev_b32_e32 v76, 16, v31
	v_and_b32_e32 v77, 0xffff0000, v31
	s_waitcnt lgkmcnt(0)
	v_add_f32_e32 v39, v65, v68
	ds_bpermute_b32 v65, v61, v39
	v_lshlrev_b32_e32 v68, 16, v35
	v_lshlrev_b32_e32 v78, 16, v28
	v_and_b32_e32 v79, 0xffff0000, v28
	v_lshlrev_b32_e32 v80, 16, v29
	s_waitcnt lgkmcnt(0)
	v_add_f32_e32 v39, v39, v65
	ds_bpermute_b32 v65, v62, v39
	v_and_b32_e32 v81, 0xffff0000, v29
	s_waitcnt lgkmcnt(0)
	v_add_f32_e32 v39, v39, v65
	ds_bpermute_b32 v65, v63, v39
	s_waitcnt lgkmcnt(0)
	v_add_f32_e32 v39, v39, v65
	v_fmamk_f32 v39, v39, 0x3a800000, v64
	v_mul_f32_e32 v65, 0x4b800000, v39
	v_cmp_gt_f32_e32 vcc, s11, v39
	s_nop 1
	v_cndmask_b32_e32 v39, v39, v65, vcc
	v_rsq_f32_e32 v39, v39
	s_nop 0
	v_mul_f32_e32 v65, 0x45800000, v39
	v_cndmask_b32_e32 v82, v39, v65, vcc
	v_pk_mul_f32 v[40:41], v[82:83], v[40:41] op_sel_hi:[0,1]
	v_pk_mul_f32 v[42:43], v[82:83], v[42:43] op_sel_hi:[0,1]
	v_pk_fma_f32 v[40:41], v[12:13], v[40:41], v[66:67]
	v_pk_fma_f32 v[42:43], v[14:15], v[42:43], v[68:69]
	global_store_dwordx4 v[48:49], v[40:43], off sc1
	s_nop 1
	v_pk_mul_f32 v[40:41], v[82:83], v[44:45] op_sel_hi:[0,1]
	v_pk_mul_f32 v[42:43], v[82:83], v[46:47] op_sel_hi:[0,1]
	v_pk_fma_f32 v[40:41], v[4:5], v[40:41], v[70:71]
	v_pk_fma_f32 v[42:43], v[6:7], v[42:43], v[72:73]
	global_store_dwordx4 v[48:49], v[40:43], off offset:1024 sc1
	s_nop 1
	v_pk_mul_f32 v[40:41], v[82:83], v[50:51] op_sel_hi:[0,1]
	v_pk_mul_f32 v[42:43], v[82:83], v[52:53] op_sel_hi:[0,1]
	v_pk_fma_f32 v[40:41], v[0:1], v[40:41], v[74:75]
	v_pk_fma_f32 v[42:43], v[2:3], v[42:43], v[76:77]
	global_store_dwordx4 v[48:49], v[40:43], off offset:2048 sc1
	s_nop 1
	v_pk_mul_f32 v[40:41], v[82:83], v[54:55] op_sel_hi:[0,1]
	v_pk_mul_f32 v[42:43], v[82:83], v[56:57] op_sel_hi:[0,1]
	v_pk_fma_f32 v[40:41], v[8:9], v[40:41], v[78:79]
	v_pk_fma_f32 v[42:43], v[10:11], v[42:43], v[80:81]
	global_store_dwordx4 v[48:49], v[40:43], off offset:3072 sc1
	s_branch .LBB0_1453
